# speedup vs baseline: 1.0294x; 1.0210x over previous
; #define WAIT_V(n) asm volatile("s_waitcnt vmcnt(" #n ")" ::: "memory")
; #define BAR __builtin_amdgcn_s_barrier()
; template <bool SWAP>
; __device__ __forceinline__ void gemm_main(const u16* __restrict__ A, const u16* __restrict__ Bt, int brow, int bcol,
;                                           u16* shm, f32x4 (&acc)[2][2][4][2]) {
;     ...
;   int tx = threadIdx.x; asm volatile("" : "+v"(tx));
;   const int wid = tx >> 6, lane = tx & 63, wr = wid >> 2, wc = wid & 3, fr = lane & 15, fq = lane >> 4;
; #pragma unroll
;   for (int a = 0; a < 2; ++a)
; #pragma unroll
;     for (int b = 0; b < 2; ++b)
; #pragma unroll
;       for (int m = 0; m < 4; ++m)
; #pragma unroll
;         for (int n = 0; n < 2; ++n) acc[a][b][m][n] = f32x4{0.f, 0.f, 0.f, 0.f};
;   bf16x8 At[4][2], B0[2][2], B1[2][2];
;   constexpr int nt = GK / BK;
;   GEMM_VOFF
;   const int lpart = (fr * 64 + fq * 16) ^ ((fr >> 3) << 5);
;   const int abase = wr * 8192 + lpart; int bbase = 65536 + wc * 4096 + lpart;
;   asm volatile("" : "+v"(bbase));
;   if (wr == 1) BAR;
;   WAIT_V(0); BAR;
;   BAR;
.LBB0_83:
	s_or_b64 exec, exec, s[26:27]
	v_bfe_i32 v4, v144, 27, 1
	v_lshlrev_b32_e32 v146, 4, v144
	v_lshrrev_b32_e32 v4, 22, v4
	v_add_u32_e32 v4, v146, v4
	v_and_b32_e32 v4, 0xfffffc00, v4
	v_sub_u32_e32 v4, v146, v4
	v_lshrrev_b32_e32 v5, 4, v4
	v_bitop3_b32 v4, v5, v4, 32 bitop3:0x6c
	v_ashrrev_i32_e32 v5, 31, v4
	v_lshrrev_b32_e32 v5, 26, v5
	v_add_u32_e32 v5, v4, v5
	v_ashrrev_i32_e32 v148, 6, v5
	v_and_b32_e32 v5, 0xc0, v5
	v_sub_u32_e32 v4, v4, v5
	v_ashrrev_i16_sdwa v4, v139, sext(v4) dst_sel:DWORD dst_unused:UNUSED_PAD src0_sel:DWORD src1_sel:BYTE_0
	v_bfe_i32 v149, v4, 0, 16
	v_add_u32_e32 v4, 0x2000, v146
	v_ashrrev_i32_e32 v5, 31, v4
	v_lshrrev_b32_e32 v5, 22, v5
	v_add_u32_e32 v5, v4, v5
	v_ashrrev_i32_e32 v150, 10, v5
	v_mul_i32_i24_e32 v5, 0x400, v150
	v_sub_u32_e32 v4, v4, v5
	v_lshrrev_b32_e32 v5, 4, v4
	v_bitop3_b32 v4, v5, v4, 32 bitop3:0x6c
	v_ashrrev_i32_e32 v5, 31, v4
	v_lshrrev_b32_e32 v5, 26, v5
	v_ashrrev_i32_e32 v3, 31, v144
	v_add_u32_e32 v5, v4, v5
	v_lshrrev_b32_e32 v3, 26, v3
	v_ashrrev_i32_e32 v151, 6, v5
	v_and_b32_e32 v5, 0xc0, v5
	v_add_u32_e32 v3, v144, v3
	v_sub_u32_e32 v4, v4, v5
	v_ashrrev_i32_e32 v147, 6, v3
	v_ashrrev_i16_sdwa v4, v139, sext(v4) dst_sel:DWORD dst_unused:UNUSED_PAD src0_sel:DWORD src1_sel:BYTE_0
	v_bfe_i32 v152, v4, 0, 16
	v_lshlrev_b32_e32 v4, 13, v0
	v_lshlrev_b32_e32 v0, 15, v147
	v_and_b32_e32 v0, 0xffff0000, v0
	v_lshl_add_u32 v0, v148, 12, v0
	v_and_or_b32 v0, v3, 64, v0
	v_lshl_add_u32 v128, v149, 1, v0
	v_lshlrev_b32_e32 v0, 15, v150
	v_and_b32_e32 v0, 0xffff0000, v0
	v_add_u32_e32 v5, 0, v2
	v_lshl_add_u32 v0, v151, 12, v0
	v_lshlrev_b32_e32 v2, 6, v150
	s_waitcnt vmcnt(0)
	s_lshl_b32 s26, s28, 19
	s_mov_b32 s27, s5
	v_and_or_b32 v0, v2, 64, v0
	s_lshl_b32 s4, s25, 20
	s_lshl_b64 s[26:27], s[26:27], 1
	v_lshl_add_u32 v2, v152, 1, v0
	v_mov_b32_e32 v3, v129
	v_mov_b32_e32 v0, 0
	v_lshl_add_u64 v[130:131], s[26:27], 0, v[128:129]
	v_lshl_add_u64 v[132:133], s[26:27], 0, v[2:3]
	v_lshl_add_u64 v[134:135], v[128:129], 0, s[4:5]
	v_lshl_add_u64 v[136:137], v[2:3], 0, s[4:5]
	s_mov_b32 s28, -2
	v_add_u32_e32 v145, 0, v1
	v_add_u32_e32 v128, v5, v4
	s_mov_b64 s[26:27], s[50:51]
	v_mov_b32_e32 v1, v0
	v_mov_b32_e32 v2, v0
	v_mov_b32_e32 v3, v0
	v_mov_b32_e32 v4, v0
	v_mov_b32_e32 v5, v0
	v_mov_b32_e32 v6, v0
	v_mov_b32_e32 v7, v0
	v_mov_b32_e32 v8, v0
	v_mov_b32_e32 v9, v0
	v_mov_b32_e32 v10, v0
	v_mov_b32_e32 v11, v0
	v_mov_b32_e32 v12, v0
	v_mov_b32_e32 v13, v0
	v_mov_b32_e32 v14, v0
	v_mov_b32_e32 v15, v0
	v_mov_b32_e32 v16, v0
	v_mov_b32_e32 v17, v0
	v_mov_b32_e32 v18, v0
	v_mov_b32_e32 v19, v0
	v_mov_b32_e32 v20, v0
	v_mov_b32_e32 v21, v0
	v_mov_b32_e32 v22, v0
	v_mov_b32_e32 v23, v0
	v_mov_b32_e32 v24, v0
	v_mov_b32_e32 v25, v0
	v_mov_b32_e32 v26, v0
	v_mov_b32_e32 v27, v0
	v_mov_b32_e32 v28, v0
	v_mov_b32_e32 v29, v0
	v_mov_b32_e32 v30, v0
	v_mov_b32_e32 v31, v0
	v_mov_b32_e32 v32, v0
	v_mov_b32_e32 v33, v0
	v_mov_b32_e32 v34, v0
	v_mov_b32_e32 v35, v0
	v_mov_b32_e32 v36, v0
	v_mov_b32_e32 v37, v0
	v_mov_b32_e32 v38, v0
	v_mov_b32_e32 v39, v0
	v_mov_b32_e32 v40, v0
	v_mov_b32_e32 v41, v0
	v_mov_b32_e32 v42, v0
	v_mov_b32_e32 v43, v0
	v_mov_b32_e32 v44, v0
	v_mov_b32_e32 v45, v0
	v_mov_b32_e32 v46, v0
	v_mov_b32_e32 v47, v0
	v_mov_b32_e32 v48, v0
	v_mov_b32_e32 v49, v0
	v_mov_b32_e32 v50, v0
	v_mov_b32_e32 v51, v0
	v_mov_b32_e32 v52, v0
	v_mov_b32_e32 v53, v0
	v_mov_b32_e32 v54, v0
	v_mov_b32_e32 v55, v0
	v_mov_b32_e32 v56, v0
	v_mov_b32_e32 v57, v0
	v_mov_b32_e32 v58, v0
	v_mov_b32_e32 v59, v0
	v_mov_b32_e32 v60, v0
	v_mov_b32_e32 v61, v0
	v_mov_b32_e32 v62, v0
	v_mov_b32_e32 v63, v0
	v_mov_b32_e32 v64, v0
	v_mov_b32_e32 v65, v0
	v_mov_b32_e32 v66, v0
	v_mov_b32_e32 v67, v0
	v_mov_b32_e32 v68, v0
	v_mov_b32_e32 v69, v0
	v_mov_b32_e32 v70, v0
	v_mov_b32_e32 v71, v0
	v_mov_b32_e32 v72, v0
	v_mov_b32_e32 v73, v0
	v_mov_b32_e32 v74, v0
	v_mov_b32_e32 v75, v0
	v_mov_b32_e32 v76, v0
	v_mov_b32_e32 v77, v0
	v_mov_b32_e32 v78, v0
	v_mov_b32_e32 v79, v0
	v_mov_b32_e32 v80, v0
	v_mov_b32_e32 v81, v0
	v_mov_b32_e32 v82, v0
	v_mov_b32_e32 v83, v0
	v_mov_b32_e32 v84, v0
	v_mov_b32_e32 v85, v0
	v_mov_b32_e32 v86, v0
	v_mov_b32_e32 v87, v0
	v_mov_b32_e32 v88, v0
	v_mov_b32_e32 v89, v0
	v_mov_b32_e32 v90, v0
	v_mov_b32_e32 v91, v0
	v_mov_b32_e32 v92, v0
	v_mov_b32_e32 v93, v0
	v_mov_b32_e32 v94, v0
	v_mov_b32_e32 v95, v0
	v_mov_b32_e32 v96, v0
	v_mov_b32_e32 v97, v0
	v_mov_b32_e32 v98, v0
	v_mov_b32_e32 v99, v0
	v_mov_b32_e32 v100, v0
	v_mov_b32_e32 v101, v0
	v_mov_b32_e32 v102, v0
	v_mov_b32_e32 v103, v0
	v_mov_b32_e32 v104, v0
	v_mov_b32_e32 v105, v0
	v_mov_b32_e32 v106, v0
	v_mov_b32_e32 v107, v0
	v_mov_b32_e32 v108, v0
	v_mov_b32_e32 v109, v0
	v_mov_b32_e32 v110, v0
	v_mov_b32_e32 v111, v0
	v_mov_b32_e32 v112, v0
	v_mov_b32_e32 v113, v0
	v_mov_b32_e32 v114, v0
	v_mov_b32_e32 v115, v0
	v_mov_b32_e32 v116, v0
	v_mov_b32_e32 v117, v0
	v_mov_b32_e32 v118, v0
	v_mov_b32_e32 v119, v0
	v_mov_b32_e32 v120, v0
	v_mov_b32_e32 v121, v0
	v_mov_b32_e32 v122, v0
	v_mov_b32_e32 v123, v0
	v_mov_b32_e32 v124, v0
	v_mov_b32_e32 v125, v0
	v_mov_b32_e32 v126, v0
	v_mov_b32_e32 v127, v0
	v_readfirstlane_b32 s29, v146
	s_barrier
	s_barrier
; #define WAIT_L(n) asm volatile("s_waitcnt lgkmcnt(" #n ")" ::: "memory")
; #define BAR __builtin_amdgcn_s_barrier()
; #define SCHED __builtin_amdgcn_sched_barrier(0)
; #define STAGE(P, BASE, br, kt) do { const char* _g = (const char*)((BASE) + (size_t)(br) * GK + (kt) * BK); \
;     __builtin_amdgcn_global_load_lds((const unsigned*)(_g + voff0), (unsigned*)((char*)(P) + tx * 16), 16, 0, 0); \
;     __builtin_amdgcn_global_load_lds((const unsigned*)(_g + voff1), (unsigned*)((char*)(P) + tx * 16 + 8192), 16, 0, 0); } while (0)
; #define LDA(dst, b, h) _Pragma("unroll") for (int m = 0; m < 4; ++m) _Pragma("unroll") for (int k = 0; k < 2; ++k) \
;     dst[m][k] = *reinterpret_cast<const bf16x8*>((char*)shm + abase + (((b) * 2 + (h)) * 16384 + (m * 2 + k) * 1024))
; #define LDB(dst, b, h) _Pragma("unroll") for (int n = 0; n < 2; ++n) _Pragma("unroll") for (int k = 0; k < 2; ++k) \
;     dst[n][k] = *reinterpret_cast<const bf16x8*>((char*)shm + bbase + (((b) * 2 + (h)) * 16384 + (n * 2 + k) * 1024))
; template <bool SWAP>
; __device__ __forceinline__ void gemm_main(const u16* __restrict__ A, const u16* __restrict__ Bt, int brow, int bcol,
;                                           u16* shm, f32x4 (&acc)[2][2][4][2]) {
;     ...
;   for (int t = 0; t < nt - 2; t += 2) {
;     LDB(B0, 0, 0); SCHED; LDA(At, 0, 0); STAGE(SA(1, 1), A, brow + HALF, t + 1);
;     WAIT_L(8); BAR; WAIT_L(0); MMA(0, 0, At, B0); BAR; SCHED;
;     LDB(B1, 0, 1); STAGE(SB(0, 0), Bt, bcol, t + 2);
;     BAR; WAIT_L(0); MMA(0, 1, At, B1); BAR;
;     LDA(At, 0, 1); STAGE(SA(0, 0), A, brow, t + 2);
.LBB0_84:
	ds_read_b128 v[156:159], v145
	ds_read_b128 v[160:163], v145 offset:1024
	ds_read_b128 v[164:167], v145 offset:2048
	ds_read_b128 v[168:171], v145 offset:3072
	ds_read_b128 v[172:175], v128
	ds_read_b128 v[176:179], v128 offset:1024
	ds_read_b128 v[180:183], v128 offset:2048
	ds_read_b128 v[184:187], v128 offset:3072
	ds_read_b128 v[188:191], v128 offset:4096
	ds_read_b128 v[192:195], v128 offset:5120
	ds_read_b128 v[196:199], v128 offset:6144
	ds_read_b128 v[200:203], v128 offset:7168
	v_add_u32_e32 v211, 0, v146
	v_add_u32_e32 v153, 0xc000, v211
	v_lshl_add_u64 v[208:209], s[26:27], 0, v[134:135]
	v_lshl_add_u64 v[154:155], v[208:209], 0, s[6:7]
	s_add_u32 m0, s29, 0xc000
	s_nop 0
	global_load_lds_dwordx4 v[154:155], off
	v_add_u32_e32 v154, 0xe000, v211
	v_lshl_add_u64 v[224:225], s[26:27], 0, v[136:137]
	v_lshl_add_u64 v[204:205], v[224:225], 0, s[6:7]
	s_add_u32 m0, s29, 0xe000
	s_nop 0
	global_load_lds_dwordx4 v[204:205], off
	s_waitcnt lgkmcnt(8)
	s_setprio 1
	s_barrier
	s_waitcnt lgkmcnt(0)
	v_mfma_f32_16x16x32_bf16 v[124:127], v[172:175], v[156:159], v[124:127]
	v_mfma_f32_16x16x32_bf16 v[120:123], v[172:175], v[164:167], v[120:123]
	v_mfma_f32_16x16x32_bf16 v[116:119], v[180:183], v[156:159], v[116:119]
	v_mfma_f32_16x16x32_bf16 v[112:115], v[180:183], v[164:167], v[112:115]
	v_mfma_f32_16x16x32_bf16 v[108:111], v[188:191], v[156:159], v[108:111]
	v_mfma_f32_16x16x32_bf16 v[104:107], v[188:191], v[164:167], v[104:107]
	v_mfma_f32_16x16x32_bf16 v[100:103], v[196:199], v[156:159], v[100:103]
	v_mfma_f32_16x16x32_bf16 v[96:99], v[196:199], v[164:167], v[96:99]
	v_mfma_f32_16x16x32_bf16 v[124:127], v[176:179], v[160:163], v[124:127]
	v_mfma_f32_16x16x32_bf16 v[120:123], v[176:179], v[168:171], v[120:123]
	v_mfma_f32_16x16x32_bf16 v[116:119], v[184:187], v[160:163], v[116:119]
	v_mfma_f32_16x16x32_bf16 v[112:115], v[184:187], v[168:171], v[112:115]
	v_mfma_f32_16x16x32_bf16 v[108:111], v[192:195], v[160:163], v[108:111]
	v_mfma_f32_16x16x32_bf16 v[104:107], v[192:195], v[168:171], v[104:107]
	v_mfma_f32_16x16x32_bf16 v[100:103], v[200:203], v[160:163], v[100:103]
	v_mfma_f32_16x16x32_bf16 v[96:99], v[200:203], v[168:171], v[96:99]
	s_barrier
	s_setprio 0
	ds_read_b128 v[204:207], v145 offset:16384
	ds_read_b128 v[212:215], v145 offset:17408
	ds_read_b128 v[216:219], v145 offset:18432
	ds_read_b128 v[220:223], v145 offset:19456
	v_lshl_add_u64 v[226:227], s[26:27], 0, v[130:131]
	v_lshl_add_u64 v[228:229], v[226:227], 0, s[8:9]
	s_add_u32 m0, s29, s44
	s_nop 0
	global_load_lds_dwordx4 v[228:229], off
	v_lshl_add_u64 v[228:229], s[26:27], 0, v[132:133]
	v_lshl_add_u64 v[230:231], v[228:229], 0, s[8:9]
	s_add_u32 m0, s29, s44
	s_add_u32 m0, m0, 0x2000
	s_nop 0
	global_load_lds_dwordx4 v[230:231], off
	s_setprio 1
	s_barrier
	s_waitcnt lgkmcnt(0)
	v_mfma_f32_16x16x32_bf16 v[92:95], v[172:175], v[204:207], v[92:95]
	v_mfma_f32_16x16x32_bf16 v[88:91], v[172:175], v[216:219], v[88:91]
	v_mfma_f32_16x16x32_bf16 v[84:87], v[180:183], v[204:207], v[84:87]
	v_mfma_f32_16x16x32_bf16 v[80:83], v[180:183], v[216:219], v[80:83]
	v_mfma_f32_16x16x32_bf16 v[76:79], v[188:191], v[204:207], v[76:79]
	v_mfma_f32_16x16x32_bf16 v[72:75], v[188:191], v[216:219], v[72:75]
	v_mfma_f32_16x16x32_bf16 v[68:71], v[196:199], v[204:207], v[68:71]
	v_mfma_f32_16x16x32_bf16 v[64:67], v[196:199], v[216:219], v[64:67]
	v_mfma_f32_16x16x32_bf16 v[92:95], v[176:179], v[212:215], v[92:95]
	v_mfma_f32_16x16x32_bf16 v[88:91], v[176:179], v[220:223], v[88:91]
	v_mfma_f32_16x16x32_bf16 v[84:87], v[184:187], v[212:215], v[84:87]
	v_mfma_f32_16x16x32_bf16 v[80:83], v[184:187], v[220:223], v[80:83]
	v_mfma_f32_16x16x32_bf16 v[76:79], v[192:195], v[212:215], v[76:79]
	v_mfma_f32_16x16x32_bf16 v[72:75], v[192:195], v[220:223], v[72:75]
	v_mfma_f32_16x16x32_bf16 v[68:71], v[200:203], v[212:215], v[68:71]
	v_mfma_f32_16x16x32_bf16 v[64:67], v[200:203], v[220:223], v[64:67]
	s_barrier
	s_setprio 0
	ds_read_b128 v[172:175], v128 offset:16384
	ds_read_b128 v[176:179], v128 offset:17408
	ds_read_b128 v[180:183], v128 offset:18432
	ds_read_b128 v[184:187], v128 offset:19456
	ds_read_b128 v[188:191], v128 offset:20480
	ds_read_b128 v[192:195], v128 offset:21504
	ds_read_b128 v[196:199], v128 offset:22528
	ds_read_b128 v[200:203], v128 offset:23552
	v_lshl_add_u64 v[230:231], v[208:209], 0, s[10:11]
	s_add_u32 m0, s29, 0x0
	s_nop 0
	global_load_lds_dwordx4 v[230:231], off
	v_lshl_add_u64 v[230:231], v[224:225], 0, s[10:11]
	s_add_u32 m0, s29, 0x2000
	s_nop 0
	global_load_lds_dwordx4 v[230:231], off
	s_setprio 1
	s_barrier
	s_waitcnt lgkmcnt(0)
	v_mfma_f32_16x16x32_bf16 v[60:63], v[172:175], v[156:159], v[60:63]
	v_mfma_f32_16x16x32_bf16 v[56:59], v[172:175], v[164:167], v[56:59]
	v_mfma_f32_16x16x32_bf16 v[52:55], v[180:183], v[156:159], v[52:55]
	v_mfma_f32_16x16x32_bf16 v[48:51], v[180:183], v[164:167], v[48:51]
	v_mfma_f32_16x16x32_bf16 v[44:47], v[188:191], v[156:159], v[44:47]
	v_mfma_f32_16x16x32_bf16 v[40:43], v[188:191], v[164:167], v[40:43]
	v_mfma_f32_16x16x32_bf16 v[36:39], v[196:199], v[156:159], v[36:39]
	v_mfma_f32_16x16x32_bf16 v[32:35], v[196:199], v[164:167], v[32:35]
	v_mfma_f32_16x16x32_bf16 v[60:63], v[176:179], v[160:163], v[60:63]
	v_mfma_f32_16x16x32_bf16 v[56:59], v[176:179], v[168:171], v[56:59]
	v_mfma_f32_16x16x32_bf16 v[52:55], v[184:187], v[160:163], v[52:55]
	v_mfma_f32_16x16x32_bf16 v[48:51], v[184:187], v[168:171], v[48:51]
	v_mfma_f32_16x16x32_bf16 v[44:47], v[192:195], v[160:163], v[44:47]
	v_mfma_f32_16x16x32_bf16 v[40:43], v[192:195], v[168:171], v[40:43]
	v_mfma_f32_16x16x32_bf16 v[36:39], v[200:203], v[160:163], v[36:39]
	v_mfma_f32_16x16x32_bf16 v[32:35], v[200:203], v[168:171], v[32:35]
	s_barrier
; #define WAIT_V(n) asm volatile("s_waitcnt vmcnt(" #n ")" ::: "memory")
; #define WAIT_L(n) asm volatile("s_waitcnt lgkmcnt(" #n ")" ::: "memory")
; #define BAR __builtin_amdgcn_s_barrier()
; #define SCHED __builtin_amdgcn_sched_barrier(0)
; #define STAGE(P, BASE, br, kt) do { const char* _g = (const char*)((BASE) + (size_t)(br) * GK + (kt) * BK); \
;     __builtin_amdgcn_global_load_lds((const unsigned*)(_g + voff0), (unsigned*)((char*)(P) + tx * 16), 16, 0, 0); \
;     __builtin_amdgcn_global_load_lds((const unsigned*)(_g + voff1), (unsigned*)((char*)(P) + tx * 16 + 8192), 16, 0, 0); } while (0)
; #define LDA(dst, b, h) _Pragma("unroll") for (int m = 0; m < 4; ++m) _Pragma("unroll") for (int k = 0; k < 2; ++k) \
;     dst[m][k] = *reinterpret_cast<const bf16x8*>((char*)shm + abase + (((b) * 2 + (h)) * 16384 + (m * 2 + k) * 1024))
; #define LDB(dst, b, h) _Pragma("unroll") for (int n = 0; n < 2; ++n) _Pragma("unroll") for (int k = 0; k < 2; ++k) \
;     dst[n][k] = *reinterpret_cast<const bf16x8*>((char*)shm + bbase + (((b) * 2 + (h)) * 16384 + (n * 2 + k) * 1024))
; template <bool SWAP>
; __device__ __forceinline__ void gemm_main(const u16* __restrict__ A, const u16* __restrict__ Bt, int brow, int bcol,
;                                           u16* shm, f32x4 (&acc)[2][2][4][2]) {
;     ...
;     BAR; WAIT_L(0); MMA(1, 0, At, B0); BAR; SCHED;
;     STAGE(SB(0, 1), Bt, bcol + HALF, t + 2);
;     WAIT_V(6); BAR; MMA(1, 1, At, B1); BAR;
;     LDB(B0, 1, 0); SCHED; LDA(At, 1, 0); STAGE(SA(0, 1), A, brow + HALF, t + 2);
;     WAIT_L(8); BAR; WAIT_L(0); MMA(0, 0, At, B0); BAR; SCHED;
;     LDB(B1, 1, 1); STAGE(SB(1, 0), Bt, bcol, t + 3);
	s_setprio 0
	v_lshl_add_u64 v[156:157], v[226:227], 0, s[12:13]
	s_add_u32 m0, s29, s45
	s_nop 0
	global_load_lds_dwordx4 v[156:157], off
	v_lshl_add_u64 v[156:157], v[228:229], 0, s[12:13]
	s_add_u32 m0, s29, s45
	s_add_u32 m0, m0, 0x2000
	s_nop 0
	global_load_lds_dwordx4 v[156:157], off
	s_waitcnt vmcnt(6)
	s_setprio 1
	s_barrier
	v_mfma_f32_16x16x32_bf16 v[28:31], v[172:175], v[204:207], v[28:31]
	v_mfma_f32_16x16x32_bf16 v[24:27], v[172:175], v[216:219], v[24:27]
	v_mfma_f32_16x16x32_bf16 v[20:23], v[180:183], v[204:207], v[20:23]
	v_mfma_f32_16x16x32_bf16 v[16:19], v[180:183], v[216:219], v[16:19]
	v_mfma_f32_16x16x32_bf16 v[12:15], v[188:191], v[204:207], v[12:15]
	v_mfma_f32_16x16x32_bf16 v[8:11], v[188:191], v[216:219], v[8:11]
	v_mfma_f32_16x16x32_bf16 v[4:7], v[196:199], v[204:207], v[4:7]
	v_mfma_f32_16x16x32_bf16 v[0:3], v[196:199], v[216:219], v[0:3]
	v_mfma_f32_16x16x32_bf16 v[28:31], v[176:179], v[212:215], v[28:31]
	v_mfma_f32_16x16x32_bf16 v[24:27], v[176:179], v[220:223], v[24:27]
	v_mfma_f32_16x16x32_bf16 v[20:23], v[184:187], v[212:215], v[20:23]
	v_mfma_f32_16x16x32_bf16 v[16:19], v[184:187], v[220:223], v[16:19]
	v_mfma_f32_16x16x32_bf16 v[12:15], v[192:195], v[212:215], v[12:15]
	v_mfma_f32_16x16x32_bf16 v[8:11], v[192:195], v[220:223], v[8:11]
	v_mfma_f32_16x16x32_bf16 v[4:7], v[200:203], v[212:215], v[4:7]
	v_mfma_f32_16x16x32_bf16 v[0:3], v[200:203], v[220:223], v[0:3]
	s_barrier
	s_setprio 0
	ds_read_b128 v[156:159], v145 offset:32768
	ds_read_b128 v[160:163], v145 offset:33792
	ds_read_b128 v[164:167], v145 offset:34816
	ds_read_b128 v[168:171], v145 offset:35840
	ds_read_b128 v[172:175], v128 offset:32768
	ds_read_b128 v[176:179], v128 offset:33792
	ds_read_b128 v[180:183], v128 offset:34816
	ds_read_b128 v[184:187], v128 offset:35840
	ds_read_b128 v[188:191], v128 offset:36864
	ds_read_b128 v[192:195], v128 offset:37888
	ds_read_b128 v[196:199], v128 offset:38912
	ds_read_b128 v[200:203], v128 offset:39936
	v_lshl_add_u64 v[204:205], v[208:209], 0, s[14:15]
	s_add_u32 m0, s29, 0x4000
	s_nop 0
	global_load_lds_dwordx4 v[204:205], off
	v_lshl_add_u64 v[204:205], v[224:225], 0, s[14:15]
	s_add_u32 m0, s29, 0x6000
	s_nop 0
	global_load_lds_dwordx4 v[204:205], off
	s_waitcnt lgkmcnt(8)
	s_setprio 1
	s_barrier
	s_waitcnt lgkmcnt(0)
	v_mfma_f32_16x16x32_bf16 v[124:127], v[172:175], v[156:159], v[124:127]
	v_mfma_f32_16x16x32_bf16 v[120:123], v[172:175], v[164:167], v[120:123]
	v_mfma_f32_16x16x32_bf16 v[116:119], v[180:183], v[156:159], v[116:119]
	v_mfma_f32_16x16x32_bf16 v[112:115], v[180:183], v[164:167], v[112:115]
	v_mfma_f32_16x16x32_bf16 v[108:111], v[188:191], v[156:159], v[108:111]
	v_mfma_f32_16x16x32_bf16 v[104:107], v[188:191], v[164:167], v[104:107]
	v_mfma_f32_16x16x32_bf16 v[100:103], v[196:199], v[156:159], v[100:103]
	v_mfma_f32_16x16x32_bf16 v[96:99], v[196:199], v[164:167], v[96:99]
	v_mfma_f32_16x16x32_bf16 v[124:127], v[176:179], v[160:163], v[124:127]
	v_mfma_f32_16x16x32_bf16 v[120:123], v[176:179], v[168:171], v[120:123]
	v_mfma_f32_16x16x32_bf16 v[116:119], v[184:187], v[160:163], v[116:119]
	v_mfma_f32_16x16x32_bf16 v[112:115], v[184:187], v[168:171], v[112:115]
	v_mfma_f32_16x16x32_bf16 v[108:111], v[192:195], v[160:163], v[108:111]
	v_mfma_f32_16x16x32_bf16 v[104:107], v[192:195], v[168:171], v[104:107]
	v_mfma_f32_16x16x32_bf16 v[100:103], v[200:203], v[160:163], v[100:103]
	v_mfma_f32_16x16x32_bf16 v[96:99], v[200:203], v[168:171], v[96:99]
	s_barrier
	s_setprio 0
	ds_read_b128 v[204:207], v145 offset:49152
	ds_read_b128 v[212:215], v145 offset:50176
	ds_read_b128 v[216:219], v145 offset:51200
	ds_read_b128 v[220:223], v145 offset:52224
	v_lshl_add_u64 v[230:231], v[226:227], 0, s[16:17]
	s_add_u32 m0, s29, s52
	s_nop 0
	global_load_lds_dwordx4 v[230:231], off
	v_lshl_add_u64 v[230:231], v[228:229], 0, s[16:17]
	s_add_u32 m0, s29, s52
	s_add_u32 m0, m0, 0x2000
	s_nop 0
	global_load_lds_dwordx4 v[230:231], off
	s_setprio 1
	s_barrier
	s_waitcnt lgkmcnt(0)
	v_mfma_f32_16x16x32_bf16 v[92:95], v[172:175], v[204:207], v[92:95]
	v_mfma_f32_16x16x32_bf16 v[88:91], v[172:175], v[216:219], v[88:91]
	v_mfma_f32_16x16x32_bf16 v[84:87], v[180:183], v[204:207], v[84:87]
	v_mfma_f32_16x16x32_bf16 v[80:83], v[180:183], v[216:219], v[80:83]
	v_mfma_f32_16x16x32_bf16 v[76:79], v[188:191], v[204:207], v[76:79]
	v_mfma_f32_16x16x32_bf16 v[72:75], v[188:191], v[216:219], v[72:75]
	v_mfma_f32_16x16x32_bf16 v[68:71], v[196:199], v[204:207], v[68:71]
	v_mfma_f32_16x16x32_bf16 v[64:67], v[196:199], v[216:219], v[64:67]
	v_mfma_f32_16x16x32_bf16 v[92:95], v[176:179], v[212:215], v[92:95]
	v_mfma_f32_16x16x32_bf16 v[88:91], v[176:179], v[220:223], v[88:91]
	v_mfma_f32_16x16x32_bf16 v[84:87], v[184:187], v[212:215], v[84:87]
	v_mfma_f32_16x16x32_bf16 v[80:83], v[184:187], v[220:223], v[80:83]
	v_mfma_f32_16x16x32_bf16 v[76:79], v[192:195], v[212:215], v[76:79]
	v_mfma_f32_16x16x32_bf16 v[72:75], v[192:195], v[220:223], v[72:75]
	v_mfma_f32_16x16x32_bf16 v[68:71], v[200:203], v[212:215], v[68:71]
	v_mfma_f32_16x16x32_bf16 v[64:67], v[200:203], v[220:223], v[64:67]
	s_barrier
	s_setprio 0
	ds_read_b128 v[172:175], v128 offset:49152
	ds_read_b128 v[176:179], v128 offset:50176
	ds_read_b128 v[180:183], v128 offset:51200
	ds_read_b128 v[184:187], v128 offset:52224
	ds_read_b128 v[188:191], v128 offset:53248
	ds_read_b128 v[192:195], v128 offset:54272
	ds_read_b128 v[196:199], v128 offset:55296
	ds_read_b128 v[200:203], v128 offset:56320
	v_lshl_add_u64 v[208:209], v[208:209], 0, s[18:19]
	s_add_u32 m0, s29, 0x8000
	s_nop 0
	global_load_lds_dwordx4 v[208:209], off
	v_lshl_add_u64 v[208:209], v[224:225], 0, s[18:19]
	s_add_u32 m0, s29, 0xa000
	s_nop 0
	global_load_lds_dwordx4 v[208:209], off
	s_setprio 1
	s_barrier
; #define WAIT_V(n) asm volatile("s_waitcnt vmcnt(" #n ")" ::: "memory")
; #define WAIT_L(n) asm volatile("s_waitcnt lgkmcnt(" #n ")" ::: "memory")
; #define BAR __builtin_amdgcn_s_barrier()
; #define SCHED __builtin_amdgcn_sched_barrier(0)
; #define STAGE(P, BASE, br, kt) do { const char* _g = (const char*)((BASE) + (size_t)(br) * GK + (kt) * BK); \
;     __builtin_amdgcn_global_load_lds((const unsigned*)(_g + voff0), (unsigned*)((char*)(P) + tx * 16), 16, 0, 0); \
;     __builtin_amdgcn_global_load_lds((const unsigned*)(_g + voff1), (unsigned*)((char*)(P) + tx * 16 + 8192), 16, 0, 0); } while (0)
; #define LDA(dst, b, h) _Pragma("unroll") for (int m = 0; m < 4; ++m) _Pragma("unroll") for (int k = 0; k < 2; ++k) \
;     dst[m][k] = *reinterpret_cast<const bf16x8*>((char*)shm + abase + (((b) * 2 + (h)) * 16384 + (m * 2 + k) * 1024))
; #define LDB(dst, b, h) _Pragma("unroll") for (int n = 0; n < 2; ++n) _Pragma("unroll") for (int k = 0; k < 2; ++k) \
;     dst[n][k] = *reinterpret_cast<const bf16x8*>((char*)shm + bbase + (((b) * 2 + (h)) * 16384 + (n * 2 + k) * 1024))
; template <bool SWAP>
; __device__ __forceinline__ void gemm_main(const u16* __restrict__ A, const u16* __restrict__ Bt, int brow, int bcol,
;                                           u16* shm, f32x4 (&acc)[2][2][4][2]) {
;     ...
;     LDB(B1, 1, 1); STAGE(SB(1, 0), Bt, bcol, t + 3);
;     BAR; WAIT_L(0); MMA(0, 1, At, B1); BAR;
;     LDA(At, 1, 1); STAGE(SA(1, 0), A, brow, t + 3);
;     BAR; WAIT_L(0); MMA(1, 0, At, B0); BAR; SCHED;
;     STAGE(SB(1, 1), Bt, bcol + HALF, t + 3);
;     WAIT_V(6); BAR; MMA(1, 1, At, B1); BAR;
;   }
;   { LDB(B0, 0, 0); LDA(At, 0, 0); STAGE(SA(1, 1), A, brow + HALF, nt - 1);
;     BAR; WAIT_L(0); MMA(0, 0, At, B0); BAR;
	s_waitcnt lgkmcnt(0)
	v_mfma_f32_16x16x32_bf16 v[60:63], v[172:175], v[156:159], v[60:63]
	v_mfma_f32_16x16x32_bf16 v[56:59], v[172:175], v[164:167], v[56:59]
	v_mfma_f32_16x16x32_bf16 v[52:55], v[180:183], v[156:159], v[52:55]
	v_mfma_f32_16x16x32_bf16 v[48:51], v[180:183], v[164:167], v[48:51]
	v_mfma_f32_16x16x32_bf16 v[44:47], v[188:191], v[156:159], v[44:47]
	v_mfma_f32_16x16x32_bf16 v[40:43], v[188:191], v[164:167], v[40:43]
	v_mfma_f32_16x16x32_bf16 v[36:39], v[196:199], v[156:159], v[36:39]
	v_mfma_f32_16x16x32_bf16 v[32:35], v[196:199], v[164:167], v[32:35]
	v_mfma_f32_16x16x32_bf16 v[60:63], v[176:179], v[160:163], v[60:63]
	v_mfma_f32_16x16x32_bf16 v[56:59], v[176:179], v[168:171], v[56:59]
	v_mfma_f32_16x16x32_bf16 v[52:55], v[184:187], v[160:163], v[52:55]
	v_mfma_f32_16x16x32_bf16 v[48:51], v[184:187], v[168:171], v[48:51]
	v_mfma_f32_16x16x32_bf16 v[44:47], v[192:195], v[160:163], v[44:47]
	v_mfma_f32_16x16x32_bf16 v[40:43], v[192:195], v[168:171], v[40:43]
	v_mfma_f32_16x16x32_bf16 v[36:39], v[200:203], v[160:163], v[36:39]
	v_mfma_f32_16x16x32_bf16 v[32:35], v[200:203], v[168:171], v[32:35]
	s_barrier
	s_setprio 0
	v_lshl_add_u64 v[156:157], v[226:227], 0, s[20:21]
	s_add_u32 m0, s29, s53
	s_nop 0
	global_load_lds_dwordx4 v[156:157], off
	v_lshl_add_u64 v[156:157], v[228:229], 0, s[20:21]
	s_add_u32 m0, s29, s53
	s_add_u32 m0, m0, 0x2000
	s_nop 0
	global_load_lds_dwordx4 v[156:157], off
	s_waitcnt vmcnt(6)
	s_setprio 1
	s_barrier
	v_mfma_f32_16x16x32_bf16 v[28:31], v[172:175], v[204:207], v[28:31]
	v_mfma_f32_16x16x32_bf16 v[24:27], v[172:175], v[216:219], v[24:27]
	v_mfma_f32_16x16x32_bf16 v[20:23], v[180:183], v[204:207], v[20:23]
	v_mfma_f32_16x16x32_bf16 v[16:19], v[180:183], v[216:219], v[16:19]
	v_mfma_f32_16x16x32_bf16 v[12:15], v[188:191], v[204:207], v[12:15]
	v_mfma_f32_16x16x32_bf16 v[8:11], v[188:191], v[216:219], v[8:11]
	v_mfma_f32_16x16x32_bf16 v[4:7], v[196:199], v[204:207], v[4:7]
	v_mfma_f32_16x16x32_bf16 v[0:3], v[196:199], v[216:219], v[0:3]
	v_mfma_f32_16x16x32_bf16 v[28:31], v[176:179], v[212:215], v[28:31]
	v_mfma_f32_16x16x32_bf16 v[24:27], v[176:179], v[220:223], v[24:27]
	v_mfma_f32_16x16x32_bf16 v[20:23], v[184:187], v[212:215], v[20:23]
	v_mfma_f32_16x16x32_bf16 v[16:19], v[184:187], v[220:223], v[16:19]
	v_mfma_f32_16x16x32_bf16 v[12:15], v[192:195], v[212:215], v[12:15]
	v_mfma_f32_16x16x32_bf16 v[8:11], v[192:195], v[220:223], v[8:11]
	v_mfma_f32_16x16x32_bf16 v[4:7], v[200:203], v[212:215], v[4:7]
	v_mfma_f32_16x16x32_bf16 v[0:3], v[200:203], v[220:223], v[0:3]
	s_add_i32 s28, s28, 2
	s_add_u32 s26, s26, 0x100
	s_addc_u32 s27, s27, 0
	s_cmp_lt_u32 s28, 28
	s_barrier
	s_setprio 0
	s_cbranch_scc1 .LBB0_84
	v_lshlrev_b32_e32 v130, 3, v147
	v_lshlrev_b32_e32 v131, 5, v147
	v_and_b32_e32 v130, 0xffff0, v130
	v_and_b32_e32 v131, 32, v131
	v_add_u32_e32 v131, v131, v149
	v_add_lshl_u32 v130, v148, v130, 12
	s_add_u32 s4, s37, s4
	v_lshl_add_u32 v155, v131, 1, v130
	v_lshlrev_b32_e32 v130, 3, v150
	v_lshlrev_b32_e32 v131, 5, v150
	s_addc_u32 s27, s38, 0
	v_and_b32_e32 v130, 0xffff0, v130
	v_and_b32_e32 v131, 32, v131
	s_add_u32 s26, s4, 0x80f80
	v_readfirstlane_b32 s4, v153
	v_add_u32_e32 v131, v131, v152
	v_add_lshl_u32 v130, v151, v130, 12
	s_addc_u32 s27, s27, 0
	s_mov_b32 m0, s4
	v_readfirstlane_b32 s4, v154
	v_lshl_add_u32 v150, v131, 1, v130
	ds_read_b128 v[130:133], v145
	ds_read_b128 v[134:137], v145 offset:1024
	ds_read_b128 v[146:149], v145 offset:2048
	ds_read_b128 v[156:159], v145 offset:3072
	ds_read_b128 v[160:163], v128
	ds_read_b128 v[164:167], v128 offset:1024
	ds_read_b128 v[168:171], v128 offset:2048
	ds_read_b128 v[172:175], v128 offset:3072
	ds_read_b128 v[176:179], v128 offset:4096
	ds_read_b128 v[180:183], v128 offset:5120
	ds_read_b128 v[184:187], v128 offset:6144
	ds_read_b128 v[188:191], v128 offset:7168
	global_load_lds_dwordx4 v155, s[26:27]
	s_mov_b32 m0, s4
	s_nop 0
	global_load_lds_dwordx4 v150, s[26:27]
	s_barrier
	s_waitcnt lgkmcnt(0)
	s_setprio 1
	s_waitcnt lgkmcnt(0)
	v_mfma_f32_16x16x32_bf16 v[124:127], v[160:163], v[130:133], v[124:127]
	v_mfma_f32_16x16x32_bf16 v[116:119], v[168:171], v[130:133], v[116:119]
	v_mfma_f32_16x16x32_bf16 v[108:111], v[176:179], v[130:133], v[108:111]
	v_mfma_f32_16x16x32_bf16 v[100:103], v[184:187], v[130:133], v[100:103]
	v_mfma_f32_16x16x32_bf16 v[96:99], v[184:187], v[146:149], v[96:99]
	v_mfma_f32_16x16x32_bf16 v[124:127], v[164:167], v[134:137], v[124:127]
	v_mfma_f32_16x16x32_bf16 v[120:123], v[160:163], v[146:149], v[120:123]
	v_mfma_f32_16x16x32_bf16 v[116:119], v[172:175], v[134:137], v[116:119]
	v_mfma_f32_16x16x32_bf16 v[112:115], v[168:171], v[146:149], v[112:115]
	v_mfma_f32_16x16x32_bf16 v[108:111], v[180:183], v[134:137], v[108:111]
	v_mfma_f32_16x16x32_bf16 v[104:107], v[176:179], v[146:149], v[104:107]
	v_mfma_f32_16x16x32_bf16 v[100:103], v[188:191], v[134:137], v[100:103]
	v_mfma_f32_16x16x32_bf16 v[96:99], v[188:191], v[156:159], v[96:99]
	v_mfma_f32_16x16x32_bf16 v[150:153], v[164:167], v[156:159], v[120:123]
	v_mfma_f32_16x16x32_bf16 v[192:195], v[172:175], v[156:159], v[112:115]
	v_mfma_f32_16x16x32_bf16 v[196:199], v[180:183], v[156:159], v[104:107]
	s_setprio 0
	s_barrier
	s_nop 0
	ds_read_b128 v[104:107], v145 offset:16384
	ds_read_b128 v[112:115], v145 offset:17408
	ds_read_b128 v[120:123], v145 offset:18432
	ds_read_b128 v[200:203], v145 offset:19456
	s_barrier
; #define WAIT_V(n) asm volatile("s_waitcnt vmcnt(" #n ")" ::: "memory")
; #define WAIT_L(n) asm volatile("s_waitcnt lgkmcnt(" #n ")" ::: "memory")
; #define BAR __builtin_amdgcn_s_barrier()
; #define LDA(dst, b, h) _Pragma("unroll") for (int m = 0; m < 4; ++m) _Pragma("unroll") for (int k = 0; k < 2; ++k) \
;     dst[m][k] = *reinterpret_cast<const bf16x8*>((char*)shm + abase + (((b) * 2 + (h)) * 16384 + (m * 2 + k) * 1024))
; #define LDB(dst, b, h) _Pragma("unroll") for (int n = 0; n < 2; ++n) _Pragma("unroll") for (int k = 0; k < 2; ++k) \
;     dst[n][k] = *reinterpret_cast<const bf16x8*>((char*)shm + bbase + (((b) * 2 + (h)) * 16384 + (n * 2 + k) * 1024))
; template <bool SWAP>
; __device__ __forceinline__ void gemm_main(const u16* __restrict__ A, const u16* __restrict__ Bt, int brow, int bcol,
;                                           u16* shm, f32x4 (&acc)[2][2][4][2]) {
;     ...
;     BAR; WAIT_L(0); MMA(0, 0, At, B0); BAR;
;     LDB(B1, 0, 1); BAR; WAIT_L(0); MMA(0, 1, At, B1); BAR;
;     LDA(At, 0, 1); WAIT_V(4); BAR; WAIT_L(0); MMA(1, 0, At, B0); MMA(1, 1, At, B1); BAR; }
;   { LDB(B0, 1, 0); LDA(At, 1, 0); WAIT_V(2); BAR; WAIT_L(0); MMA(0, 0, At, B0); BAR;
	s_waitcnt lgkmcnt(0)
	s_setprio 1
	s_waitcnt lgkmcnt(0)
	v_mfma_f32_16x16x32_bf16 v[84:87], v[168:171], v[104:107], v[84:87]
	v_mfma_f32_16x16x32_bf16 v[76:79], v[176:179], v[104:107], v[76:79]
	v_mfma_f32_16x16x32_bf16 v[68:71], v[184:187], v[104:107], v[68:71]
	v_mfma_f32_16x16x32_bf16 v[92:95], v[160:163], v[104:107], v[92:95]
	v_mfma_f32_16x16x32_bf16 v[88:91], v[160:163], v[120:123], v[88:91]
	v_mfma_f32_16x16x32_bf16 v[84:87], v[172:175], v[112:115], v[84:87]
	v_mfma_f32_16x16x32_bf16 v[80:83], v[168:171], v[120:123], v[80:83]
	v_mfma_f32_16x16x32_bf16 v[76:79], v[180:183], v[112:115], v[76:79]
	v_mfma_f32_16x16x32_bf16 v[72:75], v[176:179], v[120:123], v[72:75]
	v_mfma_f32_16x16x32_bf16 v[68:71], v[188:191], v[112:115], v[68:71]
	v_mfma_f32_16x16x32_bf16 v[64:67], v[184:187], v[120:123], v[64:67]
	v_mfma_f32_16x16x32_bf16 v[204:207], v[164:167], v[112:115], v[92:95]
	v_mfma_f32_16x16x32_bf16 v[160:163], v[164:167], v[200:203], v[88:91]
	v_mfma_f32_16x16x32_bf16 v[164:167], v[172:175], v[200:203], v[80:83]
	v_mfma_f32_16x16x32_bf16 v[168:171], v[180:183], v[200:203], v[72:75]
	v_mfma_f32_16x16x32_bf16 v[172:175], v[188:191], v[200:203], v[64:67]
	s_setprio 0
	s_barrier
	s_nop 0
	ds_read_b128 v[64:67], v128 offset:16384
	ds_read_b128 v[72:75], v128 offset:17408
	ds_read_b128 v[80:83], v128 offset:18432
	ds_read_b128 v[88:91], v128 offset:19456
	ds_read_b128 v[92:95], v128 offset:20480
	ds_read_b128 v[176:179], v128 offset:21504
	ds_read_b128 v[180:183], v128 offset:22528
	ds_read_b128 v[184:187], v128 offset:23552
	s_waitcnt vmcnt(4)
	s_barrier
	s_waitcnt lgkmcnt(0)
	s_setprio 1
	s_waitcnt lgkmcnt(0)
	v_mfma_f32_16x16x32_bf16 v[60:63], v[64:67], v[130:133], v[60:63]
	v_mfma_f32_16x16x32_bf16 v[52:55], v[80:83], v[130:133], v[52:55]
	v_mfma_f32_16x16x32_bf16 v[44:47], v[92:95], v[130:133], v[44:47]
	v_mfma_f32_16x16x32_bf16 v[36:39], v[180:183], v[130:133], v[36:39]
	v_mfma_f32_16x16x32_bf16 v[60:63], v[72:75], v[134:137], v[60:63]
	v_mfma_f32_16x16x32_bf16 v[56:59], v[64:67], v[146:149], v[56:59]
	v_mfma_f32_16x16x32_bf16 v[52:55], v[88:91], v[134:137], v[52:55]
	v_mfma_f32_16x16x32_bf16 v[48:51], v[80:83], v[146:149], v[48:51]
	v_mfma_f32_16x16x32_bf16 v[44:47], v[176:179], v[134:137], v[44:47]
	v_mfma_f32_16x16x32_bf16 v[40:43], v[92:95], v[146:149], v[40:43]
	v_mfma_f32_16x16x32_bf16 v[36:39], v[184:187], v[134:137], v[36:39]
	v_mfma_f32_16x16x32_bf16 v[32:35], v[180:183], v[146:149], v[32:35]
	v_mfma_f32_16x16x32_bf16 v[188:191], v[72:75], v[156:159], v[56:59]
	v_mfma_f32_16x16x32_bf16 v[212:215], v[88:91], v[156:159], v[48:51]
	v_mfma_f32_16x16x32_bf16 v[216:219], v[176:179], v[156:159], v[40:43]
	v_mfma_f32_16x16x32_bf16 v[130:133], v[184:187], v[156:159], v[32:35]
	s_setprio 0
	s_setprio 1
	v_mfma_f32_16x16x32_bf16 v[28:31], v[64:67], v[104:107], v[28:31]
	v_mfma_f32_16x16x32_bf16 v[20:23], v[80:83], v[104:107], v[20:23]
	v_mfma_f32_16x16x32_bf16 v[12:15], v[92:95], v[104:107], v[12:15]
	v_mfma_f32_16x16x32_bf16 v[4:7], v[180:183], v[104:107], v[4:7]
	v_mfma_f32_16x16x32_bf16 v[28:31], v[72:75], v[112:115], v[28:31]
	v_mfma_f32_16x16x32_bf16 v[24:27], v[64:67], v[120:123], v[24:27]
	v_mfma_f32_16x16x32_bf16 v[20:23], v[88:91], v[112:115], v[20:23]
	v_mfma_f32_16x16x32_bf16 v[16:19], v[80:83], v[120:123], v[16:19]
	v_mfma_f32_16x16x32_bf16 v[12:15], v[176:179], v[112:115], v[12:15]
	v_mfma_f32_16x16x32_bf16 v[8:11], v[92:95], v[120:123], v[8:11]
	v_mfma_f32_16x16x32_bf16 v[4:7], v[184:187], v[112:115], v[4:7]
	v_mfma_f32_16x16x32_bf16 v[0:3], v[180:183], v[120:123], v[0:3]
	v_mfma_f32_16x16x32_bf16 v[134:137], v[72:75], v[200:203], v[24:27]
	v_mfma_f32_16x16x32_bf16 v[146:149], v[88:91], v[200:203], v[16:19]
	v_mfma_f32_16x16x32_bf16 v[154:157], v[176:179], v[200:203], v[8:11]
	v_mfma_f32_16x16x32_bf16 v[176:179], v[184:187], v[200:203], v[0:3]
	s_setprio 0
	s_barrier
	s_nop 1
	ds_read_b128 v[0:3], v145 offset:32768
	ds_read_b128 v[8:11], v145 offset:33792
	ds_read_b128 v[16:19], v145 offset:34816
	ds_read_b128 v[24:27], v145 offset:35840
	ds_read_b128 v[32:35], v128 offset:32768
	ds_read_b128 v[40:43], v128 offset:33792
	ds_read_b128 v[48:51], v128 offset:34816
	ds_read_b128 v[56:59], v128 offset:35840
	ds_read_b128 v[64:67], v128 offset:36864
	ds_read_b128 v[180:183], v128 offset:37888
	ds_read_b128 v[184:187], v128 offset:38912
	ds_read_b128 v[200:203], v128 offset:39936
	s_waitcnt vmcnt(2)
	s_barrier
; #define WAIT_V(n) asm volatile("s_waitcnt vmcnt(" #n ")" ::: "memory")
; #define WAIT_L(n) asm volatile("s_waitcnt lgkmcnt(" #n ")" ::: "memory")
; #define BAR __builtin_amdgcn_s_barrier()
; #define LDA(dst, b, h) _Pragma("unroll") for (int m = 0; m < 4; ++m) _Pragma("unroll") for (int k = 0; k < 2; ++k) \
;     dst[m][k] = *reinterpret_cast<const bf16x8*>((char*)shm + abase + (((b) * 2 + (h)) * 16384 + (m * 2 + k) * 1024))
; #define LDB(dst, b, h) _Pragma("unroll") for (int n = 0; n < 2; ++n) _Pragma("unroll") for (int k = 0; k < 2; ++k) \
;     dst[n][k] = *reinterpret_cast<const bf16x8*>((char*)shm + bbase + (((b) * 2 + (h)) * 16384 + (n * 2 + k) * 1024))
; template <bool SWAP>
; __device__ __forceinline__ void gemm_main(const u16* __restrict__ A, const u16* __restrict__ Bt, int brow, int bcol,
;                                           u16* shm, f32x4 (&acc)[2][2][4][2]) {
;     ...
;   { LDB(B0, 1, 0); LDA(At, 1, 0); WAIT_V(2); BAR; WAIT_L(0); MMA(0, 0, At, B0); BAR;
;     LDB(B1, 1, 1); WAIT_V(0); BAR; WAIT_L(0); MMA(0, 1, At, B1); BAR;
;     LDA(At, 1, 1); BAR; WAIT_L(0); MMA(1, 0, At, B0); MMA(1, 1, At, B1); BAR; }
;   if (wr == 0) BAR;
	s_waitcnt lgkmcnt(0)
	s_setprio 1
	s_waitcnt lgkmcnt(0)
	v_mfma_f32_16x16x32_bf16 v[72:75], v[32:35], v[0:3], v[124:127]
	v_mfma_f32_16x16x32_bf16 v[120:123], v[40:43], v[8:11], v[72:75]
	v_mfma_f32_16x16x32_bf16 v[72:75], v[32:35], v[16:19], v[150:153]
	v_mfma_f32_16x16x32_bf16 v[112:115], v[40:43], v[24:27], v[72:75]
	v_mfma_f32_16x16x32_bf16 v[72:75], v[48:51], v[0:3], v[116:119]
	v_mfma_f32_16x16x32_bf16 v[124:127], v[56:59], v[8:11], v[72:75]
	v_mfma_f32_16x16x32_bf16 v[72:75], v[48:51], v[16:19], v[192:195]
	v_mfma_f32_16x16x32_bf16 v[116:119], v[56:59], v[24:27], v[72:75]
	v_mfma_f32_16x16x32_bf16 v[72:75], v[64:67], v[0:3], v[108:111]
	v_mfma_f32_16x16x32_bf16 v[104:107], v[180:183], v[8:11], v[72:75]
	v_mfma_f32_16x16x32_bf16 v[72:75], v[64:67], v[16:19], v[196:199]
	v_mfma_f32_16x16x32_bf16 v[92:95], v[180:183], v[24:27], v[72:75]
	v_mfma_f32_16x16x32_bf16 v[72:75], v[184:187], v[0:3], v[100:103]
	v_mfma_f32_16x16x32_bf16 v[108:111], v[200:203], v[8:11], v[72:75]
	v_mfma_f32_16x16x32_bf16 v[72:75], v[184:187], v[16:19], v[96:99]
	v_mfma_f32_16x16x32_bf16 v[100:103], v[200:203], v[24:27], v[72:75]
	s_setprio 0
	s_barrier
	ds_read_b128 v[150:153], v145 offset:49152
	ds_read_b128 v[192:195], v145 offset:50176
	ds_read_b128 v[196:199], v145 offset:51200
	ds_read_b128 v[220:223], v145 offset:52224
	s_waitcnt vmcnt(0)
	s_barrier
	s_waitcnt lgkmcnt(0)
	s_setprio 1
	s_waitcnt lgkmcnt(0)
	v_mfma_f32_16x16x32_bf16 v[72:75], v[32:35], v[150:153], v[204:207]
	v_mfma_f32_16x16x32_bf16 v[32:35], v[32:35], v[196:199], v[160:163]
	v_mfma_f32_16x16x32_bf16 v[80:83], v[40:43], v[220:223], v[32:35]
	v_mfma_f32_16x16x32_bf16 v[32:35], v[48:51], v[150:153], v[84:87]
	v_mfma_f32_16x16x32_bf16 v[96:99], v[56:59], v[192:195], v[32:35]
	v_mfma_f32_16x16x32_bf16 v[32:35], v[48:51], v[196:199], v[164:167]
	v_mfma_f32_16x16x32_bf16 v[84:87], v[56:59], v[220:223], v[32:35]
	v_mfma_f32_16x16x32_bf16 v[32:35], v[64:67], v[150:153], v[76:79]
	v_mfma_f32_16x16x32_bf16 v[88:91], v[40:43], v[192:195], v[72:75]
	v_mfma_f32_16x16x32_bf16 v[72:75], v[180:183], v[192:195], v[32:35]
	v_mfma_f32_16x16x32_bf16 v[32:35], v[64:67], v[196:199], v[168:171]
	v_mfma_f32_16x16x32_bf16 v[64:67], v[180:183], v[220:223], v[32:35]
	v_mfma_f32_16x16x32_bf16 v[32:35], v[184:187], v[150:153], v[68:71]
	v_mfma_f32_16x16x32_bf16 v[76:79], v[200:203], v[192:195], v[32:35]
	v_mfma_f32_16x16x32_bf16 v[32:35], v[184:187], v[196:199], v[172:175]
	v_mfma_f32_16x16x32_bf16 v[68:71], v[200:203], v[220:223], v[32:35]
	s_setprio 0
	s_barrier
	ds_read_b128 v[158:161], v128 offset:49152
	ds_read_b128 v[162:165], v128 offset:50176
	ds_read_b128 v[166:169], v128 offset:51200
	ds_read_b128 v[170:173], v128 offset:52224
	ds_read_b128 v[180:183], v128 offset:53248
	ds_read_b128 v[184:187], v128 offset:54272
	ds_read_b128 v[200:203], v128 offset:55296
	ds_read_b128 v[204:207], v128 offset:56320
	s_barrier
	s_waitcnt lgkmcnt(0)
	s_setprio 1
	s_waitcnt lgkmcnt(0)
	v_mfma_f32_16x16x32_bf16 v[32:35], v[158:161], v[0:3], v[60:63]
	v_mfma_f32_16x16x32_bf16 v[56:59], v[162:165], v[8:11], v[32:35]
	v_mfma_f32_16x16x32_bf16 v[32:35], v[158:161], v[16:19], v[188:191]
	v_mfma_f32_16x16x32_bf16 v[48:51], v[162:165], v[24:27], v[32:35]
	v_mfma_f32_16x16x32_bf16 v[32:35], v[166:169], v[0:3], v[52:55]
	v_mfma_f32_16x16x32_bf16 v[60:63], v[170:173], v[8:11], v[32:35]
	v_mfma_f32_16x16x32_bf16 v[32:35], v[166:169], v[16:19], v[212:215]
	v_mfma_f32_16x16x32_bf16 v[52:55], v[170:173], v[24:27], v[32:35]
	v_mfma_f32_16x16x32_bf16 v[32:35], v[180:183], v[0:3], v[44:47]
	v_mfma_f32_16x16x32_bf16 v[0:3], v[200:203], v[0:3], v[36:39]
	v_mfma_f32_16x16x32_bf16 v[40:43], v[184:187], v[8:11], v[32:35]
	v_mfma_f32_16x16x32_bf16 v[32:35], v[180:183], v[16:19], v[216:219]
	v_mfma_f32_16x16x32_bf16 v[44:47], v[204:207], v[8:11], v[0:3]
	v_mfma_f32_16x16x32_bf16 v[0:3], v[200:203], v[16:19], v[130:133]
	v_mfma_f32_16x16x32_bf16 v[32:35], v[184:187], v[24:27], v[32:35]
	v_mfma_f32_16x16x32_bf16 v[36:39], v[204:207], v[24:27], v[0:3]
	s_setprio 0
	s_setprio 1
	v_mfma_f32_16x16x32_bf16 v[0:3], v[158:161], v[150:153], v[28:31]
	v_mfma_f32_16x16x32_bf16 v[24:27], v[162:165], v[192:195], v[0:3]
	v_mfma_f32_16x16x32_bf16 v[0:3], v[158:161], v[196:199], v[134:137]
	v_mfma_f32_16x16x32_bf16 v[16:19], v[162:165], v[220:223], v[0:3]
	v_mfma_f32_16x16x32_bf16 v[0:3], v[166:169], v[150:153], v[20:23]
	v_mfma_f32_16x16x32_bf16 v[28:31], v[170:173], v[192:195], v[0:3]
	v_mfma_f32_16x16x32_bf16 v[0:3], v[166:169], v[196:199], v[146:149]
	v_mfma_f32_16x16x32_bf16 v[20:23], v[170:173], v[220:223], v[0:3]
	v_mfma_f32_16x16x32_bf16 v[0:3], v[180:183], v[150:153], v[12:15]
	v_mfma_f32_16x16x32_bf16 v[4:7], v[200:203], v[150:153], v[4:7]
	v_mfma_f32_16x16x32_bf16 v[8:11], v[184:187], v[192:195], v[0:3]
	v_mfma_f32_16x16x32_bf16 v[0:3], v[180:183], v[196:199], v[154:157]
	v_mfma_f32_16x16x32_bf16 v[12:15], v[204:207], v[192:195], v[4:7]
	v_mfma_f32_16x16x32_bf16 v[4:7], v[200:203], v[196:199], v[176:179]
	v_mfma_f32_16x16x32_bf16 v[0:3], v[184:187], v[220:223], v[0:3]
	v_mfma_f32_16x16x32_bf16 v[4:7], v[204:207], v[220:223], v[4:7]
	s_setprio 0
	v_cmp_gt_u32_e32 vcc, s55, v144
	s_barrier
	s_and_saveexec_b64 s[26:27], vcc
	s_cbranch_execz .LBB0_87
	s_barrier

; #define WAIT_V(n) asm volatile("s_waitcnt vmcnt(" #n ")" ::: "memory")
; #define BAR __builtin_amdgcn_s_barrier()
; template <bool SWAP>
; __device__ __forceinline__ void gemm_main(const u16* __restrict__ A, const u16* __restrict__ Bt, int brow, int bcol,
;                                           u16* shm, f32x4 (&acc)[2][2][4][2]) {
;     ...
;   int tx = threadIdx.x; asm volatile("" : "+v"(tx));
;   const int wid = tx >> 6, lane = tx & 63, wr = wid >> 2, wc = wid & 3, fr = lane & 15, fq = lane >> 4;
; #pragma unroll
;   for (int a = 0; a < 2; ++a)
; #pragma unroll
;     for (int b = 0; b < 2; ++b)
; #pragma unroll
;       for (int m = 0; m < 4; ++m)
; #pragma unroll
;         for (int n = 0; n < 2; ++n) acc[a][b][m][n] = f32x4{0.f, 0.f, 0.f, 0.f};
;   bf16x8 At[4][2], B0[2][2], B1[2][2];
;   constexpr int nt = GK / BK;
;   GEMM_VOFF
;   const int lpart = (fr * 64 + fq * 16) ^ ((fr >> 3) << 5);
;   const int abase = wr * 8192 + lpart; int bbase = 65536 + wc * 4096 + lpart;
;   asm volatile("" : "+v"(bbase));
;   if (wr == 1) BAR;
;   WAIT_V(0); BAR;
;   BAR;
.LBB0_93:
	s_or_b64 exec, exec, s[26:27]
	v_bfe_i32 v4, v144, 27, 1
	v_lshlrev_b32_e32 v147, 4, v144
	v_lshrrev_b32_e32 v4, 22, v4
	v_add_u32_e32 v4, v147, v4
	v_and_b32_e32 v4, 0xfffffc00, v4
	v_sub_u32_e32 v4, v147, v4
	v_lshrrev_b32_e32 v5, 4, v4
	v_bitop3_b32 v4, v5, v4, 32 bitop3:0x6c
	v_ashrrev_i32_e32 v5, 31, v4
	v_lshrrev_b32_e32 v5, 26, v5
	v_add_u32_e32 v5, v4, v5
	v_ashrrev_i32_e32 v149, 6, v5
	v_and_b32_e32 v5, 0xc0, v5
	v_sub_u32_e32 v4, v4, v5
	v_ashrrev_i16_sdwa v4, v139, sext(v4) dst_sel:DWORD dst_unused:UNUSED_PAD src0_sel:DWORD src1_sel:BYTE_0
	v_bfe_i32 v150, v4, 0, 16
	v_add_u32_e32 v4, 0x2000, v147
	v_ashrrev_i32_e32 v5, 31, v4
	v_lshrrev_b32_e32 v5, 22, v5
	v_add_u32_e32 v5, v4, v5
	v_ashrrev_i32_e32 v151, 10, v5
	v_mul_i32_i24_e32 v5, 0x400, v151
	v_sub_u32_e32 v4, v4, v5
	v_lshrrev_b32_e32 v5, 4, v4
	v_bitop3_b32 v4, v5, v4, 32 bitop3:0x6c
	v_ashrrev_i32_e32 v3, 31, v144
	v_ashrrev_i32_e32 v5, 31, v4
	v_lshrrev_b32_e32 v3, 26, v3
	v_lshrrev_b32_e32 v5, 26, v5
	v_add_u32_e32 v3, v144, v3
	v_add_u32_e32 v5, v4, v5
	v_ashrrev_i32_e32 v148, 6, v3
	v_ashrrev_i32_e32 v152, 6, v5
	v_and_b32_e32 v5, 0xc0, v5
	v_sub_u32_e32 v4, v4, v5
	v_add_u32_e32 v5, 0, v0
	v_lshlrev_b32_e32 v0, 15, v148
	v_and_b32_e32 v0, 0xffff0000, v0
	v_lshl_add_u32 v0, v149, 12, v0
	v_and_or_b32 v0, v3, 64, v0
	v_lshl_add_u32 v128, v150, 1, v0
	v_lshlrev_b32_e32 v0, 15, v151
	v_ashrrev_i16_sdwa v4, v139, sext(v4) dst_sel:DWORD dst_unused:UNUSED_PAD src0_sel:DWORD src1_sel:BYTE_0
	v_and_b32_e32 v0, 0xffff0000, v0
	v_bfe_i32 v153, v4, 0, 16
	v_lshlrev_b32_e32 v4, 13, v2
	s_lshl_b32 s26, s25, 8
	v_lshl_add_u32 v0, v152, 12, v0
	v_lshlrev_b32_e32 v2, 6, v151
	s_waitcnt vmcnt(0)
	s_ashr_i32 s25, s24, 31
	s_ashr_i32 s27, s26, 31
	v_and_or_b32 v0, v2, 64, v0
	s_lshl_b64 s[30:31], s[24:25], 12
	s_lshl_b64 s[34:35], s[26:27], 12
	v_lshl_add_u32 v2, v153, 1, v0
	v_mov_b32_e32 v3, v129
	v_mov_b32_e32 v0, 0
	v_lshl_add_u64 v[130:131], s[30:31], 0, v[2:3]
	v_lshl_add_u64 v[132:133], s[34:35], 0, v[2:3]
	s_mov_b32 s4, -2
	v_add_u32_e32 v146, 0, v1
	v_add_u32_e32 v145, v5, v4
	s_mov_b64 s[28:29], s[50:51]
	v_mov_b32_e32 v1, v0
	v_mov_b32_e32 v2, v0
	v_mov_b32_e32 v3, v0
	v_mov_b32_e32 v4, v0
	v_mov_b32_e32 v5, v0
	v_mov_b32_e32 v6, v0
	v_mov_b32_e32 v7, v0
	v_mov_b32_e32 v8, v0
	v_mov_b32_e32 v9, v0
	v_mov_b32_e32 v10, v0
	v_mov_b32_e32 v11, v0
	v_mov_b32_e32 v12, v0
	v_mov_b32_e32 v13, v0
	v_mov_b32_e32 v14, v0
	v_mov_b32_e32 v15, v0
	v_mov_b32_e32 v16, v0
	v_mov_b32_e32 v17, v0
	v_mov_b32_e32 v18, v0
	v_mov_b32_e32 v19, v0
	v_mov_b32_e32 v20, v0
	v_mov_b32_e32 v21, v0
	v_mov_b32_e32 v22, v0
	v_mov_b32_e32 v23, v0
	v_mov_b32_e32 v24, v0
	v_mov_b32_e32 v25, v0
	v_mov_b32_e32 v26, v0
	v_mov_b32_e32 v27, v0
	v_mov_b32_e32 v28, v0
	v_mov_b32_e32 v29, v0
	v_mov_b32_e32 v30, v0
	v_mov_b32_e32 v31, v0
	v_mov_b32_e32 v32, v0
	v_mov_b32_e32 v33, v0
	v_mov_b32_e32 v34, v0
	v_mov_b32_e32 v35, v0
	v_mov_b32_e32 v36, v0
	v_mov_b32_e32 v37, v0
	v_mov_b32_e32 v38, v0
	v_mov_b32_e32 v39, v0
	v_mov_b32_e32 v40, v0
	v_mov_b32_e32 v41, v0
	v_mov_b32_e32 v42, v0
	v_mov_b32_e32 v43, v0
	v_mov_b32_e32 v44, v0
	v_mov_b32_e32 v45, v0
	v_mov_b32_e32 v46, v0
	v_mov_b32_e32 v47, v0
	v_mov_b32_e32 v48, v0
	v_mov_b32_e32 v49, v0
	v_mov_b32_e32 v50, v0
	v_mov_b32_e32 v51, v0
	v_mov_b32_e32 v52, v0
	v_mov_b32_e32 v53, v0
	v_mov_b32_e32 v54, v0
	v_mov_b32_e32 v55, v0
	v_mov_b32_e32 v56, v0
	v_mov_b32_e32 v57, v0
	v_mov_b32_e32 v58, v0
	v_mov_b32_e32 v59, v0
	v_mov_b32_e32 v60, v0
	v_mov_b32_e32 v61, v0
	v_mov_b32_e32 v62, v0
	v_mov_b32_e32 v63, v0
	v_mov_b32_e32 v64, v0
	v_mov_b32_e32 v65, v0
	v_mov_b32_e32 v66, v0
	v_mov_b32_e32 v67, v0
	v_mov_b32_e32 v68, v0
	v_mov_b32_e32 v69, v0
	v_mov_b32_e32 v70, v0
	v_mov_b32_e32 v71, v0
	v_mov_b32_e32 v72, v0
	v_mov_b32_e32 v73, v0
	v_mov_b32_e32 v74, v0
	v_mov_b32_e32 v75, v0
	v_mov_b32_e32 v76, v0
	v_mov_b32_e32 v77, v0
	v_mov_b32_e32 v78, v0
	v_mov_b32_e32 v79, v0
	v_mov_b32_e32 v80, v0
	v_mov_b32_e32 v81, v0
	v_mov_b32_e32 v82, v0
	v_mov_b32_e32 v83, v0
	v_mov_b32_e32 v84, v0
	v_mov_b32_e32 v85, v0
	v_mov_b32_e32 v86, v0
	v_mov_b32_e32 v87, v0
	v_mov_b32_e32 v88, v0
	v_mov_b32_e32 v89, v0
	v_mov_b32_e32 v90, v0
	v_mov_b32_e32 v91, v0
	v_mov_b32_e32 v92, v0
	v_mov_b32_e32 v93, v0
	v_mov_b32_e32 v94, v0
	v_mov_b32_e32 v95, v0
	v_mov_b32_e32 v96, v0
	v_mov_b32_e32 v97, v0
	v_mov_b32_e32 v98, v0
	v_mov_b32_e32 v99, v0
	v_mov_b32_e32 v100, v0
	v_mov_b32_e32 v101, v0
	v_mov_b32_e32 v102, v0
	v_mov_b32_e32 v103, v0
	v_mov_b32_e32 v104, v0
	v_mov_b32_e32 v105, v0
	v_mov_b32_e32 v106, v0
	v_mov_b32_e32 v107, v0
	v_mov_b32_e32 v108, v0
	v_mov_b32_e32 v109, v0
	v_mov_b32_e32 v110, v0
	v_mov_b32_e32 v111, v0
	v_mov_b32_e32 v112, v0
	v_mov_b32_e32 v113, v0
	v_mov_b32_e32 v114, v0
	v_mov_b32_e32 v115, v0
	v_mov_b32_e32 v116, v0
	v_mov_b32_e32 v117, v0
	v_mov_b32_e32 v118, v0
	v_mov_b32_e32 v119, v0
	v_mov_b32_e32 v120, v0
	v_mov_b32_e32 v121, v0
	v_mov_b32_e32 v122, v0
	v_mov_b32_e32 v123, v0
	v_mov_b32_e32 v124, v0
	v_mov_b32_e32 v125, v0
	v_mov_b32_e32 v126, v0
	v_mov_b32_e32 v127, v0
	v_lshl_add_u64 v[134:135], s[30:31], 0, v[128:129]
	v_lshl_add_u64 v[136:137], s[34:35], 0, v[128:129]
	v_readfirstlane_b32 s25, v147
	s_barrier
	s_barrier
; #define WAIT_L(n) asm volatile("s_waitcnt lgkmcnt(" #n ")" ::: "memory")
; #define BAR __builtin_amdgcn_s_barrier()
; #define SCHED __builtin_amdgcn_sched_barrier(0)
; #define STAGE(P, BASE, br, kt) do { const char* _g = (const char*)((BASE) + (size_t)(br) * GK + (kt) * BK); \
;     __builtin_amdgcn_global_load_lds((const unsigned*)(_g + voff0), (unsigned*)((char*)(P) + tx * 16), 16, 0, 0); \
;     __builtin_amdgcn_global_load_lds((const unsigned*)(_g + voff1), (unsigned*)((char*)(P) + tx * 16 + 8192), 16, 0, 0); } while (0)
; #define LDA(dst, b, h) _Pragma("unroll") for (int m = 0; m < 4; ++m) _Pragma("unroll") for (int k = 0; k < 2; ++k) \
;     dst[m][k] = *reinterpret_cast<const bf16x8*>((char*)shm + abase + (((b) * 2 + (h)) * 16384 + (m * 2 + k) * 1024))
; #define LDB(dst, b, h) _Pragma("unroll") for (int n = 0; n < 2; ++n) _Pragma("unroll") for (int k = 0; k < 2; ++k) \
;     dst[n][k] = *reinterpret_cast<const bf16x8*>((char*)shm + bbase + (((b) * 2 + (h)) * 16384 + (n * 2 + k) * 1024))
; template <bool SWAP>
; __device__ __forceinline__ void gemm_main(const u16* __restrict__ A, const u16* __restrict__ Bt, int brow, int bcol,
;                                           u16* shm, f32x4 (&acc)[2][2][4][2]) {
;     ...
;   for (int t = 0; t < nt - 2; t += 2) {
;     LDB(B0, 0, 0); SCHED; LDA(At, 0, 0); STAGE(SA(1, 1), A, brow + HALF, t + 1);
;     WAIT_L(8); BAR; WAIT_L(0); MMA(0, 0, At, B0); BAR; SCHED;
;     LDB(B1, 0, 1); STAGE(SB(0, 0), Bt, bcol, t + 2);
;     BAR; WAIT_L(0); MMA(0, 1, At, B1); BAR;
;     LDA(At, 0, 1); STAGE(SA(0, 0), A, brow, t + 2);
.LBB0_94:
	ds_read_b128 v[156:159], v146
	ds_read_b128 v[160:163], v146 offset:1024
	ds_read_b128 v[164:167], v146 offset:2048
	ds_read_b128 v[168:171], v146 offset:3072
	ds_read_b128 v[172:175], v145
	ds_read_b128 v[176:179], v145 offset:1024
	ds_read_b128 v[180:183], v145 offset:2048
	ds_read_b128 v[184:187], v145 offset:3072
	ds_read_b128 v[188:191], v145 offset:4096
	ds_read_b128 v[192:195], v145 offset:5120
	ds_read_b128 v[196:199], v145 offset:6144
	ds_read_b128 v[200:203], v145 offset:7168
	v_add_u32_e32 v128, 0, v147
	v_add_u32_e32 v154, 0xc000, v128
	v_lshl_add_u64 v[208:209], s[28:29], 0, v[136:137]
	v_add_u32_e32 v155, 0xe000, v128
	v_lshl_add_u64 v[204:205], v[208:209], 0, s[6:7]
	s_add_u32 m0, s25, 0xc000
	v_lshl_add_u64 v[224:225], s[28:29], 0, v[132:133]
	global_load_lds_dwordx4 v[204:205], off
	v_lshl_add_u64 v[204:205], v[224:225], 0, s[6:7]
	s_add_u32 m0, s25, 0xe000
	s_nop 0
	global_load_lds_dwordx4 v[204:205], off
	s_waitcnt lgkmcnt(8)
	s_setprio 1
	s_barrier
	s_waitcnt lgkmcnt(0)
	v_mfma_f32_16x16x32_bf16 v[124:127], v[156:159], v[172:175], v[124:127]
	v_mfma_f32_16x16x32_bf16 v[120:123], v[164:167], v[172:175], v[120:123]
	v_mfma_f32_16x16x32_bf16 v[116:119], v[156:159], v[180:183], v[116:119]
	v_mfma_f32_16x16x32_bf16 v[112:115], v[164:167], v[180:183], v[112:115]
	v_mfma_f32_16x16x32_bf16 v[108:111], v[156:159], v[188:191], v[108:111]
	v_mfma_f32_16x16x32_bf16 v[104:107], v[164:167], v[188:191], v[104:107]
	v_mfma_f32_16x16x32_bf16 v[100:103], v[156:159], v[196:199], v[100:103]
	v_mfma_f32_16x16x32_bf16 v[96:99], v[164:167], v[196:199], v[96:99]
	v_mfma_f32_16x16x32_bf16 v[124:127], v[160:163], v[176:179], v[124:127]
	v_mfma_f32_16x16x32_bf16 v[120:123], v[168:171], v[176:179], v[120:123]
	v_mfma_f32_16x16x32_bf16 v[116:119], v[160:163], v[184:187], v[116:119]
	v_mfma_f32_16x16x32_bf16 v[112:115], v[168:171], v[184:187], v[112:115]
	v_mfma_f32_16x16x32_bf16 v[108:111], v[160:163], v[192:195], v[108:111]
	v_mfma_f32_16x16x32_bf16 v[104:107], v[168:171], v[192:195], v[104:107]
	v_mfma_f32_16x16x32_bf16 v[100:103], v[160:163], v[200:203], v[100:103]
	v_mfma_f32_16x16x32_bf16 v[96:99], v[168:171], v[200:203], v[96:99]
	s_barrier
	s_setprio 0
	ds_read_b128 v[204:207], v146 offset:16384
	ds_read_b128 v[212:215], v146 offset:17408
	ds_read_b128 v[216:219], v146 offset:18432
	ds_read_b128 v[220:223], v146 offset:19456
	v_lshl_add_u64 v[226:227], s[28:29], 0, v[134:135]
	v_lshl_add_u64 v[228:229], v[226:227], 0, s[8:9]
	s_add_u32 m0, s25, s44
	s_nop 0
	global_load_lds_dwordx4 v[228:229], off
	v_lshl_add_u64 v[228:229], s[28:29], 0, v[130:131]
	v_lshl_add_u64 v[230:231], v[228:229], 0, s[8:9]
	s_add_u32 m0, s25, s44
	s_add_u32 m0, m0, 0x2000
	s_nop 0
	global_load_lds_dwordx4 v[230:231], off
	s_setprio 1
	s_barrier
	s_waitcnt lgkmcnt(0)
	v_mfma_f32_16x16x32_bf16 v[92:95], v[204:207], v[172:175], v[92:95]
	v_mfma_f32_16x16x32_bf16 v[88:91], v[216:219], v[172:175], v[88:91]
	v_mfma_f32_16x16x32_bf16 v[84:87], v[204:207], v[180:183], v[84:87]
	v_mfma_f32_16x16x32_bf16 v[80:83], v[216:219], v[180:183], v[80:83]
	v_mfma_f32_16x16x32_bf16 v[76:79], v[204:207], v[188:191], v[76:79]
	v_mfma_f32_16x16x32_bf16 v[72:75], v[216:219], v[188:191], v[72:75]
	v_mfma_f32_16x16x32_bf16 v[68:71], v[204:207], v[196:199], v[68:71]
	v_mfma_f32_16x16x32_bf16 v[64:67], v[216:219], v[196:199], v[64:67]
	v_mfma_f32_16x16x32_bf16 v[92:95], v[212:215], v[176:179], v[92:95]
	v_mfma_f32_16x16x32_bf16 v[88:91], v[220:223], v[176:179], v[88:91]
	v_mfma_f32_16x16x32_bf16 v[84:87], v[212:215], v[184:187], v[84:87]
	v_mfma_f32_16x16x32_bf16 v[80:83], v[220:223], v[184:187], v[80:83]
	v_mfma_f32_16x16x32_bf16 v[76:79], v[212:215], v[192:195], v[76:79]
	v_mfma_f32_16x16x32_bf16 v[72:75], v[220:223], v[192:195], v[72:75]
	v_mfma_f32_16x16x32_bf16 v[68:71], v[212:215], v[200:203], v[68:71]
	v_mfma_f32_16x16x32_bf16 v[64:67], v[220:223], v[200:203], v[64:67]
	s_barrier
	s_setprio 0
	ds_read_b128 v[172:175], v145 offset:16384
	ds_read_b128 v[176:179], v145 offset:17408
	ds_read_b128 v[180:183], v145 offset:18432
	ds_read_b128 v[184:187], v145 offset:19456
	ds_read_b128 v[188:191], v145 offset:20480
	ds_read_b128 v[192:195], v145 offset:21504
	ds_read_b128 v[196:199], v145 offset:22528
	ds_read_b128 v[200:203], v145 offset:23552
	v_lshl_add_u64 v[230:231], v[208:209], 0, s[10:11]
	s_add_u32 m0, s25, 0x0
	s_nop 0
	global_load_lds_dwordx4 v[230:231], off
	v_lshl_add_u64 v[230:231], v[224:225], 0, s[10:11]
	s_add_u32 m0, s25, 0x2000
	s_nop 0
	global_load_lds_dwordx4 v[230:231], off
	s_setprio 1
	s_barrier
	s_waitcnt lgkmcnt(0)
	v_mfma_f32_16x16x32_bf16 v[60:63], v[156:159], v[172:175], v[60:63]
	v_mfma_f32_16x16x32_bf16 v[56:59], v[164:167], v[172:175], v[56:59]
	v_mfma_f32_16x16x32_bf16 v[52:55], v[156:159], v[180:183], v[52:55]
	v_mfma_f32_16x16x32_bf16 v[48:51], v[164:167], v[180:183], v[48:51]
	v_mfma_f32_16x16x32_bf16 v[44:47], v[156:159], v[188:191], v[44:47]
	v_mfma_f32_16x16x32_bf16 v[40:43], v[164:167], v[188:191], v[40:43]
	v_mfma_f32_16x16x32_bf16 v[36:39], v[156:159], v[196:199], v[36:39]
	v_mfma_f32_16x16x32_bf16 v[32:35], v[164:167], v[196:199], v[32:35]
	v_mfma_f32_16x16x32_bf16 v[60:63], v[160:163], v[176:179], v[60:63]
	v_mfma_f32_16x16x32_bf16 v[56:59], v[168:171], v[176:179], v[56:59]
	v_mfma_f32_16x16x32_bf16 v[52:55], v[160:163], v[184:187], v[52:55]
	v_mfma_f32_16x16x32_bf16 v[48:51], v[168:171], v[184:187], v[48:51]
	v_mfma_f32_16x16x32_bf16 v[44:47], v[160:163], v[192:195], v[44:47]
	v_mfma_f32_16x16x32_bf16 v[40:43], v[168:171], v[192:195], v[40:43]
	v_mfma_f32_16x16x32_bf16 v[36:39], v[160:163], v[200:203], v[36:39]
	v_mfma_f32_16x16x32_bf16 v[32:35], v[168:171], v[200:203], v[32:35]
	s_barrier
; #define WAIT_V(n) asm volatile("s_waitcnt vmcnt(" #n ")" ::: "memory")
; #define WAIT_L(n) asm volatile("s_waitcnt lgkmcnt(" #n ")" ::: "memory")
; #define BAR __builtin_amdgcn_s_barrier()
; #define SCHED __builtin_amdgcn_sched_barrier(0)
; #define STAGE(P, BASE, br, kt) do { const char* _g = (const char*)((BASE) + (size_t)(br) * GK + (kt) * BK); \
;     __builtin_amdgcn_global_load_lds((const unsigned*)(_g + voff0), (unsigned*)((char*)(P) + tx * 16), 16, 0, 0); \
;     __builtin_amdgcn_global_load_lds((const unsigned*)(_g + voff1), (unsigned*)((char*)(P) + tx * 16 + 8192), 16, 0, 0); } while (0)
; #define LDA(dst, b, h) _Pragma("unroll") for (int m = 0; m < 4; ++m) _Pragma("unroll") for (int k = 0; k < 2; ++k) \
;     dst[m][k] = *reinterpret_cast<const bf16x8*>((char*)shm + abase + (((b) * 2 + (h)) * 16384 + (m * 2 + k) * 1024))
; #define LDB(dst, b, h) _Pragma("unroll") for (int n = 0; n < 2; ++n) _Pragma("unroll") for (int k = 0; k < 2; ++k) \
;     dst[n][k] = *reinterpret_cast<const bf16x8*>((char*)shm + bbase + (((b) * 2 + (h)) * 16384 + (n * 2 + k) * 1024))
; template <bool SWAP>
; __device__ __forceinline__ void gemm_main(const u16* __restrict__ A, const u16* __restrict__ Bt, int brow, int bcol,
;                                           u16* shm, f32x4 (&acc)[2][2][4][2]) {
;     ...
;     BAR; WAIT_L(0); MMA(1, 0, At, B0); BAR; SCHED;
;     STAGE(SB(0, 1), Bt, bcol + HALF, t + 2);
;     WAIT_V(6); BAR; MMA(1, 1, At, B1); BAR;
;     LDB(B0, 1, 0); SCHED; LDA(At, 1, 0); STAGE(SA(0, 1), A, brow + HALF, t + 2);
;     WAIT_L(8); BAR; WAIT_L(0); MMA(0, 0, At, B0); BAR; SCHED;
;     LDB(B1, 1, 1); STAGE(SB(1, 0), Bt, bcol, t + 3);
	s_setprio 0
	v_lshl_add_u64 v[156:157], v[226:227], 0, s[12:13]
	s_add_u32 m0, s25, s45
	s_nop 0
	global_load_lds_dwordx4 v[156:157], off
	v_lshl_add_u64 v[156:157], v[228:229], 0, s[12:13]
	s_add_u32 m0, s25, s45
	s_add_u32 m0, m0, 0x2000
	s_nop 0
	global_load_lds_dwordx4 v[156:157], off
	s_waitcnt vmcnt(6)
	s_setprio 1
	s_barrier
	v_mfma_f32_16x16x32_bf16 v[28:31], v[204:207], v[172:175], v[28:31]
	v_mfma_f32_16x16x32_bf16 v[24:27], v[216:219], v[172:175], v[24:27]
	v_mfma_f32_16x16x32_bf16 v[20:23], v[204:207], v[180:183], v[20:23]
	v_mfma_f32_16x16x32_bf16 v[16:19], v[216:219], v[180:183], v[16:19]
	v_mfma_f32_16x16x32_bf16 v[12:15], v[204:207], v[188:191], v[12:15]
	v_mfma_f32_16x16x32_bf16 v[8:11], v[216:219], v[188:191], v[8:11]
	v_mfma_f32_16x16x32_bf16 v[4:7], v[204:207], v[196:199], v[4:7]
	v_mfma_f32_16x16x32_bf16 v[0:3], v[216:219], v[196:199], v[0:3]
	v_mfma_f32_16x16x32_bf16 v[28:31], v[212:215], v[176:179], v[28:31]
	v_mfma_f32_16x16x32_bf16 v[24:27], v[220:223], v[176:179], v[24:27]
	v_mfma_f32_16x16x32_bf16 v[20:23], v[212:215], v[184:187], v[20:23]
	v_mfma_f32_16x16x32_bf16 v[16:19], v[220:223], v[184:187], v[16:19]
	v_mfma_f32_16x16x32_bf16 v[12:15], v[212:215], v[192:195], v[12:15]
	v_mfma_f32_16x16x32_bf16 v[8:11], v[220:223], v[192:195], v[8:11]
	v_mfma_f32_16x16x32_bf16 v[4:7], v[212:215], v[200:203], v[4:7]
	v_mfma_f32_16x16x32_bf16 v[0:3], v[220:223], v[200:203], v[0:3]
	s_barrier
	s_setprio 0
	ds_read_b128 v[156:159], v146 offset:32768
	ds_read_b128 v[160:163], v146 offset:33792
	ds_read_b128 v[164:167], v146 offset:34816
	ds_read_b128 v[168:171], v146 offset:35840
	ds_read_b128 v[172:175], v145 offset:32768
	ds_read_b128 v[176:179], v145 offset:33792
	ds_read_b128 v[180:183], v145 offset:34816
	ds_read_b128 v[184:187], v145 offset:35840
	ds_read_b128 v[188:191], v145 offset:36864
	ds_read_b128 v[192:195], v145 offset:37888
	ds_read_b128 v[196:199], v145 offset:38912
	ds_read_b128 v[200:203], v145 offset:39936
	v_lshl_add_u64 v[204:205], v[208:209], 0, s[14:15]
	s_add_u32 m0, s25, 0x4000
	s_nop 0
	global_load_lds_dwordx4 v[204:205], off
	v_lshl_add_u64 v[204:205], v[224:225], 0, s[14:15]
	s_add_u32 m0, s25, 0x6000
	s_nop 0
	global_load_lds_dwordx4 v[204:205], off
	s_waitcnt lgkmcnt(8)
	s_setprio 1
	s_barrier
	s_waitcnt lgkmcnt(0)
	v_mfma_f32_16x16x32_bf16 v[124:127], v[156:159], v[172:175], v[124:127]
	v_mfma_f32_16x16x32_bf16 v[120:123], v[164:167], v[172:175], v[120:123]
	v_mfma_f32_16x16x32_bf16 v[116:119], v[156:159], v[180:183], v[116:119]
	v_mfma_f32_16x16x32_bf16 v[112:115], v[164:167], v[180:183], v[112:115]
	v_mfma_f32_16x16x32_bf16 v[108:111], v[156:159], v[188:191], v[108:111]
	v_mfma_f32_16x16x32_bf16 v[104:107], v[164:167], v[188:191], v[104:107]
	v_mfma_f32_16x16x32_bf16 v[100:103], v[156:159], v[196:199], v[100:103]
	v_mfma_f32_16x16x32_bf16 v[96:99], v[164:167], v[196:199], v[96:99]
	v_mfma_f32_16x16x32_bf16 v[124:127], v[160:163], v[176:179], v[124:127]
	v_mfma_f32_16x16x32_bf16 v[120:123], v[168:171], v[176:179], v[120:123]
	v_mfma_f32_16x16x32_bf16 v[116:119], v[160:163], v[184:187], v[116:119]
	v_mfma_f32_16x16x32_bf16 v[112:115], v[168:171], v[184:187], v[112:115]
	v_mfma_f32_16x16x32_bf16 v[108:111], v[160:163], v[192:195], v[108:111]
	v_mfma_f32_16x16x32_bf16 v[104:107], v[168:171], v[192:195], v[104:107]
	v_mfma_f32_16x16x32_bf16 v[100:103], v[160:163], v[200:203], v[100:103]
	v_mfma_f32_16x16x32_bf16 v[96:99], v[168:171], v[200:203], v[96:99]
	s_barrier
	s_setprio 0
	ds_read_b128 v[204:207], v146 offset:49152
	ds_read_b128 v[212:215], v146 offset:50176
	ds_read_b128 v[216:219], v146 offset:51200
	ds_read_b128 v[220:223], v146 offset:52224
	v_lshl_add_u64 v[230:231], v[226:227], 0, s[16:17]
	s_add_u32 m0, s25, s52
	s_nop 0
	global_load_lds_dwordx4 v[230:231], off
	v_lshl_add_u64 v[230:231], v[228:229], 0, s[16:17]
	s_add_u32 m0, s25, s52
	s_add_u32 m0, m0, 0x2000
	s_nop 0
	global_load_lds_dwordx4 v[230:231], off
	s_setprio 1
	s_barrier
	s_waitcnt lgkmcnt(0)
	v_mfma_f32_16x16x32_bf16 v[92:95], v[204:207], v[172:175], v[92:95]
	v_mfma_f32_16x16x32_bf16 v[88:91], v[216:219], v[172:175], v[88:91]
	v_mfma_f32_16x16x32_bf16 v[84:87], v[204:207], v[180:183], v[84:87]
	v_mfma_f32_16x16x32_bf16 v[80:83], v[216:219], v[180:183], v[80:83]
	v_mfma_f32_16x16x32_bf16 v[76:79], v[204:207], v[188:191], v[76:79]
	v_mfma_f32_16x16x32_bf16 v[72:75], v[216:219], v[188:191], v[72:75]
	v_mfma_f32_16x16x32_bf16 v[68:71], v[204:207], v[196:199], v[68:71]
	v_mfma_f32_16x16x32_bf16 v[64:67], v[216:219], v[196:199], v[64:67]
	v_mfma_f32_16x16x32_bf16 v[92:95], v[212:215], v[176:179], v[92:95]
	v_mfma_f32_16x16x32_bf16 v[88:91], v[220:223], v[176:179], v[88:91]
	v_mfma_f32_16x16x32_bf16 v[84:87], v[212:215], v[184:187], v[84:87]
	v_mfma_f32_16x16x32_bf16 v[80:83], v[220:223], v[184:187], v[80:83]
	v_mfma_f32_16x16x32_bf16 v[76:79], v[212:215], v[192:195], v[76:79]
	v_mfma_f32_16x16x32_bf16 v[72:75], v[220:223], v[192:195], v[72:75]
	v_mfma_f32_16x16x32_bf16 v[68:71], v[212:215], v[200:203], v[68:71]
	v_mfma_f32_16x16x32_bf16 v[64:67], v[220:223], v[200:203], v[64:67]
	s_barrier
	s_setprio 0
	ds_read_b128 v[172:175], v145 offset:49152
	ds_read_b128 v[176:179], v145 offset:50176
	ds_read_b128 v[180:183], v145 offset:51200
	ds_read_b128 v[184:187], v145 offset:52224
	ds_read_b128 v[188:191], v145 offset:53248
	ds_read_b128 v[192:195], v145 offset:54272
	ds_read_b128 v[196:199], v145 offset:55296
	ds_read_b128 v[200:203], v145 offset:56320
	v_lshl_add_u64 v[208:209], v[208:209], 0, s[18:19]
	s_add_u32 m0, s25, 0x8000
	s_nop 0
	global_load_lds_dwordx4 v[208:209], off
	v_lshl_add_u64 v[208:209], v[224:225], 0, s[18:19]
	s_add_u32 m0, s25, 0xa000
	s_nop 0
	global_load_lds_dwordx4 v[208:209], off
	s_setprio 1
	s_barrier
; #define WAIT_V(n) asm volatile("s_waitcnt vmcnt(" #n ")" ::: "memory")
; #define WAIT_L(n) asm volatile("s_waitcnt lgkmcnt(" #n ")" ::: "memory")
; #define BAR __builtin_amdgcn_s_barrier()
; #define SCHED __builtin_amdgcn_sched_barrier(0)
; #define STAGE(P, BASE, br, kt) do { const char* _g = (const char*)((BASE) + (size_t)(br) * GK + (kt) * BK); \
;     __builtin_amdgcn_global_load_lds((const unsigned*)(_g + voff0), (unsigned*)((char*)(P) + tx * 16), 16, 0, 0); \
;     __builtin_amdgcn_global_load_lds((const unsigned*)(_g + voff1), (unsigned*)((char*)(P) + tx * 16 + 8192), 16, 0, 0); } while (0)
; #define LDA(dst, b, h) _Pragma("unroll") for (int m = 0; m < 4; ++m) _Pragma("unroll") for (int k = 0; k < 2; ++k) \
;     dst[m][k] = *reinterpret_cast<const bf16x8*>((char*)shm + abase + (((b) * 2 + (h)) * 16384 + (m * 2 + k) * 1024))
; #define LDB(dst, b, h) _Pragma("unroll") for (int n = 0; n < 2; ++n) _Pragma("unroll") for (int k = 0; k < 2; ++k) \
;     dst[n][k] = *reinterpret_cast<const bf16x8*>((char*)shm + bbase + (((b) * 2 + (h)) * 16384 + (n * 2 + k) * 1024))
; template <bool SWAP>
; __device__ __forceinline__ void gemm_main(const u16* __restrict__ A, const u16* __restrict__ Bt, int brow, int bcol,
;                                           u16* shm, f32x4 (&acc)[2][2][4][2]) {
;     ...
;     LDB(B1, 1, 1); STAGE(SB(1, 0), Bt, bcol, t + 3);
;     BAR; WAIT_L(0); MMA(0, 1, At, B1); BAR;
;     LDA(At, 1, 1); STAGE(SA(1, 0), A, brow, t + 3);
;     BAR; WAIT_L(0); MMA(1, 0, At, B0); BAR; SCHED;
;     STAGE(SB(1, 1), Bt, bcol + HALF, t + 3);
;     WAIT_V(6); BAR; MMA(1, 1, At, B1); BAR;
;   }
;   { LDB(B0, 0, 0); LDA(At, 0, 0); STAGE(SA(1, 1), A, brow + HALF, nt - 1);
;     BAR; WAIT_L(0); MMA(0, 0, At, B0); BAR;
	s_waitcnt lgkmcnt(0)
	v_mfma_f32_16x16x32_bf16 v[60:63], v[156:159], v[172:175], v[60:63]
	v_mfma_f32_16x16x32_bf16 v[56:59], v[164:167], v[172:175], v[56:59]
	v_mfma_f32_16x16x32_bf16 v[52:55], v[156:159], v[180:183], v[52:55]
	v_mfma_f32_16x16x32_bf16 v[48:51], v[164:167], v[180:183], v[48:51]
	v_mfma_f32_16x16x32_bf16 v[44:47], v[156:159], v[188:191], v[44:47]
	v_mfma_f32_16x16x32_bf16 v[40:43], v[164:167], v[188:191], v[40:43]
	v_mfma_f32_16x16x32_bf16 v[36:39], v[156:159], v[196:199], v[36:39]
	v_mfma_f32_16x16x32_bf16 v[32:35], v[164:167], v[196:199], v[32:35]
	v_mfma_f32_16x16x32_bf16 v[60:63], v[160:163], v[176:179], v[60:63]
	v_mfma_f32_16x16x32_bf16 v[56:59], v[168:171], v[176:179], v[56:59]
	v_mfma_f32_16x16x32_bf16 v[52:55], v[160:163], v[184:187], v[52:55]
	v_mfma_f32_16x16x32_bf16 v[48:51], v[168:171], v[184:187], v[48:51]
	v_mfma_f32_16x16x32_bf16 v[44:47], v[160:163], v[192:195], v[44:47]
	v_mfma_f32_16x16x32_bf16 v[40:43], v[168:171], v[192:195], v[40:43]
	v_mfma_f32_16x16x32_bf16 v[36:39], v[160:163], v[200:203], v[36:39]
	v_mfma_f32_16x16x32_bf16 v[32:35], v[168:171], v[200:203], v[32:35]
	s_barrier
	s_setprio 0
	v_lshl_add_u64 v[156:157], v[226:227], 0, s[20:21]
	s_add_u32 m0, s25, s53
	s_nop 0
	global_load_lds_dwordx4 v[156:157], off
	v_lshl_add_u64 v[156:157], v[228:229], 0, s[20:21]
	s_add_u32 m0, s25, s53
	s_add_u32 m0, m0, 0x2000
	s_nop 0
	global_load_lds_dwordx4 v[156:157], off
	s_waitcnt vmcnt(6)
	s_setprio 1
	s_barrier
	v_mfma_f32_16x16x32_bf16 v[28:31], v[204:207], v[172:175], v[28:31]
	v_mfma_f32_16x16x32_bf16 v[24:27], v[216:219], v[172:175], v[24:27]
	v_mfma_f32_16x16x32_bf16 v[20:23], v[204:207], v[180:183], v[20:23]
	v_mfma_f32_16x16x32_bf16 v[16:19], v[216:219], v[180:183], v[16:19]
	v_mfma_f32_16x16x32_bf16 v[12:15], v[204:207], v[188:191], v[12:15]
	v_mfma_f32_16x16x32_bf16 v[8:11], v[216:219], v[188:191], v[8:11]
	v_mfma_f32_16x16x32_bf16 v[4:7], v[204:207], v[196:199], v[4:7]
	v_mfma_f32_16x16x32_bf16 v[0:3], v[216:219], v[196:199], v[0:3]
	v_mfma_f32_16x16x32_bf16 v[28:31], v[212:215], v[176:179], v[28:31]
	v_mfma_f32_16x16x32_bf16 v[24:27], v[220:223], v[176:179], v[24:27]
	v_mfma_f32_16x16x32_bf16 v[20:23], v[212:215], v[184:187], v[20:23]
	v_mfma_f32_16x16x32_bf16 v[16:19], v[220:223], v[184:187], v[16:19]
	v_mfma_f32_16x16x32_bf16 v[12:15], v[212:215], v[192:195], v[12:15]
	v_mfma_f32_16x16x32_bf16 v[8:11], v[220:223], v[192:195], v[8:11]
	v_mfma_f32_16x16x32_bf16 v[4:7], v[212:215], v[200:203], v[4:7]
	v_mfma_f32_16x16x32_bf16 v[0:3], v[220:223], v[200:203], v[0:3]
	s_add_i32 s4, s4, 2
	s_add_u32 s28, s28, 0x100
	s_addc_u32 s29, s29, 0
	s_cmp_lt_u32 s4, 28
	s_barrier
	s_setprio 0
	s_cbranch_scc1 .LBB0_94
	v_lshlrev_b32_e32 v128, 3, v148
	v_lshlrev_b32_e32 v130, 5, v148
	v_and_b32_e32 v128, 0xffff0, v128
	v_and_b32_e32 v130, 32, v130
	s_or_b32 s28, s26, 0x80
	v_add_u32_e32 v130, v130, v150
	v_add_lshl_u32 v128, v149, v128, 12
	s_ashr_i32 s29, s28, 31
	v_lshl_add_u32 v128, v130, 1, v128
	v_lshlrev_b32_e32 v130, 3, v151
	v_lshlrev_b32_e32 v131, 5, v151
	s_lshl_b64 s[28:29], s[28:29], 12
	v_and_b32_e32 v130, 0xffff0, v130
	v_and_b32_e32 v131, 32, v131
	s_add_u32 s28, s37, s28
	v_add_u32_e32 v131, v131, v153
	v_add_lshl_u32 v130, v152, v130, 12
	s_addc_u32 s29, s38, s29
	v_lshl_add_u32 v152, v131, 1, v130
	v_mov_b32_e32 v153, v129
	v_lshl_add_u64 v[192:193], s[28:29], 0, v[128:129]
	v_readfirstlane_b32 s4, v154
	v_lshl_add_u64 v[192:193], v[192:193], 0, s[22:23]
	s_mov_b32 m0, s4
	v_lshl_add_u64 v[152:153], s[28:29], 0, v[152:153]
	v_readfirstlane_b32 s4, v155
	ds_read_b128 v[130:133], v146
	ds_read_b128 v[134:137], v146 offset:1024
	ds_read_b128 v[148:151], v146 offset:2048
	ds_read_b128 v[156:159], v146 offset:3072
	ds_read_b128 v[160:163], v145
	ds_read_b128 v[164:167], v145 offset:1024
	ds_read_b128 v[168:171], v145 offset:2048
	ds_read_b128 v[172:175], v145 offset:3072
	ds_read_b128 v[176:179], v145 offset:4096
	ds_read_b128 v[180:183], v145 offset:5120
	ds_read_b128 v[184:187], v145 offset:6144
	ds_read_b128 v[188:191], v145 offset:7168
	global_load_lds_dwordx4 v[192:193], off
	v_lshl_add_u64 v[152:153], v[152:153], 0, s[22:23]
	s_mov_b32 m0, s4
	s_nop 0
	global_load_lds_dwordx4 v[152:153], off
	s_barrier
	s_waitcnt lgkmcnt(0)
	s_setprio 1
	s_waitcnt lgkmcnt(0)
	v_mfma_f32_16x16x32_bf16 v[124:127], v[130:133], v[160:163], v[124:127]
	v_mfma_f32_16x16x32_bf16 v[116:119], v[130:133], v[168:171], v[116:119]
	v_mfma_f32_16x16x32_bf16 v[108:111], v[130:133], v[176:179], v[108:111]
	v_mfma_f32_16x16x32_bf16 v[100:103], v[130:133], v[184:187], v[100:103]
	v_mfma_f32_16x16x32_bf16 v[124:127], v[134:137], v[164:167], v[124:127]
	v_mfma_f32_16x16x32_bf16 v[120:123], v[148:151], v[160:163], v[120:123]
	v_mfma_f32_16x16x32_bf16 v[116:119], v[134:137], v[172:175], v[116:119]
	v_mfma_f32_16x16x32_bf16 v[112:115], v[148:151], v[168:171], v[112:115]
	v_mfma_f32_16x16x32_bf16 v[108:111], v[134:137], v[180:183], v[108:111]
	v_mfma_f32_16x16x32_bf16 v[104:107], v[148:151], v[176:179], v[104:107]
	v_mfma_f32_16x16x32_bf16 v[100:103], v[134:137], v[188:191], v[100:103]
	v_mfma_f32_16x16x32_bf16 v[96:99], v[148:151], v[184:187], v[96:99]
	v_mfma_f32_16x16x32_bf16 v[152:155], v[156:159], v[164:167], v[120:123]
	v_mfma_f32_16x16x32_bf16 v[192:195], v[156:159], v[172:175], v[112:115]
	v_mfma_f32_16x16x32_bf16 v[196:199], v[156:159], v[180:183], v[104:107]
	v_mfma_f32_16x16x32_bf16 v[200:203], v[156:159], v[188:191], v[96:99]
	s_setprio 0
	s_barrier
	s_nop 1
	ds_read_b128 v[96:99], v146 offset:16384
	ds_read_b128 v[104:107], v146 offset:17408
	ds_read_b128 v[112:115], v146 offset:18432
	ds_read_b128 v[120:123], v146 offset:19456
	s_barrier
; #define WAIT_V(n) asm volatile("s_waitcnt vmcnt(" #n ")" ::: "memory")
; #define WAIT_L(n) asm volatile("s_waitcnt lgkmcnt(" #n ")" ::: "memory")
; #define BAR __builtin_amdgcn_s_barrier()
; #define LDA(dst, b, h) _Pragma("unroll") for (int m = 0; m < 4; ++m) _Pragma("unroll") for (int k = 0; k < 2; ++k) \
;     dst[m][k] = *reinterpret_cast<const bf16x8*>((char*)shm + abase + (((b) * 2 + (h)) * 16384 + (m * 2 + k) * 1024))
; #define LDB(dst, b, h) _Pragma("unroll") for (int n = 0; n < 2; ++n) _Pragma("unroll") for (int k = 0; k < 2; ++k) \
;     dst[n][k] = *reinterpret_cast<const bf16x8*>((char*)shm + bbase + (((b) * 2 + (h)) * 16384 + (n * 2 + k) * 1024))
; template <bool SWAP>
; __device__ __forceinline__ void gemm_main(const u16* __restrict__ A, const u16* __restrict__ Bt, int brow, int bcol,
;                                           u16* shm, f32x4 (&acc)[2][2][4][2]) {
;     ...
;     BAR; WAIT_L(0); MMA(0, 0, At, B0); BAR;
;     LDB(B1, 0, 1); BAR; WAIT_L(0); MMA(0, 1, At, B1); BAR;
;     LDA(At, 0, 1); WAIT_V(4); BAR; WAIT_L(0); MMA(1, 0, At, B0); MMA(1, 1, At, B1); BAR; }
;   { LDB(B0, 1, 0); LDA(At, 1, 0); WAIT_V(2); BAR; WAIT_L(0); MMA(0, 0, At, B0); BAR;
	s_waitcnt lgkmcnt(0)
	s_setprio 1
	s_waitcnt lgkmcnt(0)
	v_mfma_f32_16x16x32_bf16 v[92:95], v[96:99], v[160:163], v[92:95]
	v_mfma_f32_16x16x32_bf16 v[84:87], v[96:99], v[168:171], v[84:87]
	v_mfma_f32_16x16x32_bf16 v[76:79], v[96:99], v[176:179], v[76:79]
	v_mfma_f32_16x16x32_bf16 v[68:71], v[96:99], v[184:187], v[68:71]
	v_mfma_f32_16x16x32_bf16 v[92:95], v[104:107], v[164:167], v[92:95]
	v_mfma_f32_16x16x32_bf16 v[88:91], v[112:115], v[160:163], v[88:91]
	v_mfma_f32_16x16x32_bf16 v[84:87], v[104:107], v[172:175], v[84:87]
	v_mfma_f32_16x16x32_bf16 v[80:83], v[112:115], v[168:171], v[80:83]
	v_mfma_f32_16x16x32_bf16 v[76:79], v[104:107], v[180:183], v[76:79]
	v_mfma_f32_16x16x32_bf16 v[72:75], v[112:115], v[176:179], v[72:75]
	v_mfma_f32_16x16x32_bf16 v[68:71], v[104:107], v[188:191], v[68:71]
	v_mfma_f32_16x16x32_bf16 v[64:67], v[112:115], v[184:187], v[64:67]
	v_mfma_f32_16x16x32_bf16 v[160:163], v[120:123], v[164:167], v[88:91]
	v_mfma_f32_16x16x32_bf16 v[164:167], v[120:123], v[172:175], v[80:83]
	v_mfma_f32_16x16x32_bf16 v[168:171], v[120:123], v[180:183], v[72:75]
	v_mfma_f32_16x16x32_bf16 v[172:175], v[120:123], v[188:191], v[64:67]
	s_setprio 0
	s_barrier
	s_nop 1
	ds_read_b128 v[64:67], v145 offset:16384
	ds_read_b128 v[72:75], v145 offset:17408
	ds_read_b128 v[80:83], v145 offset:18432
	ds_read_b128 v[88:91], v145 offset:19456
	ds_read_b128 v[176:179], v145 offset:20480
	ds_read_b128 v[180:183], v145 offset:21504
	ds_read_b128 v[184:187], v145 offset:22528
	ds_read_b128 v[188:191], v145 offset:23552
	s_waitcnt vmcnt(4)
	s_barrier
	s_waitcnt lgkmcnt(0)
	s_setprio 1
	s_waitcnt lgkmcnt(0)
	v_mfma_f32_16x16x32_bf16 v[60:63], v[130:133], v[64:67], v[60:63]
	v_mfma_f32_16x16x32_bf16 v[52:55], v[130:133], v[80:83], v[52:55]
	v_mfma_f32_16x16x32_bf16 v[44:47], v[130:133], v[176:179], v[44:47]
	v_mfma_f32_16x16x32_bf16 v[36:39], v[130:133], v[184:187], v[36:39]
	v_mfma_f32_16x16x32_bf16 v[60:63], v[134:137], v[72:75], v[60:63]
	v_mfma_f32_16x16x32_bf16 v[56:59], v[148:151], v[64:67], v[56:59]
	v_mfma_f32_16x16x32_bf16 v[52:55], v[134:137], v[88:91], v[52:55]
	v_mfma_f32_16x16x32_bf16 v[48:51], v[148:151], v[80:83], v[48:51]
	v_mfma_f32_16x16x32_bf16 v[44:47], v[134:137], v[180:183], v[44:47]
	v_mfma_f32_16x16x32_bf16 v[40:43], v[148:151], v[176:179], v[40:43]
	v_mfma_f32_16x16x32_bf16 v[36:39], v[134:137], v[188:191], v[36:39]
	v_mfma_f32_16x16x32_bf16 v[32:35], v[148:151], v[184:187], v[32:35]
	v_mfma_f32_16x16x32_bf16 v[204:207], v[156:159], v[72:75], v[56:59]
	v_mfma_f32_16x16x32_bf16 v[212:215], v[156:159], v[88:91], v[48:51]
	v_mfma_f32_16x16x32_bf16 v[216:219], v[156:159], v[180:183], v[40:43]
	v_mfma_f32_16x16x32_bf16 v[130:133], v[156:159], v[188:191], v[32:35]
	s_setprio 0
	s_setprio 1
	v_mfma_f32_16x16x32_bf16 v[28:31], v[96:99], v[64:67], v[28:31]
	v_mfma_f32_16x16x32_bf16 v[20:23], v[96:99], v[80:83], v[20:23]
	v_mfma_f32_16x16x32_bf16 v[12:15], v[96:99], v[176:179], v[12:15]
	v_mfma_f32_16x16x32_bf16 v[4:7], v[96:99], v[184:187], v[4:7]
	v_mfma_f32_16x16x32_bf16 v[28:31], v[104:107], v[72:75], v[28:31]
	v_mfma_f32_16x16x32_bf16 v[24:27], v[112:115], v[64:67], v[24:27]
	v_mfma_f32_16x16x32_bf16 v[20:23], v[104:107], v[88:91], v[20:23]
	v_mfma_f32_16x16x32_bf16 v[16:19], v[112:115], v[80:83], v[16:19]
	v_mfma_f32_16x16x32_bf16 v[12:15], v[104:107], v[180:183], v[12:15]
	v_mfma_f32_16x16x32_bf16 v[8:11], v[112:115], v[176:179], v[8:11]
	v_mfma_f32_16x16x32_bf16 v[4:7], v[104:107], v[188:191], v[4:7]
	v_mfma_f32_16x16x32_bf16 v[0:3], v[112:115], v[184:187], v[0:3]
	v_mfma_f32_16x16x32_bf16 v[134:137], v[120:123], v[72:75], v[24:27]
	v_mfma_f32_16x16x32_bf16 v[148:151], v[120:123], v[88:91], v[16:19]
	v_mfma_f32_16x16x32_bf16 v[156:159], v[120:123], v[180:183], v[8:11]
	v_mfma_f32_16x16x32_bf16 v[176:179], v[120:123], v[188:191], v[0:3]
	s_setprio 0
	s_barrier
	s_nop 1
	ds_read_b128 v[0:3], v146 offset:32768
	ds_read_b128 v[8:11], v146 offset:33792
	ds_read_b128 v[16:19], v146 offset:34816
	ds_read_b128 v[24:27], v146 offset:35840
	ds_read_b128 v[32:35], v145 offset:32768
	ds_read_b128 v[40:43], v145 offset:33792
	ds_read_b128 v[48:51], v145 offset:34816
	ds_read_b128 v[56:59], v145 offset:35840
	ds_read_b128 v[64:67], v145 offset:36864
	ds_read_b128 v[180:183], v145 offset:37888
	ds_read_b128 v[184:187], v145 offset:38912
	ds_read_b128 v[188:191], v145 offset:39936
	s_waitcnt vmcnt(2)
	s_barrier
; #define WAIT_V(n) asm volatile("s_waitcnt vmcnt(" #n ")" ::: "memory")
; #define WAIT_L(n) asm volatile("s_waitcnt lgkmcnt(" #n ")" ::: "memory")
; #define BAR __builtin_amdgcn_s_barrier()
; #define LDA(dst, b, h) _Pragma("unroll") for (int m = 0; m < 4; ++m) _Pragma("unroll") for (int k = 0; k < 2; ++k) \
;     dst[m][k] = *reinterpret_cast<const bf16x8*>((char*)shm + abase + (((b) * 2 + (h)) * 16384 + (m * 2 + k) * 1024))
; #define LDB(dst, b, h) _Pragma("unroll") for (int n = 0; n < 2; ++n) _Pragma("unroll") for (int k = 0; k < 2; ++k) \
;     dst[n][k] = *reinterpret_cast<const bf16x8*>((char*)shm + bbase + (((b) * 2 + (h)) * 16384 + (n * 2 + k) * 1024))
; template <bool SWAP>
; __device__ __forceinline__ void gemm_main(const u16* __restrict__ A, const u16* __restrict__ Bt, int brow, int bcol,
;                                           u16* shm, f32x4 (&acc)[2][2][4][2]) {
;     ...
;   { LDB(B0, 1, 0); LDA(At, 1, 0); WAIT_V(2); BAR; WAIT_L(0); MMA(0, 0, At, B0); BAR;
;     LDB(B1, 1, 1); WAIT_V(0); BAR; WAIT_L(0); MMA(0, 1, At, B1); BAR;
;     LDA(At, 1, 1); BAR; WAIT_L(0); MMA(1, 0, At, B0); MMA(1, 1, At, B1); BAR; }
;   if (wr == 0) BAR;
	s_waitcnt lgkmcnt(0)
	s_setprio 1
	s_waitcnt lgkmcnt(0)
	v_mfma_f32_16x16x32_bf16 v[72:75], v[0:3], v[32:35], v[124:127]
	v_mfma_f32_16x16x32_bf16 v[120:123], v[8:11], v[40:43], v[72:75]
	v_mfma_f32_16x16x32_bf16 v[72:75], v[16:19], v[32:35], v[152:155]
	v_mfma_f32_16x16x32_bf16 v[124:127], v[24:27], v[40:43], v[72:75]
	v_mfma_f32_16x16x32_bf16 v[72:75], v[0:3], v[48:51], v[116:119]
	v_mfma_f32_16x16x32_bf16 v[112:115], v[8:11], v[56:59], v[72:75]
	v_mfma_f32_16x16x32_bf16 v[72:75], v[16:19], v[48:51], v[192:195]
	v_mfma_f32_16x16x32_bf16 v[116:119], v[24:27], v[56:59], v[72:75]
	v_mfma_f32_16x16x32_bf16 v[72:75], v[0:3], v[64:67], v[108:111]
	v_mfma_f32_16x16x32_bf16 v[104:107], v[8:11], v[180:183], v[72:75]
	v_mfma_f32_16x16x32_bf16 v[72:75], v[16:19], v[64:67], v[196:199]
	v_mfma_f32_16x16x32_bf16 v[108:111], v[24:27], v[180:183], v[72:75]
	v_mfma_f32_16x16x32_bf16 v[72:75], v[0:3], v[184:187], v[100:103]
	v_mfma_f32_16x16x32_bf16 v[96:99], v[8:11], v[188:191], v[72:75]
	v_mfma_f32_16x16x32_bf16 v[72:75], v[16:19], v[184:187], v[200:203]
	v_mfma_f32_16x16x32_bf16 v[100:103], v[24:27], v[188:191], v[72:75]
	s_setprio 0
	s_barrier
	ds_read_b128 v[152:155], v146 offset:49152
	ds_read_b128 v[192:195], v146 offset:50176
	ds_read_b128 v[196:199], v146 offset:51200
	ds_read_b128 v[200:203], v146 offset:52224
	s_waitcnt vmcnt(0)
	s_barrier
	s_waitcnt lgkmcnt(0)
	s_setprio 1
	s_waitcnt lgkmcnt(0)
	v_mfma_f32_16x16x32_bf16 v[72:75], v[152:155], v[32:35], v[92:95]
	v_mfma_f32_16x16x32_bf16 v[32:35], v[196:199], v[32:35], v[160:163]
	v_mfma_f32_16x16x32_bf16 v[92:95], v[200:203], v[40:43], v[32:35]
	v_mfma_f32_16x16x32_bf16 v[32:35], v[152:155], v[48:51], v[84:87]
	v_mfma_f32_16x16x32_bf16 v[80:83], v[192:195], v[56:59], v[32:35]
	v_mfma_f32_16x16x32_bf16 v[32:35], v[196:199], v[48:51], v[164:167]
	v_mfma_f32_16x16x32_bf16 v[84:87], v[200:203], v[56:59], v[32:35]
	v_mfma_f32_16x16x32_bf16 v[32:35], v[152:155], v[64:67], v[76:79]
	v_mfma_f32_16x16x32_bf16 v[88:91], v[192:195], v[40:43], v[72:75]
	v_mfma_f32_16x16x32_bf16 v[72:75], v[192:195], v[180:183], v[32:35]
	v_mfma_f32_16x16x32_bf16 v[32:35], v[196:199], v[64:67], v[168:171]
	v_mfma_f32_16x16x32_bf16 v[76:79], v[200:203], v[180:183], v[32:35]
	v_mfma_f32_16x16x32_bf16 v[32:35], v[152:155], v[184:187], v[68:71]
	v_mfma_f32_16x16x32_bf16 v[64:67], v[192:195], v[188:191], v[32:35]
	v_mfma_f32_16x16x32_bf16 v[32:35], v[196:199], v[184:187], v[172:175]
	v_mfma_f32_16x16x32_bf16 v[68:71], v[200:203], v[188:191], v[32:35]
	s_setprio 0
	s_barrier
	ds_read_b128 v[160:163], v145 offset:49152
	ds_read_b128 v[164:167], v145 offset:50176
	ds_read_b128 v[168:171], v145 offset:51200
	ds_read_b128 v[172:175], v145 offset:52224
	ds_read_b128 v[180:183], v145 offset:53248
	ds_read_b128 v[184:187], v145 offset:54272
	ds_read_b128 v[188:191], v145 offset:55296
	ds_read_b128 v[220:223], v145 offset:56320
	s_barrier
	s_waitcnt lgkmcnt(0)
	s_setprio 1
	s_waitcnt lgkmcnt(0)
	v_mfma_f32_16x16x32_bf16 v[32:35], v[0:3], v[160:163], v[60:63]
	v_mfma_f32_16x16x32_bf16 v[56:59], v[8:11], v[164:167], v[32:35]
	v_mfma_f32_16x16x32_bf16 v[32:35], v[16:19], v[160:163], v[204:207]
	v_mfma_f32_16x16x32_bf16 v[60:63], v[24:27], v[164:167], v[32:35]
	v_mfma_f32_16x16x32_bf16 v[32:35], v[0:3], v[168:171], v[52:55]
	v_mfma_f32_16x16x32_bf16 v[48:51], v[8:11], v[172:175], v[32:35]
	v_mfma_f32_16x16x32_bf16 v[32:35], v[16:19], v[168:171], v[212:215]
	v_mfma_f32_16x16x32_bf16 v[52:55], v[24:27], v[172:175], v[32:35]
	v_mfma_f32_16x16x32_bf16 v[32:35], v[0:3], v[180:183], v[44:47]
	v_mfma_f32_16x16x32_bf16 v[40:43], v[8:11], v[184:187], v[32:35]
	v_mfma_f32_16x16x32_bf16 v[32:35], v[16:19], v[180:183], v[216:219]
	v_mfma_f32_16x16x32_bf16 v[0:3], v[0:3], v[188:191], v[36:39]
	v_mfma_f32_16x16x32_bf16 v[44:47], v[24:27], v[184:187], v[32:35]
	v_mfma_f32_16x16x32_bf16 v[32:35], v[8:11], v[220:223], v[0:3]
	v_mfma_f32_16x16x32_bf16 v[0:3], v[16:19], v[188:191], v[130:133]
	v_mfma_f32_16x16x32_bf16 v[36:39], v[24:27], v[220:223], v[0:3]
	s_setprio 0
	s_setprio 1
	v_mfma_f32_16x16x32_bf16 v[0:3], v[152:155], v[160:163], v[28:31]
	v_mfma_f32_16x16x32_bf16 v[24:27], v[192:195], v[164:167], v[0:3]
	v_mfma_f32_16x16x32_bf16 v[0:3], v[196:199], v[160:163], v[134:137]
	v_mfma_f32_16x16x32_bf16 v[28:31], v[200:203], v[164:167], v[0:3]
	v_mfma_f32_16x16x32_bf16 v[0:3], v[152:155], v[168:171], v[20:23]
	v_mfma_f32_16x16x32_bf16 v[16:19], v[192:195], v[172:175], v[0:3]
	v_mfma_f32_16x16x32_bf16 v[0:3], v[196:199], v[168:171], v[148:151]
	v_mfma_f32_16x16x32_bf16 v[20:23], v[200:203], v[172:175], v[0:3]
	v_mfma_f32_16x16x32_bf16 v[0:3], v[152:155], v[180:183], v[12:15]
	v_mfma_f32_16x16x32_bf16 v[8:11], v[192:195], v[184:187], v[0:3]
	v_mfma_f32_16x16x32_bf16 v[0:3], v[196:199], v[180:183], v[156:159]
	v_mfma_f32_16x16x32_bf16 v[12:15], v[200:203], v[184:187], v[0:3]
	v_mfma_f32_16x16x32_bf16 v[0:3], v[152:155], v[188:191], v[4:7]
	v_mfma_f32_16x16x32_bf16 v[4:7], v[196:199], v[188:191], v[176:179]
	v_mfma_f32_16x16x32_bf16 v[0:3], v[192:195], v[220:223], v[0:3]
	v_mfma_f32_16x16x32_bf16 v[4:7], v[200:203], v[220:223], v[4:7]
	s_setprio 0
	v_cmp_gt_u32_e32 vcc, s55, v144
	s_barrier
	s_and_saveexec_b64 s[28:29], vcc
	s_cbranch_execz .LBB0_97
	s_barrier

; #define WAIT_V(n) asm volatile("s_waitcnt vmcnt(" #n ")" ::: "memory")
; #define BAR __builtin_amdgcn_s_barrier()
; template <bool SWAP>
; __device__ __forceinline__ void gemm_main(const u16* __restrict__ A, const u16* __restrict__ Bt, int brow, int bcol,
;                                           u16* shm, f32x4 (&acc)[2][2][4][2]) {
;     ...
;   int tx = threadIdx.x; asm volatile("" : "+v"(tx));
;   const int wid = tx >> 6, lane = tx & 63, wr = wid >> 2, wc = wid & 3, fr = lane & 15, fq = lane >> 4;
; #pragma unroll
;   for (int a = 0; a < 2; ++a)
; #pragma unroll
;     for (int b = 0; b < 2; ++b)
; #pragma unroll
;       for (int m = 0; m < 4; ++m)
; #pragma unroll
;         for (int n = 0; n < 2; ++n) acc[a][b][m][n] = f32x4{0.f, 0.f, 0.f, 0.f};
;   bf16x8 At[4][2], B0[2][2], B1[2][2];
;   constexpr int nt = GK / BK;
;   GEMM_VOFF
;   const int lpart = (fr * 64 + fq * 16) ^ ((fr >> 3) << 5);
;   const int abase = wr * 8192 + lpart; int bbase = 65536 + wc * 4096 + lpart;
;   asm volatile("" : "+v"(bbase));
;   if (wr == 1) BAR;
;   WAIT_V(0); BAR;
;   BAR;
.LBB0_113:
	s_or_b64 exec, exec, s[0:1]
	v_bfe_i32 v4, v136, 27, 1
	v_lshlrev_b32_e32 v153, 4, v136
	v_lshrrev_b32_e32 v4, 22, v4
	v_add_u32_e32 v4, v153, v4
	v_and_b32_e32 v4, 0xfffffc00, v4
	v_sub_u32_e32 v4, v153, v4
	v_lshrrev_b32_e32 v5, 4, v4
	v_bitop3_b32 v4, v5, v4, 32 bitop3:0x6c
	v_ashrrev_i32_e32 v5, 31, v4
	v_lshrrev_b32_e32 v5, 26, v5
	v_add_u32_e32 v5, v4, v5
	v_ashrrev_i32_e32 v155, 6, v5
	v_and_b32_e32 v5, 0xc0, v5
	v_sub_u32_e32 v4, v4, v5
	v_ashrrev_i16_sdwa v4, v215, sext(v4) dst_sel:DWORD dst_unused:UNUSED_PAD src0_sel:DWORD src1_sel:BYTE_0
	v_bfe_i32 v156, v4, 0, 16
	v_add_u32_e32 v4, 0x2000, v153
	v_ashrrev_i32_e32 v5, 31, v4
	v_lshrrev_b32_e32 v5, 22, v5
	v_add_u32_e32 v5, v4, v5
	v_ashrrev_i32_e32 v157, 10, v5
	v_mul_i32_i24_e32 v5, 0x400, v157
	v_sub_u32_e32 v4, v4, v5
	v_lshrrev_b32_e32 v5, 4, v4
	v_bitop3_b32 v4, v5, v4, 32 bitop3:0x6c
	v_ashrrev_i32_e32 v5, 31, v4
	v_lshrrev_b32_e32 v5, 26, v5
	v_ashrrev_i32_e32 v3, 31, v136
	v_add_u32_e32 v5, v4, v5
	v_lshrrev_b32_e32 v3, 26, v3
	v_ashrrev_i32_e32 v158, 6, v5
	v_and_b32_e32 v5, 0xc0, v5
	v_add_u32_e32 v3, v136, v3
	v_sub_u32_e32 v4, v4, v5
	v_ashrrev_i32_e32 v154, 6, v3
	v_ashrrev_i16_sdwa v4, v215, sext(v4) dst_sel:DWORD dst_unused:UNUSED_PAD src0_sel:DWORD src1_sel:BYTE_0
	v_bfe_i32 v159, v4, 0, 16
	v_lshlrev_b32_e32 v4, 13, v0
	v_lshlrev_b32_e32 v0, 15, v154
	v_and_b32_e32 v0, 0xffff0000, v0
	v_lshl_add_u32 v0, v155, 12, v0
	v_and_or_b32 v0, v3, 64, v0
	v_lshl_add_u32 v192, v156, 1, v0
	v_lshlrev_b32_e32 v0, 15, v157
	v_readlane_b32 s0, v253, 59
	v_and_b32_e32 v0, 0xffff0000, v0
	v_add_u32_e32 v5, 0, v2
	v_readlane_b32 s1, v253, 60
	v_lshl_add_u32 v0, v158, 12, v0
	v_lshlrev_b32_e32 v2, 6, v157
	s_mov_b32 s5, s1
	s_lshl_b32 s4, s2, 19
	v_writelane_b32 v253, s0, 59
	v_and_or_b32 v0, v2, 64, v0
	v_lshl_add_u32 v2, v159, 1, v0
	v_writelane_b32 v253, s1, 60
	s_lshl_b64 s[0:1], s[4:5], 1
	v_mov_b32_e32 v3, v193
	v_lshl_add_u64 v[128:129], s[0:1], 0, v[192:193]
	v_lshl_add_u64 v[130:131], s[0:1], 0, v[2:3]
	s_add_i32 s0, s93, s73
	s_waitcnt vmcnt(0)
	s_ashr_i32 s1, s0, 31
	s_lshl_b64 s[0:1], s[0:1], 12
	v_mov_b32_e32 v0, 0
	v_lshl_add_u64 v[132:133], s[0:1], 0, v[192:193]
	v_lshl_add_u64 v[134:135], s[0:1], 0, v[2:3]
	s_mov_b32 s3, -2
	v_add_u32_e32 v152, 0, v1
	v_add_u32_e32 v137, v5, v4
	s_mov_b64 s[0:1], s[50:51]
	v_mov_b32_e32 v1, v0
	v_mov_b32_e32 v2, v0
	v_mov_b32_e32 v3, v0
	v_mov_b32_e32 v4, v0
	v_mov_b32_e32 v5, v0
	v_mov_b32_e32 v6, v0
	v_mov_b32_e32 v7, v0
	v_mov_b32_e32 v8, v0
	v_mov_b32_e32 v9, v0
	v_mov_b32_e32 v10, v0
	v_mov_b32_e32 v11, v0
	v_mov_b32_e32 v12, v0
	v_mov_b32_e32 v13, v0
	v_mov_b32_e32 v14, v0
	v_mov_b32_e32 v15, v0
	v_mov_b32_e32 v16, v0
	v_mov_b32_e32 v17, v0
	v_mov_b32_e32 v18, v0
	v_mov_b32_e32 v19, v0
	v_mov_b32_e32 v20, v0
	v_mov_b32_e32 v21, v0
	v_mov_b32_e32 v22, v0
	v_mov_b32_e32 v23, v0
	v_mov_b32_e32 v24, v0
	v_mov_b32_e32 v25, v0
	v_mov_b32_e32 v26, v0
	v_mov_b32_e32 v27, v0
	v_mov_b32_e32 v28, v0
	v_mov_b32_e32 v29, v0
	v_mov_b32_e32 v30, v0
	v_mov_b32_e32 v31, v0
	v_mov_b32_e32 v32, v0
	v_mov_b32_e32 v33, v0
	v_mov_b32_e32 v34, v0
	v_mov_b32_e32 v35, v0
	v_mov_b32_e32 v36, v0
	v_mov_b32_e32 v37, v0
	v_mov_b32_e32 v38, v0
	v_mov_b32_e32 v39, v0
	v_mov_b32_e32 v40, v0
	v_mov_b32_e32 v41, v0
	v_mov_b32_e32 v42, v0
	v_mov_b32_e32 v43, v0
	v_mov_b32_e32 v44, v0
	v_mov_b32_e32 v45, v0
	v_mov_b32_e32 v46, v0
	v_mov_b32_e32 v47, v0
	v_mov_b32_e32 v48, v0
	v_mov_b32_e32 v49, v0
	v_mov_b32_e32 v50, v0
	v_mov_b32_e32 v51, v0
	v_mov_b32_e32 v52, v0
	v_mov_b32_e32 v53, v0
	v_mov_b32_e32 v54, v0
	v_mov_b32_e32 v55, v0
	v_mov_b32_e32 v56, v0
	v_mov_b32_e32 v57, v0
	v_mov_b32_e32 v58, v0
	v_mov_b32_e32 v59, v0
	v_mov_b32_e32 v60, v0
	v_mov_b32_e32 v61, v0
	v_mov_b32_e32 v62, v0
	v_mov_b32_e32 v63, v0
	v_mov_b32_e32 v64, v0
	v_mov_b32_e32 v65, v0
	v_mov_b32_e32 v66, v0
	v_mov_b32_e32 v67, v0
	v_mov_b32_e32 v68, v0
	v_mov_b32_e32 v69, v0
	v_mov_b32_e32 v70, v0
	v_mov_b32_e32 v71, v0
	v_mov_b32_e32 v72, v0
	v_mov_b32_e32 v73, v0
	v_mov_b32_e32 v74, v0
	v_mov_b32_e32 v75, v0
	v_mov_b32_e32 v76, v0
	v_mov_b32_e32 v77, v0
	v_mov_b32_e32 v78, v0
	v_mov_b32_e32 v79, v0
	v_mov_b32_e32 v80, v0
	v_mov_b32_e32 v81, v0
	v_mov_b32_e32 v82, v0
	v_mov_b32_e32 v83, v0
	v_mov_b32_e32 v84, v0
	v_mov_b32_e32 v85, v0
	v_mov_b32_e32 v86, v0
	v_mov_b32_e32 v87, v0
	v_mov_b32_e32 v88, v0
	v_mov_b32_e32 v89, v0
	v_mov_b32_e32 v90, v0
	v_mov_b32_e32 v91, v0
	v_mov_b32_e32 v92, v0
	v_mov_b32_e32 v93, v0
	v_mov_b32_e32 v94, v0
	v_mov_b32_e32 v95, v0
	v_mov_b32_e32 v96, v0
	v_mov_b32_e32 v97, v0
	v_mov_b32_e32 v98, v0
	v_mov_b32_e32 v99, v0
	v_mov_b32_e32 v100, v0
	v_mov_b32_e32 v101, v0
	v_mov_b32_e32 v102, v0
	v_mov_b32_e32 v103, v0
	v_mov_b32_e32 v104, v0
	v_mov_b32_e32 v105, v0
	v_mov_b32_e32 v106, v0
	v_mov_b32_e32 v107, v0
	v_mov_b32_e32 v108, v0
	v_mov_b32_e32 v109, v0
	v_mov_b32_e32 v110, v0
	v_mov_b32_e32 v111, v0
	v_mov_b32_e32 v112, v0
	v_mov_b32_e32 v113, v0
	v_mov_b32_e32 v114, v0
	v_mov_b32_e32 v115, v0
	v_mov_b32_e32 v116, v0
	v_mov_b32_e32 v117, v0
	v_mov_b32_e32 v118, v0
	v_mov_b32_e32 v119, v0
	v_mov_b32_e32 v120, v0
	v_mov_b32_e32 v121, v0
	v_mov_b32_e32 v122, v0
	v_mov_b32_e32 v123, v0
	v_mov_b32_e32 v124, v0
	v_mov_b32_e32 v125, v0
	v_mov_b32_e32 v126, v0
	v_mov_b32_e32 v127, v0
	v_readfirstlane_b32 s4, v153
	s_barrier
	s_barrier
; #define WAIT_L(n) asm volatile("s_waitcnt lgkmcnt(" #n ")" ::: "memory")
; #define BAR __builtin_amdgcn_s_barrier()
; #define SCHED __builtin_amdgcn_sched_barrier(0)
; #define STAGE(P, BASE, br, kt) do { const char* _g = (const char*)((BASE) + (size_t)(br) * GK + (kt) * BK); \
;     __builtin_amdgcn_global_load_lds((const unsigned*)(_g + voff0), (unsigned*)((char*)(P) + tx * 16), 16, 0, 0); \
;     __builtin_amdgcn_global_load_lds((const unsigned*)(_g + voff1), (unsigned*)((char*)(P) + tx * 16 + 8192), 16, 0, 0); } while (0)
; #define LDA(dst, b, h) _Pragma("unroll") for (int m = 0; m < 4; ++m) _Pragma("unroll") for (int k = 0; k < 2; ++k) \
;     dst[m][k] = *reinterpret_cast<const bf16x8*>((char*)shm + abase + (((b) * 2 + (h)) * 16384 + (m * 2 + k) * 1024))
; #define LDB(dst, b, h) _Pragma("unroll") for (int n = 0; n < 2; ++n) _Pragma("unroll") for (int k = 0; k < 2; ++k) \
;     dst[n][k] = *reinterpret_cast<const bf16x8*>((char*)shm + bbase + (((b) * 2 + (h)) * 16384 + (n * 2 + k) * 1024))
; template <bool SWAP>
; __device__ __forceinline__ void gemm_main(const u16* __restrict__ A, const u16* __restrict__ Bt, int brow, int bcol,
;                                           u16* shm, f32x4 (&acc)[2][2][4][2]) {
;     ...
;   for (int t = 0; t < nt - 2; t += 2) {
;     LDB(B0, 0, 0); SCHED; LDA(At, 0, 0); STAGE(SA(1, 1), A, brow + HALF, t + 1);
;     WAIT_L(8); BAR; WAIT_L(0); MMA(0, 0, At, B0); BAR; SCHED;
;     LDB(B1, 0, 1); STAGE(SB(0, 0), Bt, bcol, t + 2);
;     BAR; WAIT_L(0); MMA(0, 1, At, B1); BAR;
;     LDA(At, 0, 1); STAGE(SA(0, 0), A, brow, t + 2);
.LBB0_114:
	ds_read_b128 v[162:165], v152
	ds_read_b128 v[166:169], v152 offset:1024
	ds_read_b128 v[170:173], v152 offset:2048
	ds_read_b128 v[174:177], v152 offset:3072
	ds_read_b128 v[178:181], v137
	ds_read_b128 v[182:185], v137 offset:1024
	ds_read_b128 v[186:189], v137 offset:2048
	ds_read_b128 v[194:197], v137 offset:3072
	ds_read_b128 v[198:201], v137 offset:4096
	ds_read_b128 v[202:205], v137 offset:5120
	ds_read_b128 v[206:209], v137 offset:6144
	ds_read_b128 v[222:225], v137 offset:7168
	v_add_u32_e32 v192, 0, v153
	v_add_u32_e32 v160, 0xc000, v192
	v_lshl_add_u64 v[190:191], s[0:1], 0, v[132:133]
	v_add_u32_e32 v161, 0xe000, v192
	v_lshl_add_u64 v[226:227], v[190:191], 0, s[82:83]
	s_add_u32 m0, s4, 0xc000
	v_lshl_add_u64 v[242:243], s[0:1], 0, v[134:135]
	global_load_lds_dwordx4 v[226:227], off
	v_lshl_add_u64 v[226:227], v[242:243], 0, s[82:83]
	s_add_u32 m0, s4, 0xe000
	s_nop 0
	global_load_lds_dwordx4 v[226:227], off
	s_waitcnt lgkmcnt(8)
	s_setprio 1
	s_barrier
	s_waitcnt lgkmcnt(0)
	v_mfma_f32_16x16x32_bf16 v[124:127], v[178:181], v[162:165], v[124:127]
	v_mfma_f32_16x16x32_bf16 v[120:123], v[178:181], v[170:173], v[120:123]
	v_mfma_f32_16x16x32_bf16 v[116:119], v[186:189], v[162:165], v[116:119]
	v_mfma_f32_16x16x32_bf16 v[112:115], v[186:189], v[170:173], v[112:115]
	v_mfma_f32_16x16x32_bf16 v[108:111], v[198:201], v[162:165], v[108:111]
	v_mfma_f32_16x16x32_bf16 v[104:107], v[198:201], v[170:173], v[104:107]
	v_mfma_f32_16x16x32_bf16 v[100:103], v[206:209], v[162:165], v[100:103]
	v_mfma_f32_16x16x32_bf16 v[96:99], v[206:209], v[170:173], v[96:99]
	v_mfma_f32_16x16x32_bf16 v[124:127], v[182:185], v[166:169], v[124:127]
	v_mfma_f32_16x16x32_bf16 v[120:123], v[182:185], v[174:177], v[120:123]
	v_mfma_f32_16x16x32_bf16 v[116:119], v[194:197], v[166:169], v[116:119]
	v_mfma_f32_16x16x32_bf16 v[112:115], v[194:197], v[174:177], v[112:115]
	v_mfma_f32_16x16x32_bf16 v[108:111], v[202:205], v[166:169], v[108:111]
	v_mfma_f32_16x16x32_bf16 v[104:107], v[202:205], v[174:177], v[104:107]
	v_mfma_f32_16x16x32_bf16 v[100:103], v[222:225], v[166:169], v[100:103]
	v_mfma_f32_16x16x32_bf16 v[96:99], v[222:225], v[174:177], v[96:99]
	s_barrier
	s_setprio 0
	ds_read_b128 v[226:229], v152 offset:16384
	ds_read_b128 v[230:233], v152 offset:17408
	ds_read_b128 v[234:237], v152 offset:18432
	ds_read_b128 v[238:241], v152 offset:19456
	v_lshl_add_u64 v[244:245], s[0:1], 0, v[128:129]
	v_lshl_add_u64 v[246:247], v[244:245], 0, s[74:75]
	s_add_u32 m0, s4, s28
	s_nop 0
	global_load_lds_dwordx4 v[246:247], off
	v_lshl_add_u64 v[246:247], s[0:1], 0, v[130:131]
	v_lshl_add_u64 v[248:249], v[246:247], 0, s[74:75]
	s_add_u32 m0, s4, s28
	s_add_u32 m0, m0, 0x2000
	s_nop 0
	global_load_lds_dwordx4 v[248:249], off
	s_setprio 1
	s_barrier
	s_waitcnt lgkmcnt(0)
	v_mfma_f32_16x16x32_bf16 v[92:95], v[178:181], v[226:229], v[92:95]
	v_mfma_f32_16x16x32_bf16 v[88:91], v[178:181], v[234:237], v[88:91]
	v_mfma_f32_16x16x32_bf16 v[84:87], v[186:189], v[226:229], v[84:87]
	v_mfma_f32_16x16x32_bf16 v[80:83], v[186:189], v[234:237], v[80:83]
	v_mfma_f32_16x16x32_bf16 v[76:79], v[198:201], v[226:229], v[76:79]
	v_mfma_f32_16x16x32_bf16 v[72:75], v[198:201], v[234:237], v[72:75]
	v_mfma_f32_16x16x32_bf16 v[68:71], v[206:209], v[226:229], v[68:71]
	v_mfma_f32_16x16x32_bf16 v[64:67], v[206:209], v[234:237], v[64:67]
	v_mfma_f32_16x16x32_bf16 v[92:95], v[182:185], v[230:233], v[92:95]
	v_mfma_f32_16x16x32_bf16 v[88:91], v[182:185], v[238:241], v[88:91]
	v_mfma_f32_16x16x32_bf16 v[84:87], v[194:197], v[230:233], v[84:87]
	v_mfma_f32_16x16x32_bf16 v[80:83], v[194:197], v[238:241], v[80:83]
	v_mfma_f32_16x16x32_bf16 v[76:79], v[202:205], v[230:233], v[76:79]
	v_mfma_f32_16x16x32_bf16 v[72:75], v[202:205], v[238:241], v[72:75]
	v_mfma_f32_16x16x32_bf16 v[68:71], v[222:225], v[230:233], v[68:71]
	v_mfma_f32_16x16x32_bf16 v[64:67], v[222:225], v[238:241], v[64:67]
	s_barrier
	s_setprio 0
	ds_read_b128 v[178:181], v137 offset:16384
	ds_read_b128 v[182:185], v137 offset:17408
	ds_read_b128 v[186:189], v137 offset:18432
	ds_read_b128 v[194:197], v137 offset:19456
	ds_read_b128 v[198:201], v137 offset:20480
	ds_read_b128 v[202:205], v137 offset:21504
	ds_read_b128 v[206:209], v137 offset:22528
	ds_read_b128 v[222:225], v137 offset:23552
	v_lshl_add_u64 v[248:249], v[190:191], 0, s[76:77]
	s_add_u32 m0, s4, 0x0
	s_nop 0
	global_load_lds_dwordx4 v[248:249], off
	v_lshl_add_u64 v[248:249], v[242:243], 0, s[76:77]
	s_add_u32 m0, s4, 0x2000
	s_nop 0
	global_load_lds_dwordx4 v[248:249], off
	s_setprio 1
	s_barrier
	s_waitcnt lgkmcnt(0)
	v_mfma_f32_16x16x32_bf16 v[60:63], v[178:181], v[162:165], v[60:63]
	v_mfma_f32_16x16x32_bf16 v[56:59], v[178:181], v[170:173], v[56:59]
	v_mfma_f32_16x16x32_bf16 v[52:55], v[186:189], v[162:165], v[52:55]
	v_mfma_f32_16x16x32_bf16 v[48:51], v[186:189], v[170:173], v[48:51]
	v_mfma_f32_16x16x32_bf16 v[44:47], v[198:201], v[162:165], v[44:47]
	v_mfma_f32_16x16x32_bf16 v[40:43], v[198:201], v[170:173], v[40:43]
	v_mfma_f32_16x16x32_bf16 v[36:39], v[206:209], v[162:165], v[36:39]
	v_mfma_f32_16x16x32_bf16 v[32:35], v[206:209], v[170:173], v[32:35]
	v_mfma_f32_16x16x32_bf16 v[60:63], v[182:185], v[166:169], v[60:63]
	v_mfma_f32_16x16x32_bf16 v[56:59], v[182:185], v[174:177], v[56:59]
	v_mfma_f32_16x16x32_bf16 v[52:55], v[194:197], v[166:169], v[52:55]
	v_mfma_f32_16x16x32_bf16 v[48:51], v[194:197], v[174:177], v[48:51]
	v_mfma_f32_16x16x32_bf16 v[44:47], v[202:205], v[166:169], v[44:47]
	v_mfma_f32_16x16x32_bf16 v[40:43], v[202:205], v[174:177], v[40:43]
	v_mfma_f32_16x16x32_bf16 v[36:39], v[222:225], v[166:169], v[36:39]
	v_mfma_f32_16x16x32_bf16 v[32:35], v[222:225], v[174:177], v[32:35]
	s_barrier
; #define WAIT_V(n) asm volatile("s_waitcnt vmcnt(" #n ")" ::: "memory")
; #define WAIT_L(n) asm volatile("s_waitcnt lgkmcnt(" #n ")" ::: "memory")
; #define BAR __builtin_amdgcn_s_barrier()
; #define SCHED __builtin_amdgcn_sched_barrier(0)
; #define STAGE(P, BASE, br, kt) do { const char* _g = (const char*)((BASE) + (size_t)(br) * GK + (kt) * BK); \
;     __builtin_amdgcn_global_load_lds((const unsigned*)(_g + voff0), (unsigned*)((char*)(P) + tx * 16), 16, 0, 0); \
;     __builtin_amdgcn_global_load_lds((const unsigned*)(_g + voff1), (unsigned*)((char*)(P) + tx * 16 + 8192), 16, 0, 0); } while (0)
; #define LDA(dst, b, h) _Pragma("unroll") for (int m = 0; m < 4; ++m) _Pragma("unroll") for (int k = 0; k < 2; ++k) \
;     dst[m][k] = *reinterpret_cast<const bf16x8*>((char*)shm + abase + (((b) * 2 + (h)) * 16384 + (m * 2 + k) * 1024))
; #define LDB(dst, b, h) _Pragma("unroll") for (int n = 0; n < 2; ++n) _Pragma("unroll") for (int k = 0; k < 2; ++k) \
;     dst[n][k] = *reinterpret_cast<const bf16x8*>((char*)shm + bbase + (((b) * 2 + (h)) * 16384 + (n * 2 + k) * 1024))
; template <bool SWAP>
; __device__ __forceinline__ void gemm_main(const u16* __restrict__ A, const u16* __restrict__ Bt, int brow, int bcol,
;                                           u16* shm, f32x4 (&acc)[2][2][4][2]) {
;     ...
;     BAR; WAIT_L(0); MMA(1, 0, At, B0); BAR; SCHED;
;     STAGE(SB(0, 1), Bt, bcol + HALF, t + 2);
;     WAIT_V(6); BAR; MMA(1, 1, At, B1); BAR;
;     LDB(B0, 1, 0); SCHED; LDA(At, 1, 0); STAGE(SA(0, 1), A, brow + HALF, t + 2);
;     WAIT_L(8); BAR; WAIT_L(0); MMA(0, 0, At, B0); BAR; SCHED;
;     LDB(B1, 1, 1); STAGE(SB(1, 0), Bt, bcol, t + 3);
	s_setprio 0
	v_lshl_add_u64 v[162:163], v[244:245], 0, s[70:71]
	s_add_u32 m0, s4, s29
	s_nop 0
	global_load_lds_dwordx4 v[162:163], off
	v_lshl_add_u64 v[162:163], v[246:247], 0, s[70:71]
	s_add_u32 m0, s4, s29
	s_add_u32 m0, m0, 0x2000
	s_nop 0
	global_load_lds_dwordx4 v[162:163], off
	s_waitcnt vmcnt(6)
	s_setprio 1
	s_barrier
	v_mfma_f32_16x16x32_bf16 v[28:31], v[178:181], v[226:229], v[28:31]
	v_mfma_f32_16x16x32_bf16 v[24:27], v[178:181], v[234:237], v[24:27]
	v_mfma_f32_16x16x32_bf16 v[20:23], v[186:189], v[226:229], v[20:23]
	v_mfma_f32_16x16x32_bf16 v[16:19], v[186:189], v[234:237], v[16:19]
	v_mfma_f32_16x16x32_bf16 v[12:15], v[198:201], v[226:229], v[12:15]
	v_mfma_f32_16x16x32_bf16 v[8:11], v[198:201], v[234:237], v[8:11]
	v_mfma_f32_16x16x32_bf16 v[4:7], v[206:209], v[226:229], v[4:7]
	v_mfma_f32_16x16x32_bf16 v[0:3], v[206:209], v[234:237], v[0:3]
	v_mfma_f32_16x16x32_bf16 v[28:31], v[182:185], v[230:233], v[28:31]
	v_mfma_f32_16x16x32_bf16 v[24:27], v[182:185], v[238:241], v[24:27]
	v_mfma_f32_16x16x32_bf16 v[20:23], v[194:197], v[230:233], v[20:23]
	v_mfma_f32_16x16x32_bf16 v[16:19], v[194:197], v[238:241], v[16:19]
	v_mfma_f32_16x16x32_bf16 v[12:15], v[202:205], v[230:233], v[12:15]
	v_mfma_f32_16x16x32_bf16 v[8:11], v[202:205], v[238:241], v[8:11]
	v_mfma_f32_16x16x32_bf16 v[4:7], v[222:225], v[230:233], v[4:7]
	v_mfma_f32_16x16x32_bf16 v[0:3], v[222:225], v[238:241], v[0:3]
	s_barrier
	s_setprio 0
	ds_read_b128 v[162:165], v152 offset:32768
	ds_read_b128 v[166:169], v152 offset:33792
	ds_read_b128 v[170:173], v152 offset:34816
	ds_read_b128 v[174:177], v152 offset:35840
	ds_read_b128 v[178:181], v137 offset:32768
	ds_read_b128 v[182:185], v137 offset:33792
	ds_read_b128 v[186:189], v137 offset:34816
	ds_read_b128 v[194:197], v137 offset:35840
	ds_read_b128 v[198:201], v137 offset:36864
	ds_read_b128 v[202:205], v137 offset:37888
	ds_read_b128 v[206:209], v137 offset:38912
	ds_read_b128 v[222:225], v137 offset:39936
	v_lshl_add_u64 v[226:227], v[190:191], 0, s[96:97]
	s_add_u32 m0, s4, 0x4000
	s_nop 0
	global_load_lds_dwordx4 v[226:227], off
	v_lshl_add_u64 v[226:227], v[242:243], 0, s[96:97]
	s_add_u32 m0, s4, 0x6000
	s_nop 0
	global_load_lds_dwordx4 v[226:227], off
	s_waitcnt lgkmcnt(8)
	s_setprio 1
	s_barrier
	s_waitcnt lgkmcnt(0)
	v_mfma_f32_16x16x32_bf16 v[124:127], v[178:181], v[162:165], v[124:127]
	v_mfma_f32_16x16x32_bf16 v[120:123], v[178:181], v[170:173], v[120:123]
	v_mfma_f32_16x16x32_bf16 v[116:119], v[186:189], v[162:165], v[116:119]
	v_mfma_f32_16x16x32_bf16 v[112:115], v[186:189], v[170:173], v[112:115]
	v_mfma_f32_16x16x32_bf16 v[108:111], v[198:201], v[162:165], v[108:111]
	v_mfma_f32_16x16x32_bf16 v[104:107], v[198:201], v[170:173], v[104:107]
	v_mfma_f32_16x16x32_bf16 v[100:103], v[206:209], v[162:165], v[100:103]
	v_mfma_f32_16x16x32_bf16 v[96:99], v[206:209], v[170:173], v[96:99]
	v_mfma_f32_16x16x32_bf16 v[124:127], v[182:185], v[166:169], v[124:127]
	v_mfma_f32_16x16x32_bf16 v[120:123], v[182:185], v[174:177], v[120:123]
	v_mfma_f32_16x16x32_bf16 v[116:119], v[194:197], v[166:169], v[116:119]
	v_mfma_f32_16x16x32_bf16 v[112:115], v[194:197], v[174:177], v[112:115]
	v_mfma_f32_16x16x32_bf16 v[108:111], v[202:205], v[166:169], v[108:111]
	v_mfma_f32_16x16x32_bf16 v[104:107], v[202:205], v[174:177], v[104:107]
	v_mfma_f32_16x16x32_bf16 v[100:103], v[222:225], v[166:169], v[100:103]
	v_mfma_f32_16x16x32_bf16 v[96:99], v[222:225], v[174:177], v[96:99]
	s_barrier
	s_setprio 0
	ds_read_b128 v[226:229], v152 offset:49152
	ds_read_b128 v[230:233], v152 offset:50176
	ds_read_b128 v[234:237], v152 offset:51200
	ds_read_b128 v[238:241], v152 offset:52224
	v_add_u32_e32 v250, s30, v153
	v_lshl_add_u64 v[248:249], v[244:245], 0, s[34:35]
	v_add_u32_e32 v250, 0x2000, v250
	s_add_u32 m0, s4, s30
	s_nop 0
	global_load_lds_dwordx4 v[248:249], off
	v_lshl_add_u64 v[248:249], v[246:247], 0, s[34:35]
	s_add_u32 m0, s4, s30
	s_add_u32 m0, m0, 0x2000
	s_nop 0
	global_load_lds_dwordx4 v[248:249], off
	s_setprio 1
	s_barrier
	s_waitcnt lgkmcnt(0)
	v_mfma_f32_16x16x32_bf16 v[92:95], v[178:181], v[226:229], v[92:95]
	v_mfma_f32_16x16x32_bf16 v[88:91], v[178:181], v[234:237], v[88:91]
	v_mfma_f32_16x16x32_bf16 v[84:87], v[186:189], v[226:229], v[84:87]
	v_mfma_f32_16x16x32_bf16 v[80:83], v[186:189], v[234:237], v[80:83]
	v_mfma_f32_16x16x32_bf16 v[76:79], v[198:201], v[226:229], v[76:79]
	v_mfma_f32_16x16x32_bf16 v[72:75], v[198:201], v[234:237], v[72:75]
	v_mfma_f32_16x16x32_bf16 v[68:71], v[206:209], v[226:229], v[68:71]
	v_mfma_f32_16x16x32_bf16 v[64:67], v[206:209], v[234:237], v[64:67]
	v_mfma_f32_16x16x32_bf16 v[92:95], v[182:185], v[230:233], v[92:95]
	v_mfma_f32_16x16x32_bf16 v[88:91], v[182:185], v[238:241], v[88:91]
	v_mfma_f32_16x16x32_bf16 v[84:87], v[194:197], v[230:233], v[84:87]
	v_mfma_f32_16x16x32_bf16 v[80:83], v[194:197], v[238:241], v[80:83]
	v_mfma_f32_16x16x32_bf16 v[76:79], v[202:205], v[230:233], v[76:79]
	v_mfma_f32_16x16x32_bf16 v[72:75], v[202:205], v[238:241], v[72:75]
	v_mfma_f32_16x16x32_bf16 v[68:71], v[222:225], v[230:233], v[68:71]
	v_mfma_f32_16x16x32_bf16 v[64:67], v[222:225], v[238:241], v[64:67]
	s_barrier
	s_setprio 0
	ds_read_b128 v[178:181], v137 offset:49152
	ds_read_b128 v[182:185], v137 offset:50176
	ds_read_b128 v[186:189], v137 offset:51200
	ds_read_b128 v[194:197], v137 offset:52224
	ds_read_b128 v[198:201], v137 offset:53248
	ds_read_b128 v[202:205], v137 offset:54272
	ds_read_b128 v[206:209], v137 offset:55296
	ds_read_b128 v[222:225], v137 offset:56320
	v_add_u32_e32 v248, 0x8000, v192
	v_lshl_add_u64 v[190:191], v[190:191], 0, s[36:37]
	s_add_u32 m0, s4, 0x8000
	s_nop 0
	global_load_lds_dwordx4 v[190:191], off
	v_lshl_add_u64 v[190:191], v[242:243], 0, s[36:37]
	s_add_u32 m0, s4, 0xa000
	s_nop 0
	global_load_lds_dwordx4 v[190:191], off
	s_setprio 1
	s_barrier
; #define WAIT_V(n) asm volatile("s_waitcnt vmcnt(" #n ")" ::: "memory")
; #define WAIT_L(n) asm volatile("s_waitcnt lgkmcnt(" #n ")" ::: "memory")
; #define BAR __builtin_amdgcn_s_barrier()
; #define SCHED __builtin_amdgcn_sched_barrier(0)
; #define STAGE(P, BASE, br, kt) do { const char* _g = (const char*)((BASE) + (size_t)(br) * GK + (kt) * BK); \
;     __builtin_amdgcn_global_load_lds((const unsigned*)(_g + voff0), (unsigned*)((char*)(P) + tx * 16), 16, 0, 0); \
;     __builtin_amdgcn_global_load_lds((const unsigned*)(_g + voff1), (unsigned*)((char*)(P) + tx * 16 + 8192), 16, 0, 0); } while (0)
; #define LDA(dst, b, h) _Pragma("unroll") for (int m = 0; m < 4; ++m) _Pragma("unroll") for (int k = 0; k < 2; ++k) \
;     dst[m][k] = *reinterpret_cast<const bf16x8*>((char*)shm + abase + (((b) * 2 + (h)) * 16384 + (m * 2 + k) * 1024))
; #define LDB(dst, b, h) _Pragma("unroll") for (int n = 0; n < 2; ++n) _Pragma("unroll") for (int k = 0; k < 2; ++k) \
;     dst[n][k] = *reinterpret_cast<const bf16x8*>((char*)shm + bbase + (((b) * 2 + (h)) * 16384 + (n * 2 + k) * 1024))
; template <bool SWAP>
; __device__ __forceinline__ void gemm_main(const u16* __restrict__ A, const u16* __restrict__ Bt, int brow, int bcol,
;                                           u16* shm, f32x4 (&acc)[2][2][4][2]) {
;     ...
;     LDB(B1, 1, 1); STAGE(SB(1, 0), Bt, bcol, t + 3);
;     BAR; WAIT_L(0); MMA(0, 1, At, B1); BAR;
;     LDA(At, 1, 1); STAGE(SA(1, 0), A, brow, t + 3);
;     BAR; WAIT_L(0); MMA(1, 0, At, B0); BAR; SCHED;
;     STAGE(SB(1, 1), Bt, bcol + HALF, t + 3);
;     WAIT_V(6); BAR; MMA(1, 1, At, B1); BAR;
;   }
;   { LDB(B0, 0, 0); LDA(At, 0, 0); STAGE(SA(1, 1), A, brow + HALF, nt - 1);
;     BAR; WAIT_L(0); MMA(0, 0, At, B0); BAR;
	s_waitcnt lgkmcnt(0)
	v_mfma_f32_16x16x32_bf16 v[60:63], v[178:181], v[162:165], v[60:63]
	v_mfma_f32_16x16x32_bf16 v[56:59], v[178:181], v[170:173], v[56:59]
	v_mfma_f32_16x16x32_bf16 v[52:55], v[186:189], v[162:165], v[52:55]
	v_mfma_f32_16x16x32_bf16 v[48:51], v[186:189], v[170:173], v[48:51]
	v_mfma_f32_16x16x32_bf16 v[44:47], v[198:201], v[162:165], v[44:47]
	v_mfma_f32_16x16x32_bf16 v[40:43], v[198:201], v[170:173], v[40:43]
	v_mfma_f32_16x16x32_bf16 v[36:39], v[206:209], v[162:165], v[36:39]
	v_mfma_f32_16x16x32_bf16 v[32:35], v[206:209], v[170:173], v[32:35]
	v_mfma_f32_16x16x32_bf16 v[60:63], v[182:185], v[166:169], v[60:63]
	v_mfma_f32_16x16x32_bf16 v[56:59], v[182:185], v[174:177], v[56:59]
	v_mfma_f32_16x16x32_bf16 v[52:55], v[194:197], v[166:169], v[52:55]
	v_mfma_f32_16x16x32_bf16 v[48:51], v[194:197], v[174:177], v[48:51]
	v_mfma_f32_16x16x32_bf16 v[44:47], v[202:205], v[166:169], v[44:47]
	v_mfma_f32_16x16x32_bf16 v[40:43], v[202:205], v[174:177], v[40:43]
	v_mfma_f32_16x16x32_bf16 v[36:39], v[222:225], v[166:169], v[36:39]
	v_mfma_f32_16x16x32_bf16 v[32:35], v[222:225], v[174:177], v[32:35]
	s_barrier
	s_setprio 0
	v_lshl_add_u64 v[162:163], v[244:245], 0, s[64:65]
	s_add_u32 m0, s4, s31
	s_nop 0
	global_load_lds_dwordx4 v[162:163], off
	v_lshl_add_u64 v[162:163], v[246:247], 0, s[64:65]
	s_add_u32 m0, s4, s31
	s_add_u32 m0, m0, 0x2000
	s_nop 0
	global_load_lds_dwordx4 v[162:163], off
	s_waitcnt vmcnt(6)
	s_setprio 1
	s_barrier
	v_mfma_f32_16x16x32_bf16 v[28:31], v[178:181], v[226:229], v[28:31]
	v_mfma_f32_16x16x32_bf16 v[24:27], v[178:181], v[234:237], v[24:27]
	v_mfma_f32_16x16x32_bf16 v[20:23], v[186:189], v[226:229], v[20:23]
	v_mfma_f32_16x16x32_bf16 v[16:19], v[186:189], v[234:237], v[16:19]
	v_mfma_f32_16x16x32_bf16 v[12:15], v[198:201], v[226:229], v[12:15]
	v_mfma_f32_16x16x32_bf16 v[8:11], v[198:201], v[234:237], v[8:11]
	v_mfma_f32_16x16x32_bf16 v[4:7], v[206:209], v[226:229], v[4:7]
	v_mfma_f32_16x16x32_bf16 v[0:3], v[206:209], v[234:237], v[0:3]
	v_mfma_f32_16x16x32_bf16 v[28:31], v[182:185], v[230:233], v[28:31]
	v_mfma_f32_16x16x32_bf16 v[24:27], v[182:185], v[238:241], v[24:27]
	v_mfma_f32_16x16x32_bf16 v[20:23], v[194:197], v[230:233], v[20:23]
	v_mfma_f32_16x16x32_bf16 v[16:19], v[194:197], v[238:241], v[16:19]
	v_mfma_f32_16x16x32_bf16 v[12:15], v[202:205], v[230:233], v[12:15]
	v_mfma_f32_16x16x32_bf16 v[8:11], v[202:205], v[238:241], v[8:11]
	v_mfma_f32_16x16x32_bf16 v[4:7], v[222:225], v[230:233], v[4:7]
	v_mfma_f32_16x16x32_bf16 v[0:3], v[222:225], v[238:241], v[0:3]
	s_add_i32 s3, s3, 2
	s_add_u32 s0, s0, 0x100
	s_addc_u32 s1, s1, 0
	s_cmp_lt_u32 s3, 28
	s_barrier
	s_setprio 0
	s_cbranch_scc1 .LBB0_114
	v_lshlrev_b32_e32 v128, 3, v154
	v_lshlrev_b32_e32 v129, 5, v154
	v_and_b32_e32 v128, 0xffff0, v128
	v_and_b32_e32 v129, 32, v129
	s_or_b32 s0, s24, 0x80
	v_add_u32_e32 v129, v129, v156
	v_add_lshl_u32 v128, v155, v128, 12
	s_ashr_i32 s1, s0, 31
	v_lshl_add_u32 v192, v129, 1, v128
	v_lshlrev_b32_e32 v128, 3, v157
	v_lshlrev_b32_e32 v129, 5, v157
	s_mov_b32 s22, s0
	s_lshl_b64 s[0:1], s[0:1], 12
	v_readlane_b32 s4, v253, 35
	v_and_b32_e32 v128, 0xffff0, v128
	v_and_b32_e32 v129, 32, v129
	v_readlane_b32 s5, v253, 36
	s_add_u32 s0, s4, s0
	v_add_u32_e32 v129, v129, v159
	v_add_lshl_u32 v128, v158, v128, 12
	s_addc_u32 s1, s5, s1
	v_lshl_add_u32 v158, v129, 1, v128
	v_mov_b32_e32 v159, v193
	v_lshl_add_u64 v[190:191], s[0:1], 0, v[192:193]
	s_mov_b64 s[4:5], 0xf80
	v_readfirstlane_b32 s3, v160
	v_lshl_add_u64 v[190:191], v[190:191], 0, s[4:5]
	s_mov_b32 m0, s3
	v_lshl_add_u64 v[158:159], s[0:1], 0, v[158:159]
	v_readfirstlane_b32 s0, v161
	ds_read_b128 v[128:131], v152
	ds_read_b128 v[132:135], v152 offset:1024
	ds_read_b128 v[154:157], v152 offset:2048
	ds_read_b128 v[162:165], v152 offset:3072
	ds_read_b128 v[166:169], v137
	ds_read_b128 v[170:173], v137 offset:1024
	ds_read_b128 v[174:177], v137 offset:2048
	ds_read_b128 v[178:181], v137 offset:3072
	ds_read_b128 v[182:185], v137 offset:4096
	ds_read_b128 v[186:189], v137 offset:5120
	ds_read_b128 v[194:197], v137 offset:6144
	ds_read_b128 v[198:201], v137 offset:7168
	global_load_lds_dwordx4 v[190:191], off
	v_lshl_add_u64 v[158:159], v[158:159], 0, s[4:5]
	s_mov_b32 m0, s0
	s_nop 0
	global_load_lds_dwordx4 v[158:159], off
	s_barrier
	s_waitcnt lgkmcnt(0)
	s_setprio 1
	s_waitcnt lgkmcnt(0)
	v_mfma_f32_16x16x32_bf16 v[124:127], v[166:169], v[128:131], v[124:127]
	v_mfma_f32_16x16x32_bf16 v[120:123], v[166:169], v[154:157], v[120:123]
	v_mfma_f32_16x16x32_bf16 v[116:119], v[174:177], v[128:131], v[116:119]
	v_mfma_f32_16x16x32_bf16 v[112:115], v[174:177], v[154:157], v[112:115]
	v_mfma_f32_16x16x32_bf16 v[108:111], v[182:185], v[128:131], v[108:111]
	v_mfma_f32_16x16x32_bf16 v[104:107], v[182:185], v[154:157], v[104:107]
	v_mfma_f32_16x16x32_bf16 v[100:103], v[194:197], v[128:131], v[100:103]
	v_mfma_f32_16x16x32_bf16 v[96:99], v[194:197], v[154:157], v[96:99]
	v_mfma_f32_16x16x32_bf16 v[124:127], v[170:173], v[132:135], v[124:127]
	v_mfma_f32_16x16x32_bf16 v[120:123], v[170:173], v[162:165], v[120:123]
	v_mfma_f32_16x16x32_bf16 v[116:119], v[178:181], v[132:135], v[116:119]
	v_mfma_f32_16x16x32_bf16 v[112:115], v[178:181], v[162:165], v[112:115]
	v_mfma_f32_16x16x32_bf16 v[108:111], v[186:189], v[132:135], v[108:111]
	v_mfma_f32_16x16x32_bf16 v[104:107], v[186:189], v[162:165], v[104:107]
	v_mfma_f32_16x16x32_bf16 v[100:103], v[198:201], v[132:135], v[100:103]
	v_mfma_f32_16x16x32_bf16 v[96:99], v[198:201], v[162:165], v[96:99]
	s_setprio 0
	s_barrier
; #define WAIT_V(n) asm volatile("s_waitcnt vmcnt(" #n ")" ::: "memory")
; #define WAIT_L(n) asm volatile("s_waitcnt lgkmcnt(" #n ")" ::: "memory")
; #define BAR __builtin_amdgcn_s_barrier()
; #define LDA(dst, b, h) _Pragma("unroll") for (int m = 0; m < 4; ++m) _Pragma("unroll") for (int k = 0; k < 2; ++k) \
;     dst[m][k] = *reinterpret_cast<const bf16x8*>((char*)shm + abase + (((b) * 2 + (h)) * 16384 + (m * 2 + k) * 1024))
; #define LDB(dst, b, h) _Pragma("unroll") for (int n = 0; n < 2; ++n) _Pragma("unroll") for (int k = 0; k < 2; ++k) \
;     dst[n][k] = *reinterpret_cast<const bf16x8*>((char*)shm + bbase + (((b) * 2 + (h)) * 16384 + (n * 2 + k) * 1024))
; template <bool SWAP>
; __device__ __forceinline__ void gemm_main(const u16* __restrict__ A, const u16* __restrict__ Bt, int brow, int bcol,
;                                           u16* shm, f32x4 (&acc)[2][2][4][2]) {
;     ...
;     LDB(B1, 0, 1); BAR; WAIT_L(0); MMA(0, 1, At, B1); BAR;
;     LDA(At, 0, 1); WAIT_V(4); BAR; WAIT_L(0); MMA(1, 0, At, B0); MMA(1, 1, At, B1); BAR; }
;   { LDB(B0, 1, 0); LDA(At, 1, 0); WAIT_V(2); BAR; WAIT_L(0); MMA(0, 0, At, B0); BAR;
	ds_read_b128 v[158:161], v152 offset:16384
	ds_read_b128 v[202:205], v152 offset:17408
	ds_read_b128 v[206:209], v152 offset:18432
	ds_read_b128 v[222:225], v152 offset:19456
	s_barrier
	s_waitcnt lgkmcnt(0)
	s_setprio 1
	s_waitcnt lgkmcnt(0)
	v_mfma_f32_16x16x32_bf16 v[92:95], v[166:169], v[158:161], v[92:95]
	v_mfma_f32_16x16x32_bf16 v[88:91], v[166:169], v[206:209], v[88:91]
	v_mfma_f32_16x16x32_bf16 v[84:87], v[174:177], v[158:161], v[84:87]
	v_mfma_f32_16x16x32_bf16 v[80:83], v[174:177], v[206:209], v[80:83]
	v_mfma_f32_16x16x32_bf16 v[76:79], v[182:185], v[158:161], v[76:79]
	v_mfma_f32_16x16x32_bf16 v[72:75], v[182:185], v[206:209], v[72:75]
	v_mfma_f32_16x16x32_bf16 v[68:71], v[194:197], v[158:161], v[68:71]
	v_mfma_f32_16x16x32_bf16 v[64:67], v[194:197], v[206:209], v[64:67]
	v_mfma_f32_16x16x32_bf16 v[92:95], v[170:173], v[202:205], v[92:95]
	v_mfma_f32_16x16x32_bf16 v[88:91], v[170:173], v[222:225], v[88:91]
	v_mfma_f32_16x16x32_bf16 v[84:87], v[178:181], v[202:205], v[84:87]
	v_mfma_f32_16x16x32_bf16 v[80:83], v[178:181], v[222:225], v[80:83]
	v_mfma_f32_16x16x32_bf16 v[76:79], v[186:189], v[202:205], v[76:79]
	v_mfma_f32_16x16x32_bf16 v[72:75], v[186:189], v[222:225], v[72:75]
	v_mfma_f32_16x16x32_bf16 v[68:71], v[198:201], v[202:205], v[68:71]
	v_mfma_f32_16x16x32_bf16 v[64:67], v[198:201], v[222:225], v[64:67]
	s_setprio 0
	s_barrier
	ds_read_b128 v[166:169], v137 offset:16384
	ds_read_b128 v[170:173], v137 offset:17408
	ds_read_b128 v[174:177], v137 offset:18432
	ds_read_b128 v[178:181], v137 offset:19456
	ds_read_b128 v[182:185], v137 offset:20480
	ds_read_b128 v[186:189], v137 offset:21504
	ds_read_b128 v[194:197], v137 offset:22528
	ds_read_b128 v[198:201], v137 offset:23552
	s_waitcnt vmcnt(4)
	s_barrier
	s_waitcnt lgkmcnt(0)
	s_setprio 1
	s_waitcnt lgkmcnt(0)
	v_mfma_f32_16x16x32_bf16 v[60:63], v[166:169], v[128:131], v[60:63]
	v_mfma_f32_16x16x32_bf16 v[56:59], v[166:169], v[154:157], v[56:59]
	v_mfma_f32_16x16x32_bf16 v[52:55], v[174:177], v[128:131], v[52:55]
	v_mfma_f32_16x16x32_bf16 v[48:51], v[174:177], v[154:157], v[48:51]
	v_mfma_f32_16x16x32_bf16 v[44:47], v[182:185], v[128:131], v[44:47]
	v_mfma_f32_16x16x32_bf16 v[40:43], v[182:185], v[154:157], v[40:43]
	v_mfma_f32_16x16x32_bf16 v[36:39], v[194:197], v[128:131], v[36:39]
	v_mfma_f32_16x16x32_bf16 v[32:35], v[194:197], v[154:157], v[32:35]
	v_mfma_f32_16x16x32_bf16 v[60:63], v[170:173], v[132:135], v[60:63]
	v_mfma_f32_16x16x32_bf16 v[56:59], v[170:173], v[162:165], v[56:59]
	v_mfma_f32_16x16x32_bf16 v[52:55], v[178:181], v[132:135], v[52:55]
	v_mfma_f32_16x16x32_bf16 v[48:51], v[178:181], v[162:165], v[48:51]
	v_mfma_f32_16x16x32_bf16 v[44:47], v[186:189], v[132:135], v[44:47]
	v_mfma_f32_16x16x32_bf16 v[40:43], v[186:189], v[162:165], v[40:43]
	v_mfma_f32_16x16x32_bf16 v[36:39], v[198:201], v[132:135], v[36:39]
	v_mfma_f32_16x16x32_bf16 v[32:35], v[198:201], v[162:165], v[32:35]
	s_setprio 0
	s_setprio 1
	v_mfma_f32_16x16x32_bf16 v[28:31], v[166:169], v[158:161], v[28:31]
	v_mfma_f32_16x16x32_bf16 v[24:27], v[166:169], v[206:209], v[24:27]
	v_mfma_f32_16x16x32_bf16 v[20:23], v[174:177], v[158:161], v[20:23]
	v_mfma_f32_16x16x32_bf16 v[16:19], v[174:177], v[206:209], v[16:19]
	v_mfma_f32_16x16x32_bf16 v[12:15], v[182:185], v[158:161], v[12:15]
	v_mfma_f32_16x16x32_bf16 v[8:11], v[182:185], v[206:209], v[8:11]
	v_mfma_f32_16x16x32_bf16 v[4:7], v[194:197], v[158:161], v[4:7]
	v_mfma_f32_16x16x32_bf16 v[0:3], v[194:197], v[206:209], v[0:3]
	v_mfma_f32_16x16x32_bf16 v[28:31], v[170:173], v[202:205], v[28:31]
	v_mfma_f32_16x16x32_bf16 v[24:27], v[170:173], v[222:225], v[24:27]
	v_mfma_f32_16x16x32_bf16 v[20:23], v[178:181], v[202:205], v[20:23]
	v_mfma_f32_16x16x32_bf16 v[16:19], v[178:181], v[222:225], v[16:19]
	v_mfma_f32_16x16x32_bf16 v[12:15], v[186:189], v[202:205], v[12:15]
	v_mfma_f32_16x16x32_bf16 v[8:11], v[186:189], v[222:225], v[8:11]
	v_mfma_f32_16x16x32_bf16 v[4:7], v[198:201], v[202:205], v[4:7]
	v_mfma_f32_16x16x32_bf16 v[0:3], v[198:201], v[222:225], v[0:3]
	s_setprio 0
	s_barrier
	ds_read_b128 v[128:131], v152 offset:32768
	ds_read_b128 v[132:135], v152 offset:33792
	ds_read_b128 v[154:157], v152 offset:34816
	ds_read_b128 v[158:161], v152 offset:35840
	ds_read_b128 v[162:165], v137 offset:32768
	ds_read_b128 v[166:169], v137 offset:33792
	ds_read_b128 v[170:173], v137 offset:34816
	ds_read_b128 v[174:177], v137 offset:35840
	ds_read_b128 v[178:181], v137 offset:36864
	ds_read_b128 v[182:185], v137 offset:37888
	ds_read_b128 v[186:189], v137 offset:38912
	ds_read_b128 v[194:197], v137 offset:39936
	s_waitcnt vmcnt(2)
	s_barrier
; #define WAIT_V(n) asm volatile("s_waitcnt vmcnt(" #n ")" ::: "memory")
; #define WAIT_L(n) asm volatile("s_waitcnt lgkmcnt(" #n ")" ::: "memory")
; #define BAR __builtin_amdgcn_s_barrier()
; #define LDA(dst, b, h) _Pragma("unroll") for (int m = 0; m < 4; ++m) _Pragma("unroll") for (int k = 0; k < 2; ++k) \
;     dst[m][k] = *reinterpret_cast<const bf16x8*>((char*)shm + abase + (((b) * 2 + (h)) * 16384 + (m * 2 + k) * 1024))
; #define LDB(dst, b, h) _Pragma("unroll") for (int n = 0; n < 2; ++n) _Pragma("unroll") for (int k = 0; k < 2; ++k) \
;     dst[n][k] = *reinterpret_cast<const bf16x8*>((char*)shm + bbase + (((b) * 2 + (h)) * 16384 + (n * 2 + k) * 1024))
; template <bool SWAP>
; __device__ __forceinline__ void gemm_main(const u16* __restrict__ A, const u16* __restrict__ Bt, int brow, int bcol,
;                                           u16* shm, f32x4 (&acc)[2][2][4][2]) {
;     ...
;   { LDB(B0, 1, 0); LDA(At, 1, 0); WAIT_V(2); BAR; WAIT_L(0); MMA(0, 0, At, B0); BAR;
;     LDB(B1, 1, 1); WAIT_V(0); BAR; WAIT_L(0); MMA(0, 1, At, B1); BAR;
;     LDA(At, 1, 1); BAR; WAIT_L(0); MMA(1, 0, At, B0); MMA(1, 1, At, B1); BAR; }
;   if (wr == 0) BAR;
; __device__ __forceinline__ void phase_inproj1(const Params& p, char* smem) {
;     ...
;       if (nt < 16) {
	s_waitcnt lgkmcnt(0)
	s_setprio 1
	s_waitcnt lgkmcnt(0)
	v_mfma_f32_16x16x32_bf16 v[124:127], v[162:165], v[128:131], v[124:127]
	v_mfma_f32_16x16x32_bf16 v[120:123], v[162:165], v[154:157], v[120:123]
	v_mfma_f32_16x16x32_bf16 v[116:119], v[170:173], v[128:131], v[116:119]
	v_mfma_f32_16x16x32_bf16 v[112:115], v[170:173], v[154:157], v[112:115]
	v_mfma_f32_16x16x32_bf16 v[108:111], v[178:181], v[128:131], v[108:111]
	v_mfma_f32_16x16x32_bf16 v[104:107], v[178:181], v[154:157], v[104:107]
	v_mfma_f32_16x16x32_bf16 v[100:103], v[186:189], v[128:131], v[100:103]
	v_mfma_f32_16x16x32_bf16 v[96:99], v[186:189], v[154:157], v[96:99]
	v_mfma_f32_16x16x32_bf16 v[124:127], v[166:169], v[132:135], v[124:127]
	v_mfma_f32_16x16x32_bf16 v[120:123], v[166:169], v[158:161], v[120:123]
	v_mfma_f32_16x16x32_bf16 v[116:119], v[174:177], v[132:135], v[116:119]
	v_mfma_f32_16x16x32_bf16 v[112:115], v[174:177], v[158:161], v[112:115]
	v_mfma_f32_16x16x32_bf16 v[108:111], v[182:185], v[132:135], v[108:111]
	v_mfma_f32_16x16x32_bf16 v[104:107], v[182:185], v[158:161], v[104:107]
	v_mfma_f32_16x16x32_bf16 v[100:103], v[194:197], v[132:135], v[100:103]
	v_mfma_f32_16x16x32_bf16 v[96:99], v[194:197], v[158:161], v[96:99]
	s_setprio 0
	s_barrier
	ds_read_b128 v[198:201], v152 offset:49152
	ds_read_b128 v[202:205], v152 offset:50176
	ds_read_b128 v[206:209], v152 offset:51200
	ds_read_b128 v[222:225], v152 offset:52224
	s_waitcnt vmcnt(0)
	s_barrier
	s_waitcnt lgkmcnt(0)
	s_setprio 1
	s_waitcnt lgkmcnt(0)
	v_mfma_f32_16x16x32_bf16 v[92:95], v[162:165], v[198:201], v[92:95]
	v_mfma_f32_16x16x32_bf16 v[88:91], v[162:165], v[206:209], v[88:91]
	v_mfma_f32_16x16x32_bf16 v[84:87], v[170:173], v[198:201], v[84:87]
	v_mfma_f32_16x16x32_bf16 v[80:83], v[170:173], v[206:209], v[80:83]
	v_mfma_f32_16x16x32_bf16 v[76:79], v[178:181], v[198:201], v[76:79]
	v_mfma_f32_16x16x32_bf16 v[72:75], v[178:181], v[206:209], v[72:75]
	v_mfma_f32_16x16x32_bf16 v[68:71], v[186:189], v[198:201], v[68:71]
	v_mfma_f32_16x16x32_bf16 v[64:67], v[186:189], v[206:209], v[64:67]
	v_mfma_f32_16x16x32_bf16 v[92:95], v[166:169], v[202:205], v[92:95]
	v_mfma_f32_16x16x32_bf16 v[88:91], v[166:169], v[222:225], v[88:91]
	v_mfma_f32_16x16x32_bf16 v[84:87], v[174:177], v[202:205], v[84:87]
	v_mfma_f32_16x16x32_bf16 v[80:83], v[174:177], v[222:225], v[80:83]
	v_mfma_f32_16x16x32_bf16 v[76:79], v[182:185], v[202:205], v[76:79]
	v_mfma_f32_16x16x32_bf16 v[72:75], v[182:185], v[222:225], v[72:75]
	v_mfma_f32_16x16x32_bf16 v[68:71], v[194:197], v[202:205], v[68:71]
	v_mfma_f32_16x16x32_bf16 v[64:67], v[194:197], v[222:225], v[64:67]
	s_setprio 0
	s_barrier
	ds_read_b128 v[162:165], v137 offset:49152
	ds_read_b128 v[166:169], v137 offset:50176
	ds_read_b128 v[170:173], v137 offset:51200
	ds_read_b128 v[174:177], v137 offset:52224
	ds_read_b128 v[178:181], v137 offset:53248
	ds_read_b128 v[182:185], v137 offset:54272
	ds_read_b128 v[186:189], v137 offset:55296
	ds_read_b128 v[194:197], v137 offset:56320
	s_barrier
	s_waitcnt lgkmcnt(0)
	s_setprio 1
	s_waitcnt lgkmcnt(0)
	v_mfma_f32_16x16x32_bf16 v[60:63], v[162:165], v[128:131], v[60:63]
	v_mfma_f32_16x16x32_bf16 v[56:59], v[162:165], v[154:157], v[56:59]
	v_mfma_f32_16x16x32_bf16 v[52:55], v[170:173], v[128:131], v[52:55]
	v_mfma_f32_16x16x32_bf16 v[48:51], v[170:173], v[154:157], v[48:51]
	v_mfma_f32_16x16x32_bf16 v[44:47], v[178:181], v[128:131], v[44:47]
	v_mfma_f32_16x16x32_bf16 v[40:43], v[178:181], v[154:157], v[40:43]
	v_mfma_f32_16x16x32_bf16 v[36:39], v[186:189], v[128:131], v[36:39]
	v_mfma_f32_16x16x32_bf16 v[32:35], v[186:189], v[154:157], v[32:35]
	v_mfma_f32_16x16x32_bf16 v[60:63], v[166:169], v[132:135], v[60:63]
	v_mfma_f32_16x16x32_bf16 v[56:59], v[166:169], v[158:161], v[56:59]
	v_mfma_f32_16x16x32_bf16 v[52:55], v[174:177], v[132:135], v[52:55]
	v_mfma_f32_16x16x32_bf16 v[48:51], v[174:177], v[158:161], v[48:51]
	v_mfma_f32_16x16x32_bf16 v[44:47], v[182:185], v[132:135], v[44:47]
	v_mfma_f32_16x16x32_bf16 v[40:43], v[182:185], v[158:161], v[40:43]
	v_mfma_f32_16x16x32_bf16 v[36:39], v[194:197], v[132:135], v[36:39]
	v_mfma_f32_16x16x32_bf16 v[32:35], v[194:197], v[158:161], v[32:35]
	s_setprio 0
	s_setprio 1
	v_mfma_f32_16x16x32_bf16 v[28:31], v[162:165], v[198:201], v[28:31]
	v_mfma_f32_16x16x32_bf16 v[24:27], v[162:165], v[206:209], v[24:27]
	v_mfma_f32_16x16x32_bf16 v[20:23], v[170:173], v[198:201], v[20:23]
	v_mfma_f32_16x16x32_bf16 v[16:19], v[170:173], v[206:209], v[16:19]
	v_mfma_f32_16x16x32_bf16 v[12:15], v[178:181], v[198:201], v[12:15]
	v_mfma_f32_16x16x32_bf16 v[8:11], v[178:181], v[206:209], v[8:11]
	v_mfma_f32_16x16x32_bf16 v[4:7], v[186:189], v[198:201], v[4:7]
	v_mfma_f32_16x16x32_bf16 v[0:3], v[186:189], v[206:209], v[0:3]
	v_mfma_f32_16x16x32_bf16 v[28:31], v[166:169], v[202:205], v[28:31]
	v_mfma_f32_16x16x32_bf16 v[24:27], v[166:169], v[222:225], v[24:27]
	v_mfma_f32_16x16x32_bf16 v[20:23], v[174:177], v[202:205], v[20:23]
	v_mfma_f32_16x16x32_bf16 v[16:19], v[174:177], v[222:225], v[16:19]
	v_mfma_f32_16x16x32_bf16 v[12:15], v[182:185], v[202:205], v[12:15]
	v_mfma_f32_16x16x32_bf16 v[8:11], v[182:185], v[222:225], v[8:11]
	v_mfma_f32_16x16x32_bf16 v[4:7], v[194:197], v[202:205], v[4:7]
	v_mfma_f32_16x16x32_bf16 v[0:3], v[194:197], v[222:225], v[0:3]
	s_setprio 0
	s_movk_i32 s0, 0x100
	v_cmp_gt_u32_e32 vcc, s0, v136
	s_barrier
	s_and_saveexec_b64 s[0:1], vcc
	s_cbranch_execz .LBB0_118
	s_barrier
	s_or_b64 exec, exec, s[0:1]
	s_cmp_gt_u32 s2, 15
	s_mov_b64 s[0:1], -1
	s_cbranch_scc1 .LBB0_119

; #define WAIT_V(n) asm volatile("s_waitcnt vmcnt(" #n ")" ::: "memory")
; #define BAR __builtin_amdgcn_s_barrier()
; template <bool SWAP>
; __device__ __forceinline__ void gemm_main(const u16* __restrict__ A, const u16* __restrict__ Bt, int brow, int bcol,
;                                           u16* shm, f32x4 (&acc)[2][2][4][2]) {
;     ...
;   int tx = threadIdx.x; asm volatile("" : "+v"(tx));
;   const int wid = tx >> 6, lane = tx & 63, wr = wid >> 2, wc = wid & 3, fr = lane & 15, fq = lane >> 4;
; #pragma unroll
;   for (int a = 0; a < 2; ++a)
; #pragma unroll
;     for (int b = 0; b < 2; ++b)
; #pragma unroll
;       for (int m = 0; m < 4; ++m)
; #pragma unroll
;         for (int n = 0; n < 2; ++n) acc[a][b][m][n] = f32x4{0.f, 0.f, 0.f, 0.f};
;   bf16x8 At[4][2], B0[2][2], B1[2][2];
;   constexpr int nt = GK / BK;
;   GEMM_VOFF
;   const int lpart = (fr * 64 + fq * 16) ^ ((fr >> 3) << 5);
;   const int abase = wr * 8192 + lpart; int bbase = 65536 + wc * 4096 + lpart;
;   asm volatile("" : "+v"(bbase));
;   if (wr == 1) BAR;
;   WAIT_V(0); BAR;
;   BAR;
.LBB0_199:
	s_or_b64 exec, exec, s[0:1]
	v_bfe_i32 v4, v136, 27, 1
	v_lshlrev_b32_e32 v153, 4, v136
	v_lshrrev_b32_e32 v4, 22, v4
	v_add_u32_e32 v4, v153, v4
	v_and_b32_e32 v4, 0xfffffc00, v4
	v_sub_u32_e32 v4, v153, v4
	v_lshrrev_b32_e32 v5, 4, v4
	v_bitop3_b32 v4, v5, v4, 32 bitop3:0x6c
	v_ashrrev_i32_e32 v5, 31, v4
	v_lshrrev_b32_e32 v5, 26, v5
	v_add_u32_e32 v5, v4, v5
	v_ashrrev_i32_e32 v155, 6, v5
	v_and_b32_e32 v5, 0xc0, v5
	v_sub_u32_e32 v4, v4, v5
	v_ashrrev_i16_sdwa v4, v215, sext(v4) dst_sel:DWORD dst_unused:UNUSED_PAD src0_sel:DWORD src1_sel:BYTE_0
	v_bfe_i32 v156, v4, 0, 16
	v_add_u32_e32 v4, 0x2000, v153
	v_ashrrev_i32_e32 v5, 31, v4
	v_lshrrev_b32_e32 v5, 22, v5
	v_add_u32_e32 v5, v4, v5
	v_ashrrev_i32_e32 v157, 10, v5
	v_mul_i32_i24_e32 v5, 0x400, v157
	v_sub_u32_e32 v4, v4, v5
	v_lshrrev_b32_e32 v5, 4, v4
	v_bitop3_b32 v4, v5, v4, 32 bitop3:0x6c
	v_ashrrev_i32_e32 v5, 31, v4
	v_lshrrev_b32_e32 v5, 26, v5
	v_ashrrev_i32_e32 v3, 31, v136
	v_add_u32_e32 v5, v4, v5
	v_lshrrev_b32_e32 v3, 26, v3
	v_ashrrev_i32_e32 v158, 6, v5
	v_and_b32_e32 v5, 0xc0, v5
	v_add_u32_e32 v3, v136, v3
	v_sub_u32_e32 v4, v4, v5
	v_ashrrev_i32_e32 v154, 6, v3
	v_ashrrev_i16_sdwa v4, v215, sext(v4) dst_sel:DWORD dst_unused:UNUSED_PAD src0_sel:DWORD src1_sel:BYTE_0
	v_bfe_i32 v159, v4, 0, 16
	v_lshlrev_b32_e32 v4, 13, v0
	v_lshlrev_b32_e32 v0, 15, v154
	v_and_b32_e32 v0, 0xffff0000, v0
	v_lshl_add_u32 v0, v155, 12, v0
	v_and_or_b32 v0, v3, 64, v0
	v_lshl_add_u32 v192, v156, 1, v0
	v_lshlrev_b32_e32 v0, 15, v157
	v_and_b32_e32 v0, 0xffff0000, v0
	v_add_u32_e32 v5, 0, v2
	v_lshl_add_u32 v0, v158, 12, v0
	v_lshlrev_b32_e32 v2, 6, v157
	s_ashr_i32 s43, s42, 31
	v_and_or_b32 v0, v2, 64, v0
	s_lshl_b64 s[0:1], s[42:43], 12
	v_lshl_add_u32 v2, v159, 1, v0
	v_mov_b32_e32 v3, v193
	v_lshl_add_u64 v[128:129], s[0:1], 0, v[192:193]
	v_lshl_add_u64 v[130:131], s[0:1], 0, v[2:3]
	s_add_i32 s0, s93, s73
	s_waitcnt vmcnt(0)
	s_ashr_i32 s1, s0, 31
	s_lshl_b64 s[0:1], s[0:1], 12
	v_mov_b32_e32 v0, 0
	v_lshl_add_u64 v[132:133], s[0:1], 0, v[192:193]
	v_lshl_add_u64 v[134:135], s[0:1], 0, v[2:3]
	s_mov_b32 s2, -2
	v_add_u32_e32 v152, 0, v1
	v_add_u32_e32 v137, v5, v4
	s_mov_b64 s[0:1], s[50:51]
	v_mov_b32_e32 v1, v0
	v_mov_b32_e32 v2, v0
	v_mov_b32_e32 v3, v0
	v_mov_b32_e32 v4, v0
	v_mov_b32_e32 v5, v0
	v_mov_b32_e32 v6, v0
	v_mov_b32_e32 v7, v0
	v_mov_b32_e32 v8, v0
	v_mov_b32_e32 v9, v0
	v_mov_b32_e32 v10, v0
	v_mov_b32_e32 v11, v0
	v_mov_b32_e32 v12, v0
	v_mov_b32_e32 v13, v0
	v_mov_b32_e32 v14, v0
	v_mov_b32_e32 v15, v0
	v_mov_b32_e32 v16, v0
	v_mov_b32_e32 v17, v0
	v_mov_b32_e32 v18, v0
	v_mov_b32_e32 v19, v0
	v_mov_b32_e32 v20, v0
	v_mov_b32_e32 v21, v0
	v_mov_b32_e32 v22, v0
	v_mov_b32_e32 v23, v0
	v_mov_b32_e32 v24, v0
	v_mov_b32_e32 v25, v0
	v_mov_b32_e32 v26, v0
	v_mov_b32_e32 v27, v0
	v_mov_b32_e32 v28, v0
	v_mov_b32_e32 v29, v0
	v_mov_b32_e32 v30, v0
	v_mov_b32_e32 v31, v0
	v_mov_b32_e32 v32, v0
	v_mov_b32_e32 v33, v0
	v_mov_b32_e32 v34, v0
	v_mov_b32_e32 v35, v0
	v_mov_b32_e32 v36, v0
	v_mov_b32_e32 v37, v0
	v_mov_b32_e32 v38, v0
	v_mov_b32_e32 v39, v0
	v_mov_b32_e32 v40, v0
	v_mov_b32_e32 v41, v0
	v_mov_b32_e32 v42, v0
	v_mov_b32_e32 v43, v0
	v_mov_b32_e32 v44, v0
	v_mov_b32_e32 v45, v0
	v_mov_b32_e32 v46, v0
	v_mov_b32_e32 v47, v0
	v_mov_b32_e32 v48, v0
	v_mov_b32_e32 v49, v0
	v_mov_b32_e32 v50, v0
	v_mov_b32_e32 v51, v0
	v_mov_b32_e32 v52, v0
	v_mov_b32_e32 v53, v0
	v_mov_b32_e32 v54, v0
	v_mov_b32_e32 v55, v0
	v_mov_b32_e32 v56, v0
	v_mov_b32_e32 v57, v0
	v_mov_b32_e32 v58, v0
	v_mov_b32_e32 v59, v0
	v_mov_b32_e32 v60, v0
	v_mov_b32_e32 v61, v0
	v_mov_b32_e32 v62, v0
	v_mov_b32_e32 v63, v0
	v_mov_b32_e32 v64, v0
	v_mov_b32_e32 v65, v0
	v_mov_b32_e32 v66, v0
	v_mov_b32_e32 v67, v0
	v_mov_b32_e32 v68, v0
	v_mov_b32_e32 v69, v0
	v_mov_b32_e32 v70, v0
	v_mov_b32_e32 v71, v0
	v_mov_b32_e32 v72, v0
	v_mov_b32_e32 v73, v0
	v_mov_b32_e32 v74, v0
	v_mov_b32_e32 v75, v0
	v_mov_b32_e32 v76, v0
	v_mov_b32_e32 v77, v0
	v_mov_b32_e32 v78, v0
	v_mov_b32_e32 v79, v0
	v_mov_b32_e32 v80, v0
	v_mov_b32_e32 v81, v0
	v_mov_b32_e32 v82, v0
	v_mov_b32_e32 v83, v0
	v_mov_b32_e32 v84, v0
	v_mov_b32_e32 v85, v0
	v_mov_b32_e32 v86, v0
	v_mov_b32_e32 v87, v0
	v_mov_b32_e32 v88, v0
	v_mov_b32_e32 v89, v0
	v_mov_b32_e32 v90, v0
	v_mov_b32_e32 v91, v0
	v_mov_b32_e32 v92, v0
	v_mov_b32_e32 v93, v0
	v_mov_b32_e32 v94, v0
	v_mov_b32_e32 v95, v0
	v_mov_b32_e32 v96, v0
	v_mov_b32_e32 v97, v0
	v_mov_b32_e32 v98, v0
	v_mov_b32_e32 v99, v0
	v_mov_b32_e32 v100, v0
	v_mov_b32_e32 v101, v0
	v_mov_b32_e32 v102, v0
	v_mov_b32_e32 v103, v0
	v_mov_b32_e32 v104, v0
	v_mov_b32_e32 v105, v0
	v_mov_b32_e32 v106, v0
	v_mov_b32_e32 v107, v0
	v_mov_b32_e32 v108, v0
	v_mov_b32_e32 v109, v0
	v_mov_b32_e32 v110, v0
	v_mov_b32_e32 v111, v0
	v_mov_b32_e32 v112, v0
	v_mov_b32_e32 v113, v0
	v_mov_b32_e32 v114, v0
	v_mov_b32_e32 v115, v0
	v_mov_b32_e32 v116, v0
	v_mov_b32_e32 v117, v0
	v_mov_b32_e32 v118, v0
	v_mov_b32_e32 v119, v0
	v_mov_b32_e32 v120, v0
	v_mov_b32_e32 v121, v0
	v_mov_b32_e32 v122, v0
	v_mov_b32_e32 v123, v0
	v_mov_b32_e32 v124, v0
	v_mov_b32_e32 v125, v0
	v_mov_b32_e32 v126, v0
	v_mov_b32_e32 v127, v0
	v_readfirstlane_b32 s3, v153
	s_barrier
	s_barrier
; #define WAIT_L(n) asm volatile("s_waitcnt lgkmcnt(" #n ")" ::: "memory")
; #define BAR __builtin_amdgcn_s_barrier()
; #define SCHED __builtin_amdgcn_sched_barrier(0)
; #define STAGE(P, BASE, br, kt) do { const char* _g = (const char*)((BASE) + (size_t)(br) * GK + (kt) * BK); \
;     __builtin_amdgcn_global_load_lds((const unsigned*)(_g + voff0), (unsigned*)((char*)(P) + tx * 16), 16, 0, 0); \
;     __builtin_amdgcn_global_load_lds((const unsigned*)(_g + voff1), (unsigned*)((char*)(P) + tx * 16 + 8192), 16, 0, 0); } while (0)
; #define LDA(dst, b, h) _Pragma("unroll") for (int m = 0; m < 4; ++m) _Pragma("unroll") for (int k = 0; k < 2; ++k) \
;     dst[m][k] = *reinterpret_cast<const bf16x8*>((char*)shm + abase + (((b) * 2 + (h)) * 16384 + (m * 2 + k) * 1024))
; #define LDB(dst, b, h) _Pragma("unroll") for (int n = 0; n < 2; ++n) _Pragma("unroll") for (int k = 0; k < 2; ++k) \
;     dst[n][k] = *reinterpret_cast<const bf16x8*>((char*)shm + bbase + (((b) * 2 + (h)) * 16384 + (n * 2 + k) * 1024))
; template <bool SWAP>
; __device__ __forceinline__ void gemm_main(const u16* __restrict__ A, const u16* __restrict__ Bt, int brow, int bcol,
;                                           u16* shm, f32x4 (&acc)[2][2][4][2]) {
;     ...
;   for (int t = 0; t < nt - 2; t += 2) {
;     LDB(B0, 0, 0); SCHED; LDA(At, 0, 0); STAGE(SA(1, 1), A, brow + HALF, t + 1);
;     WAIT_L(8); BAR; WAIT_L(0); MMA(0, 0, At, B0); BAR; SCHED;
;     LDB(B1, 0, 1); STAGE(SB(0, 0), Bt, bcol, t + 2);
;     BAR; WAIT_L(0); MMA(0, 1, At, B1); BAR;
;     LDA(At, 0, 1); STAGE(SA(0, 0), A, brow, t + 2);
;     BAR; WAIT_L(0); MMA(1, 0, At, B0); BAR; SCHED;
.LBB0_200:
	ds_read_b128 v[162:165], v152
	ds_read_b128 v[166:169], v152 offset:1024
	ds_read_b128 v[170:173], v152 offset:2048
	ds_read_b128 v[174:177], v152 offset:3072
	ds_read_b128 v[178:181], v137
	ds_read_b128 v[182:185], v137 offset:1024
	ds_read_b128 v[186:189], v137 offset:2048
	ds_read_b128 v[194:197], v137 offset:3072
	ds_read_b128 v[198:201], v137 offset:4096
	ds_read_b128 v[202:205], v137 offset:5120
	ds_read_b128 v[206:209], v137 offset:6144
	ds_read_b128 v[222:225], v137 offset:7168
	v_add_u32_e32 v192, 0, v153
	v_add_u32_e32 v160, 0xc000, v192
	v_lshl_add_u64 v[190:191], s[0:1], 0, v[132:133]
	v_add_u32_e32 v161, 0xe000, v192
	v_lshl_add_u64 v[226:227], v[190:191], 0, s[82:83]
	s_add_u32 m0, s3, 0xc000
	v_lshl_add_u64 v[242:243], s[0:1], 0, v[134:135]
	global_load_lds_dwordx4 v[226:227], off
	v_lshl_add_u64 v[226:227], v[242:243], 0, s[82:83]
	s_add_u32 m0, s3, 0xe000
	s_nop 0
	global_load_lds_dwordx4 v[226:227], off
	s_waitcnt lgkmcnt(8)
	s_setprio 1
	s_barrier
	s_waitcnt lgkmcnt(0)
	v_mfma_f32_16x16x32_bf16 v[124:127], v[162:165], v[178:181], v[124:127]
	v_mfma_f32_16x16x32_bf16 v[120:123], v[170:173], v[178:181], v[120:123]
	v_mfma_f32_16x16x32_bf16 v[116:119], v[162:165], v[186:189], v[116:119]
	v_mfma_f32_16x16x32_bf16 v[112:115], v[170:173], v[186:189], v[112:115]
	v_mfma_f32_16x16x32_bf16 v[108:111], v[162:165], v[198:201], v[108:111]
	v_mfma_f32_16x16x32_bf16 v[104:107], v[170:173], v[198:201], v[104:107]
	v_mfma_f32_16x16x32_bf16 v[100:103], v[162:165], v[206:209], v[100:103]
	v_mfma_f32_16x16x32_bf16 v[96:99], v[170:173], v[206:209], v[96:99]
	v_mfma_f32_16x16x32_bf16 v[124:127], v[166:169], v[182:185], v[124:127]
	v_mfma_f32_16x16x32_bf16 v[120:123], v[174:177], v[182:185], v[120:123]
	v_mfma_f32_16x16x32_bf16 v[116:119], v[166:169], v[194:197], v[116:119]
	v_mfma_f32_16x16x32_bf16 v[112:115], v[174:177], v[194:197], v[112:115]
	v_mfma_f32_16x16x32_bf16 v[108:111], v[166:169], v[202:205], v[108:111]
	v_mfma_f32_16x16x32_bf16 v[104:107], v[174:177], v[202:205], v[104:107]
	v_mfma_f32_16x16x32_bf16 v[100:103], v[166:169], v[222:225], v[100:103]
	v_mfma_f32_16x16x32_bf16 v[96:99], v[174:177], v[222:225], v[96:99]
	s_barrier
	s_setprio 0
	ds_read_b128 v[226:229], v152 offset:16384
	ds_read_b128 v[230:233], v152 offset:17408
	ds_read_b128 v[234:237], v152 offset:18432
	ds_read_b128 v[238:241], v152 offset:19456
	v_lshl_add_u64 v[244:245], s[0:1], 0, v[128:129]
	v_lshl_add_u64 v[246:247], v[244:245], 0, s[74:75]
	s_add_u32 m0, s3, s28
	s_nop 0
	global_load_lds_dwordx4 v[246:247], off
	v_lshl_add_u64 v[246:247], s[0:1], 0, v[130:131]
	v_lshl_add_u64 v[248:249], v[246:247], 0, s[74:75]
	s_add_u32 m0, s3, s28
	s_add_u32 m0, m0, 0x2000
	s_nop 0
	global_load_lds_dwordx4 v[248:249], off
	s_setprio 1
	s_barrier
	s_waitcnt lgkmcnt(0)
	v_mfma_f32_16x16x32_bf16 v[92:95], v[226:229], v[178:181], v[92:95]
	v_mfma_f32_16x16x32_bf16 v[88:91], v[234:237], v[178:181], v[88:91]
	v_mfma_f32_16x16x32_bf16 v[84:87], v[226:229], v[186:189], v[84:87]
	v_mfma_f32_16x16x32_bf16 v[80:83], v[234:237], v[186:189], v[80:83]
	v_mfma_f32_16x16x32_bf16 v[76:79], v[226:229], v[198:201], v[76:79]
	v_mfma_f32_16x16x32_bf16 v[72:75], v[234:237], v[198:201], v[72:75]
	v_mfma_f32_16x16x32_bf16 v[68:71], v[226:229], v[206:209], v[68:71]
	v_mfma_f32_16x16x32_bf16 v[64:67], v[234:237], v[206:209], v[64:67]
	v_mfma_f32_16x16x32_bf16 v[92:95], v[230:233], v[182:185], v[92:95]
	v_mfma_f32_16x16x32_bf16 v[88:91], v[238:241], v[182:185], v[88:91]
	v_mfma_f32_16x16x32_bf16 v[84:87], v[230:233], v[194:197], v[84:87]
	v_mfma_f32_16x16x32_bf16 v[80:83], v[238:241], v[194:197], v[80:83]
	v_mfma_f32_16x16x32_bf16 v[76:79], v[230:233], v[202:205], v[76:79]
	v_mfma_f32_16x16x32_bf16 v[72:75], v[238:241], v[202:205], v[72:75]
	v_mfma_f32_16x16x32_bf16 v[68:71], v[230:233], v[222:225], v[68:71]
	v_mfma_f32_16x16x32_bf16 v[64:67], v[238:241], v[222:225], v[64:67]
	s_barrier
	s_setprio 0
	ds_read_b128 v[178:181], v137 offset:16384
	ds_read_b128 v[182:185], v137 offset:17408
	ds_read_b128 v[186:189], v137 offset:18432
	ds_read_b128 v[194:197], v137 offset:19456
	ds_read_b128 v[198:201], v137 offset:20480
	ds_read_b128 v[202:205], v137 offset:21504
	ds_read_b128 v[206:209], v137 offset:22528
	ds_read_b128 v[222:225], v137 offset:23552
	v_lshl_add_u64 v[248:249], v[190:191], 0, s[76:77]
	s_add_u32 m0, s3, 0x0
	s_nop 0
	global_load_lds_dwordx4 v[248:249], off
	v_lshl_add_u64 v[248:249], v[242:243], 0, s[76:77]
	s_add_u32 m0, s3, 0x2000
	s_nop 0
	global_load_lds_dwordx4 v[248:249], off
	s_setprio 1
	s_barrier
	s_waitcnt lgkmcnt(0)
	v_mfma_f32_16x16x32_bf16 v[60:63], v[162:165], v[178:181], v[60:63]
	v_mfma_f32_16x16x32_bf16 v[56:59], v[170:173], v[178:181], v[56:59]
	v_mfma_f32_16x16x32_bf16 v[52:55], v[162:165], v[186:189], v[52:55]
	v_mfma_f32_16x16x32_bf16 v[48:51], v[170:173], v[186:189], v[48:51]
	v_mfma_f32_16x16x32_bf16 v[44:47], v[162:165], v[198:201], v[44:47]
	v_mfma_f32_16x16x32_bf16 v[40:43], v[170:173], v[198:201], v[40:43]
	v_mfma_f32_16x16x32_bf16 v[36:39], v[162:165], v[206:209], v[36:39]
	v_mfma_f32_16x16x32_bf16 v[32:35], v[170:173], v[206:209], v[32:35]
	v_mfma_f32_16x16x32_bf16 v[60:63], v[166:169], v[182:185], v[60:63]
	v_mfma_f32_16x16x32_bf16 v[56:59], v[174:177], v[182:185], v[56:59]
	v_mfma_f32_16x16x32_bf16 v[52:55], v[166:169], v[194:197], v[52:55]
	v_mfma_f32_16x16x32_bf16 v[48:51], v[174:177], v[194:197], v[48:51]
	v_mfma_f32_16x16x32_bf16 v[44:47], v[166:169], v[202:205], v[44:47]
	v_mfma_f32_16x16x32_bf16 v[40:43], v[174:177], v[202:205], v[40:43]
	v_mfma_f32_16x16x32_bf16 v[36:39], v[166:169], v[222:225], v[36:39]
	v_mfma_f32_16x16x32_bf16 v[32:35], v[174:177], v[222:225], v[32:35]
	s_barrier
; #define WAIT_V(n) asm volatile("s_waitcnt vmcnt(" #n ")" ::: "memory")
; #define WAIT_L(n) asm volatile("s_waitcnt lgkmcnt(" #n ")" ::: "memory")
; #define BAR __builtin_amdgcn_s_barrier()
; #define SCHED __builtin_amdgcn_sched_barrier(0)
; #define STAGE(P, BASE, br, kt) do { const char* _g = (const char*)((BASE) + (size_t)(br) * GK + (kt) * BK); \
;     __builtin_amdgcn_global_load_lds((const unsigned*)(_g + voff0), (unsigned*)((char*)(P) + tx * 16), 16, 0, 0); \
;     __builtin_amdgcn_global_load_lds((const unsigned*)(_g + voff1), (unsigned*)((char*)(P) + tx * 16 + 8192), 16, 0, 0); } while (0)
; #define LDA(dst, b, h) _Pragma("unroll") for (int m = 0; m < 4; ++m) _Pragma("unroll") for (int k = 0; k < 2; ++k) \
;     dst[m][k] = *reinterpret_cast<const bf16x8*>((char*)shm + abase + (((b) * 2 + (h)) * 16384 + (m * 2 + k) * 1024))
; #define LDB(dst, b, h) _Pragma("unroll") for (int n = 0; n < 2; ++n) _Pragma("unroll") for (int k = 0; k < 2; ++k) \
;     dst[n][k] = *reinterpret_cast<const bf16x8*>((char*)shm + bbase + (((b) * 2 + (h)) * 16384 + (n * 2 + k) * 1024))
; template <bool SWAP>
; __device__ __forceinline__ void gemm_main(const u16* __restrict__ A, const u16* __restrict__ Bt, int brow, int bcol,
;                                           u16* shm, f32x4 (&acc)[2][2][4][2]) {
;     ...
;     STAGE(SB(0, 1), Bt, bcol + HALF, t + 2);
;     WAIT_V(6); BAR; MMA(1, 1, At, B1); BAR;
;     LDB(B0, 1, 0); SCHED; LDA(At, 1, 0); STAGE(SA(0, 1), A, brow + HALF, t + 2);
;     WAIT_L(8); BAR; WAIT_L(0); MMA(0, 0, At, B0); BAR; SCHED;
;     LDB(B1, 1, 1); STAGE(SB(1, 0), Bt, bcol, t + 3);
;     BAR; WAIT_L(0); MMA(0, 1, At, B1); BAR;
;     LDA(At, 1, 1); STAGE(SA(1, 0), A, brow, t + 3);
;     BAR; WAIT_L(0); MMA(1, 0, At, B0); BAR; SCHED;
	s_setprio 0
	v_lshl_add_u64 v[162:163], v[244:245], 0, s[70:71]
	s_add_u32 m0, s3, s29
	s_nop 0
	global_load_lds_dwordx4 v[162:163], off
	v_lshl_add_u64 v[162:163], v[246:247], 0, s[70:71]
	s_add_u32 m0, s3, s29
	s_add_u32 m0, m0, 0x2000
	s_nop 0
	global_load_lds_dwordx4 v[162:163], off
	s_waitcnt vmcnt(6)
	s_setprio 1
	s_barrier
	v_mfma_f32_16x16x32_bf16 v[28:31], v[226:229], v[178:181], v[28:31]
	v_mfma_f32_16x16x32_bf16 v[24:27], v[234:237], v[178:181], v[24:27]
	v_mfma_f32_16x16x32_bf16 v[20:23], v[226:229], v[186:189], v[20:23]
	v_mfma_f32_16x16x32_bf16 v[16:19], v[234:237], v[186:189], v[16:19]
	v_mfma_f32_16x16x32_bf16 v[12:15], v[226:229], v[198:201], v[12:15]
	v_mfma_f32_16x16x32_bf16 v[8:11], v[234:237], v[198:201], v[8:11]
	v_mfma_f32_16x16x32_bf16 v[4:7], v[226:229], v[206:209], v[4:7]
	v_mfma_f32_16x16x32_bf16 v[0:3], v[234:237], v[206:209], v[0:3]
	v_mfma_f32_16x16x32_bf16 v[28:31], v[230:233], v[182:185], v[28:31]
	v_mfma_f32_16x16x32_bf16 v[24:27], v[238:241], v[182:185], v[24:27]
	v_mfma_f32_16x16x32_bf16 v[20:23], v[230:233], v[194:197], v[20:23]
	v_mfma_f32_16x16x32_bf16 v[16:19], v[238:241], v[194:197], v[16:19]
	v_mfma_f32_16x16x32_bf16 v[12:15], v[230:233], v[202:205], v[12:15]
	v_mfma_f32_16x16x32_bf16 v[8:11], v[238:241], v[202:205], v[8:11]
	v_mfma_f32_16x16x32_bf16 v[4:7], v[230:233], v[222:225], v[4:7]
	v_mfma_f32_16x16x32_bf16 v[0:3], v[238:241], v[222:225], v[0:3]
	s_barrier
	s_setprio 0
	ds_read_b128 v[162:165], v152 offset:32768
	ds_read_b128 v[166:169], v152 offset:33792
	ds_read_b128 v[170:173], v152 offset:34816
	ds_read_b128 v[174:177], v152 offset:35840
	ds_read_b128 v[178:181], v137 offset:32768
	ds_read_b128 v[182:185], v137 offset:33792
	ds_read_b128 v[186:189], v137 offset:34816
	ds_read_b128 v[194:197], v137 offset:35840
	ds_read_b128 v[198:201], v137 offset:36864
	ds_read_b128 v[202:205], v137 offset:37888
	ds_read_b128 v[206:209], v137 offset:38912
	ds_read_b128 v[222:225], v137 offset:39936
	v_lshl_add_u64 v[226:227], v[190:191], 0, s[96:97]
	s_add_u32 m0, s3, 0x4000
	s_nop 0
	global_load_lds_dwordx4 v[226:227], off
	v_lshl_add_u64 v[226:227], v[242:243], 0, s[96:97]
	s_add_u32 m0, s3, 0x6000
	s_nop 0
	global_load_lds_dwordx4 v[226:227], off
	s_waitcnt lgkmcnt(8)
	s_setprio 1
	s_barrier
	s_waitcnt lgkmcnt(0)
	v_mfma_f32_16x16x32_bf16 v[124:127], v[162:165], v[178:181], v[124:127]
	v_mfma_f32_16x16x32_bf16 v[120:123], v[170:173], v[178:181], v[120:123]
	v_mfma_f32_16x16x32_bf16 v[116:119], v[162:165], v[186:189], v[116:119]
	v_mfma_f32_16x16x32_bf16 v[112:115], v[170:173], v[186:189], v[112:115]
	v_mfma_f32_16x16x32_bf16 v[108:111], v[162:165], v[198:201], v[108:111]
	v_mfma_f32_16x16x32_bf16 v[104:107], v[170:173], v[198:201], v[104:107]
	v_mfma_f32_16x16x32_bf16 v[100:103], v[162:165], v[206:209], v[100:103]
	v_mfma_f32_16x16x32_bf16 v[96:99], v[170:173], v[206:209], v[96:99]
	v_mfma_f32_16x16x32_bf16 v[124:127], v[166:169], v[182:185], v[124:127]
	v_mfma_f32_16x16x32_bf16 v[120:123], v[174:177], v[182:185], v[120:123]
	v_mfma_f32_16x16x32_bf16 v[116:119], v[166:169], v[194:197], v[116:119]
	v_mfma_f32_16x16x32_bf16 v[112:115], v[174:177], v[194:197], v[112:115]
	v_mfma_f32_16x16x32_bf16 v[108:111], v[166:169], v[202:205], v[108:111]
	v_mfma_f32_16x16x32_bf16 v[104:107], v[174:177], v[202:205], v[104:107]
	v_mfma_f32_16x16x32_bf16 v[100:103], v[166:169], v[222:225], v[100:103]
	v_mfma_f32_16x16x32_bf16 v[96:99], v[174:177], v[222:225], v[96:99]
	s_barrier
	s_setprio 0
	ds_read_b128 v[226:229], v152 offset:49152
	ds_read_b128 v[230:233], v152 offset:50176
	ds_read_b128 v[234:237], v152 offset:51200
	ds_read_b128 v[238:241], v152 offset:52224
	v_add_u32_e32 v250, s30, v153
	v_lshl_add_u64 v[248:249], v[244:245], 0, s[34:35]
	v_add_u32_e32 v250, 0x2000, v250
	s_add_u32 m0, s3, s30
	s_nop 0
	global_load_lds_dwordx4 v[248:249], off
	v_lshl_add_u64 v[248:249], v[246:247], 0, s[34:35]
	s_add_u32 m0, s3, s30
	s_add_u32 m0, m0, 0x2000
	s_nop 0
	global_load_lds_dwordx4 v[248:249], off
	s_setprio 1
	s_barrier
	s_waitcnt lgkmcnt(0)
	v_mfma_f32_16x16x32_bf16 v[92:95], v[226:229], v[178:181], v[92:95]
	v_mfma_f32_16x16x32_bf16 v[88:91], v[234:237], v[178:181], v[88:91]
	v_mfma_f32_16x16x32_bf16 v[84:87], v[226:229], v[186:189], v[84:87]
	v_mfma_f32_16x16x32_bf16 v[80:83], v[234:237], v[186:189], v[80:83]
	v_mfma_f32_16x16x32_bf16 v[76:79], v[226:229], v[198:201], v[76:79]
	v_mfma_f32_16x16x32_bf16 v[72:75], v[234:237], v[198:201], v[72:75]
	v_mfma_f32_16x16x32_bf16 v[68:71], v[226:229], v[206:209], v[68:71]
	v_mfma_f32_16x16x32_bf16 v[64:67], v[234:237], v[206:209], v[64:67]
	v_mfma_f32_16x16x32_bf16 v[92:95], v[230:233], v[182:185], v[92:95]
	v_mfma_f32_16x16x32_bf16 v[88:91], v[238:241], v[182:185], v[88:91]
	v_mfma_f32_16x16x32_bf16 v[84:87], v[230:233], v[194:197], v[84:87]
	v_mfma_f32_16x16x32_bf16 v[80:83], v[238:241], v[194:197], v[80:83]
	v_mfma_f32_16x16x32_bf16 v[76:79], v[230:233], v[202:205], v[76:79]
	v_mfma_f32_16x16x32_bf16 v[72:75], v[238:241], v[202:205], v[72:75]
	v_mfma_f32_16x16x32_bf16 v[68:71], v[230:233], v[222:225], v[68:71]
	v_mfma_f32_16x16x32_bf16 v[64:67], v[238:241], v[222:225], v[64:67]
	s_barrier
	s_setprio 0
	ds_read_b128 v[178:181], v137 offset:49152
	ds_read_b128 v[182:185], v137 offset:50176
	ds_read_b128 v[186:189], v137 offset:51200
	ds_read_b128 v[194:197], v137 offset:52224
	ds_read_b128 v[198:201], v137 offset:53248
	ds_read_b128 v[202:205], v137 offset:54272
	ds_read_b128 v[206:209], v137 offset:55296
	ds_read_b128 v[222:225], v137 offset:56320
	v_add_u32_e32 v248, 0x8000, v192
	v_lshl_add_u64 v[190:191], v[190:191], 0, s[36:37]
	s_add_u32 m0, s3, 0x8000
	s_nop 0
	global_load_lds_dwordx4 v[190:191], off
	v_lshl_add_u64 v[190:191], v[242:243], 0, s[36:37]
	s_add_u32 m0, s3, 0xa000
	s_nop 0
	global_load_lds_dwordx4 v[190:191], off
	s_setprio 1
	s_barrier
; #define WAIT_V(n) asm volatile("s_waitcnt vmcnt(" #n ")" ::: "memory")
; #define WAIT_L(n) asm volatile("s_waitcnt lgkmcnt(" #n ")" ::: "memory")
; #define BAR __builtin_amdgcn_s_barrier()
; #define SCHED __builtin_amdgcn_sched_barrier(0)
; #define STAGE(P, BASE, br, kt) do { const char* _g = (const char*)((BASE) + (size_t)(br) * GK + (kt) * BK); \
;     __builtin_amdgcn_global_load_lds((const unsigned*)(_g + voff0), (unsigned*)((char*)(P) + tx * 16), 16, 0, 0); \
;     __builtin_amdgcn_global_load_lds((const unsigned*)(_g + voff1), (unsigned*)((char*)(P) + tx * 16 + 8192), 16, 0, 0); } while (0)
; #define LDA(dst, b, h) _Pragma("unroll") for (int m = 0; m < 4; ++m) _Pragma("unroll") for (int k = 0; k < 2; ++k) \
;     dst[m][k] = *reinterpret_cast<const bf16x8*>((char*)shm + abase + (((b) * 2 + (h)) * 16384 + (m * 2 + k) * 1024))
; #define LDB(dst, b, h) _Pragma("unroll") for (int n = 0; n < 2; ++n) _Pragma("unroll") for (int k = 0; k < 2; ++k) \
;     dst[n][k] = *reinterpret_cast<const bf16x8*>((char*)shm + bbase + (((b) * 2 + (h)) * 16384 + (n * 2 + k) * 1024))
; template <bool SWAP>
; __device__ __forceinline__ void gemm_main(const u16* __restrict__ A, const u16* __restrict__ Bt, int brow, int bcol,
;                                           u16* shm, f32x4 (&acc)[2][2][4][2]) {
;     ...
;     BAR; WAIT_L(0); MMA(1, 0, At, B0); BAR; SCHED;
;     STAGE(SB(1, 1), Bt, bcol + HALF, t + 3);
;     WAIT_V(6); BAR; MMA(1, 1, At, B1); BAR;
;   }
;   { LDB(B0, 0, 0); LDA(At, 0, 0); STAGE(SA(1, 1), A, brow + HALF, nt - 1);
;     BAR; WAIT_L(0); MMA(0, 0, At, B0); BAR;
	s_waitcnt lgkmcnt(0)
	v_mfma_f32_16x16x32_bf16 v[60:63], v[162:165], v[178:181], v[60:63]
	v_mfma_f32_16x16x32_bf16 v[56:59], v[170:173], v[178:181], v[56:59]
	v_mfma_f32_16x16x32_bf16 v[52:55], v[162:165], v[186:189], v[52:55]
	v_mfma_f32_16x16x32_bf16 v[48:51], v[170:173], v[186:189], v[48:51]
	v_mfma_f32_16x16x32_bf16 v[44:47], v[162:165], v[198:201], v[44:47]
	v_mfma_f32_16x16x32_bf16 v[40:43], v[170:173], v[198:201], v[40:43]
	v_mfma_f32_16x16x32_bf16 v[36:39], v[162:165], v[206:209], v[36:39]
	v_mfma_f32_16x16x32_bf16 v[32:35], v[170:173], v[206:209], v[32:35]
	v_mfma_f32_16x16x32_bf16 v[60:63], v[166:169], v[182:185], v[60:63]
	v_mfma_f32_16x16x32_bf16 v[56:59], v[174:177], v[182:185], v[56:59]
	v_mfma_f32_16x16x32_bf16 v[52:55], v[166:169], v[194:197], v[52:55]
	v_mfma_f32_16x16x32_bf16 v[48:51], v[174:177], v[194:197], v[48:51]
	v_mfma_f32_16x16x32_bf16 v[44:47], v[166:169], v[202:205], v[44:47]
	v_mfma_f32_16x16x32_bf16 v[40:43], v[174:177], v[202:205], v[40:43]
	v_mfma_f32_16x16x32_bf16 v[36:39], v[166:169], v[222:225], v[36:39]
	v_mfma_f32_16x16x32_bf16 v[32:35], v[174:177], v[222:225], v[32:35]
	s_barrier
	s_setprio 0
	v_lshl_add_u64 v[162:163], v[244:245], 0, s[64:65]
	s_add_u32 m0, s3, s31
	s_nop 0
	global_load_lds_dwordx4 v[162:163], off
	v_lshl_add_u64 v[162:163], v[246:247], 0, s[64:65]
	s_add_u32 m0, s3, s31
	s_add_u32 m0, m0, 0x2000
	s_nop 0
	global_load_lds_dwordx4 v[162:163], off
	s_waitcnt vmcnt(6)
	s_setprio 1
	s_barrier
	v_mfma_f32_16x16x32_bf16 v[28:31], v[226:229], v[178:181], v[28:31]
	v_mfma_f32_16x16x32_bf16 v[24:27], v[234:237], v[178:181], v[24:27]
	v_mfma_f32_16x16x32_bf16 v[20:23], v[226:229], v[186:189], v[20:23]
	v_mfma_f32_16x16x32_bf16 v[16:19], v[234:237], v[186:189], v[16:19]
	v_mfma_f32_16x16x32_bf16 v[12:15], v[226:229], v[198:201], v[12:15]
	v_mfma_f32_16x16x32_bf16 v[8:11], v[234:237], v[198:201], v[8:11]
	v_mfma_f32_16x16x32_bf16 v[4:7], v[226:229], v[206:209], v[4:7]
	v_mfma_f32_16x16x32_bf16 v[0:3], v[234:237], v[206:209], v[0:3]
	v_mfma_f32_16x16x32_bf16 v[28:31], v[230:233], v[182:185], v[28:31]
	v_mfma_f32_16x16x32_bf16 v[24:27], v[238:241], v[182:185], v[24:27]
	v_mfma_f32_16x16x32_bf16 v[20:23], v[230:233], v[194:197], v[20:23]
	v_mfma_f32_16x16x32_bf16 v[16:19], v[238:241], v[194:197], v[16:19]
	v_mfma_f32_16x16x32_bf16 v[12:15], v[230:233], v[202:205], v[12:15]
	v_mfma_f32_16x16x32_bf16 v[8:11], v[238:241], v[202:205], v[8:11]
	v_mfma_f32_16x16x32_bf16 v[4:7], v[230:233], v[222:225], v[4:7]
	v_mfma_f32_16x16x32_bf16 v[0:3], v[238:241], v[222:225], v[0:3]
	s_add_i32 s2, s2, 2
	s_add_u32 s0, s0, 0x100
	s_addc_u32 s1, s1, 0
	s_cmp_lt_u32 s2, 28
	s_barrier
	s_setprio 0
	s_cbranch_scc1 .LBB0_200
	v_lshlrev_b32_e32 v128, 3, v154
	v_lshlrev_b32_e32 v129, 5, v154
	v_and_b32_e32 v128, 0xffff0, v128
	v_and_b32_e32 v129, 32, v129
	s_or_b32 s0, s24, 0x80
	v_add_u32_e32 v129, v129, v156
	v_add_lshl_u32 v128, v155, v128, 12
	s_ashr_i32 s1, s0, 31
	v_lshl_add_u32 v192, v129, 1, v128
	v_lshlrev_b32_e32 v128, 3, v157
	v_lshlrev_b32_e32 v129, 5, v157
	s_lshl_b64 s[0:1], s[0:1], 12
	v_readlane_b32 s2, v253, 35
	v_and_b32_e32 v128, 0xffff0, v128
	v_and_b32_e32 v129, 32, v129
	v_readlane_b32 s3, v253, 36
	s_add_u32 s0, s2, s0
	v_add_u32_e32 v129, v129, v159
	v_add_lshl_u32 v128, v158, v128, 12
	s_addc_u32 s1, s3, s1
	v_lshl_add_u32 v158, v129, 1, v128
	v_mov_b32_e32 v159, v193
	v_lshl_add_u64 v[190:191], s[0:1], 0, v[192:193]
	s_mov_b64 s[4:5], 0xf80
	v_readfirstlane_b32 s2, v160
	v_lshl_add_u64 v[190:191], v[190:191], 0, s[4:5]
	s_mov_b32 m0, s2
	v_lshl_add_u64 v[158:159], s[0:1], 0, v[158:159]
	v_readfirstlane_b32 s0, v161
	ds_read_b128 v[128:131], v152
	ds_read_b128 v[132:135], v152 offset:1024
	ds_read_b128 v[154:157], v152 offset:2048
	ds_read_b128 v[162:165], v152 offset:3072
	ds_read_b128 v[166:169], v137
	ds_read_b128 v[170:173], v137 offset:1024
	ds_read_b128 v[174:177], v137 offset:2048
	ds_read_b128 v[178:181], v137 offset:3072
	ds_read_b128 v[182:185], v137 offset:4096
	ds_read_b128 v[186:189], v137 offset:5120
	ds_read_b128 v[194:197], v137 offset:6144
	ds_read_b128 v[198:201], v137 offset:7168
	global_load_lds_dwordx4 v[190:191], off
	v_lshl_add_u64 v[158:159], v[158:159], 0, s[4:5]
	s_mov_b32 m0, s0
	s_nop 0
	global_load_lds_dwordx4 v[158:159], off
	s_barrier
	s_waitcnt lgkmcnt(0)
	s_setprio 1
	s_waitcnt lgkmcnt(0)
	v_mfma_f32_16x16x32_bf16 v[124:127], v[128:131], v[166:169], v[124:127]
	v_mfma_f32_16x16x32_bf16 v[116:119], v[128:131], v[174:177], v[116:119]
	v_mfma_f32_16x16x32_bf16 v[108:111], v[128:131], v[182:185], v[108:111]
	v_mfma_f32_16x16x32_bf16 v[100:103], v[128:131], v[194:197], v[100:103]
	v_mfma_f32_16x16x32_bf16 v[124:127], v[132:135], v[170:173], v[124:127]
	v_mfma_f32_16x16x32_bf16 v[120:123], v[154:157], v[166:169], v[120:123]
	v_mfma_f32_16x16x32_bf16 v[116:119], v[132:135], v[178:181], v[116:119]
	v_mfma_f32_16x16x32_bf16 v[112:115], v[154:157], v[174:177], v[112:115]
	v_mfma_f32_16x16x32_bf16 v[108:111], v[132:135], v[186:189], v[108:111]
	v_mfma_f32_16x16x32_bf16 v[104:107], v[154:157], v[182:185], v[104:107]
	v_mfma_f32_16x16x32_bf16 v[100:103], v[132:135], v[198:201], v[100:103]
	v_mfma_f32_16x16x32_bf16 v[96:99], v[154:157], v[194:197], v[96:99]
	v_mfma_f32_16x16x32_bf16 v[158:161], v[162:165], v[170:173], v[120:123]
	v_mfma_f32_16x16x32_bf16 v[202:205], v[162:165], v[178:181], v[112:115]
	v_mfma_f32_16x16x32_bf16 v[206:209], v[162:165], v[186:189], v[104:107]
	v_mfma_f32_16x16x32_bf16 v[222:225], v[162:165], v[198:201], v[96:99]
	s_setprio 0
	s_barrier
	s_nop 1
	ds_read_b128 v[96:99], v152 offset:16384
	ds_read_b128 v[104:107], v152 offset:17408
	ds_read_b128 v[112:115], v152 offset:18432
	ds_read_b128 v[120:123], v152 offset:19456
	s_barrier
; #define WAIT_V(n) asm volatile("s_waitcnt vmcnt(" #n ")" ::: "memory")
; #define WAIT_L(n) asm volatile("s_waitcnt lgkmcnt(" #n ")" ::: "memory")
; #define BAR __builtin_amdgcn_s_barrier()
; #define LDA(dst, b, h) _Pragma("unroll") for (int m = 0; m < 4; ++m) _Pragma("unroll") for (int k = 0; k < 2; ++k) \
;     dst[m][k] = *reinterpret_cast<const bf16x8*>((char*)shm + abase + (((b) * 2 + (h)) * 16384 + (m * 2 + k) * 1024))
; #define LDB(dst, b, h) _Pragma("unroll") for (int n = 0; n < 2; ++n) _Pragma("unroll") for (int k = 0; k < 2; ++k) \
;     dst[n][k] = *reinterpret_cast<const bf16x8*>((char*)shm + bbase + (((b) * 2 + (h)) * 16384 + (n * 2 + k) * 1024))
; template <bool SWAP>
; __device__ __forceinline__ void gemm_main(const u16* __restrict__ A, const u16* __restrict__ Bt, int brow, int bcol,
;                                           u16* shm, f32x4 (&acc)[2][2][4][2]) {
;     ...
;     BAR; WAIT_L(0); MMA(0, 0, At, B0); BAR;
;     LDB(B1, 0, 1); BAR; WAIT_L(0); MMA(0, 1, At, B1); BAR;
;     LDA(At, 0, 1); WAIT_V(4); BAR; WAIT_L(0); MMA(1, 0, At, B0); MMA(1, 1, At, B1); BAR; }
;   { LDB(B0, 1, 0); LDA(At, 1, 0); WAIT_V(2); BAR; WAIT_L(0); MMA(0, 0, At, B0); BAR;
	s_waitcnt lgkmcnt(0)
	s_setprio 1
	s_waitcnt lgkmcnt(0)
	v_mfma_f32_16x16x32_bf16 v[92:95], v[96:99], v[166:169], v[92:95]
	v_mfma_f32_16x16x32_bf16 v[84:87], v[96:99], v[174:177], v[84:87]
	v_mfma_f32_16x16x32_bf16 v[76:79], v[96:99], v[182:185], v[76:79]
	v_mfma_f32_16x16x32_bf16 v[68:71], v[96:99], v[194:197], v[68:71]
	v_mfma_f32_16x16x32_bf16 v[92:95], v[104:107], v[170:173], v[92:95]
	v_mfma_f32_16x16x32_bf16 v[88:91], v[112:115], v[166:169], v[88:91]
	v_mfma_f32_16x16x32_bf16 v[84:87], v[104:107], v[178:181], v[84:87]
	v_mfma_f32_16x16x32_bf16 v[80:83], v[112:115], v[174:177], v[80:83]
	v_mfma_f32_16x16x32_bf16 v[76:79], v[104:107], v[186:189], v[76:79]
	v_mfma_f32_16x16x32_bf16 v[72:75], v[112:115], v[182:185], v[72:75]
	v_mfma_f32_16x16x32_bf16 v[68:71], v[104:107], v[198:201], v[68:71]
	v_mfma_f32_16x16x32_bf16 v[64:67], v[112:115], v[194:197], v[64:67]
	v_mfma_f32_16x16x32_bf16 v[166:169], v[120:123], v[170:173], v[88:91]
	v_mfma_f32_16x16x32_bf16 v[170:173], v[120:123], v[178:181], v[80:83]
	v_mfma_f32_16x16x32_bf16 v[174:177], v[120:123], v[186:189], v[72:75]
	v_mfma_f32_16x16x32_bf16 v[178:181], v[120:123], v[198:201], v[64:67]
	s_setprio 0
	s_barrier
	s_nop 1
	ds_read_b128 v[64:67], v137 offset:16384
	ds_read_b128 v[72:75], v137 offset:17408
	ds_read_b128 v[80:83], v137 offset:18432
	ds_read_b128 v[88:91], v137 offset:19456
	ds_read_b128 v[182:185], v137 offset:20480
	ds_read_b128 v[186:189], v137 offset:21504
	ds_read_b128 v[194:197], v137 offset:22528
	ds_read_b128 v[198:201], v137 offset:23552
	s_waitcnt vmcnt(4)
	s_barrier
	s_waitcnt lgkmcnt(0)
	s_setprio 1
	s_waitcnt lgkmcnt(0)
	v_mfma_f32_16x16x32_bf16 v[60:63], v[128:131], v[64:67], v[60:63]
	v_mfma_f32_16x16x32_bf16 v[52:55], v[128:131], v[80:83], v[52:55]
	v_mfma_f32_16x16x32_bf16 v[44:47], v[128:131], v[182:185], v[44:47]
	v_mfma_f32_16x16x32_bf16 v[36:39], v[128:131], v[194:197], v[36:39]
	v_mfma_f32_16x16x32_bf16 v[60:63], v[132:135], v[72:75], v[60:63]
	v_mfma_f32_16x16x32_bf16 v[56:59], v[154:157], v[64:67], v[56:59]
	v_mfma_f32_16x16x32_bf16 v[52:55], v[132:135], v[88:91], v[52:55]
	v_mfma_f32_16x16x32_bf16 v[48:51], v[154:157], v[80:83], v[48:51]
	v_mfma_f32_16x16x32_bf16 v[44:47], v[132:135], v[186:189], v[44:47]
	v_mfma_f32_16x16x32_bf16 v[40:43], v[154:157], v[182:185], v[40:43]
	v_mfma_f32_16x16x32_bf16 v[36:39], v[132:135], v[198:201], v[36:39]
	v_mfma_f32_16x16x32_bf16 v[32:35], v[154:157], v[194:197], v[32:35]
	v_mfma_f32_16x16x32_bf16 v[226:229], v[162:165], v[72:75], v[56:59]
	v_mfma_f32_16x16x32_bf16 v[230:233], v[162:165], v[88:91], v[48:51]
	v_mfma_f32_16x16x32_bf16 v[234:237], v[162:165], v[186:189], v[40:43]
	v_mfma_f32_16x16x32_bf16 v[128:131], v[162:165], v[198:201], v[32:35]
	s_setprio 0
	s_setprio 1
	v_mfma_f32_16x16x32_bf16 v[28:31], v[96:99], v[64:67], v[28:31]
	v_mfma_f32_16x16x32_bf16 v[20:23], v[96:99], v[80:83], v[20:23]
	v_mfma_f32_16x16x32_bf16 v[12:15], v[96:99], v[182:185], v[12:15]
	v_mfma_f32_16x16x32_bf16 v[4:7], v[96:99], v[194:197], v[4:7]
	v_mfma_f32_16x16x32_bf16 v[28:31], v[104:107], v[72:75], v[28:31]
	v_mfma_f32_16x16x32_bf16 v[24:27], v[112:115], v[64:67], v[24:27]
	v_mfma_f32_16x16x32_bf16 v[20:23], v[104:107], v[88:91], v[20:23]
	v_mfma_f32_16x16x32_bf16 v[16:19], v[112:115], v[80:83], v[16:19]
	v_mfma_f32_16x16x32_bf16 v[12:15], v[104:107], v[186:189], v[12:15]
	v_mfma_f32_16x16x32_bf16 v[8:11], v[112:115], v[182:185], v[8:11]
	v_mfma_f32_16x16x32_bf16 v[4:7], v[104:107], v[198:201], v[4:7]
	v_mfma_f32_16x16x32_bf16 v[0:3], v[112:115], v[194:197], v[0:3]
	v_mfma_f32_16x16x32_bf16 v[132:135], v[120:123], v[72:75], v[24:27]
	v_mfma_f32_16x16x32_bf16 v[154:157], v[120:123], v[88:91], v[16:19]
	v_mfma_f32_16x16x32_bf16 v[162:165], v[120:123], v[186:189], v[8:11]
	v_mfma_f32_16x16x32_bf16 v[182:185], v[120:123], v[198:201], v[0:3]
	s_setprio 0
	s_barrier
	s_nop 1
	ds_read_b128 v[0:3], v152 offset:32768
	ds_read_b128 v[8:11], v152 offset:33792
	ds_read_b128 v[16:19], v152 offset:34816
	ds_read_b128 v[24:27], v152 offset:35840
	ds_read_b128 v[32:35], v137 offset:32768
	ds_read_b128 v[40:43], v137 offset:33792
	ds_read_b128 v[48:51], v137 offset:34816
	ds_read_b128 v[56:59], v137 offset:35840
	ds_read_b128 v[64:67], v137 offset:36864
	ds_read_b128 v[186:189], v137 offset:37888
	ds_read_b128 v[194:197], v137 offset:38912
	ds_read_b128 v[198:201], v137 offset:39936
	s_waitcnt vmcnt(2)
	s_barrier
; #define WAIT_V(n) asm volatile("s_waitcnt vmcnt(" #n ")" ::: "memory")
; #define WAIT_L(n) asm volatile("s_waitcnt lgkmcnt(" #n ")" ::: "memory")
; #define BAR __builtin_amdgcn_s_barrier()
; #define LDA(dst, b, h) _Pragma("unroll") for (int m = 0; m < 4; ++m) _Pragma("unroll") for (int k = 0; k < 2; ++k) \
;     dst[m][k] = *reinterpret_cast<const bf16x8*>((char*)shm + abase + (((b) * 2 + (h)) * 16384 + (m * 2 + k) * 1024))
; #define LDB(dst, b, h) _Pragma("unroll") for (int n = 0; n < 2; ++n) _Pragma("unroll") for (int k = 0; k < 2; ++k) \
;     dst[n][k] = *reinterpret_cast<const bf16x8*>((char*)shm + bbase + (((b) * 2 + (h)) * 16384 + (n * 2 + k) * 1024))
; template <bool SWAP>
; __device__ __forceinline__ void gemm_main(const u16* __restrict__ A, const u16* __restrict__ Bt, int brow, int bcol,
;                                           u16* shm, f32x4 (&acc)[2][2][4][2]) {
;     ...
;   { LDB(B0, 1, 0); LDA(At, 1, 0); WAIT_V(2); BAR; WAIT_L(0); MMA(0, 0, At, B0); BAR;
;     LDB(B1, 1, 1); WAIT_V(0); BAR; WAIT_L(0); MMA(0, 1, At, B1); BAR;
;     LDA(At, 1, 1); BAR; WAIT_L(0); MMA(1, 0, At, B0); MMA(1, 1, At, B1); BAR; }
;   if (wr == 0) BAR;
	s_waitcnt lgkmcnt(0)
	s_setprio 1
	s_waitcnt lgkmcnt(0)
	v_mfma_f32_16x16x32_bf16 v[72:75], v[0:3], v[32:35], v[124:127]
	v_mfma_f32_16x16x32_bf16 v[120:123], v[8:11], v[40:43], v[72:75]
	v_mfma_f32_16x16x32_bf16 v[72:75], v[16:19], v[32:35], v[158:161]
	v_mfma_f32_16x16x32_bf16 v[124:127], v[24:27], v[40:43], v[72:75]
	v_mfma_f32_16x16x32_bf16 v[72:75], v[0:3], v[48:51], v[116:119]
	v_mfma_f32_16x16x32_bf16 v[112:115], v[8:11], v[56:59], v[72:75]
	v_mfma_f32_16x16x32_bf16 v[72:75], v[16:19], v[48:51], v[202:205]
	v_mfma_f32_16x16x32_bf16 v[116:119], v[24:27], v[56:59], v[72:75]
	v_mfma_f32_16x16x32_bf16 v[72:75], v[0:3], v[64:67], v[108:111]
	v_mfma_f32_16x16x32_bf16 v[104:107], v[8:11], v[186:189], v[72:75]
	v_mfma_f32_16x16x32_bf16 v[72:75], v[16:19], v[64:67], v[206:209]
	v_mfma_f32_16x16x32_bf16 v[108:111], v[24:27], v[186:189], v[72:75]
	v_mfma_f32_16x16x32_bf16 v[72:75], v[0:3], v[194:197], v[100:103]
	v_mfma_f32_16x16x32_bf16 v[96:99], v[8:11], v[198:201], v[72:75]
	v_mfma_f32_16x16x32_bf16 v[72:75], v[16:19], v[194:197], v[222:225]
	v_mfma_f32_16x16x32_bf16 v[100:103], v[24:27], v[198:201], v[72:75]
	s_setprio 0
	s_barrier
	ds_read_b128 v[158:161], v152 offset:49152
	ds_read_b128 v[202:205], v152 offset:50176
	ds_read_b128 v[206:209], v152 offset:51200
	ds_read_b128 v[222:225], v152 offset:52224
	s_waitcnt vmcnt(0)
	s_barrier
	s_waitcnt lgkmcnt(0)
	s_setprio 1
	s_waitcnt lgkmcnt(0)
	v_mfma_f32_16x16x32_bf16 v[72:75], v[158:161], v[32:35], v[92:95]
	v_mfma_f32_16x16x32_bf16 v[32:35], v[206:209], v[32:35], v[166:169]
	v_mfma_f32_16x16x32_bf16 v[92:95], v[222:225], v[40:43], v[32:35]
	v_mfma_f32_16x16x32_bf16 v[32:35], v[158:161], v[48:51], v[84:87]
	v_mfma_f32_16x16x32_bf16 v[80:83], v[202:205], v[56:59], v[32:35]
	v_mfma_f32_16x16x32_bf16 v[32:35], v[206:209], v[48:51], v[170:173]
	v_mfma_f32_16x16x32_bf16 v[84:87], v[222:225], v[56:59], v[32:35]
	v_mfma_f32_16x16x32_bf16 v[32:35], v[158:161], v[64:67], v[76:79]
	v_mfma_f32_16x16x32_bf16 v[88:91], v[202:205], v[40:43], v[72:75]
	v_mfma_f32_16x16x32_bf16 v[72:75], v[202:205], v[186:189], v[32:35]
	v_mfma_f32_16x16x32_bf16 v[32:35], v[206:209], v[64:67], v[174:177]
	v_mfma_f32_16x16x32_bf16 v[76:79], v[222:225], v[186:189], v[32:35]
	v_mfma_f32_16x16x32_bf16 v[32:35], v[158:161], v[194:197], v[68:71]
	v_mfma_f32_16x16x32_bf16 v[64:67], v[202:205], v[198:201], v[32:35]
	v_mfma_f32_16x16x32_bf16 v[32:35], v[206:209], v[194:197], v[178:181]
	v_mfma_f32_16x16x32_bf16 v[68:71], v[222:225], v[198:201], v[32:35]
	s_setprio 0
	s_barrier
	ds_read_b128 v[166:169], v137 offset:49152
	ds_read_b128 v[170:173], v137 offset:50176
	ds_read_b128 v[174:177], v137 offset:51200
	ds_read_b128 v[178:181], v137 offset:52224
	ds_read_b128 v[186:189], v137 offset:53248
	ds_read_b128 v[194:197], v137 offset:54272
	ds_read_b128 v[198:201], v137 offset:55296
	ds_read_b128 v[238:241], v137 offset:56320
	s_barrier
	s_waitcnt lgkmcnt(0)
	s_setprio 1
	s_waitcnt lgkmcnt(0)
	v_mfma_f32_16x16x32_bf16 v[32:35], v[0:3], v[166:169], v[60:63]
	v_mfma_f32_16x16x32_bf16 v[56:59], v[8:11], v[170:173], v[32:35]
	v_mfma_f32_16x16x32_bf16 v[32:35], v[16:19], v[166:169], v[226:229]
	v_mfma_f32_16x16x32_bf16 v[60:63], v[24:27], v[170:173], v[32:35]
	v_mfma_f32_16x16x32_bf16 v[32:35], v[0:3], v[174:177], v[52:55]
	v_mfma_f32_16x16x32_bf16 v[48:51], v[8:11], v[178:181], v[32:35]
	v_mfma_f32_16x16x32_bf16 v[32:35], v[16:19], v[174:177], v[230:233]
	v_mfma_f32_16x16x32_bf16 v[52:55], v[24:27], v[178:181], v[32:35]
	v_mfma_f32_16x16x32_bf16 v[32:35], v[0:3], v[186:189], v[44:47]
	v_mfma_f32_16x16x32_bf16 v[40:43], v[8:11], v[194:197], v[32:35]
	v_mfma_f32_16x16x32_bf16 v[32:35], v[16:19], v[186:189], v[234:237]
	v_mfma_f32_16x16x32_bf16 v[0:3], v[0:3], v[198:201], v[36:39]
	v_mfma_f32_16x16x32_bf16 v[44:47], v[24:27], v[194:197], v[32:35]
	v_mfma_f32_16x16x32_bf16 v[32:35], v[8:11], v[238:241], v[0:3]
	v_mfma_f32_16x16x32_bf16 v[0:3], v[16:19], v[198:201], v[128:131]
	v_mfma_f32_16x16x32_bf16 v[36:39], v[24:27], v[238:241], v[0:3]
	s_setprio 0
	s_setprio 1
	v_mfma_f32_16x16x32_bf16 v[0:3], v[158:161], v[166:169], v[28:31]
	v_mfma_f32_16x16x32_bf16 v[24:27], v[202:205], v[170:173], v[0:3]
	v_mfma_f32_16x16x32_bf16 v[0:3], v[206:209], v[166:169], v[132:135]
	v_mfma_f32_16x16x32_bf16 v[28:31], v[222:225], v[170:173], v[0:3]
	v_mfma_f32_16x16x32_bf16 v[0:3], v[158:161], v[174:177], v[20:23]
	v_mfma_f32_16x16x32_bf16 v[16:19], v[202:205], v[178:181], v[0:3]
	v_mfma_f32_16x16x32_bf16 v[0:3], v[206:209], v[174:177], v[154:157]
	v_mfma_f32_16x16x32_bf16 v[20:23], v[222:225], v[178:181], v[0:3]
	v_mfma_f32_16x16x32_bf16 v[0:3], v[158:161], v[186:189], v[12:15]
	v_mfma_f32_16x16x32_bf16 v[8:11], v[202:205], v[194:197], v[0:3]
	v_mfma_f32_16x16x32_bf16 v[0:3], v[206:209], v[186:189], v[162:165]
	v_mfma_f32_16x16x32_bf16 v[12:15], v[222:225], v[194:197], v[0:3]
	v_mfma_f32_16x16x32_bf16 v[0:3], v[158:161], v[198:201], v[4:7]
	v_mfma_f32_16x16x32_bf16 v[4:7], v[206:209], v[198:201], v[182:185]
	v_mfma_f32_16x16x32_bf16 v[0:3], v[202:205], v[238:241], v[0:3]
	v_mfma_f32_16x16x32_bf16 v[4:7], v[222:225], v[238:241], v[4:7]
	s_setprio 0
	s_movk_i32 s0, 0x100
	v_cmp_gt_u32_e32 vcc, s0, v136
	s_barrier
	s_and_saveexec_b64 s[0:1], vcc
	s_cbranch_execz .LBB0_203
	s_barrier

; #define WAIT_V(n) asm volatile("s_waitcnt vmcnt(" #n ")" ::: "memory")
; #define BAR __builtin_amdgcn_s_barrier()
; template <bool SWAP>
; __device__ __forceinline__ void gemm_main(const u16* __restrict__ A, const u16* __restrict__ Bt, int brow, int bcol,
;                                           u16* shm, f32x4 (&acc)[2][2][4][2]) {
;     ...
;   int tx = threadIdx.x; asm volatile("" : "+v"(tx));
;   const int wid = tx >> 6, lane = tx & 63, wr = wid >> 2, wc = wid & 3, fr = lane & 15, fq = lane >> 4;
; #pragma unroll
;   for (int a = 0; a < 2; ++a)
; #pragma unroll
;     for (int b = 0; b < 2; ++b)
; #pragma unroll
;       for (int m = 0; m < 4; ++m)
; #pragma unroll
;         for (int n = 0; n < 2; ++n) acc[a][b][m][n] = f32x4{0.f, 0.f, 0.f, 0.f};
;   bf16x8 At[4][2], B0[2][2], B1[2][2];
;   constexpr int nt = GK / BK;
;   GEMM_VOFF
;   const int lpart = (fr * 64 + fq * 16) ^ ((fr >> 3) << 5);
;   const int abase = wr * 8192 + lpart; int bbase = 65536 + wc * 4096 + lpart;
;   asm volatile("" : "+v"(bbase));
;   if (wr == 1) BAR;
;   WAIT_V(0); BAR;
;   BAR;
; __device__ __forceinline__ void phase_inproj2(const Params& p, int half, int sg, char* smem) {
;     ...
;   constexpr int NT2 = MTSG * 88;
;   if (blockIdx.x < NT2) { IN2_TILE(blockIdx.x, nt0, brow0) gemm_issue(A, Bt, brow0, nt0 * 256, (u16*)smem); }
;   for (int it = blockIdx.x; it < NT2; it += gridDim.x) {
;     IN2_TILE(it, nt, brow)
;     const int itn = it + gridDim.x;
;     f32x4 acc[2][2][4][2];
;     gemm_main<true>(A, Bt, brow, nt * 256, (u16*)smem, acc);
.LBB0_435:
	s_or_b64 exec, exec, s[0:1]
	v_bfe_i32 v4, v136, 27, 1
	v_lshlrev_b32_e32 v139, 4, v136
	v_lshrrev_b32_e32 v4, 22, v4
	v_add_u32_e32 v4, v139, v4
	v_and_b32_e32 v4, 0xfffffc00, v4
	v_sub_u32_e32 v4, v139, v4
	v_lshrrev_b32_e32 v5, 4, v4
	v_bitop3_b32 v4, v5, v4, 32 bitop3:0x6c
	v_ashrrev_i32_e32 v5, 31, v4
	v_lshrrev_b32_e32 v5, 26, v5
	v_add_u32_e32 v5, v4, v5
	v_ashrrev_i32_e32 v143, 6, v5
	v_and_b32_e32 v5, 0xc0, v5
	v_sub_u32_e32 v4, v4, v5
	v_ashrrev_i16_sdwa v4, v215, sext(v4) dst_sel:DWORD dst_unused:UNUSED_PAD src0_sel:DWORD src1_sel:BYTE_0
	s_waitcnt vmcnt(0)
	v_bfe_i32 v144, v4, 0, 16
	v_add_u32_e32 v4, 0x2000, v139
	v_ashrrev_i32_e32 v5, 31, v4
	v_lshrrev_b32_e32 v5, 22, v5
	v_add_u32_e32 v5, v4, v5
	v_ashrrev_i32_e32 v145, 10, v5
	v_mul_i32_i24_e32 v5, 0x400, v145
	v_sub_u32_e32 v4, v4, v5
	v_lshrrev_b32_e32 v5, 4, v4
	v_bitop3_b32 v4, v5, v4, 32 bitop3:0x6c
	v_ashrrev_i32_e32 v5, 31, v4
	v_lshrrev_b32_e32 v5, 26, v5
	v_ashrrev_i32_e32 v3, 31, v136
	v_add_u32_e32 v5, v4, v5
	v_lshrrev_b32_e32 v3, 26, v3
	v_ashrrev_i32_e32 v146, 6, v5
	v_and_b32_e32 v5, 0xc0, v5
	v_add_u32_e32 v3, v136, v3
	v_sub_u32_e32 v4, v4, v5
	s_mul_hi_i32 s0, s24, 0x2e8ba2e9
	v_ashrrev_i32_e32 v142, 6, v3
	v_ashrrev_i16_sdwa v4, v215, sext(v4) dst_sel:DWORD dst_unused:UNUSED_PAD src0_sel:DWORD src1_sel:BYTE_0
	s_lshr_b32 s1, s0, 31
	s_ashr_i32 s0, s0, 9
	v_bfe_i32 v147, v4, 0, 16
	v_lshlrev_b32_e32 v4, 13, v0
	v_lshlrev_b32_e32 v0, 15, v142
	s_add_i32 s0, s0, s1
	v_and_b32_e32 v0, 0xffff0000, v0
	s_mul_i32 s1, s0, 0xb00
	v_lshl_add_u32 v0, v143, 12, v0
	s_sub_i32 s1, s24, s1
	v_and_or_b32 v0, v3, 64, v0
	s_ashr_i32 s25, s1, 5
	v_lshl_add_u32 v192, v144, 1, v0
	v_lshlrev_b32_e32 v0, 15, v145
	s_lshl_b32 s2, s0, 13
	s_lshl_b32 s0, s1, 8
	s_lshl_b32 s6, s25, 8
	v_and_b32_e32 v0, 0xffff0000, v0
	s_and_b32 s3, s0, 0x1f00
	s_add_i32 s0, s6, 0x1900
	v_add_u32_e32 v5, 0, v2
	v_lshl_add_u32 v0, v146, 12, v0
	v_lshlrev_b32_e32 v2, 6, v145
	s_ashr_i32 s1, s0, 31
	v_and_or_b32 v0, v2, 64, v0
	s_lshl_b64 s[0:1], s[0:1], 12
	v_lshl_add_u32 v2, v147, 1, v0
	v_mov_b32_e32 v3, v193
	v_lshl_add_u64 v[128:129], s[0:1], 0, v[192:193]
	v_lshl_add_u64 v[130:131], s[0:1], 0, v[2:3]
	s_or_b32 s0, s2, s3
	s_ashr_i32 s1, s0, 31
	s_lshl_b64 s[2:3], s[0:1], 12
	s_waitcnt vmcnt(0)
	s_add_u32 s2, s4, s2
	s_addc_u32 s3, s5, s3
	v_mov_b32_e32 v0, 0
	v_lshl_add_u64 v[132:133], s[2:3], 0, v[192:193]
	v_lshl_add_u64 v[134:135], s[2:3], 0, v[2:3]
	s_mov_b32 s1, -2
	v_add_u32_e32 v138, 0, v1
	v_add_u32_e32 v137, v5, v4
	v_mov_b32_e32 v1, v0
	v_mov_b32_e32 v2, v0
	v_mov_b32_e32 v3, v0
	v_mov_b32_e32 v4, v0
	v_mov_b32_e32 v5, v0
	v_mov_b32_e32 v6, v0
	v_mov_b32_e32 v7, v0
	v_mov_b32_e32 v8, v0
	v_mov_b32_e32 v9, v0
	v_mov_b32_e32 v10, v0
	v_mov_b32_e32 v11, v0
	v_mov_b32_e32 v12, v0
	v_mov_b32_e32 v13, v0
	v_mov_b32_e32 v14, v0
	v_mov_b32_e32 v15, v0
	v_mov_b32_e32 v16, v0
	v_mov_b32_e32 v17, v0
	v_mov_b32_e32 v18, v0
	v_mov_b32_e32 v19, v0
	v_mov_b32_e32 v20, v0
	v_mov_b32_e32 v21, v0
	v_mov_b32_e32 v22, v0
	v_mov_b32_e32 v23, v0
	v_mov_b32_e32 v24, v0
	v_mov_b32_e32 v25, v0
	v_mov_b32_e32 v26, v0
	v_mov_b32_e32 v27, v0
	v_mov_b32_e32 v28, v0
	v_mov_b32_e32 v29, v0
	v_mov_b32_e32 v30, v0
	v_mov_b32_e32 v31, v0
	v_mov_b32_e32 v32, v0
	v_mov_b32_e32 v33, v0
	v_mov_b32_e32 v34, v0
	v_mov_b32_e32 v35, v0
	v_mov_b32_e32 v36, v0
	v_mov_b32_e32 v37, v0
	v_mov_b32_e32 v38, v0
	v_mov_b32_e32 v39, v0
	v_mov_b32_e32 v40, v0
	v_mov_b32_e32 v41, v0
	v_mov_b32_e32 v42, v0
	v_mov_b32_e32 v43, v0
	v_mov_b32_e32 v44, v0
	v_mov_b32_e32 v45, v0
	v_mov_b32_e32 v46, v0
	v_mov_b32_e32 v47, v0
	v_mov_b32_e32 v48, v0
	v_mov_b32_e32 v49, v0
	v_mov_b32_e32 v50, v0
	v_mov_b32_e32 v51, v0
	v_mov_b32_e32 v52, v0
	v_mov_b32_e32 v53, v0
	v_mov_b32_e32 v54, v0
	v_mov_b32_e32 v55, v0
	v_mov_b32_e32 v56, v0
	v_mov_b32_e32 v57, v0
	v_mov_b32_e32 v58, v0
	v_mov_b32_e32 v59, v0
	v_mov_b32_e32 v60, v0
	v_mov_b32_e32 v61, v0
	v_mov_b32_e32 v62, v0
	v_mov_b32_e32 v63, v0
	v_mov_b32_e32 v64, v0
	v_mov_b32_e32 v65, v0
	v_mov_b32_e32 v66, v0
	v_mov_b32_e32 v67, v0
	v_mov_b32_e32 v68, v0
	v_mov_b32_e32 v69, v0
	v_mov_b32_e32 v70, v0
	v_mov_b32_e32 v71, v0
	v_mov_b32_e32 v72, v0
	v_mov_b32_e32 v73, v0
	v_mov_b32_e32 v74, v0
	v_mov_b32_e32 v75, v0
	v_mov_b32_e32 v76, v0
	v_mov_b32_e32 v77, v0
	v_mov_b32_e32 v78, v0
	v_mov_b32_e32 v79, v0
	v_mov_b32_e32 v80, v0
	v_mov_b32_e32 v81, v0
	v_mov_b32_e32 v82, v0
	v_mov_b32_e32 v83, v0
	v_mov_b32_e32 v84, v0
	v_mov_b32_e32 v85, v0
	v_mov_b32_e32 v86, v0
	v_mov_b32_e32 v87, v0
	v_mov_b32_e32 v88, v0
	v_mov_b32_e32 v89, v0
	v_mov_b32_e32 v90, v0
	v_mov_b32_e32 v91, v0
	v_mov_b32_e32 v92, v0
	v_mov_b32_e32 v93, v0
	v_mov_b32_e32 v94, v0
	v_mov_b32_e32 v95, v0
	v_mov_b32_e32 v96, v0
	v_mov_b32_e32 v97, v0
	v_mov_b32_e32 v98, v0
	v_mov_b32_e32 v99, v0
	v_mov_b32_e32 v100, v0
	v_mov_b32_e32 v101, v0
	v_mov_b32_e32 v102, v0
	v_mov_b32_e32 v103, v0
	v_mov_b32_e32 v104, v0
	v_mov_b32_e32 v105, v0
	v_mov_b32_e32 v106, v0
	v_mov_b32_e32 v107, v0
	v_mov_b32_e32 v108, v0
	v_mov_b32_e32 v109, v0
	v_mov_b32_e32 v110, v0
	v_mov_b32_e32 v111, v0
	v_mov_b32_e32 v112, v0
	v_mov_b32_e32 v113, v0
	v_mov_b32_e32 v114, v0
	v_mov_b32_e32 v115, v0
	v_mov_b32_e32 v116, v0
	v_mov_b32_e32 v117, v0
	v_mov_b32_e32 v118, v0
	v_mov_b32_e32 v119, v0
	v_mov_b32_e32 v120, v0
	v_mov_b32_e32 v121, v0
	v_mov_b32_e32 v122, v0
	v_mov_b32_e32 v123, v0
	v_mov_b32_e32 v124, v0
	v_mov_b32_e32 v125, v0
	v_mov_b32_e32 v126, v0
	v_mov_b32_e32 v127, v0
	v_readfirstlane_b32 s2, v139
	s_barrier
	s_barrier
; #define WAIT_L(n) asm volatile("s_waitcnt lgkmcnt(" #n ")" ::: "memory")
; #define BAR __builtin_amdgcn_s_barrier()
; #define SCHED __builtin_amdgcn_sched_barrier(0)
; #define STAGE(P, BASE, br, kt) do { const char* _g = (const char*)((BASE) + (size_t)(br) * GK + (kt) * BK); \
;     __builtin_amdgcn_global_load_lds((const unsigned*)(_g + voff0), (unsigned*)((char*)(P) + tx * 16), 16, 0, 0); \
;     __builtin_amdgcn_global_load_lds((const unsigned*)(_g + voff1), (unsigned*)((char*)(P) + tx * 16 + 8192), 16, 0, 0); } while (0)
; #define LDA(dst, b, h) _Pragma("unroll") for (int m = 0; m < 4; ++m) _Pragma("unroll") for (int k = 0; k < 2; ++k) \
;     dst[m][k] = *reinterpret_cast<const bf16x8*>((char*)shm + abase + (((b) * 2 + (h)) * 16384 + (m * 2 + k) * 1024))
; #define LDB(dst, b, h) _Pragma("unroll") for (int n = 0; n < 2; ++n) _Pragma("unroll") for (int k = 0; k < 2; ++k) \
;     dst[n][k] = *reinterpret_cast<const bf16x8*>((char*)shm + bbase + (((b) * 2 + (h)) * 16384 + (n * 2 + k) * 1024))
; template <bool SWAP>
; __device__ __forceinline__ void gemm_main(const u16* __restrict__ A, const u16* __restrict__ Bt, int brow, int bcol,
;                                           u16* shm, f32x4 (&acc)[2][2][4][2]) {
;     ...
;   for (int t = 0; t < nt - 2; t += 2) {
;     LDB(B0, 0, 0); SCHED; LDA(At, 0, 0); STAGE(SA(1, 1), A, brow + HALF, t + 1);
;     WAIT_L(8); BAR; WAIT_L(0); MMA(0, 0, At, B0); BAR; SCHED;
;     LDB(B1, 0, 1); STAGE(SB(0, 0), Bt, bcol, t + 2);
;     BAR; WAIT_L(0); MMA(0, 1, At, B1); BAR;
;     LDA(At, 0, 1); STAGE(SA(0, 0), A, brow, t + 2);
;     BAR; WAIT_L(0); MMA(1, 0, At, B0); BAR; SCHED;
.LBB0_436:
	ds_read_b128 v[150:153], v138
	ds_read_b128 v[154:157], v138 offset:1024
	ds_read_b128 v[158:161], v138 offset:2048
	ds_read_b128 v[162:165], v138 offset:3072
	ds_read_b128 v[166:169], v137
	ds_read_b128 v[170:173], v137 offset:1024
	ds_read_b128 v[174:177], v137 offset:2048
	ds_read_b128 v[178:181], v137 offset:3072
	ds_read_b128 v[182:185], v137 offset:4096
	ds_read_b128 v[186:189], v137 offset:5120
	ds_read_b128 v[194:197], v137 offset:6144
	ds_read_b128 v[198:201], v137 offset:7168
	v_add_u32_e32 v192, 0, v139
	v_add_u32_e32 v148, 0xc000, v192
	v_lshl_add_u64 v[190:191], s[50:51], 0, v[132:133]
	v_add_u32_e32 v149, 0xe000, v192
	v_lshl_add_u64 v[202:203], v[190:191], 0, s[82:83]
	s_add_u32 m0, s2, 0xc000
	v_lshl_add_u64 v[232:233], s[50:51], 0, v[134:135]
	global_load_lds_dwordx4 v[202:203], off
	v_lshl_add_u64 v[202:203], v[232:233], 0, s[82:83]
	s_add_u32 m0, s2, 0xe000
	s_nop 0
	global_load_lds_dwordx4 v[202:203], off
	s_waitcnt lgkmcnt(8)
	s_setprio 1
	s_barrier
	s_waitcnt lgkmcnt(0)
	v_mfma_f32_16x16x32_bf16 v[124:127], v[150:153], v[166:169], v[124:127]
	v_mfma_f32_16x16x32_bf16 v[120:123], v[158:161], v[166:169], v[120:123]
	v_mfma_f32_16x16x32_bf16 v[116:119], v[150:153], v[174:177], v[116:119]
	v_mfma_f32_16x16x32_bf16 v[112:115], v[158:161], v[174:177], v[112:115]
	v_mfma_f32_16x16x32_bf16 v[108:111], v[150:153], v[182:185], v[108:111]
	v_mfma_f32_16x16x32_bf16 v[104:107], v[158:161], v[182:185], v[104:107]
	v_mfma_f32_16x16x32_bf16 v[100:103], v[150:153], v[194:197], v[100:103]
	v_mfma_f32_16x16x32_bf16 v[96:99], v[158:161], v[194:197], v[96:99]
	v_mfma_f32_16x16x32_bf16 v[124:127], v[154:157], v[170:173], v[124:127]
	v_mfma_f32_16x16x32_bf16 v[120:123], v[162:165], v[170:173], v[120:123]
	v_mfma_f32_16x16x32_bf16 v[116:119], v[154:157], v[178:181], v[116:119]
	v_mfma_f32_16x16x32_bf16 v[112:115], v[162:165], v[178:181], v[112:115]
	v_mfma_f32_16x16x32_bf16 v[108:111], v[154:157], v[186:189], v[108:111]
	v_mfma_f32_16x16x32_bf16 v[104:107], v[162:165], v[186:189], v[104:107]
	v_mfma_f32_16x16x32_bf16 v[100:103], v[154:157], v[198:201], v[100:103]
	v_mfma_f32_16x16x32_bf16 v[96:99], v[162:165], v[198:201], v[96:99]
	s_barrier
	s_setprio 0
	ds_read_b128 v[202:205], v138 offset:16384
	ds_read_b128 v[206:209], v138 offset:17408
	ds_read_b128 v[224:227], v138 offset:18432
	ds_read_b128 v[228:231], v138 offset:19456
	v_lshl_add_u64 v[234:235], s[50:51], 0, v[128:129]
	v_lshl_add_u64 v[236:237], v[234:235], 0, s[74:75]
	s_add_u32 m0, s2, s28
	s_nop 0
	global_load_lds_dwordx4 v[236:237], off
	v_lshl_add_u64 v[236:237], s[50:51], 0, v[130:131]
	v_lshl_add_u64 v[238:239], v[236:237], 0, s[74:75]
	s_add_u32 m0, s2, s28
	s_add_u32 m0, m0, 0x2000
	s_nop 0
	global_load_lds_dwordx4 v[238:239], off
	s_setprio 1
	s_barrier
	s_waitcnt lgkmcnt(0)
	v_mfma_f32_16x16x32_bf16 v[92:95], v[202:205], v[166:169], v[92:95]
	v_mfma_f32_16x16x32_bf16 v[88:91], v[224:227], v[166:169], v[88:91]
	v_mfma_f32_16x16x32_bf16 v[84:87], v[202:205], v[174:177], v[84:87]
	v_mfma_f32_16x16x32_bf16 v[80:83], v[224:227], v[174:177], v[80:83]
	v_mfma_f32_16x16x32_bf16 v[76:79], v[202:205], v[182:185], v[76:79]
	v_mfma_f32_16x16x32_bf16 v[72:75], v[224:227], v[182:185], v[72:75]
	v_mfma_f32_16x16x32_bf16 v[68:71], v[202:205], v[194:197], v[68:71]
	v_mfma_f32_16x16x32_bf16 v[64:67], v[224:227], v[194:197], v[64:67]
	v_mfma_f32_16x16x32_bf16 v[92:95], v[206:209], v[170:173], v[92:95]
	v_mfma_f32_16x16x32_bf16 v[88:91], v[228:231], v[170:173], v[88:91]
	v_mfma_f32_16x16x32_bf16 v[84:87], v[206:209], v[178:181], v[84:87]
	v_mfma_f32_16x16x32_bf16 v[80:83], v[228:231], v[178:181], v[80:83]
	v_mfma_f32_16x16x32_bf16 v[76:79], v[206:209], v[186:189], v[76:79]
	v_mfma_f32_16x16x32_bf16 v[72:75], v[228:231], v[186:189], v[72:75]
	v_mfma_f32_16x16x32_bf16 v[68:71], v[206:209], v[198:201], v[68:71]
	v_mfma_f32_16x16x32_bf16 v[64:67], v[228:231], v[198:201], v[64:67]
	s_barrier
	s_setprio 0
	ds_read_b128 v[166:169], v137 offset:16384
	ds_read_b128 v[170:173], v137 offset:17408
	ds_read_b128 v[174:177], v137 offset:18432
	ds_read_b128 v[178:181], v137 offset:19456
	ds_read_b128 v[182:185], v137 offset:20480
	ds_read_b128 v[186:189], v137 offset:21504
	ds_read_b128 v[194:197], v137 offset:22528
	ds_read_b128 v[198:201], v137 offset:23552
	v_lshl_add_u64 v[238:239], v[190:191], 0, s[76:77]
	s_add_u32 m0, s2, 0x0
	s_nop 0
	global_load_lds_dwordx4 v[238:239], off
	v_lshl_add_u64 v[238:239], v[232:233], 0, s[76:77]
	s_add_u32 m0, s2, 0x2000
	s_nop 0
	global_load_lds_dwordx4 v[238:239], off
	s_setprio 1
	s_barrier
	s_waitcnt lgkmcnt(0)
	v_mfma_f32_16x16x32_bf16 v[60:63], v[150:153], v[166:169], v[60:63]
	v_mfma_f32_16x16x32_bf16 v[56:59], v[158:161], v[166:169], v[56:59]
	v_mfma_f32_16x16x32_bf16 v[52:55], v[150:153], v[174:177], v[52:55]
	v_mfma_f32_16x16x32_bf16 v[48:51], v[158:161], v[174:177], v[48:51]
	v_mfma_f32_16x16x32_bf16 v[44:47], v[150:153], v[182:185], v[44:47]
	v_mfma_f32_16x16x32_bf16 v[40:43], v[158:161], v[182:185], v[40:43]
	v_mfma_f32_16x16x32_bf16 v[36:39], v[150:153], v[194:197], v[36:39]
	v_mfma_f32_16x16x32_bf16 v[32:35], v[158:161], v[194:197], v[32:35]
	v_mfma_f32_16x16x32_bf16 v[60:63], v[154:157], v[170:173], v[60:63]
	v_mfma_f32_16x16x32_bf16 v[56:59], v[162:165], v[170:173], v[56:59]
	v_mfma_f32_16x16x32_bf16 v[52:55], v[154:157], v[178:181], v[52:55]
	v_mfma_f32_16x16x32_bf16 v[48:51], v[162:165], v[178:181], v[48:51]
	v_mfma_f32_16x16x32_bf16 v[44:47], v[154:157], v[186:189], v[44:47]
	v_mfma_f32_16x16x32_bf16 v[40:43], v[162:165], v[186:189], v[40:43]
	v_mfma_f32_16x16x32_bf16 v[36:39], v[154:157], v[198:201], v[36:39]
	v_mfma_f32_16x16x32_bf16 v[32:35], v[162:165], v[198:201], v[32:35]
	s_barrier
; #define WAIT_V(n) asm volatile("s_waitcnt vmcnt(" #n ")" ::: "memory")
; #define WAIT_L(n) asm volatile("s_waitcnt lgkmcnt(" #n ")" ::: "memory")
; #define BAR __builtin_amdgcn_s_barrier()
; #define SCHED __builtin_amdgcn_sched_barrier(0)
; #define STAGE(P, BASE, br, kt) do { const char* _g = (const char*)((BASE) + (size_t)(br) * GK + (kt) * BK); \
;     __builtin_amdgcn_global_load_lds((const unsigned*)(_g + voff0), (unsigned*)((char*)(P) + tx * 16), 16, 0, 0); \
;     __builtin_amdgcn_global_load_lds((const unsigned*)(_g + voff1), (unsigned*)((char*)(P) + tx * 16 + 8192), 16, 0, 0); } while (0)
; #define LDA(dst, b, h) _Pragma("unroll") for (int m = 0; m < 4; ++m) _Pragma("unroll") for (int k = 0; k < 2; ++k) \
;     dst[m][k] = *reinterpret_cast<const bf16x8*>((char*)shm + abase + (((b) * 2 + (h)) * 16384 + (m * 2 + k) * 1024))
; #define LDB(dst, b, h) _Pragma("unroll") for (int n = 0; n < 2; ++n) _Pragma("unroll") for (int k = 0; k < 2; ++k) \
;     dst[n][k] = *reinterpret_cast<const bf16x8*>((char*)shm + bbase + (((b) * 2 + (h)) * 16384 + (n * 2 + k) * 1024))
; template <bool SWAP>
; __device__ __forceinline__ void gemm_main(const u16* __restrict__ A, const u16* __restrict__ Bt, int brow, int bcol,
;                                           u16* shm, f32x4 (&acc)[2][2][4][2]) {
;     ...
;     STAGE(SB(0, 1), Bt, bcol + HALF, t + 2);
;     WAIT_V(6); BAR; MMA(1, 1, At, B1); BAR;
;     LDB(B0, 1, 0); SCHED; LDA(At, 1, 0); STAGE(SA(0, 1), A, brow + HALF, t + 2);
;     WAIT_L(8); BAR; WAIT_L(0); MMA(0, 0, At, B0); BAR; SCHED;
;     LDB(B1, 1, 1); STAGE(SB(1, 0), Bt, bcol, t + 3);
;     BAR; WAIT_L(0); MMA(0, 1, At, B1); BAR;
;     LDA(At, 1, 1); STAGE(SA(1, 0), A, brow, t + 3);
;     BAR; WAIT_L(0); MMA(1, 0, At, B0); BAR; SCHED;
	s_setprio 0
	v_lshl_add_u64 v[150:151], v[234:235], 0, s[70:71]
	s_add_u32 m0, s2, s29
	s_nop 0
	global_load_lds_dwordx4 v[150:151], off
	v_lshl_add_u64 v[150:151], v[236:237], 0, s[70:71]
	s_add_u32 m0, s2, s29
	s_add_u32 m0, m0, 0x2000
	s_nop 0
	global_load_lds_dwordx4 v[150:151], off
	s_waitcnt vmcnt(6)
	s_setprio 1
	s_barrier
	v_mfma_f32_16x16x32_bf16 v[28:31], v[202:205], v[166:169], v[28:31]
	v_mfma_f32_16x16x32_bf16 v[24:27], v[224:227], v[166:169], v[24:27]
	v_mfma_f32_16x16x32_bf16 v[20:23], v[202:205], v[174:177], v[20:23]
	v_mfma_f32_16x16x32_bf16 v[16:19], v[224:227], v[174:177], v[16:19]
	v_mfma_f32_16x16x32_bf16 v[12:15], v[202:205], v[182:185], v[12:15]
	v_mfma_f32_16x16x32_bf16 v[8:11], v[224:227], v[182:185], v[8:11]
	v_mfma_f32_16x16x32_bf16 v[4:7], v[202:205], v[194:197], v[4:7]
	v_mfma_f32_16x16x32_bf16 v[0:3], v[224:227], v[194:197], v[0:3]
	v_mfma_f32_16x16x32_bf16 v[28:31], v[206:209], v[170:173], v[28:31]
	v_mfma_f32_16x16x32_bf16 v[24:27], v[228:231], v[170:173], v[24:27]
	v_mfma_f32_16x16x32_bf16 v[20:23], v[206:209], v[178:181], v[20:23]
	v_mfma_f32_16x16x32_bf16 v[16:19], v[228:231], v[178:181], v[16:19]
	v_mfma_f32_16x16x32_bf16 v[12:15], v[206:209], v[186:189], v[12:15]
	v_mfma_f32_16x16x32_bf16 v[8:11], v[228:231], v[186:189], v[8:11]
	v_mfma_f32_16x16x32_bf16 v[4:7], v[206:209], v[198:201], v[4:7]
	v_mfma_f32_16x16x32_bf16 v[0:3], v[228:231], v[198:201], v[0:3]
	s_barrier
	s_setprio 0
	ds_read_b128 v[150:153], v138 offset:32768
	ds_read_b128 v[154:157], v138 offset:33792
	ds_read_b128 v[158:161], v138 offset:34816
	ds_read_b128 v[162:165], v138 offset:35840
	ds_read_b128 v[166:169], v137 offset:32768
	ds_read_b128 v[170:173], v137 offset:33792
	ds_read_b128 v[174:177], v137 offset:34816
	ds_read_b128 v[178:181], v137 offset:35840
	ds_read_b128 v[182:185], v137 offset:36864
	ds_read_b128 v[186:189], v137 offset:37888
	ds_read_b128 v[194:197], v137 offset:38912
	ds_read_b128 v[198:201], v137 offset:39936
	v_lshl_add_u64 v[202:203], v[190:191], 0, s[96:97]
	s_add_u32 m0, s2, 0x4000
	s_nop 0
	global_load_lds_dwordx4 v[202:203], off
	v_lshl_add_u64 v[202:203], v[232:233], 0, s[96:97]
	s_add_u32 m0, s2, 0x6000
	s_nop 0
	global_load_lds_dwordx4 v[202:203], off
	s_waitcnt lgkmcnt(8)
	s_setprio 1
	s_barrier
	s_waitcnt lgkmcnt(0)
	v_mfma_f32_16x16x32_bf16 v[124:127], v[150:153], v[166:169], v[124:127]
	v_mfma_f32_16x16x32_bf16 v[120:123], v[158:161], v[166:169], v[120:123]
	v_mfma_f32_16x16x32_bf16 v[116:119], v[150:153], v[174:177], v[116:119]
	v_mfma_f32_16x16x32_bf16 v[112:115], v[158:161], v[174:177], v[112:115]
	v_mfma_f32_16x16x32_bf16 v[108:111], v[150:153], v[182:185], v[108:111]
	v_mfma_f32_16x16x32_bf16 v[104:107], v[158:161], v[182:185], v[104:107]
	v_mfma_f32_16x16x32_bf16 v[100:103], v[150:153], v[194:197], v[100:103]
	v_mfma_f32_16x16x32_bf16 v[96:99], v[158:161], v[194:197], v[96:99]
	v_mfma_f32_16x16x32_bf16 v[124:127], v[154:157], v[170:173], v[124:127]
	v_mfma_f32_16x16x32_bf16 v[120:123], v[162:165], v[170:173], v[120:123]
	v_mfma_f32_16x16x32_bf16 v[116:119], v[154:157], v[178:181], v[116:119]
	v_mfma_f32_16x16x32_bf16 v[112:115], v[162:165], v[178:181], v[112:115]
	v_mfma_f32_16x16x32_bf16 v[108:111], v[154:157], v[186:189], v[108:111]
	v_mfma_f32_16x16x32_bf16 v[104:107], v[162:165], v[186:189], v[104:107]
	v_mfma_f32_16x16x32_bf16 v[100:103], v[154:157], v[198:201], v[100:103]
	v_mfma_f32_16x16x32_bf16 v[96:99], v[162:165], v[198:201], v[96:99]
	s_barrier
	s_setprio 0
	ds_read_b128 v[202:205], v138 offset:49152
	ds_read_b128 v[206:209], v138 offset:50176
	ds_read_b128 v[224:227], v138 offset:51200
	ds_read_b128 v[228:231], v138 offset:52224
	v_lshl_add_u64 v[238:239], v[234:235], 0, s[34:35]
	s_add_u32 m0, s2, s30
	s_nop 0
	global_load_lds_dwordx4 v[238:239], off
	v_lshl_add_u64 v[238:239], v[236:237], 0, s[34:35]
	s_add_u32 m0, s2, s30
	s_add_u32 m0, m0, 0x2000
	s_nop 0
	global_load_lds_dwordx4 v[238:239], off
	s_setprio 1
	s_barrier
	s_waitcnt lgkmcnt(0)
	v_mfma_f32_16x16x32_bf16 v[92:95], v[202:205], v[166:169], v[92:95]
	v_mfma_f32_16x16x32_bf16 v[88:91], v[224:227], v[166:169], v[88:91]
	v_mfma_f32_16x16x32_bf16 v[84:87], v[202:205], v[174:177], v[84:87]
	v_mfma_f32_16x16x32_bf16 v[80:83], v[224:227], v[174:177], v[80:83]
	v_mfma_f32_16x16x32_bf16 v[76:79], v[202:205], v[182:185], v[76:79]
	v_mfma_f32_16x16x32_bf16 v[72:75], v[224:227], v[182:185], v[72:75]
	v_mfma_f32_16x16x32_bf16 v[68:71], v[202:205], v[194:197], v[68:71]
	v_mfma_f32_16x16x32_bf16 v[64:67], v[224:227], v[194:197], v[64:67]
	v_mfma_f32_16x16x32_bf16 v[92:95], v[206:209], v[170:173], v[92:95]
	v_mfma_f32_16x16x32_bf16 v[88:91], v[228:231], v[170:173], v[88:91]
	v_mfma_f32_16x16x32_bf16 v[84:87], v[206:209], v[178:181], v[84:87]
	v_mfma_f32_16x16x32_bf16 v[80:83], v[228:231], v[178:181], v[80:83]
	v_mfma_f32_16x16x32_bf16 v[76:79], v[206:209], v[186:189], v[76:79]
	v_mfma_f32_16x16x32_bf16 v[72:75], v[228:231], v[186:189], v[72:75]
	v_mfma_f32_16x16x32_bf16 v[68:71], v[206:209], v[198:201], v[68:71]
	v_mfma_f32_16x16x32_bf16 v[64:67], v[228:231], v[198:201], v[64:67]
	s_barrier
	s_setprio 0
	ds_read_b128 v[166:169], v137 offset:49152
	ds_read_b128 v[170:173], v137 offset:50176
	ds_read_b128 v[174:177], v137 offset:51200
	ds_read_b128 v[178:181], v137 offset:52224
	ds_read_b128 v[182:185], v137 offset:53248
	ds_read_b128 v[186:189], v137 offset:54272
	ds_read_b128 v[194:197], v137 offset:55296
	ds_read_b128 v[198:201], v137 offset:56320
	v_add_u32_e32 v223, 0x8000, v192
	v_lshl_add_u64 v[190:191], v[190:191], 0, s[36:37]
	s_add_u32 m0, s2, 0x8000
	s_nop 0
	global_load_lds_dwordx4 v[190:191], off
	v_lshl_add_u64 v[190:191], v[232:233], 0, s[36:37]
	s_add_u32 m0, s2, 0xa000
	s_nop 0
	global_load_lds_dwordx4 v[190:191], off
	s_setprio 1
	s_barrier
; #define WAIT_V(n) asm volatile("s_waitcnt vmcnt(" #n ")" ::: "memory")
; #define WAIT_L(n) asm volatile("s_waitcnt lgkmcnt(" #n ")" ::: "memory")
; #define BAR __builtin_amdgcn_s_barrier()
; #define SCHED __builtin_amdgcn_sched_barrier(0)
; #define STAGE(P, BASE, br, kt) do { const char* _g = (const char*)((BASE) + (size_t)(br) * GK + (kt) * BK); \
;     __builtin_amdgcn_global_load_lds((const unsigned*)(_g + voff0), (unsigned*)((char*)(P) + tx * 16), 16, 0, 0); \
;     __builtin_amdgcn_global_load_lds((const unsigned*)(_g + voff1), (unsigned*)((char*)(P) + tx * 16 + 8192), 16, 0, 0); } while (0)
; #define LDA(dst, b, h) _Pragma("unroll") for (int m = 0; m < 4; ++m) _Pragma("unroll") for (int k = 0; k < 2; ++k) \
;     dst[m][k] = *reinterpret_cast<const bf16x8*>((char*)shm + abase + (((b) * 2 + (h)) * 16384 + (m * 2 + k) * 1024))
; #define LDB(dst, b, h) _Pragma("unroll") for (int n = 0; n < 2; ++n) _Pragma("unroll") for (int k = 0; k < 2; ++k) \
;     dst[n][k] = *reinterpret_cast<const bf16x8*>((char*)shm + bbase + (((b) * 2 + (h)) * 16384 + (n * 2 + k) * 1024))
; template <bool SWAP>
; __device__ __forceinline__ void gemm_main(const u16* __restrict__ A, const u16* __restrict__ Bt, int brow, int bcol,
;                                           u16* shm, f32x4 (&acc)[2][2][4][2]) {
;     ...
;     BAR; WAIT_L(0); MMA(1, 0, At, B0); BAR; SCHED;
;     STAGE(SB(1, 1), Bt, bcol + HALF, t + 3);
;     WAIT_V(6); BAR; MMA(1, 1, At, B1); BAR;
;   }
;   { LDB(B0, 0, 0); LDA(At, 0, 0); STAGE(SA(1, 1), A, brow + HALF, nt - 1);
;     BAR; WAIT_L(0); MMA(0, 0, At, B0); BAR;
	s_waitcnt lgkmcnt(0)
	v_mfma_f32_16x16x32_bf16 v[60:63], v[150:153], v[166:169], v[60:63]
	v_mfma_f32_16x16x32_bf16 v[56:59], v[158:161], v[166:169], v[56:59]
	v_mfma_f32_16x16x32_bf16 v[52:55], v[150:153], v[174:177], v[52:55]
	v_mfma_f32_16x16x32_bf16 v[48:51], v[158:161], v[174:177], v[48:51]
	v_mfma_f32_16x16x32_bf16 v[44:47], v[150:153], v[182:185], v[44:47]
	v_mfma_f32_16x16x32_bf16 v[40:43], v[158:161], v[182:185], v[40:43]
	v_mfma_f32_16x16x32_bf16 v[36:39], v[150:153], v[194:197], v[36:39]
	v_mfma_f32_16x16x32_bf16 v[32:35], v[158:161], v[194:197], v[32:35]
	v_mfma_f32_16x16x32_bf16 v[60:63], v[154:157], v[170:173], v[60:63]
	v_mfma_f32_16x16x32_bf16 v[56:59], v[162:165], v[170:173], v[56:59]
	v_mfma_f32_16x16x32_bf16 v[52:55], v[154:157], v[178:181], v[52:55]
	v_mfma_f32_16x16x32_bf16 v[48:51], v[162:165], v[178:181], v[48:51]
	v_mfma_f32_16x16x32_bf16 v[44:47], v[154:157], v[186:189], v[44:47]
	v_mfma_f32_16x16x32_bf16 v[40:43], v[162:165], v[186:189], v[40:43]
	v_mfma_f32_16x16x32_bf16 v[36:39], v[154:157], v[198:201], v[36:39]
	v_mfma_f32_16x16x32_bf16 v[32:35], v[162:165], v[198:201], v[32:35]
	s_barrier
	s_setprio 0
	v_lshl_add_u64 v[150:151], v[234:235], 0, s[64:65]
	s_add_u32 m0, s2, s31
	s_nop 0
	global_load_lds_dwordx4 v[150:151], off
	v_lshl_add_u64 v[150:151], v[236:237], 0, s[64:65]
	s_add_u32 m0, s2, s31
	s_add_u32 m0, m0, 0x2000
	s_nop 0
	global_load_lds_dwordx4 v[150:151], off
	s_waitcnt vmcnt(6)
	s_setprio 1
	s_barrier
	v_mfma_f32_16x16x32_bf16 v[28:31], v[202:205], v[166:169], v[28:31]
	v_mfma_f32_16x16x32_bf16 v[24:27], v[224:227], v[166:169], v[24:27]
	v_mfma_f32_16x16x32_bf16 v[20:23], v[202:205], v[174:177], v[20:23]
	v_mfma_f32_16x16x32_bf16 v[16:19], v[224:227], v[174:177], v[16:19]
	v_mfma_f32_16x16x32_bf16 v[12:15], v[202:205], v[182:185], v[12:15]
	v_mfma_f32_16x16x32_bf16 v[8:11], v[224:227], v[182:185], v[8:11]
	v_mfma_f32_16x16x32_bf16 v[4:7], v[202:205], v[194:197], v[4:7]
	v_mfma_f32_16x16x32_bf16 v[0:3], v[224:227], v[194:197], v[0:3]
	v_mfma_f32_16x16x32_bf16 v[28:31], v[206:209], v[170:173], v[28:31]
	v_mfma_f32_16x16x32_bf16 v[24:27], v[228:231], v[170:173], v[24:27]
	v_mfma_f32_16x16x32_bf16 v[20:23], v[206:209], v[178:181], v[20:23]
	v_mfma_f32_16x16x32_bf16 v[16:19], v[228:231], v[178:181], v[16:19]
	v_mfma_f32_16x16x32_bf16 v[12:15], v[206:209], v[186:189], v[12:15]
	v_mfma_f32_16x16x32_bf16 v[8:11], v[228:231], v[186:189], v[8:11]
	v_mfma_f32_16x16x32_bf16 v[4:7], v[206:209], v[198:201], v[4:7]
	v_mfma_f32_16x16x32_bf16 v[0:3], v[228:231], v[198:201], v[0:3]
	s_add_i32 s1, s1, 2
	v_lshl_add_u64 v[128:129], v[128:129], 0, s[74:75]
	v_lshl_add_u64 v[130:131], v[130:131], 0, s[74:75]
	v_lshl_add_u64 v[132:133], v[132:133], 0, s[74:75]
	s_cmp_lt_u32 s1, 28
	v_lshl_add_u64 v[134:135], v[134:135], 0, s[74:75]
	s_barrier
	s_setprio 0
	s_cbranch_scc1 .LBB0_436
	v_lshlrev_b32_e32 v128, 3, v142
	v_lshlrev_b32_e32 v129, 5, v142
	v_and_b32_e32 v128, 0xffff0, v128
	v_and_b32_e32 v129, 32, v129
	s_or_b32 s2, s0, 0x80
	v_add_u32_e32 v129, v129, v144
	v_add_lshl_u32 v128, v143, v128, 12
	s_ashr_i32 s3, s2, 31
	v_lshl_add_u32 v192, v129, 1, v128
	v_lshlrev_b32_e32 v128, 3, v145
	v_lshlrev_b32_e32 v129, 5, v145
	s_lshl_b64 s[2:3], s[2:3], 12
	v_and_b32_e32 v128, 0xffff0, v128
	v_and_b32_e32 v129, 32, v129
	s_add_u32 s2, s16, s2
	v_add_u32_e32 v129, v129, v147
	v_add_lshl_u32 v128, v146, v128, 12
	s_addc_u32 s3, s17, s3
	v_lshl_add_u32 v146, v129, 1, v128
	v_mov_b32_e32 v147, v193
	v_lshl_add_u64 v[186:187], s[2:3], 0, v[192:193]
	s_mov_b64 s[8:9], 0xf80
	v_readfirstlane_b32 s1, v148
	v_lshl_add_u64 v[186:187], v[186:187], 0, s[8:9]
	s_mov_b32 m0, s1
	v_lshl_add_u64 v[146:147], s[2:3], 0, v[146:147]
	v_readfirstlane_b32 s1, v149
	ds_read_b128 v[128:131], v138
	ds_read_b128 v[132:135], v138 offset:1024
	ds_read_b128 v[142:145], v138 offset:2048
	ds_read_b128 v[150:153], v138 offset:3072
	ds_read_b128 v[154:157], v137
	ds_read_b128 v[158:161], v137 offset:1024
	ds_read_b128 v[162:165], v137 offset:2048
	ds_read_b128 v[166:169], v137 offset:3072
	ds_read_b128 v[170:173], v137 offset:4096
	ds_read_b128 v[174:177], v137 offset:5120
	ds_read_b128 v[178:181], v137 offset:6144
	ds_read_b128 v[182:185], v137 offset:7168
	global_load_lds_dwordx4 v[186:187], off
	v_lshl_add_u64 v[146:147], v[146:147], 0, s[8:9]
	s_mov_b32 m0, s1
	s_nop 0
	global_load_lds_dwordx4 v[146:147], off
	s_barrier
	s_waitcnt lgkmcnt(0)
	s_setprio 1
	s_waitcnt lgkmcnt(0)
	v_mfma_f32_16x16x32_bf16 v[124:127], v[128:131], v[154:157], v[124:127]
	v_mfma_f32_16x16x32_bf16 v[112:115], v[142:145], v[162:165], v[112:115]
	v_mfma_f32_16x16x32_bf16 v[104:107], v[142:145], v[170:173], v[104:107]
	v_mfma_f32_16x16x32_bf16 v[96:99], v[142:145], v[178:181], v[96:99]
	v_mfma_f32_16x16x32_bf16 v[124:127], v[132:135], v[158:161], v[124:127]
	v_mfma_f32_16x16x32_bf16 v[120:123], v[142:145], v[154:157], v[120:123]
	v_mfma_f32_16x16x32_bf16 v[116:119], v[128:131], v[162:165], v[116:119]
	v_mfma_f32_16x16x32_bf16 v[112:115], v[150:153], v[166:169], v[112:115]
	v_mfma_f32_16x16x32_bf16 v[108:111], v[128:131], v[170:173], v[108:111]
	v_mfma_f32_16x16x32_bf16 v[104:107], v[150:153], v[174:177], v[104:107]
	v_mfma_f32_16x16x32_bf16 v[100:103], v[128:131], v[178:181], v[100:103]
	v_mfma_f32_16x16x32_bf16 v[96:99], v[150:153], v[182:185], v[96:99]
	v_mfma_f32_16x16x32_bf16 v[146:149], v[150:153], v[158:161], v[120:123]
	v_mfma_f32_16x16x32_bf16 v[186:189], v[132:135], v[166:169], v[116:119]
	v_mfma_f32_16x16x32_bf16 v[194:197], v[132:135], v[174:177], v[108:111]
	v_mfma_f32_16x16x32_bf16 v[198:201], v[132:135], v[182:185], v[100:103]
	s_setprio 0
	s_barrier
; #define WAIT_V(n) asm volatile("s_waitcnt vmcnt(" #n ")" ::: "memory")
; #define WAIT_L(n) asm volatile("s_waitcnt lgkmcnt(" #n ")" ::: "memory")
; #define BAR __builtin_amdgcn_s_barrier()
; #define LDA(dst, b, h) _Pragma("unroll") for (int m = 0; m < 4; ++m) _Pragma("unroll") for (int k = 0; k < 2; ++k) \
;     dst[m][k] = *reinterpret_cast<const bf16x8*>((char*)shm + abase + (((b) * 2 + (h)) * 16384 + (m * 2 + k) * 1024))
; #define LDB(dst, b, h) _Pragma("unroll") for (int n = 0; n < 2; ++n) _Pragma("unroll") for (int k = 0; k < 2; ++k) \
;     dst[n][k] = *reinterpret_cast<const bf16x8*>((char*)shm + bbase + (((b) * 2 + (h)) * 16384 + (n * 2 + k) * 1024))
; template <bool SWAP>
; __device__ __forceinline__ void gemm_main(const u16* __restrict__ A, const u16* __restrict__ Bt, int brow, int bcol,
;                                           u16* shm, f32x4 (&acc)[2][2][4][2]) {
;     ...
;     BAR; WAIT_L(0); MMA(0, 0, At, B0); BAR;
;     LDB(B1, 0, 1); BAR; WAIT_L(0); MMA(0, 1, At, B1); BAR;
;     LDA(At, 0, 1); WAIT_V(4); BAR; WAIT_L(0); MMA(1, 0, At, B0); MMA(1, 1, At, B1); BAR; }
;   { LDB(B0, 1, 0); LDA(At, 1, 0); WAIT_V(2); BAR; WAIT_L(0); MMA(0, 0, At, B0); BAR;
	s_nop 0
	ds_read_b128 v[100:103], v138 offset:16384
	ds_read_b128 v[108:111], v138 offset:17408
	ds_read_b128 v[116:119], v138 offset:18432
	ds_read_b128 v[120:123], v138 offset:19456
	s_barrier
	s_waitcnt lgkmcnt(0)
	s_setprio 1
	s_waitcnt lgkmcnt(0)
	v_mfma_f32_16x16x32_bf16 v[88:91], v[116:119], v[154:157], v[88:91]
	v_mfma_f32_16x16x32_bf16 v[80:83], v[116:119], v[162:165], v[80:83]
	v_mfma_f32_16x16x32_bf16 v[72:75], v[116:119], v[170:173], v[72:75]
	v_mfma_f32_16x16x32_bf16 v[64:67], v[116:119], v[178:181], v[64:67]
	v_mfma_f32_16x16x32_bf16 v[92:95], v[100:103], v[154:157], v[92:95]
	v_mfma_f32_16x16x32_bf16 v[88:91], v[120:123], v[158:161], v[88:91]
	v_mfma_f32_16x16x32_bf16 v[84:87], v[100:103], v[162:165], v[84:87]
	v_mfma_f32_16x16x32_bf16 v[80:83], v[120:123], v[166:169], v[80:83]
	v_mfma_f32_16x16x32_bf16 v[76:79], v[100:103], v[170:173], v[76:79]
	v_mfma_f32_16x16x32_bf16 v[72:75], v[120:123], v[174:177], v[72:75]
	v_mfma_f32_16x16x32_bf16 v[68:71], v[100:103], v[178:181], v[68:71]
	v_mfma_f32_16x16x32_bf16 v[64:67], v[120:123], v[182:185], v[64:67]
	v_mfma_f32_16x16x32_bf16 v[202:205], v[108:111], v[158:161], v[92:95]
	v_mfma_f32_16x16x32_bf16 v[154:157], v[108:111], v[166:169], v[84:87]
	v_mfma_f32_16x16x32_bf16 v[158:161], v[108:111], v[174:177], v[76:79]
	v_mfma_f32_16x16x32_bf16 v[162:165], v[108:111], v[182:185], v[68:71]
	s_setprio 0
	s_barrier
	s_nop 0
	ds_read_b128 v[68:71], v137 offset:16384
	ds_read_b128 v[76:79], v137 offset:17408
	ds_read_b128 v[84:87], v137 offset:18432
	ds_read_b128 v[92:95], v137 offset:19456
	ds_read_b128 v[166:169], v137 offset:20480
	ds_read_b128 v[170:173], v137 offset:21504
	ds_read_b128 v[174:177], v137 offset:22528
	ds_read_b128 v[178:181], v137 offset:23552
	s_waitcnt vmcnt(4)
	s_barrier
	s_waitcnt lgkmcnt(0)
	s_setprio 1
	s_waitcnt lgkmcnt(0)
	v_mfma_f32_16x16x32_bf16 v[60:63], v[128:131], v[68:71], v[60:63]
	v_mfma_f32_16x16x32_bf16 v[56:59], v[142:145], v[68:71], v[56:59]
	v_mfma_f32_16x16x32_bf16 v[48:51], v[142:145], v[84:87], v[48:51]
	v_mfma_f32_16x16x32_bf16 v[40:43], v[142:145], v[166:169], v[40:43]
	v_mfma_f32_16x16x32_bf16 v[32:35], v[142:145], v[174:177], v[32:35]
	v_mfma_f32_16x16x32_bf16 v[60:63], v[132:135], v[76:79], v[60:63]
	v_mfma_f32_16x16x32_bf16 v[56:59], v[150:153], v[76:79], v[56:59]
	v_mfma_f32_16x16x32_bf16 v[52:55], v[128:131], v[84:87], v[52:55]
	v_mfma_f32_16x16x32_bf16 v[48:51], v[150:153], v[92:95], v[48:51]
	v_mfma_f32_16x16x32_bf16 v[44:47], v[128:131], v[166:169], v[44:47]
	v_mfma_f32_16x16x32_bf16 v[40:43], v[150:153], v[170:173], v[40:43]
	v_mfma_f32_16x16x32_bf16 v[36:39], v[128:131], v[174:177], v[36:39]
	v_mfma_f32_16x16x32_bf16 v[32:35], v[150:153], v[178:181], v[32:35]
	v_mfma_f32_16x16x32_bf16 v[182:185], v[132:135], v[92:95], v[52:55]
	v_mfma_f32_16x16x32_bf16 v[206:209], v[132:135], v[170:173], v[44:47]
	v_mfma_f32_16x16x32_bf16 v[128:131], v[132:135], v[178:181], v[36:39]
	s_setprio 0
	s_setprio 1
	v_mfma_f32_16x16x32_bf16 v[24:27], v[116:119], v[68:71], v[24:27]
	v_mfma_f32_16x16x32_bf16 v[16:19], v[116:119], v[84:87], v[16:19]
	v_mfma_f32_16x16x32_bf16 v[8:11], v[116:119], v[166:169], v[8:11]
	v_mfma_f32_16x16x32_bf16 v[0:3], v[116:119], v[174:177], v[0:3]
	v_mfma_f32_16x16x32_bf16 v[28:31], v[100:103], v[68:71], v[28:31]
	v_mfma_f32_16x16x32_bf16 v[24:27], v[120:123], v[76:79], v[24:27]
	v_mfma_f32_16x16x32_bf16 v[20:23], v[100:103], v[84:87], v[20:23]
	v_mfma_f32_16x16x32_bf16 v[16:19], v[120:123], v[92:95], v[16:19]
	v_mfma_f32_16x16x32_bf16 v[12:15], v[100:103], v[166:169], v[12:15]
	v_mfma_f32_16x16x32_bf16 v[8:11], v[120:123], v[170:173], v[8:11]
	v_mfma_f32_16x16x32_bf16 v[4:7], v[100:103], v[174:177], v[4:7]
	v_mfma_f32_16x16x32_bf16 v[0:3], v[120:123], v[178:181], v[0:3]
	v_mfma_f32_16x16x32_bf16 v[132:135], v[108:111], v[76:79], v[28:31]
	v_mfma_f32_16x16x32_bf16 v[142:145], v[108:111], v[92:95], v[20:23]
	v_mfma_f32_16x16x32_bf16 v[150:153], v[108:111], v[170:173], v[12:15]
	v_mfma_f32_16x16x32_bf16 v[166:169], v[108:111], v[178:181], v[4:7]
	s_setprio 0
	s_barrier
	s_nop 0
	ds_read_b128 v[4:7], v138 offset:32768
	ds_read_b128 v[12:15], v138 offset:33792
	ds_read_b128 v[170:173], v138 offset:34816
	ds_read_b128 v[174:177], v138 offset:35840
	ds_read_b128 v[20:23], v137 offset:32768
	ds_read_b128 v[28:31], v137 offset:33792
	ds_read_b128 v[36:39], v137 offset:34816
	ds_read_b128 v[44:47], v137 offset:35840
	ds_read_b128 v[52:55], v137 offset:36864
	ds_read_b128 v[178:181], v137 offset:37888
	ds_read_b128 v[224:227], v137 offset:38912
	ds_read_b128 v[228:231], v137 offset:39936
	s_waitcnt vmcnt(2)
	s_barrier
; #define WAIT_V(n) asm volatile("s_waitcnt vmcnt(" #n ")" ::: "memory")
; #define WAIT_L(n) asm volatile("s_waitcnt lgkmcnt(" #n ")" ::: "memory")
; #define BAR __builtin_amdgcn_s_barrier()
; #define LDA(dst, b, h) _Pragma("unroll") for (int m = 0; m < 4; ++m) _Pragma("unroll") for (int k = 0; k < 2; ++k) \
;     dst[m][k] = *reinterpret_cast<const bf16x8*>((char*)shm + abase + (((b) * 2 + (h)) * 16384 + (m * 2 + k) * 1024))
; #define LDB(dst, b, h) _Pragma("unroll") for (int n = 0; n < 2; ++n) _Pragma("unroll") for (int k = 0; k < 2; ++k) \
;     dst[n][k] = *reinterpret_cast<const bf16x8*>((char*)shm + bbase + (((b) * 2 + (h)) * 16384 + (n * 2 + k) * 1024))
; template <bool SWAP>
; __device__ __forceinline__ void gemm_main(const u16* __restrict__ A, const u16* __restrict__ Bt, int brow, int bcol,
;                                           u16* shm, f32x4 (&acc)[2][2][4][2]) {
;     ...
;   { LDB(B0, 1, 0); LDA(At, 1, 0); WAIT_V(2); BAR; WAIT_L(0); MMA(0, 0, At, B0); BAR;
;     LDB(B1, 1, 1); WAIT_V(0); BAR; WAIT_L(0); MMA(0, 1, At, B1); BAR;
;     LDA(At, 1, 1); BAR; WAIT_L(0); MMA(1, 0, At, B0); MMA(1, 1, At, B1); BAR; }
;   if (wr == 0) BAR;
	s_waitcnt lgkmcnt(0)
	s_setprio 1
	s_waitcnt lgkmcnt(0)
	v_mfma_f32_16x16x32_bf16 v[68:71], v[4:7], v[20:23], v[124:127]
	v_mfma_f32_16x16x32_bf16 v[120:123], v[12:15], v[28:31], v[68:71]
	v_mfma_f32_16x16x32_bf16 v[68:71], v[170:173], v[20:23], v[146:149]
	v_mfma_f32_16x16x32_bf16 v[116:119], v[174:177], v[28:31], v[68:71]
	v_mfma_f32_16x16x32_bf16 v[68:71], v[4:7], v[36:39], v[186:189]
	v_mfma_f32_16x16x32_bf16 v[108:111], v[12:15], v[44:47], v[68:71]
	v_mfma_f32_16x16x32_bf16 v[68:71], v[170:173], v[36:39], v[112:115]
	v_mfma_f32_16x16x32_bf16 v[100:103], v[174:177], v[44:47], v[68:71]
	v_mfma_f32_16x16x32_bf16 v[68:71], v[4:7], v[52:55], v[194:197]
	v_mfma_f32_16x16x32_bf16 v[92:95], v[12:15], v[178:181], v[68:71]
	v_mfma_f32_16x16x32_bf16 v[68:71], v[170:173], v[52:55], v[104:107]
	v_mfma_f32_16x16x32_bf16 v[84:87], v[174:177], v[178:181], v[68:71]
	v_mfma_f32_16x16x32_bf16 v[68:71], v[4:7], v[224:227], v[198:201]
	v_mfma_f32_16x16x32_bf16 v[76:79], v[12:15], v[228:231], v[68:71]
	v_mfma_f32_16x16x32_bf16 v[68:71], v[170:173], v[224:227], v[96:99]
	v_mfma_f32_16x16x32_bf16 v[68:71], v[174:177], v[228:231], v[68:71]
	s_setprio 0
	s_barrier
	ds_read_b128 v[146:149], v138 offset:49152
	ds_read_b128 v[186:189], v138 offset:50176
	ds_read_b128 v[194:197], v138 offset:51200
	ds_read_b128 v[198:201], v138 offset:52224
	s_waitcnt vmcnt(0)
	s_barrier
	s_waitcnt lgkmcnt(0)
	s_setprio 1
	s_waitcnt lgkmcnt(0)
	v_mfma_f32_16x16x32_bf16 v[96:99], v[146:149], v[20:23], v[202:205]
	v_mfma_f32_16x16x32_bf16 v[20:23], v[194:197], v[20:23], v[88:91]
	v_mfma_f32_16x16x32_bf16 v[112:115], v[198:201], v[28:31], v[20:23]
	v_mfma_f32_16x16x32_bf16 v[20:23], v[146:149], v[36:39], v[154:157]
	v_mfma_f32_16x16x32_bf16 v[104:107], v[186:189], v[44:47], v[20:23]
	v_mfma_f32_16x16x32_bf16 v[20:23], v[194:197], v[36:39], v[80:83]
	v_mfma_f32_16x16x32_bf16 v[124:127], v[186:189], v[28:31], v[96:99]
	v_mfma_f32_16x16x32_bf16 v[96:99], v[198:201], v[44:47], v[20:23]
	v_mfma_f32_16x16x32_bf16 v[20:23], v[146:149], v[52:55], v[158:161]
	v_mfma_f32_16x16x32_bf16 v[88:91], v[186:189], v[178:181], v[20:23]
	v_mfma_f32_16x16x32_bf16 v[20:23], v[194:197], v[52:55], v[72:75]
	v_mfma_f32_16x16x32_bf16 v[80:83], v[198:201], v[178:181], v[20:23]
	v_mfma_f32_16x16x32_bf16 v[20:23], v[146:149], v[224:227], v[162:165]
	v_mfma_f32_16x16x32_bf16 v[72:75], v[186:189], v[228:231], v[20:23]
	v_mfma_f32_16x16x32_bf16 v[20:23], v[194:197], v[224:227], v[64:67]
	v_mfma_f32_16x16x32_bf16 v[64:67], v[198:201], v[228:231], v[20:23]
	s_setprio 0
	s_barrier
	ds_read_b128 v[154:157], v137 offset:49152
	ds_read_b128 v[158:161], v137 offset:50176
	ds_read_b128 v[162:165], v137 offset:51200
	ds_read_b128 v[178:181], v137 offset:52224
	ds_read_b128 v[202:205], v137 offset:53248
	ds_read_b128 v[224:227], v137 offset:54272
	ds_read_b128 v[228:231], v137 offset:55296
	ds_read_b128 v[232:235], v137 offset:56320
	s_barrier
	s_waitcnt lgkmcnt(0)
	s_setprio 1
	s_waitcnt lgkmcnt(0)
	v_mfma_f32_16x16x32_bf16 v[20:23], v[4:7], v[154:157], v[60:63]
	v_mfma_f32_16x16x32_bf16 v[60:63], v[12:15], v[158:161], v[20:23]
	v_mfma_f32_16x16x32_bf16 v[20:23], v[170:173], v[154:157], v[56:59]
	v_mfma_f32_16x16x32_bf16 v[52:55], v[174:177], v[158:161], v[20:23]
	v_mfma_f32_16x16x32_bf16 v[20:23], v[4:7], v[162:165], v[182:185]
	v_mfma_f32_16x16x32_bf16 v[44:47], v[12:15], v[178:181], v[20:23]
	v_mfma_f32_16x16x32_bf16 v[20:23], v[170:173], v[162:165], v[48:51]
	v_mfma_f32_16x16x32_bf16 v[36:39], v[174:177], v[178:181], v[20:23]
	v_mfma_f32_16x16x32_bf16 v[20:23], v[4:7], v[202:205], v[206:209]
	v_mfma_f32_16x16x32_bf16 v[4:7], v[4:7], v[228:231], v[128:131]
	v_mfma_f32_16x16x32_bf16 v[28:31], v[12:15], v[224:227], v[20:23]
	v_mfma_f32_16x16x32_bf16 v[20:23], v[170:173], v[202:205], v[40:43]
	v_mfma_f32_16x16x32_bf16 v[12:15], v[12:15], v[232:235], v[4:7]
	v_mfma_f32_16x16x32_bf16 v[4:7], v[170:173], v[228:231], v[32:35]
	v_mfma_f32_16x16x32_bf16 v[20:23], v[174:177], v[224:227], v[20:23]
	v_mfma_f32_16x16x32_bf16 v[4:7], v[174:177], v[232:235], v[4:7]
	s_setprio 0
	s_setprio 1
	v_mfma_f32_16x16x32_bf16 v[32:35], v[146:149], v[154:157], v[132:135]
	v_mfma_f32_16x16x32_bf16 v[24:27], v[194:197], v[154:157], v[24:27]
	v_mfma_f32_16x16x32_bf16 v[16:19], v[194:197], v[162:165], v[16:19]
	v_mfma_f32_16x16x32_bf16 v[56:59], v[186:189], v[158:161], v[32:35]
	v_mfma_f32_16x16x32_bf16 v[48:51], v[198:201], v[158:161], v[24:27]
	v_mfma_f32_16x16x32_bf16 v[24:27], v[146:149], v[162:165], v[142:145]
	v_mfma_f32_16x16x32_bf16 v[32:35], v[198:201], v[178:181], v[16:19]
	v_mfma_f32_16x16x32_bf16 v[16:19], v[146:149], v[202:205], v[150:153]
	v_mfma_f32_16x16x32_bf16 v[8:11], v[194:197], v[202:205], v[8:11]
	v_mfma_f32_16x16x32_bf16 v[40:43], v[186:189], v[178:181], v[24:27]
	v_mfma_f32_16x16x32_bf16 v[24:27], v[186:189], v[224:227], v[16:19]
	v_mfma_f32_16x16x32_bf16 v[16:19], v[198:201], v[224:227], v[8:11]
	v_mfma_f32_16x16x32_bf16 v[8:11], v[146:149], v[228:231], v[166:169]
	v_mfma_f32_16x16x32_bf16 v[0:3], v[194:197], v[228:231], v[0:3]
	v_mfma_f32_16x16x32_bf16 v[8:11], v[186:189], v[232:235], v[8:11]
	v_mfma_f32_16x16x32_bf16 v[0:3], v[198:201], v[232:235], v[0:3]
	s_setprio 0
	s_movk_i32 s1, 0x100
	v_cmp_gt_u32_e32 vcc, s1, v136
	s_barrier
	s_and_saveexec_b64 s[8:9], vcc
	s_cbranch_execz .LBB0_439
	s_barrier

; #define WAIT_V(n) asm volatile("s_waitcnt vmcnt(" #n ")" ::: "memory")
; #define BAR __builtin_amdgcn_s_barrier()
; template <bool SWAP>
; __device__ __forceinline__ void gemm_main(const u16* __restrict__ A, const u16* __restrict__ Bt, int brow, int bcol,
;                                           u16* shm, f32x4 (&acc)[2][2][4][2]) {
;     ...
;   int tx = threadIdx.x; asm volatile("" : "+v"(tx));
;   const int wid = tx >> 6, lane = tx & 63, wr = wid >> 2, wc = wid & 3, fr = lane & 15, fq = lane >> 4;
; #pragma unroll
;   for (int a = 0; a < 2; ++a)
; #pragma unroll
;     for (int b = 0; b < 2; ++b)
; #pragma unroll
;       for (int m = 0; m < 4; ++m)
; #pragma unroll
;         for (int n = 0; n < 2; ++n) acc[a][b][m][n] = f32x4{0.f, 0.f, 0.f, 0.f};
;   bf16x8 At[4][2], B0[2][2], B1[2][2];
;   constexpr int nt = GK / BK;
;   GEMM_VOFF
;   const int lpart = (fr * 64 + fq * 16) ^ ((fr >> 3) << 5);
;   const int abase = wr * 8192 + lpart; int bbase = 65536 + wc * 4096 + lpart;
;   asm volatile("" : "+v"(bbase));
;   if (wr == 1) BAR;
;   WAIT_V(0); BAR;
;   BAR;
.LBB0_563:
	s_or_b64 exec, exec, s[0:1]
	v_bfe_i32 v4, v136, 27, 1
	v_lshlrev_b32_e32 v141, 4, v136
	v_lshrrev_b32_e32 v4, 22, v4
	v_add_u32_e32 v4, v141, v4
	v_and_b32_e32 v4, 0xfffffc00, v4
	v_sub_u32_e32 v4, v141, v4
	v_lshrrev_b32_e32 v5, 4, v4
	v_bitop3_b32 v4, v5, v4, 32 bitop3:0x6c
	v_ashrrev_i32_e32 v5, 31, v4
	v_lshrrev_b32_e32 v5, 26, v5
	v_add_u32_e32 v5, v4, v5
	v_ashrrev_i32_e32 v140, 6, v5
	v_and_b32_e32 v5, 0xc0, v5
	v_sub_u32_e32 v4, v4, v5
	v_ashrrev_i16_sdwa v4, v215, sext(v4) dst_sel:DWORD dst_unused:UNUSED_PAD src0_sel:DWORD src1_sel:BYTE_0
	v_bfe_i32 v142, v4, 0, 16
	v_add_u32_e32 v4, 0x2000, v141
	v_ashrrev_i32_e32 v5, 31, v4
	v_lshrrev_b32_e32 v5, 22, v5
	v_add_u32_e32 v5, v4, v5
	v_ashrrev_i32_e32 v143, 10, v5
	v_mul_i32_i24_e32 v5, 0x400, v143
	v_sub_u32_e32 v4, v4, v5
	v_lshrrev_b32_e32 v5, 4, v4
	v_bitop3_b32 v4, v5, v4, 32 bitop3:0x6c
	v_ashrrev_i32_e32 v5, 31, v4
	v_lshrrev_b32_e32 v5, 26, v5
	v_ashrrev_i32_e32 v3, 31, v136
	v_add_u32_e32 v5, v4, v5
	v_lshrrev_b32_e32 v3, 26, v3
	v_ashrrev_i32_e32 v144, 6, v5
	v_and_b32_e32 v5, 0xc0, v5
	v_add_u32_e32 v3, v136, v3
	v_sub_u32_e32 v4, v4, v5
	v_ashrrev_i32_e32 v139, 6, v3
	v_ashrrev_i16_sdwa v4, v215, sext(v4) dst_sel:DWORD dst_unused:UNUSED_PAD src0_sel:DWORD src1_sel:BYTE_0
	v_bfe_i32 v145, v4, 0, 16
	v_lshlrev_b32_e32 v4, 13, v0
	v_lshlrev_b32_e32 v0, 15, v139
	v_and_b32_e32 v0, 0xffff0000, v0
	v_readlane_b32 s2, v253, 59
	v_lshl_add_u32 v0, v140, 12, v0
	s_lshl_b32 s0, s7, 12
	s_ashr_i32 s2, s54, 3
	v_and_or_b32 v0, v3, 64, v0
	s_and_b32 s4, s0, 0x700000
	s_and_b32 s0, s6, 31
	v_lshl_add_u32 v192, v142, 1, v0
	v_lshlrev_b32_e32 v0, 15, v143
	s_lshl_b32 s1, s2, 8
	s_lshl_b32 s0, s0, 8
	v_and_b32_e32 v0, 0xffff0000, v0
	s_and_b32 s1, s1, 0xffffe000
	v_readlane_b32 s3, v253, 60
	v_add_u32_e32 v5, 0, v2
	v_lshl_add_u32 v0, v144, 12, v0
	v_lshlrev_b32_e32 v2, 6, v143
	s_or_b32 s0, s1, s0
	s_mov_b32 s5, s3
	s_waitcnt vmcnt(0)
	v_and_or_b32 v0, v2, 64, v0
	s_ashr_i32 s1, s0, 31
	v_lshl_add_u64 v[128:129], s[4:5], 0, v[192:193]
	v_lshl_add_u32 v2, v145, 1, v0
	v_mov_b32_e32 v3, v193
	v_writelane_b32 v253, s4, 59
	s_lshl_b64 s[10:11], s[0:1], 12
	v_mov_b32_e32 v0, 0
	v_writelane_b32 v253, s5, 60
	v_lshl_add_u64 v[130:131], s[4:5], 0, v[2:3]
	v_lshl_add_u64 v[132:133], s[10:11], 0, v[192:193]
	v_lshl_add_u64 v[134:135], s[10:11], 0, v[2:3]
	s_mov_b32 s3, -2
	v_add_u32_e32 v138, 0, v1
	v_add_u32_e32 v137, v5, v4
	s_mov_b64 s[0:1], s[50:51]
	v_mov_b32_e32 v1, v0
	v_mov_b32_e32 v2, v0
	v_mov_b32_e32 v3, v0
	v_mov_b32_e32 v4, v0
	v_mov_b32_e32 v5, v0
	v_mov_b32_e32 v6, v0
	v_mov_b32_e32 v7, v0
	v_mov_b32_e32 v8, v0
	v_mov_b32_e32 v9, v0
	v_mov_b32_e32 v10, v0
	v_mov_b32_e32 v11, v0
	v_mov_b32_e32 v12, v0
	v_mov_b32_e32 v13, v0
	v_mov_b32_e32 v14, v0
	v_mov_b32_e32 v15, v0
	v_mov_b32_e32 v16, v0
	v_mov_b32_e32 v17, v0
	v_mov_b32_e32 v18, v0
	v_mov_b32_e32 v19, v0
	v_mov_b32_e32 v20, v0
	v_mov_b32_e32 v21, v0
	v_mov_b32_e32 v22, v0
	v_mov_b32_e32 v23, v0
	v_mov_b32_e32 v24, v0
	v_mov_b32_e32 v25, v0
	v_mov_b32_e32 v26, v0
	v_mov_b32_e32 v27, v0
	v_mov_b32_e32 v28, v0
	v_mov_b32_e32 v29, v0
	v_mov_b32_e32 v30, v0
	v_mov_b32_e32 v31, v0
	v_mov_b32_e32 v32, v0
	v_mov_b32_e32 v33, v0
	v_mov_b32_e32 v34, v0
	v_mov_b32_e32 v35, v0
	v_mov_b32_e32 v36, v0
	v_mov_b32_e32 v37, v0
	v_mov_b32_e32 v38, v0
	v_mov_b32_e32 v39, v0
	v_mov_b32_e32 v40, v0
	v_mov_b32_e32 v41, v0
	v_mov_b32_e32 v42, v0
	v_mov_b32_e32 v43, v0
	v_mov_b32_e32 v44, v0
	v_mov_b32_e32 v45, v0
	v_mov_b32_e32 v46, v0
	v_mov_b32_e32 v47, v0
	v_mov_b32_e32 v48, v0
	v_mov_b32_e32 v49, v0
	v_mov_b32_e32 v50, v0
	v_mov_b32_e32 v51, v0
	v_mov_b32_e32 v52, v0
	v_mov_b32_e32 v53, v0
	v_mov_b32_e32 v54, v0
	v_mov_b32_e32 v55, v0
	v_mov_b32_e32 v56, v0
	v_mov_b32_e32 v57, v0
	v_mov_b32_e32 v58, v0
	v_mov_b32_e32 v59, v0
	v_mov_b32_e32 v60, v0
	v_mov_b32_e32 v61, v0
	v_mov_b32_e32 v62, v0
	v_mov_b32_e32 v63, v0
	v_mov_b32_e32 v64, v0
	v_mov_b32_e32 v65, v0
	v_mov_b32_e32 v66, v0
	v_mov_b32_e32 v67, v0
	v_mov_b32_e32 v68, v0
	v_mov_b32_e32 v69, v0
	v_mov_b32_e32 v70, v0
	v_mov_b32_e32 v71, v0
	v_mov_b32_e32 v72, v0
	v_mov_b32_e32 v73, v0
	v_mov_b32_e32 v74, v0
	v_mov_b32_e32 v75, v0
	v_mov_b32_e32 v76, v0
	v_mov_b32_e32 v77, v0
	v_mov_b32_e32 v78, v0
	v_mov_b32_e32 v79, v0
	v_mov_b32_e32 v80, v0
	v_mov_b32_e32 v81, v0
	v_mov_b32_e32 v82, v0
	v_mov_b32_e32 v83, v0
	v_mov_b32_e32 v84, v0
	v_mov_b32_e32 v85, v0
	v_mov_b32_e32 v86, v0
	v_mov_b32_e32 v87, v0
	v_mov_b32_e32 v88, v0
	v_mov_b32_e32 v89, v0
	v_mov_b32_e32 v90, v0
	v_mov_b32_e32 v91, v0
	v_mov_b32_e32 v92, v0
	v_mov_b32_e32 v93, v0
	v_mov_b32_e32 v94, v0
	v_mov_b32_e32 v95, v0
	v_mov_b32_e32 v96, v0
	v_mov_b32_e32 v97, v0
	v_mov_b32_e32 v98, v0
	v_mov_b32_e32 v99, v0
	v_mov_b32_e32 v100, v0
	v_mov_b32_e32 v101, v0
	v_mov_b32_e32 v102, v0
	v_mov_b32_e32 v103, v0
	v_mov_b32_e32 v104, v0
	v_mov_b32_e32 v105, v0
	v_mov_b32_e32 v106, v0
	v_mov_b32_e32 v107, v0
	v_mov_b32_e32 v108, v0
	v_mov_b32_e32 v109, v0
	v_mov_b32_e32 v110, v0
	v_mov_b32_e32 v111, v0
	v_mov_b32_e32 v112, v0
	v_mov_b32_e32 v113, v0
	v_mov_b32_e32 v114, v0
	v_mov_b32_e32 v115, v0
	v_mov_b32_e32 v116, v0
	v_mov_b32_e32 v117, v0
	v_mov_b32_e32 v118, v0
	v_mov_b32_e32 v119, v0
	v_mov_b32_e32 v120, v0
	v_mov_b32_e32 v121, v0
	v_mov_b32_e32 v122, v0
	v_mov_b32_e32 v123, v0
	v_mov_b32_e32 v124, v0
	v_mov_b32_e32 v125, v0
	v_mov_b32_e32 v126, v0
	v_mov_b32_e32 v127, v0
	s_mov_b64 s[8:9], 0x17580080
	s_mov_b64 s[12:13], 0x8100100
	s_mov_b64 s[14:15], 0x17500100
	s_mov_b64 s[16:17], 0x8180100
	s_mov_b64 s[18:19], 0x17580100
	s_mov_b64 s[24:25], 0x8100180
	s_mov_b64 vcc, 0x17500180
	s_mov_b64 s[42:43], 0x8180180
	v_readfirstlane_b32 s4, v141
	s_barrier
	s_barrier
; #define WAIT_L(n) asm volatile("s_waitcnt lgkmcnt(" #n ")" ::: "memory")
; #define BAR __builtin_amdgcn_s_barrier()
; #define SCHED __builtin_amdgcn_sched_barrier(0)
; #define STAGE(P, BASE, br, kt) do { const char* _g = (const char*)((BASE) + (size_t)(br) * GK + (kt) * BK); \
;     __builtin_amdgcn_global_load_lds((const unsigned*)(_g + voff0), (unsigned*)((char*)(P) + tx * 16), 16, 0, 0); \
;     __builtin_amdgcn_global_load_lds((const unsigned*)(_g + voff1), (unsigned*)((char*)(P) + tx * 16 + 8192), 16, 0, 0); } while (0)
; #define LDA(dst, b, h) _Pragma("unroll") for (int m = 0; m < 4; ++m) _Pragma("unroll") for (int k = 0; k < 2; ++k) \
;     dst[m][k] = *reinterpret_cast<const bf16x8*>((char*)shm + abase + (((b) * 2 + (h)) * 16384 + (m * 2 + k) * 1024))
; #define LDB(dst, b, h) _Pragma("unroll") for (int n = 0; n < 2; ++n) _Pragma("unroll") for (int k = 0; k < 2; ++k) \
;     dst[n][k] = *reinterpret_cast<const bf16x8*>((char*)shm + bbase + (((b) * 2 + (h)) * 16384 + (n * 2 + k) * 1024))
; template <bool SWAP>
; __device__ __forceinline__ void gemm_main(const u16* __restrict__ A, const u16* __restrict__ Bt, int brow, int bcol,
;                                           u16* shm, f32x4 (&acc)[2][2][4][2]) {
;     ...
;   for (int t = 0; t < nt - 2; t += 2) {
;     LDB(B0, 0, 0); SCHED; LDA(At, 0, 0); STAGE(SA(1, 1), A, brow + HALF, t + 1);
;     WAIT_L(8); BAR; WAIT_L(0); MMA(0, 0, At, B0); BAR; SCHED;
;     LDB(B1, 0, 1); STAGE(SB(0, 0), Bt, bcol, t + 2);
;     BAR; WAIT_L(0); MMA(0, 1, At, B1); BAR;
;     LDA(At, 0, 1); STAGE(SA(0, 0), A, brow, t + 2);
;     BAR; WAIT_L(0); MMA(1, 0, At, B0); BAR; SCHED;
.LBB0_564:
	ds_read_b128 v[148:151], v138
	ds_read_b128 v[152:155], v138 offset:1024
	ds_read_b128 v[156:159], v138 offset:2048
	ds_read_b128 v[160:163], v138 offset:3072
	ds_read_b128 v[164:167], v137
	ds_read_b128 v[168:171], v137 offset:1024
	ds_read_b128 v[172:175], v137 offset:2048
	ds_read_b128 v[176:179], v137 offset:3072
	ds_read_b128 v[180:183], v137 offset:4096
	ds_read_b128 v[184:187], v137 offset:5120
	ds_read_b128 v[188:191], v137 offset:6144
	ds_read_b128 v[194:197], v137 offset:7168
	v_add_u32_e32 v192, 0, v141
	v_add_u32_e32 v146, 0xc000, v192
	v_lshl_add_u64 v[230:231], s[0:1], 0, v[132:133]
	v_add_u32_e32 v147, 0xe000, v192
	v_lshl_add_u64 v[198:199], v[230:231], 0, s[8:9]
	s_add_u32 m0, s4, 0xc000
	v_lshl_add_u64 v[232:233], s[0:1], 0, v[134:135]
	global_load_lds_dwordx4 v[198:199], off
	v_lshl_add_u64 v[198:199], v[232:233], 0, s[8:9]
	s_add_u32 m0, s4, 0xe000
	s_nop 0
	global_load_lds_dwordx4 v[198:199], off
	s_waitcnt lgkmcnt(8)
	s_setprio 1
	s_barrier
	s_waitcnt lgkmcnt(0)
	v_mfma_f32_16x16x32_bf16 v[124:127], v[148:151], v[164:167], v[124:127]
	v_mfma_f32_16x16x32_bf16 v[120:123], v[156:159], v[164:167], v[120:123]
	v_mfma_f32_16x16x32_bf16 v[116:119], v[148:151], v[172:175], v[116:119]
	v_mfma_f32_16x16x32_bf16 v[112:115], v[156:159], v[172:175], v[112:115]
	v_mfma_f32_16x16x32_bf16 v[108:111], v[148:151], v[180:183], v[108:111]
	v_mfma_f32_16x16x32_bf16 v[104:107], v[156:159], v[180:183], v[104:107]
	v_mfma_f32_16x16x32_bf16 v[100:103], v[148:151], v[188:191], v[100:103]
	v_mfma_f32_16x16x32_bf16 v[96:99], v[156:159], v[188:191], v[96:99]
	v_mfma_f32_16x16x32_bf16 v[124:127], v[152:155], v[168:171], v[124:127]
	v_mfma_f32_16x16x32_bf16 v[120:123], v[160:163], v[168:171], v[120:123]
	v_mfma_f32_16x16x32_bf16 v[116:119], v[152:155], v[176:179], v[116:119]
	v_mfma_f32_16x16x32_bf16 v[112:115], v[160:163], v[176:179], v[112:115]
	v_mfma_f32_16x16x32_bf16 v[108:111], v[152:155], v[184:187], v[108:111]
	v_mfma_f32_16x16x32_bf16 v[104:107], v[160:163], v[184:187], v[104:107]
	v_mfma_f32_16x16x32_bf16 v[100:103], v[152:155], v[194:197], v[100:103]
	v_mfma_f32_16x16x32_bf16 v[96:99], v[160:163], v[194:197], v[96:99]
	s_barrier
	s_setprio 0
	ds_read_b128 v[198:201], v138 offset:16384
	ds_read_b128 v[202:205], v138 offset:17408
	ds_read_b128 v[206:209], v138 offset:18432
	ds_read_b128 v[226:229], v138 offset:19456
	v_lshl_add_u64 v[234:235], s[0:1], 0, v[128:129]
	v_lshl_add_u64 v[236:237], v[234:235], 0, s[12:13]
	s_add_u32 m0, s4, s28
	s_nop 0
	global_load_lds_dwordx4 v[236:237], off
	v_lshl_add_u64 v[236:237], s[0:1], 0, v[130:131]
	v_lshl_add_u64 v[238:239], v[236:237], 0, s[12:13]
	s_add_u32 m0, s4, s28
	s_add_u32 m0, m0, 0x2000
	s_nop 0
	global_load_lds_dwordx4 v[238:239], off
	s_setprio 1
	s_barrier
	s_waitcnt lgkmcnt(0)
	v_mfma_f32_16x16x32_bf16 v[92:95], v[198:201], v[164:167], v[92:95]
	v_mfma_f32_16x16x32_bf16 v[88:91], v[206:209], v[164:167], v[88:91]
	v_mfma_f32_16x16x32_bf16 v[84:87], v[198:201], v[172:175], v[84:87]
	v_mfma_f32_16x16x32_bf16 v[80:83], v[206:209], v[172:175], v[80:83]
	v_mfma_f32_16x16x32_bf16 v[76:79], v[198:201], v[180:183], v[76:79]
	v_mfma_f32_16x16x32_bf16 v[72:75], v[206:209], v[180:183], v[72:75]
	v_mfma_f32_16x16x32_bf16 v[68:71], v[198:201], v[188:191], v[68:71]
	v_mfma_f32_16x16x32_bf16 v[64:67], v[206:209], v[188:191], v[64:67]
	v_mfma_f32_16x16x32_bf16 v[92:95], v[202:205], v[168:171], v[92:95]
	v_mfma_f32_16x16x32_bf16 v[88:91], v[226:229], v[168:171], v[88:91]
	v_mfma_f32_16x16x32_bf16 v[84:87], v[202:205], v[176:179], v[84:87]
	v_mfma_f32_16x16x32_bf16 v[80:83], v[226:229], v[176:179], v[80:83]
	v_mfma_f32_16x16x32_bf16 v[76:79], v[202:205], v[184:187], v[76:79]
	v_mfma_f32_16x16x32_bf16 v[72:75], v[226:229], v[184:187], v[72:75]
	v_mfma_f32_16x16x32_bf16 v[68:71], v[202:205], v[194:197], v[68:71]
	v_mfma_f32_16x16x32_bf16 v[64:67], v[226:229], v[194:197], v[64:67]
	s_barrier
	s_setprio 0
	ds_read_b128 v[164:167], v137 offset:16384
	ds_read_b128 v[168:171], v137 offset:17408
	ds_read_b128 v[172:175], v137 offset:18432
	ds_read_b128 v[176:179], v137 offset:19456
	ds_read_b128 v[180:183], v137 offset:20480
	ds_read_b128 v[184:187], v137 offset:21504
	ds_read_b128 v[188:191], v137 offset:22528
	ds_read_b128 v[194:197], v137 offset:23552
	v_lshl_add_u64 v[238:239], v[230:231], 0, s[14:15]
	s_add_u32 m0, s4, 0x0
	s_nop 0
	global_load_lds_dwordx4 v[238:239], off
	v_lshl_add_u64 v[238:239], v[232:233], 0, s[14:15]
	s_add_u32 m0, s4, 0x2000
	s_nop 0
	global_load_lds_dwordx4 v[238:239], off
	s_setprio 1
	s_barrier
	s_waitcnt lgkmcnt(0)
	v_mfma_f32_16x16x32_bf16 v[60:63], v[148:151], v[164:167], v[60:63]
	v_mfma_f32_16x16x32_bf16 v[56:59], v[156:159], v[164:167], v[56:59]
	v_mfma_f32_16x16x32_bf16 v[52:55], v[148:151], v[172:175], v[52:55]
	v_mfma_f32_16x16x32_bf16 v[48:51], v[156:159], v[172:175], v[48:51]
	v_mfma_f32_16x16x32_bf16 v[44:47], v[148:151], v[180:183], v[44:47]
	v_mfma_f32_16x16x32_bf16 v[40:43], v[156:159], v[180:183], v[40:43]
	v_mfma_f32_16x16x32_bf16 v[36:39], v[148:151], v[188:191], v[36:39]
	v_mfma_f32_16x16x32_bf16 v[32:35], v[156:159], v[188:191], v[32:35]
	v_mfma_f32_16x16x32_bf16 v[60:63], v[152:155], v[168:171], v[60:63]
	v_mfma_f32_16x16x32_bf16 v[56:59], v[160:163], v[168:171], v[56:59]
	v_mfma_f32_16x16x32_bf16 v[52:55], v[152:155], v[176:179], v[52:55]
	v_mfma_f32_16x16x32_bf16 v[48:51], v[160:163], v[176:179], v[48:51]
	v_mfma_f32_16x16x32_bf16 v[44:47], v[152:155], v[184:187], v[44:47]
	v_mfma_f32_16x16x32_bf16 v[40:43], v[160:163], v[184:187], v[40:43]
	v_mfma_f32_16x16x32_bf16 v[36:39], v[152:155], v[194:197], v[36:39]
	v_mfma_f32_16x16x32_bf16 v[32:35], v[160:163], v[194:197], v[32:35]
	s_barrier
; #define WAIT_V(n) asm volatile("s_waitcnt vmcnt(" #n ")" ::: "memory")
; #define WAIT_L(n) asm volatile("s_waitcnt lgkmcnt(" #n ")" ::: "memory")
; #define BAR __builtin_amdgcn_s_barrier()
; #define SCHED __builtin_amdgcn_sched_barrier(0)
; #define STAGE(P, BASE, br, kt) do { const char* _g = (const char*)((BASE) + (size_t)(br) * GK + (kt) * BK); \
;     __builtin_amdgcn_global_load_lds((const unsigned*)(_g + voff0), (unsigned*)((char*)(P) + tx * 16), 16, 0, 0); \
;     __builtin_amdgcn_global_load_lds((const unsigned*)(_g + voff1), (unsigned*)((char*)(P) + tx * 16 + 8192), 16, 0, 0); } while (0)
; #define LDA(dst, b, h) _Pragma("unroll") for (int m = 0; m < 4; ++m) _Pragma("unroll") for (int k = 0; k < 2; ++k) \
;     dst[m][k] = *reinterpret_cast<const bf16x8*>((char*)shm + abase + (((b) * 2 + (h)) * 16384 + (m * 2 + k) * 1024))
; #define LDB(dst, b, h) _Pragma("unroll") for (int n = 0; n < 2; ++n) _Pragma("unroll") for (int k = 0; k < 2; ++k) \
;     dst[n][k] = *reinterpret_cast<const bf16x8*>((char*)shm + bbase + (((b) * 2 + (h)) * 16384 + (n * 2 + k) * 1024))
; template <bool SWAP>
; __device__ __forceinline__ void gemm_main(const u16* __restrict__ A, const u16* __restrict__ Bt, int brow, int bcol,
;                                           u16* shm, f32x4 (&acc)[2][2][4][2]) {
;     ...
;     STAGE(SB(0, 1), Bt, bcol + HALF, t + 2);
;     WAIT_V(6); BAR; MMA(1, 1, At, B1); BAR;
;     LDB(B0, 1, 0); SCHED; LDA(At, 1, 0); STAGE(SA(0, 1), A, brow + HALF, t + 2);
;     WAIT_L(8); BAR; WAIT_L(0); MMA(0, 0, At, B0); BAR; SCHED;
;     LDB(B1, 1, 1); STAGE(SB(1, 0), Bt, bcol, t + 3);
;     BAR; WAIT_L(0); MMA(0, 1, At, B1); BAR;
;     LDA(At, 1, 1); STAGE(SA(1, 0), A, brow, t + 3);
;     BAR; WAIT_L(0); MMA(1, 0, At, B0); BAR; SCHED;
	s_setprio 0
	v_lshl_add_u64 v[148:149], v[234:235], 0, s[16:17]
	s_add_u32 m0, s4, s29
	s_nop 0
	global_load_lds_dwordx4 v[148:149], off
	v_lshl_add_u64 v[148:149], v[236:237], 0, s[16:17]
	s_add_u32 m0, s4, s29
	s_add_u32 m0, m0, 0x2000
	s_nop 0
	global_load_lds_dwordx4 v[148:149], off
	s_waitcnt vmcnt(6)
	s_setprio 1
	s_barrier
	v_mfma_f32_16x16x32_bf16 v[28:31], v[198:201], v[164:167], v[28:31]
	v_mfma_f32_16x16x32_bf16 v[24:27], v[206:209], v[164:167], v[24:27]
	v_mfma_f32_16x16x32_bf16 v[20:23], v[198:201], v[172:175], v[20:23]
	v_mfma_f32_16x16x32_bf16 v[16:19], v[206:209], v[172:175], v[16:19]
	v_mfma_f32_16x16x32_bf16 v[12:15], v[198:201], v[180:183], v[12:15]
	v_mfma_f32_16x16x32_bf16 v[8:11], v[206:209], v[180:183], v[8:11]
	v_mfma_f32_16x16x32_bf16 v[4:7], v[198:201], v[188:191], v[4:7]
	v_mfma_f32_16x16x32_bf16 v[0:3], v[206:209], v[188:191], v[0:3]
	v_mfma_f32_16x16x32_bf16 v[28:31], v[202:205], v[168:171], v[28:31]
	v_mfma_f32_16x16x32_bf16 v[24:27], v[226:229], v[168:171], v[24:27]
	v_mfma_f32_16x16x32_bf16 v[20:23], v[202:205], v[176:179], v[20:23]
	v_mfma_f32_16x16x32_bf16 v[16:19], v[226:229], v[176:179], v[16:19]
	v_mfma_f32_16x16x32_bf16 v[12:15], v[202:205], v[184:187], v[12:15]
	v_mfma_f32_16x16x32_bf16 v[8:11], v[226:229], v[184:187], v[8:11]
	v_mfma_f32_16x16x32_bf16 v[4:7], v[202:205], v[194:197], v[4:7]
	v_mfma_f32_16x16x32_bf16 v[0:3], v[226:229], v[194:197], v[0:3]
	s_barrier
	s_setprio 0
	ds_read_b128 v[148:151], v138 offset:32768
	ds_read_b128 v[152:155], v138 offset:33792
	ds_read_b128 v[156:159], v138 offset:34816
	ds_read_b128 v[160:163], v138 offset:35840
	ds_read_b128 v[164:167], v137 offset:32768
	ds_read_b128 v[168:171], v137 offset:33792
	ds_read_b128 v[172:175], v137 offset:34816
	ds_read_b128 v[176:179], v137 offset:35840
	ds_read_b128 v[180:183], v137 offset:36864
	ds_read_b128 v[184:187], v137 offset:37888
	ds_read_b128 v[188:191], v137 offset:38912
	ds_read_b128 v[194:197], v137 offset:39936
	v_lshl_add_u64 v[198:199], v[230:231], 0, s[18:19]
	s_add_u32 m0, s4, 0x4000
	s_nop 0
	global_load_lds_dwordx4 v[198:199], off
	v_lshl_add_u64 v[198:199], v[232:233], 0, s[18:19]
	s_add_u32 m0, s4, 0x6000
	s_nop 0
	global_load_lds_dwordx4 v[198:199], off
	s_waitcnt lgkmcnt(8)
	s_setprio 1
	s_barrier
	s_waitcnt lgkmcnt(0)
	v_mfma_f32_16x16x32_bf16 v[124:127], v[148:151], v[164:167], v[124:127]
	v_mfma_f32_16x16x32_bf16 v[120:123], v[156:159], v[164:167], v[120:123]
	v_mfma_f32_16x16x32_bf16 v[116:119], v[148:151], v[172:175], v[116:119]
	v_mfma_f32_16x16x32_bf16 v[112:115], v[156:159], v[172:175], v[112:115]
	v_mfma_f32_16x16x32_bf16 v[108:111], v[148:151], v[180:183], v[108:111]
	v_mfma_f32_16x16x32_bf16 v[104:107], v[156:159], v[180:183], v[104:107]
	v_mfma_f32_16x16x32_bf16 v[100:103], v[148:151], v[188:191], v[100:103]
	v_mfma_f32_16x16x32_bf16 v[96:99], v[156:159], v[188:191], v[96:99]
	v_mfma_f32_16x16x32_bf16 v[124:127], v[152:155], v[168:171], v[124:127]
	v_mfma_f32_16x16x32_bf16 v[120:123], v[160:163], v[168:171], v[120:123]
	v_mfma_f32_16x16x32_bf16 v[116:119], v[152:155], v[176:179], v[116:119]
	v_mfma_f32_16x16x32_bf16 v[112:115], v[160:163], v[176:179], v[112:115]
	v_mfma_f32_16x16x32_bf16 v[108:111], v[152:155], v[184:187], v[108:111]
	v_mfma_f32_16x16x32_bf16 v[104:107], v[160:163], v[184:187], v[104:107]
	v_mfma_f32_16x16x32_bf16 v[100:103], v[152:155], v[194:197], v[100:103]
	v_mfma_f32_16x16x32_bf16 v[96:99], v[160:163], v[194:197], v[96:99]
	s_barrier
	s_setprio 0
	ds_read_b128 v[198:201], v138 offset:49152
	ds_read_b128 v[202:205], v138 offset:50176
	ds_read_b128 v[206:209], v138 offset:51200
	ds_read_b128 v[226:229], v138 offset:52224
	v_lshl_add_u64 v[238:239], v[234:235], 0, s[24:25]
	s_add_u32 m0, s4, s30
	s_nop 0
	global_load_lds_dwordx4 v[238:239], off
	v_lshl_add_u64 v[238:239], v[236:237], 0, s[24:25]
	s_add_u32 m0, s4, s30
	s_add_u32 m0, m0, 0x2000
	s_nop 0
	global_load_lds_dwordx4 v[238:239], off
	s_setprio 1
	s_barrier
	s_waitcnt lgkmcnt(0)
	v_mfma_f32_16x16x32_bf16 v[92:95], v[198:201], v[164:167], v[92:95]
	v_mfma_f32_16x16x32_bf16 v[88:91], v[206:209], v[164:167], v[88:91]
	v_mfma_f32_16x16x32_bf16 v[84:87], v[198:201], v[172:175], v[84:87]
	v_mfma_f32_16x16x32_bf16 v[80:83], v[206:209], v[172:175], v[80:83]
	v_mfma_f32_16x16x32_bf16 v[76:79], v[198:201], v[180:183], v[76:79]
	v_mfma_f32_16x16x32_bf16 v[72:75], v[206:209], v[180:183], v[72:75]
	v_mfma_f32_16x16x32_bf16 v[68:71], v[198:201], v[188:191], v[68:71]
	v_mfma_f32_16x16x32_bf16 v[64:67], v[206:209], v[188:191], v[64:67]
	v_mfma_f32_16x16x32_bf16 v[92:95], v[202:205], v[168:171], v[92:95]
	v_mfma_f32_16x16x32_bf16 v[88:91], v[226:229], v[168:171], v[88:91]
	v_mfma_f32_16x16x32_bf16 v[84:87], v[202:205], v[176:179], v[84:87]
	v_mfma_f32_16x16x32_bf16 v[80:83], v[226:229], v[176:179], v[80:83]
	v_mfma_f32_16x16x32_bf16 v[76:79], v[202:205], v[184:187], v[76:79]
	v_mfma_f32_16x16x32_bf16 v[72:75], v[226:229], v[184:187], v[72:75]
	v_mfma_f32_16x16x32_bf16 v[68:71], v[202:205], v[194:197], v[68:71]
	v_mfma_f32_16x16x32_bf16 v[64:67], v[226:229], v[194:197], v[64:67]
	s_barrier
	s_setprio 0
	ds_read_b128 v[164:167], v137 offset:49152
	ds_read_b128 v[168:171], v137 offset:50176
	ds_read_b128 v[172:175], v137 offset:51200
	ds_read_b128 v[176:179], v137 offset:52224
	ds_read_b128 v[180:183], v137 offset:53248
	ds_read_b128 v[184:187], v137 offset:54272
	ds_read_b128 v[188:191], v137 offset:55296
	ds_read_b128 v[194:197], v137 offset:56320
	v_add_u32_e32 v225, 0x8000, v192
	v_lshl_add_u64 v[230:231], v[230:231], 0, vcc
	s_add_u32 m0, s4, 0x8000
	s_nop 0
	global_load_lds_dwordx4 v[230:231], off
	v_lshl_add_u64 v[230:231], v[232:233], 0, vcc
	s_add_u32 m0, s4, 0xa000
	s_nop 0
	global_load_lds_dwordx4 v[230:231], off
	s_setprio 1
	s_barrier
; #define WAIT_V(n) asm volatile("s_waitcnt vmcnt(" #n ")" ::: "memory")
; #define WAIT_L(n) asm volatile("s_waitcnt lgkmcnt(" #n ")" ::: "memory")
; #define BAR __builtin_amdgcn_s_barrier()
; #define SCHED __builtin_amdgcn_sched_barrier(0)
; #define STAGE(P, BASE, br, kt) do { const char* _g = (const char*)((BASE) + (size_t)(br) * GK + (kt) * BK); \
;     __builtin_amdgcn_global_load_lds((const unsigned*)(_g + voff0), (unsigned*)((char*)(P) + tx * 16), 16, 0, 0); \
;     __builtin_amdgcn_global_load_lds((const unsigned*)(_g + voff1), (unsigned*)((char*)(P) + tx * 16 + 8192), 16, 0, 0); } while (0)
; #define LDA(dst, b, h) _Pragma("unroll") for (int m = 0; m < 4; ++m) _Pragma("unroll") for (int k = 0; k < 2; ++k) \
;     dst[m][k] = *reinterpret_cast<const bf16x8*>((char*)shm + abase + (((b) * 2 + (h)) * 16384 + (m * 2 + k) * 1024))
; #define LDB(dst, b, h) _Pragma("unroll") for (int n = 0; n < 2; ++n) _Pragma("unroll") for (int k = 0; k < 2; ++k) \
;     dst[n][k] = *reinterpret_cast<const bf16x8*>((char*)shm + bbase + (((b) * 2 + (h)) * 16384 + (n * 2 + k) * 1024))
; template <bool SWAP>
; __device__ __forceinline__ void gemm_main(const u16* __restrict__ A, const u16* __restrict__ Bt, int brow, int bcol,
;                                           u16* shm, f32x4 (&acc)[2][2][4][2]) {
;     ...
;     BAR; WAIT_L(0); MMA(1, 0, At, B0); BAR; SCHED;
;     STAGE(SB(1, 1), Bt, bcol + HALF, t + 3);
;     WAIT_V(6); BAR; MMA(1, 1, At, B1); BAR;
;   }
;   { LDB(B0, 0, 0); LDA(At, 0, 0); STAGE(SA(1, 1), A, brow + HALF, nt - 1);
;     BAR; WAIT_L(0); MMA(0, 0, At, B0); BAR;
	s_waitcnt lgkmcnt(0)
	v_mfma_f32_16x16x32_bf16 v[60:63], v[148:151], v[164:167], v[60:63]
	v_mfma_f32_16x16x32_bf16 v[56:59], v[156:159], v[164:167], v[56:59]
	v_mfma_f32_16x16x32_bf16 v[52:55], v[148:151], v[172:175], v[52:55]
	v_mfma_f32_16x16x32_bf16 v[48:51], v[156:159], v[172:175], v[48:51]
	v_mfma_f32_16x16x32_bf16 v[44:47], v[148:151], v[180:183], v[44:47]
	v_mfma_f32_16x16x32_bf16 v[40:43], v[156:159], v[180:183], v[40:43]
	v_mfma_f32_16x16x32_bf16 v[36:39], v[148:151], v[188:191], v[36:39]
	v_mfma_f32_16x16x32_bf16 v[32:35], v[156:159], v[188:191], v[32:35]
	v_mfma_f32_16x16x32_bf16 v[60:63], v[152:155], v[168:171], v[60:63]
	v_mfma_f32_16x16x32_bf16 v[56:59], v[160:163], v[168:171], v[56:59]
	v_mfma_f32_16x16x32_bf16 v[52:55], v[152:155], v[176:179], v[52:55]
	v_mfma_f32_16x16x32_bf16 v[48:51], v[160:163], v[176:179], v[48:51]
	v_mfma_f32_16x16x32_bf16 v[44:47], v[152:155], v[184:187], v[44:47]
	v_mfma_f32_16x16x32_bf16 v[40:43], v[160:163], v[184:187], v[40:43]
	v_mfma_f32_16x16x32_bf16 v[36:39], v[152:155], v[194:197], v[36:39]
	v_mfma_f32_16x16x32_bf16 v[32:35], v[160:163], v[194:197], v[32:35]
	s_barrier
	s_setprio 0
	v_lshl_add_u64 v[148:149], v[234:235], 0, s[42:43]
	s_add_u32 m0, s4, s31
	s_nop 0
	global_load_lds_dwordx4 v[148:149], off
	v_lshl_add_u64 v[148:149], v[236:237], 0, s[42:43]
	s_add_u32 m0, s4, s31
	s_add_u32 m0, m0, 0x2000
	s_nop 0
	global_load_lds_dwordx4 v[148:149], off
	s_waitcnt vmcnt(6)
	s_setprio 1
	s_barrier
	v_mfma_f32_16x16x32_bf16 v[28:31], v[198:201], v[164:167], v[28:31]
	v_mfma_f32_16x16x32_bf16 v[24:27], v[206:209], v[164:167], v[24:27]
	v_mfma_f32_16x16x32_bf16 v[20:23], v[198:201], v[172:175], v[20:23]
	v_mfma_f32_16x16x32_bf16 v[16:19], v[206:209], v[172:175], v[16:19]
	v_mfma_f32_16x16x32_bf16 v[12:15], v[198:201], v[180:183], v[12:15]
	v_mfma_f32_16x16x32_bf16 v[8:11], v[206:209], v[180:183], v[8:11]
	v_mfma_f32_16x16x32_bf16 v[4:7], v[198:201], v[188:191], v[4:7]
	v_mfma_f32_16x16x32_bf16 v[0:3], v[206:209], v[188:191], v[0:3]
	v_mfma_f32_16x16x32_bf16 v[28:31], v[202:205], v[168:171], v[28:31]
	v_mfma_f32_16x16x32_bf16 v[24:27], v[226:229], v[168:171], v[24:27]
	v_mfma_f32_16x16x32_bf16 v[20:23], v[202:205], v[176:179], v[20:23]
	v_mfma_f32_16x16x32_bf16 v[16:19], v[226:229], v[176:179], v[16:19]
	v_mfma_f32_16x16x32_bf16 v[12:15], v[202:205], v[184:187], v[12:15]
	v_mfma_f32_16x16x32_bf16 v[8:11], v[226:229], v[184:187], v[8:11]
	v_mfma_f32_16x16x32_bf16 v[4:7], v[202:205], v[194:197], v[4:7]
	v_mfma_f32_16x16x32_bf16 v[0:3], v[226:229], v[194:197], v[0:3]
	s_add_i32 s3, s3, 2
	s_add_u32 s0, s0, 0x100
	s_addc_u32 s1, s1, 0
	s_cmp_lt_u32 s3, 28
	s_barrier
	s_setprio 0
	s_cbranch_scc1 .LBB0_564
	s_and_b32 s0, s2, 0xffffe0
	s_and_b32 s1, s54, 31
	s_or_b32 s0, s0, s1
	s_lshl_b32 s8, s0, 8
	v_lshlrev_b32_e32 v128, 3, v139
	v_lshlrev_b32_e32 v129, 5, v139
	v_and_b32_e32 v128, 0xffff0, v128
	v_and_b32_e32 v129, 32, v129
	s_or_b32 s0, s8, 0x80
	v_add_u32_e32 v129, v129, v142
	v_add_lshl_u32 v128, v140, v128, 12
	s_ashr_i32 s1, s0, 31
	v_lshl_add_u32 v192, v129, 1, v128
	v_lshlrev_b32_e32 v128, 3, v143
	v_lshlrev_b32_e32 v129, 5, v143
	s_lshl_b64 s[12:13], s[0:1], 12
	v_readlane_b32 s0, v251, 36
	v_and_b32_e32 v128, 0xffff0, v128
	v_and_b32_e32 v129, 32, v129
	v_readlane_b32 s1, v251, 37
	s_add_u32 s0, s0, s12
	v_add_u32_e32 v129, v129, v145
	v_add_lshl_u32 v128, v144, v128, 12
	s_addc_u32 s1, s1, s13
	v_lshl_add_u32 v144, v129, 1, v128
	v_mov_b32_e32 v145, v193
	v_lshl_add_u64 v[184:185], s[0:1], 0, v[192:193]
	s_mov_b64 s[4:5], 0xf80
	v_readfirstlane_b32 s2, v146
	v_lshl_add_u64 v[184:185], v[184:185], 0, s[4:5]
	s_mov_b32 m0, s2
	v_lshl_add_u64 v[144:145], s[0:1], 0, v[144:145]
	v_readfirstlane_b32 s0, v147
	ds_read_b128 v[128:131], v138
	ds_read_b128 v[132:135], v138 offset:1024
	ds_read_b128 v[140:143], v138 offset:2048
	ds_read_b128 v[148:151], v138 offset:3072
	ds_read_b128 v[152:155], v137
	ds_read_b128 v[156:159], v137 offset:1024
	ds_read_b128 v[160:163], v137 offset:2048
	ds_read_b128 v[164:167], v137 offset:3072
	ds_read_b128 v[168:171], v137 offset:4096
	ds_read_b128 v[172:175], v137 offset:5120
	ds_read_b128 v[176:179], v137 offset:6144
	ds_read_b128 v[180:183], v137 offset:7168
	global_load_lds_dwordx4 v[184:185], off
	v_lshl_add_u64 v[144:145], v[144:145], 0, s[4:5]
	s_mov_b32 m0, s0
	s_nop 0
	global_load_lds_dwordx4 v[144:145], off
	s_barrier
	s_waitcnt lgkmcnt(0)
	s_setprio 1
	s_waitcnt lgkmcnt(0)
	v_mfma_f32_16x16x32_bf16 v[124:127], v[128:131], v[152:155], v[124:127]
	v_mfma_f32_16x16x32_bf16 v[116:119], v[128:131], v[160:163], v[116:119]
	v_mfma_f32_16x16x32_bf16 v[112:115], v[140:143], v[160:163], v[112:115]
	v_mfma_f32_16x16x32_bf16 v[108:111], v[128:131], v[168:171], v[108:111]
	v_mfma_f32_16x16x32_bf16 v[104:107], v[140:143], v[168:171], v[104:107]
	v_mfma_f32_16x16x32_bf16 v[100:103], v[128:131], v[176:179], v[100:103]
	v_mfma_f32_16x16x32_bf16 v[96:99], v[140:143], v[176:179], v[96:99]
	v_mfma_f32_16x16x32_bf16 v[124:127], v[132:135], v[156:159], v[124:127]
	v_mfma_f32_16x16x32_bf16 v[120:123], v[140:143], v[152:155], v[120:123]
	v_mfma_f32_16x16x32_bf16 v[116:119], v[132:135], v[164:167], v[116:119]
	v_mfma_f32_16x16x32_bf16 v[112:115], v[148:151], v[164:167], v[112:115]
	v_mfma_f32_16x16x32_bf16 v[108:111], v[132:135], v[172:175], v[108:111]
	v_mfma_f32_16x16x32_bf16 v[104:107], v[148:151], v[172:175], v[104:107]
	v_mfma_f32_16x16x32_bf16 v[100:103], v[132:135], v[180:183], v[100:103]
	v_mfma_f32_16x16x32_bf16 v[96:99], v[148:151], v[180:183], v[96:99]
	v_mfma_f32_16x16x32_bf16 v[120:123], v[148:151], v[156:159], v[120:123]
	s_setprio 0
	s_barrier
; #define WAIT_V(n) asm volatile("s_waitcnt vmcnt(" #n ")" ::: "memory")
; #define WAIT_L(n) asm volatile("s_waitcnt lgkmcnt(" #n ")" ::: "memory")
; #define BAR __builtin_amdgcn_s_barrier()
; #define LDA(dst, b, h) _Pragma("unroll") for (int m = 0; m < 4; ++m) _Pragma("unroll") for (int k = 0; k < 2; ++k) \
;     dst[m][k] = *reinterpret_cast<const bf16x8*>((char*)shm + abase + (((b) * 2 + (h)) * 16384 + (m * 2 + k) * 1024))
; #define LDB(dst, b, h) _Pragma("unroll") for (int n = 0; n < 2; ++n) _Pragma("unroll") for (int k = 0; k < 2; ++k) \
;     dst[n][k] = *reinterpret_cast<const bf16x8*>((char*)shm + bbase + (((b) * 2 + (h)) * 16384 + (n * 2 + k) * 1024))
; template <bool SWAP>
; __device__ __forceinline__ void gemm_main(const u16* __restrict__ A, const u16* __restrict__ Bt, int brow, int bcol,
;                                           u16* shm, f32x4 (&acc)[2][2][4][2]) {
;     ...
;     BAR; WAIT_L(0); MMA(0, 0, At, B0); BAR;
;     LDB(B1, 0, 1); BAR; WAIT_L(0); MMA(0, 1, At, B1); BAR;
;     LDA(At, 0, 1); WAIT_V(4); BAR; WAIT_L(0); MMA(1, 0, At, B0); MMA(1, 1, At, B1); BAR; }
;   { LDB(B0, 1, 0); LDA(At, 1, 0); WAIT_V(2); BAR; WAIT_L(0); MMA(0, 0, At, B0); BAR;
	ds_read_b128 v[144:147], v138 offset:16384
	ds_read_b128 v[184:187], v138 offset:17408
	ds_read_b128 v[188:191], v138 offset:18432
	ds_read_b128 v[194:197], v138 offset:19456
	s_barrier
	s_waitcnt lgkmcnt(0)
	s_setprio 1
	s_waitcnt lgkmcnt(0)
	v_mfma_f32_16x16x32_bf16 v[92:95], v[144:147], v[152:155], v[92:95]
	v_mfma_f32_16x16x32_bf16 v[88:91], v[188:191], v[152:155], v[88:91]
	v_mfma_f32_16x16x32_bf16 v[84:87], v[144:147], v[160:163], v[84:87]
	v_mfma_f32_16x16x32_bf16 v[80:83], v[188:191], v[160:163], v[80:83]
	v_mfma_f32_16x16x32_bf16 v[76:79], v[144:147], v[168:171], v[76:79]
	v_mfma_f32_16x16x32_bf16 v[72:75], v[188:191], v[168:171], v[72:75]
	v_mfma_f32_16x16x32_bf16 v[68:71], v[144:147], v[176:179], v[68:71]
	v_mfma_f32_16x16x32_bf16 v[64:67], v[188:191], v[176:179], v[64:67]
	v_mfma_f32_16x16x32_bf16 v[92:95], v[184:187], v[156:159], v[92:95]
	v_mfma_f32_16x16x32_bf16 v[88:91], v[194:197], v[156:159], v[88:91]
	v_mfma_f32_16x16x32_bf16 v[84:87], v[184:187], v[164:167], v[84:87]
	v_mfma_f32_16x16x32_bf16 v[80:83], v[194:197], v[164:167], v[80:83]
	v_mfma_f32_16x16x32_bf16 v[76:79], v[184:187], v[172:175], v[76:79]
	v_mfma_f32_16x16x32_bf16 v[72:75], v[194:197], v[172:175], v[72:75]
	v_mfma_f32_16x16x32_bf16 v[68:71], v[184:187], v[180:183], v[68:71]
	v_mfma_f32_16x16x32_bf16 v[64:67], v[194:197], v[180:183], v[64:67]
	s_setprio 0
	s_barrier
	ds_read_b128 v[152:155], v137 offset:16384
	ds_read_b128 v[156:159], v137 offset:17408
	ds_read_b128 v[160:163], v137 offset:18432
	ds_read_b128 v[164:167], v137 offset:19456
	ds_read_b128 v[168:171], v137 offset:20480
	ds_read_b128 v[172:175], v137 offset:21504
	ds_read_b128 v[176:179], v137 offset:22528
	ds_read_b128 v[180:183], v137 offset:23552
	s_waitcnt vmcnt(4)
	s_barrier
	s_waitcnt lgkmcnt(0)
	s_setprio 1
	s_waitcnt lgkmcnt(0)
	v_mfma_f32_16x16x32_bf16 v[60:63], v[128:131], v[152:155], v[60:63]
	v_mfma_f32_16x16x32_bf16 v[56:59], v[140:143], v[152:155], v[56:59]
	v_mfma_f32_16x16x32_bf16 v[52:55], v[128:131], v[160:163], v[52:55]
	v_mfma_f32_16x16x32_bf16 v[48:51], v[140:143], v[160:163], v[48:51]
	v_mfma_f32_16x16x32_bf16 v[44:47], v[128:131], v[168:171], v[44:47]
	v_mfma_f32_16x16x32_bf16 v[40:43], v[140:143], v[168:171], v[40:43]
	v_mfma_f32_16x16x32_bf16 v[36:39], v[128:131], v[176:179], v[36:39]
	v_mfma_f32_16x16x32_bf16 v[32:35], v[140:143], v[176:179], v[32:35]
	v_mfma_f32_16x16x32_bf16 v[60:63], v[132:135], v[156:159], v[60:63]
	v_mfma_f32_16x16x32_bf16 v[56:59], v[148:151], v[156:159], v[56:59]
	v_mfma_f32_16x16x32_bf16 v[52:55], v[132:135], v[164:167], v[52:55]
	v_mfma_f32_16x16x32_bf16 v[48:51], v[148:151], v[164:167], v[48:51]
	v_mfma_f32_16x16x32_bf16 v[44:47], v[132:135], v[172:175], v[44:47]
	v_mfma_f32_16x16x32_bf16 v[40:43], v[148:151], v[172:175], v[40:43]
	v_mfma_f32_16x16x32_bf16 v[36:39], v[132:135], v[180:183], v[36:39]
	v_mfma_f32_16x16x32_bf16 v[32:35], v[148:151], v[180:183], v[32:35]
	s_setprio 0
	s_setprio 1
	v_mfma_f32_16x16x32_bf16 v[28:31], v[144:147], v[152:155], v[28:31]
	v_mfma_f32_16x16x32_bf16 v[24:27], v[188:191], v[152:155], v[24:27]
	v_mfma_f32_16x16x32_bf16 v[20:23], v[144:147], v[160:163], v[20:23]
	v_mfma_f32_16x16x32_bf16 v[16:19], v[188:191], v[160:163], v[16:19]
	v_mfma_f32_16x16x32_bf16 v[12:15], v[144:147], v[168:171], v[12:15]
	v_mfma_f32_16x16x32_bf16 v[8:11], v[188:191], v[168:171], v[8:11]
	v_mfma_f32_16x16x32_bf16 v[4:7], v[144:147], v[176:179], v[4:7]
	v_mfma_f32_16x16x32_bf16 v[0:3], v[188:191], v[176:179], v[0:3]
	v_mfma_f32_16x16x32_bf16 v[28:31], v[184:187], v[156:159], v[28:31]
	v_mfma_f32_16x16x32_bf16 v[24:27], v[194:197], v[156:159], v[24:27]
	v_mfma_f32_16x16x32_bf16 v[20:23], v[184:187], v[164:167], v[20:23]
	v_mfma_f32_16x16x32_bf16 v[16:19], v[194:197], v[164:167], v[16:19]
	v_mfma_f32_16x16x32_bf16 v[12:15], v[184:187], v[172:175], v[12:15]
	v_mfma_f32_16x16x32_bf16 v[8:11], v[194:197], v[172:175], v[8:11]
	v_mfma_f32_16x16x32_bf16 v[4:7], v[184:187], v[180:183], v[4:7]
	v_mfma_f32_16x16x32_bf16 v[0:3], v[194:197], v[180:183], v[0:3]
	s_setprio 0
	s_barrier
	ds_read_b128 v[132:135], v138 offset:32768
	ds_read_b128 v[140:143], v138 offset:33792
	ds_read_b128 v[144:147], v138 offset:34816
	ds_read_b128 v[148:151], v138 offset:35840
	ds_read_b128 v[152:155], v137 offset:32768
	ds_read_b128 v[156:159], v137 offset:33792
	ds_read_b128 v[160:163], v137 offset:34816
	ds_read_b128 v[164:167], v137 offset:35840
	ds_read_b128 v[168:171], v137 offset:36864
	ds_read_b128 v[172:175], v137 offset:37888
	ds_read_b128 v[176:179], v137 offset:38912
	ds_read_b128 v[180:183], v137 offset:39936
	s_waitcnt vmcnt(2)
	s_barrier
; #define WAIT_V(n) asm volatile("s_waitcnt vmcnt(" #n ")" ::: "memory")
; #define WAIT_L(n) asm volatile("s_waitcnt lgkmcnt(" #n ")" ::: "memory")
; #define BAR __builtin_amdgcn_s_barrier()
; #define LDA(dst, b, h) _Pragma("unroll") for (int m = 0; m < 4; ++m) _Pragma("unroll") for (int k = 0; k < 2; ++k) \
;     dst[m][k] = *reinterpret_cast<const bf16x8*>((char*)shm + abase + (((b) * 2 + (h)) * 16384 + (m * 2 + k) * 1024))
; #define LDB(dst, b, h) _Pragma("unroll") for (int n = 0; n < 2; ++n) _Pragma("unroll") for (int k = 0; k < 2; ++k) \
;     dst[n][k] = *reinterpret_cast<const bf16x8*>((char*)shm + bbase + (((b) * 2 + (h)) * 16384 + (n * 2 + k) * 1024))
; template <bool SWAP>
; __device__ __forceinline__ void gemm_main(const u16* __restrict__ A, const u16* __restrict__ Bt, int brow, int bcol,
;                                           u16* shm, f32x4 (&acc)[2][2][4][2]) {
;     ...
;   { LDB(B0, 1, 0); LDA(At, 1, 0); WAIT_V(2); BAR; WAIT_L(0); MMA(0, 0, At, B0); BAR;
;     LDB(B1, 1, 1); WAIT_V(0); BAR; WAIT_L(0); MMA(0, 1, At, B1); BAR;
;     LDA(At, 1, 1); BAR; WAIT_L(0); MMA(1, 0, At, B0); MMA(1, 1, At, B1); BAR; }
;   if (wr == 0) BAR;
	s_waitcnt lgkmcnt(0)
	s_setprio 1
	s_waitcnt lgkmcnt(0)
	v_mfma_f32_16x16x32_bf16 v[124:127], v[132:135], v[152:155], v[124:127]
	v_mfma_f32_16x16x32_bf16 v[120:123], v[144:147], v[152:155], v[120:123]
	v_mfma_f32_16x16x32_bf16 v[116:119], v[132:135], v[160:163], v[116:119]
	v_mfma_f32_16x16x32_bf16 v[112:115], v[144:147], v[160:163], v[112:115]
	v_mfma_f32_16x16x32_bf16 v[108:111], v[132:135], v[168:171], v[108:111]
	v_mfma_f32_16x16x32_bf16 v[104:107], v[144:147], v[168:171], v[104:107]
	v_mfma_f32_16x16x32_bf16 v[100:103], v[132:135], v[176:179], v[100:103]
	v_mfma_f32_16x16x32_bf16 v[96:99], v[144:147], v[176:179], v[96:99]
	v_mfma_f32_16x16x32_bf16 v[128:131], v[140:143], v[156:159], v[124:127]
	v_mfma_f32_16x16x32_bf16 v[124:127], v[148:151], v[156:159], v[120:123]
	v_mfma_f32_16x16x32_bf16 v[116:119], v[140:143], v[164:167], v[116:119]
	v_mfma_f32_16x16x32_bf16 v[112:115], v[148:151], v[164:167], v[112:115]
	v_mfma_f32_16x16x32_bf16 v[108:111], v[140:143], v[172:175], v[108:111]
	v_mfma_f32_16x16x32_bf16 v[104:107], v[148:151], v[172:175], v[104:107]
	v_mfma_f32_16x16x32_bf16 v[100:103], v[140:143], v[180:183], v[100:103]
	v_mfma_f32_16x16x32_bf16 v[96:99], v[148:151], v[180:183], v[96:99]
	s_setprio 0
	s_barrier
	ds_read_b128 v[120:123], v138 offset:49152
	ds_read_b128 v[184:187], v138 offset:50176
	ds_read_b128 v[188:191], v138 offset:51200
	ds_read_b128 v[194:197], v138 offset:52224
	s_waitcnt vmcnt(0)
	s_barrier
	s_waitcnt lgkmcnt(0)
	s_setprio 1
	s_waitcnt lgkmcnt(0)
	v_mfma_f32_16x16x32_bf16 v[92:95], v[120:123], v[152:155], v[92:95]
	v_mfma_f32_16x16x32_bf16 v[88:91], v[188:191], v[152:155], v[88:91]
	v_mfma_f32_16x16x32_bf16 v[84:87], v[120:123], v[160:163], v[84:87]
	v_mfma_f32_16x16x32_bf16 v[80:83], v[188:191], v[160:163], v[80:83]
	v_mfma_f32_16x16x32_bf16 v[76:79], v[120:123], v[168:171], v[76:79]
	v_mfma_f32_16x16x32_bf16 v[72:75], v[188:191], v[168:171], v[72:75]
	v_mfma_f32_16x16x32_bf16 v[68:71], v[120:123], v[176:179], v[68:71]
	v_mfma_f32_16x16x32_bf16 v[64:67], v[188:191], v[176:179], v[64:67]
	v_mfma_f32_16x16x32_bf16 v[92:95], v[184:187], v[156:159], v[92:95]
	v_mfma_f32_16x16x32_bf16 v[88:91], v[194:197], v[156:159], v[88:91]
	v_mfma_f32_16x16x32_bf16 v[84:87], v[184:187], v[164:167], v[84:87]
	v_mfma_f32_16x16x32_bf16 v[80:83], v[194:197], v[164:167], v[80:83]
	v_mfma_f32_16x16x32_bf16 v[76:79], v[184:187], v[172:175], v[76:79]
	v_mfma_f32_16x16x32_bf16 v[72:75], v[194:197], v[172:175], v[72:75]
	v_mfma_f32_16x16x32_bf16 v[68:71], v[184:187], v[180:183], v[68:71]
	v_mfma_f32_16x16x32_bf16 v[64:67], v[194:197], v[180:183], v[64:67]
	s_setprio 0
	s_barrier
	ds_read_b128 v[152:155], v137 offset:49152
	ds_read_b128 v[156:159], v137 offset:50176
	ds_read_b128 v[160:163], v137 offset:51200
	ds_read_b128 v[164:167], v137 offset:52224
	ds_read_b128 v[168:171], v137 offset:53248
	ds_read_b128 v[172:175], v137 offset:54272
	ds_read_b128 v[176:179], v137 offset:55296
	ds_read_b128 v[180:183], v137 offset:56320
	s_barrier
	s_waitcnt lgkmcnt(0)
	s_setprio 1
	s_waitcnt lgkmcnt(0)
	v_mfma_f32_16x16x32_bf16 v[60:63], v[132:135], v[152:155], v[60:63]
	v_mfma_f32_16x16x32_bf16 v[56:59], v[144:147], v[152:155], v[56:59]
	v_mfma_f32_16x16x32_bf16 v[52:55], v[132:135], v[160:163], v[52:55]
	v_mfma_f32_16x16x32_bf16 v[48:51], v[144:147], v[160:163], v[48:51]
	v_mfma_f32_16x16x32_bf16 v[44:47], v[132:135], v[168:171], v[44:47]
	v_mfma_f32_16x16x32_bf16 v[40:43], v[144:147], v[168:171], v[40:43]
	v_mfma_f32_16x16x32_bf16 v[36:39], v[132:135], v[176:179], v[36:39]
	v_mfma_f32_16x16x32_bf16 v[32:35], v[144:147], v[176:179], v[32:35]
	v_mfma_f32_16x16x32_bf16 v[60:63], v[140:143], v[156:159], v[60:63]
	v_mfma_f32_16x16x32_bf16 v[56:59], v[148:151], v[156:159], v[56:59]
	v_mfma_f32_16x16x32_bf16 v[52:55], v[140:143], v[164:167], v[52:55]
	v_mfma_f32_16x16x32_bf16 v[48:51], v[148:151], v[164:167], v[48:51]
	v_mfma_f32_16x16x32_bf16 v[44:47], v[140:143], v[172:175], v[44:47]
	v_mfma_f32_16x16x32_bf16 v[40:43], v[148:151], v[172:175], v[40:43]
	v_mfma_f32_16x16x32_bf16 v[36:39], v[140:143], v[180:183], v[36:39]
	v_mfma_f32_16x16x32_bf16 v[32:35], v[148:151], v[180:183], v[32:35]
	s_setprio 0
	s_setprio 1
	v_mfma_f32_16x16x32_bf16 v[28:31], v[120:123], v[152:155], v[28:31]
	v_mfma_f32_16x16x32_bf16 v[24:27], v[188:191], v[152:155], v[24:27]
	v_mfma_f32_16x16x32_bf16 v[20:23], v[120:123], v[160:163], v[20:23]
	v_mfma_f32_16x16x32_bf16 v[16:19], v[188:191], v[160:163], v[16:19]
	v_mfma_f32_16x16x32_bf16 v[12:15], v[120:123], v[168:171], v[12:15]
	v_mfma_f32_16x16x32_bf16 v[8:11], v[188:191], v[168:171], v[8:11]
	v_mfma_f32_16x16x32_bf16 v[4:7], v[120:123], v[176:179], v[4:7]
	v_mfma_f32_16x16x32_bf16 v[0:3], v[188:191], v[176:179], v[0:3]
	v_mfma_f32_16x16x32_bf16 v[28:31], v[184:187], v[156:159], v[28:31]
	v_mfma_f32_16x16x32_bf16 v[24:27], v[194:197], v[156:159], v[24:27]
	v_mfma_f32_16x16x32_bf16 v[20:23], v[184:187], v[164:167], v[20:23]
	v_mfma_f32_16x16x32_bf16 v[16:19], v[194:197], v[164:167], v[16:19]
	v_mfma_f32_16x16x32_bf16 v[12:15], v[184:187], v[172:175], v[12:15]
	v_mfma_f32_16x16x32_bf16 v[8:11], v[194:197], v[172:175], v[8:11]
	v_mfma_f32_16x16x32_bf16 v[4:7], v[184:187], v[180:183], v[4:7]
	v_mfma_f32_16x16x32_bf16 v[0:3], v[194:197], v[180:183], v[0:3]
	s_setprio 0
	s_movk_i32 s0, 0x100
	v_cmp_gt_u32_e32 vcc, s0, v136
	s_barrier
	s_and_saveexec_b64 s[0:1], vcc
	s_cbranch_execz .LBB0_567
	s_barrier

; #define WAIT_V(n) asm volatile("s_waitcnt vmcnt(" #n ")" ::: "memory")
; #define BAR __builtin_amdgcn_s_barrier()
; template <bool SWAP>
; __device__ __forceinline__ void gemm_main(const u16* __restrict__ A, const u16* __restrict__ Bt, int brow, int bcol,
;                                           u16* shm, f32x4 (&acc)[2][2][4][2]) {
;     ...
;   int tx = threadIdx.x; asm volatile("" : "+v"(tx));
;   const int wid = tx >> 6, lane = tx & 63, wr = wid >> 2, wc = wid & 3, fr = lane & 15, fq = lane >> 4;
; #pragma unroll
;   for (int a = 0; a < 2; ++a)
; #pragma unroll
;     for (int b = 0; b < 2; ++b)
; #pragma unroll
;       for (int m = 0; m < 4; ++m)
; #pragma unroll
;         for (int n = 0; n < 2; ++n) acc[a][b][m][n] = f32x4{0.f, 0.f, 0.f, 0.f};
;   bf16x8 At[4][2], B0[2][2], B1[2][2];
;   constexpr int nt = GK / BK;
;   GEMM_VOFF
;   const int lpart = (fr * 64 + fq * 16) ^ ((fr >> 3) << 5);
;   const int abase = wr * 8192 + lpart; int bbase = 65536 + wc * 4096 + lpart;
;   asm volatile("" : "+v"(bbase));
;   if (wr == 1) BAR;
;   WAIT_V(0); BAR;
;   BAR;
.LBB0_569:
	s_or_b64 exec, exec, s[24:25]
	v_bfe_i32 v4, v136, 27, 1
	v_lshlrev_b32_e32 v140, 4, v136
	v_lshrrev_b32_e32 v4, 22, v4
	v_add_u32_e32 v4, v140, v4
	v_and_b32_e32 v4, 0xfffffc00, v4
	v_sub_u32_e32 v4, v140, v4
	v_lshrrev_b32_e32 v5, 4, v4
	v_bitop3_b32 v4, v5, v4, 32 bitop3:0x6c
	v_ashrrev_i32_e32 v5, 31, v4
	v_lshrrev_b32_e32 v5, 26, v5
	v_add_u32_e32 v5, v4, v5
	v_ashrrev_i32_e32 v141, 6, v5
	v_and_b32_e32 v5, 0xc0, v5
	v_sub_u32_e32 v4, v4, v5
	v_ashrrev_i16_sdwa v4, v215, sext(v4) dst_sel:DWORD dst_unused:UNUSED_PAD src0_sel:DWORD src1_sel:BYTE_0
	v_bfe_i32 v142, v4, 0, 16
	v_add_u32_e32 v4, 0x2000, v140
	v_ashrrev_i32_e32 v5, 31, v4
	v_lshrrev_b32_e32 v5, 22, v5
	v_add_u32_e32 v5, v4, v5
	v_ashrrev_i32_e32 v143, 10, v5
	v_mul_i32_i24_e32 v5, 0x400, v143
	v_sub_u32_e32 v4, v4, v5
	v_lshrrev_b32_e32 v5, 4, v4
	v_bitop3_b32 v4, v5, v4, 32 bitop3:0x6c
	v_ashrrev_i32_e32 v5, 31, v4
	v_lshrrev_b32_e32 v5, 26, v5
	v_ashrrev_i32_e32 v3, 31, v136
	v_add_u32_e32 v5, v4, v5
	v_lshrrev_b32_e32 v3, 26, v3
	v_ashrrev_i32_e32 v144, 6, v5
	v_and_b32_e32 v5, 0xc0, v5
	v_add_u32_e32 v3, v136, v3
	v_sub_u32_e32 v4, v4, v5
	v_ashrrev_i32_e32 v139, 6, v3
	v_ashrrev_i16_sdwa v4, v215, sext(v4) dst_sel:DWORD dst_unused:UNUSED_PAD src0_sel:DWORD src1_sel:BYTE_0
	v_bfe_i32 v145, v4, 0, 16
	v_lshlrev_b32_e32 v4, 13, v0
	v_lshlrev_b32_e32 v0, 15, v139
	v_and_b32_e32 v0, 0xffff0000, v0
	v_lshl_add_u32 v0, v141, 12, v0
	v_and_or_b32 v0, v3, 64, v0
	v_lshl_add_u32 v192, v142, 1, v0
	v_lshlrev_b32_e32 v0, 15, v143
	v_and_b32_e32 v0, 0xffff0000, v0
	v_add_u32_e32 v5, 0, v2
	v_lshl_add_u32 v0, v144, 12, v0
	v_lshlrev_b32_e32 v2, 6, v143
	s_waitcnt vmcnt(0)
	v_readlane_b32 s14, v253, 59
	v_and_or_b32 v0, v2, 64, v0
	v_readlane_b32 s15, v253, 60
	v_lshl_add_u32 v2, v145, 1, v0
	v_mov_b32_e32 v3, v193
	v_mov_b32_e32 v0, 0
	v_lshl_add_u64 v[128:129], s[14:15], 0, v[192:193]
	v_lshl_add_u64 v[130:131], s[14:15], 0, v[2:3]
	v_lshl_add_u64 v[132:133], s[10:11], 0, v[192:193]
	v_lshl_add_u64 v[134:135], s[10:11], 0, v[2:3]
	s_mov_b32 s3, -2
	v_add_u32_e32 v138, 0, v1
	v_add_u32_e32 v137, v5, v4
	s_mov_b64 vcc, s[50:51]
	v_mov_b32_e32 v1, v0
	v_mov_b32_e32 v2, v0
	v_mov_b32_e32 v3, v0
	v_mov_b32_e32 v4, v0
	v_mov_b32_e32 v5, v0
	v_mov_b32_e32 v6, v0
	v_mov_b32_e32 v7, v0
	v_mov_b32_e32 v8, v0
	v_mov_b32_e32 v9, v0
	v_mov_b32_e32 v10, v0
	v_mov_b32_e32 v11, v0
	v_mov_b32_e32 v12, v0
	v_mov_b32_e32 v13, v0
	v_mov_b32_e32 v14, v0
	v_mov_b32_e32 v15, v0
	v_mov_b32_e32 v16, v0
	v_mov_b32_e32 v17, v0
	v_mov_b32_e32 v18, v0
	v_mov_b32_e32 v19, v0
	v_mov_b32_e32 v20, v0
	v_mov_b32_e32 v21, v0
	v_mov_b32_e32 v22, v0
	v_mov_b32_e32 v23, v0
	v_mov_b32_e32 v24, v0
	v_mov_b32_e32 v25, v0
	v_mov_b32_e32 v26, v0
	v_mov_b32_e32 v27, v0
	v_mov_b32_e32 v28, v0
	v_mov_b32_e32 v29, v0
	v_mov_b32_e32 v30, v0
	v_mov_b32_e32 v31, v0
	v_mov_b32_e32 v32, v0
	v_mov_b32_e32 v33, v0
	v_mov_b32_e32 v34, v0
	v_mov_b32_e32 v35, v0
	v_mov_b32_e32 v36, v0
	v_mov_b32_e32 v37, v0
	v_mov_b32_e32 v38, v0
	v_mov_b32_e32 v39, v0
	v_mov_b32_e32 v40, v0
	v_mov_b32_e32 v41, v0
	v_mov_b32_e32 v42, v0
	v_mov_b32_e32 v43, v0
	v_mov_b32_e32 v44, v0
	v_mov_b32_e32 v45, v0
	v_mov_b32_e32 v46, v0
	v_mov_b32_e32 v47, v0
	v_mov_b32_e32 v48, v0
	v_mov_b32_e32 v49, v0
	v_mov_b32_e32 v50, v0
	v_mov_b32_e32 v51, v0
	v_mov_b32_e32 v52, v0
	v_mov_b32_e32 v53, v0
	v_mov_b32_e32 v54, v0
	v_mov_b32_e32 v55, v0
	v_mov_b32_e32 v56, v0
	v_mov_b32_e32 v57, v0
	v_mov_b32_e32 v58, v0
	v_mov_b32_e32 v59, v0
	v_mov_b32_e32 v60, v0
	v_mov_b32_e32 v61, v0
	v_mov_b32_e32 v62, v0
	v_mov_b32_e32 v63, v0
	v_mov_b32_e32 v64, v0
	v_mov_b32_e32 v65, v0
	v_mov_b32_e32 v66, v0
	v_mov_b32_e32 v67, v0
	v_mov_b32_e32 v68, v0
	v_mov_b32_e32 v69, v0
	v_mov_b32_e32 v70, v0
	v_mov_b32_e32 v71, v0
	v_mov_b32_e32 v72, v0
	v_mov_b32_e32 v73, v0
	v_mov_b32_e32 v74, v0
	v_mov_b32_e32 v75, v0
	v_mov_b32_e32 v76, v0
	v_mov_b32_e32 v77, v0
	v_mov_b32_e32 v78, v0
	v_mov_b32_e32 v79, v0
	v_mov_b32_e32 v80, v0
	v_mov_b32_e32 v81, v0
	v_mov_b32_e32 v82, v0
	v_mov_b32_e32 v83, v0
	v_mov_b32_e32 v84, v0
	v_mov_b32_e32 v85, v0
	v_mov_b32_e32 v86, v0
	v_mov_b32_e32 v87, v0
	v_mov_b32_e32 v88, v0
	v_mov_b32_e32 v89, v0
	v_mov_b32_e32 v90, v0
	v_mov_b32_e32 v91, v0
	v_mov_b32_e32 v92, v0
	v_mov_b32_e32 v93, v0
	v_mov_b32_e32 v94, v0
	v_mov_b32_e32 v95, v0
	v_mov_b32_e32 v96, v0
	v_mov_b32_e32 v97, v0
	v_mov_b32_e32 v98, v0
	v_mov_b32_e32 v99, v0
	v_mov_b32_e32 v100, v0
	v_mov_b32_e32 v101, v0
	v_mov_b32_e32 v102, v0
	v_mov_b32_e32 v103, v0
	v_mov_b32_e32 v104, v0
	v_mov_b32_e32 v105, v0
	v_mov_b32_e32 v106, v0
	v_mov_b32_e32 v107, v0
	v_mov_b32_e32 v108, v0
	v_mov_b32_e32 v109, v0
	v_mov_b32_e32 v110, v0
	v_mov_b32_e32 v111, v0
	v_mov_b32_e32 v112, v0
	v_mov_b32_e32 v113, v0
	v_mov_b32_e32 v114, v0
	v_mov_b32_e32 v115, v0
	v_mov_b32_e32 v116, v0
	v_mov_b32_e32 v117, v0
	v_mov_b32_e32 v118, v0
	v_mov_b32_e32 v119, v0
	v_mov_b32_e32 v120, v0
	v_mov_b32_e32 v121, v0
	v_mov_b32_e32 v122, v0
	v_mov_b32_e32 v123, v0
	v_mov_b32_e32 v124, v0
	v_mov_b32_e32 v125, v0
	v_mov_b32_e32 v126, v0
	v_mov_b32_e32 v127, v0
	s_mov_b64 s[14:15], 0x1b580080
	s_mov_b64 s[16:17], 0x8900100
	s_mov_b64 s[18:19], 0x1b500100
	s_mov_b64 s[42:43], 0x8980100
	s_mov_b64 s[22:23], 0x1b580100
	s_mov_b64 s[20:21], 0x8900180
	s_mov_b64 s[92:93], 0x1b500180
	s_mov_b64 s[72:73], 0x8980180
	v_readfirstlane_b32 s24, v140
	s_barrier
	s_barrier
; #define WAIT_V(n) asm volatile("s_waitcnt vmcnt(" #n ")" ::: "memory")
; #define WAIT_L(n) asm volatile("s_waitcnt lgkmcnt(" #n ")" ::: "memory")
; #define BAR __builtin_amdgcn_s_barrier()
; #define SCHED __builtin_amdgcn_sched_barrier(0)
; #define STAGE(P, BASE, br, kt) do { const char* _g = (const char*)((BASE) + (size_t)(br) * GK + (kt) * BK); \
;     __builtin_amdgcn_global_load_lds((const unsigned*)(_g + voff0), (unsigned*)((char*)(P) + tx * 16), 16, 0, 0); \
;     __builtin_amdgcn_global_load_lds((const unsigned*)(_g + voff1), (unsigned*)((char*)(P) + tx * 16 + 8192), 16, 0, 0); } while (0)
; #define LDA(dst, b, h) _Pragma("unroll") for (int m = 0; m < 4; ++m) _Pragma("unroll") for (int k = 0; k < 2; ++k) \
;     dst[m][k] = *reinterpret_cast<const bf16x8*>((char*)shm + abase + (((b) * 2 + (h)) * 16384 + (m * 2 + k) * 1024))
; #define LDB(dst, b, h) _Pragma("unroll") for (int n = 0; n < 2; ++n) _Pragma("unroll") for (int k = 0; k < 2; ++k) \
;     dst[n][k] = *reinterpret_cast<const bf16x8*>((char*)shm + bbase + (((b) * 2 + (h)) * 16384 + (n * 2 + k) * 1024))
; template <bool SWAP>
; __device__ __forceinline__ void gemm_main(const u16* __restrict__ A, const u16* __restrict__ Bt, int brow, int bcol,
;                                           u16* shm, f32x4 (&acc)[2][2][4][2]) {
;     ...
;   for (int t = 0; t < nt - 2; t += 2) {
;     LDB(B0, 0, 0); SCHED; LDA(At, 0, 0); STAGE(SA(1, 1), A, brow + HALF, t + 1);
;     WAIT_L(8); BAR; WAIT_L(0); MMA(0, 0, At, B0); BAR; SCHED;
;     LDB(B1, 0, 1); STAGE(SB(0, 0), Bt, bcol, t + 2);
;     BAR; WAIT_L(0); MMA(0, 1, At, B1); BAR;
;     LDA(At, 0, 1); STAGE(SA(0, 0), A, brow, t + 2);
;     BAR; WAIT_L(0); MMA(1, 0, At, B0); BAR; SCHED;
;     STAGE(SB(0, 1), Bt, bcol + HALF, t + 2);
;     WAIT_V(6); BAR; MMA(1, 1, At, B1); BAR;
.LBB0_570:
	ds_read_b128 v[148:151], v138
	ds_read_b128 v[152:155], v138 offset:1024
	ds_read_b128 v[156:159], v138 offset:2048
	ds_read_b128 v[160:163], v138 offset:3072
	ds_read_b128 v[164:167], v137
	ds_read_b128 v[168:171], v137 offset:1024
	ds_read_b128 v[172:175], v137 offset:2048
	ds_read_b128 v[176:179], v137 offset:3072
	ds_read_b128 v[180:183], v137 offset:4096
	ds_read_b128 v[184:187], v137 offset:5120
	ds_read_b128 v[188:191], v137 offset:6144
	ds_read_b128 v[194:197], v137 offset:7168
	v_add_u32_e32 v192, 0, v140
	v_add_u32_e32 v146, 0xc000, v192
	v_lshl_add_u64 v[230:231], vcc, 0, v[132:133]
	v_add_u32_e32 v147, 0xe000, v192
	v_lshl_add_u64 v[198:199], v[230:231], 0, s[14:15]
	s_add_u32 m0, s24, 0xc000
	v_lshl_add_u64 v[232:233], vcc, 0, v[134:135]
	global_load_lds_dwordx4 v[198:199], off
	v_lshl_add_u64 v[198:199], v[232:233], 0, s[14:15]
	s_add_u32 m0, s24, 0xe000
	s_nop 0
	global_load_lds_dwordx4 v[198:199], off
	s_waitcnt lgkmcnt(8)
	s_setprio 1
	s_barrier
	s_waitcnt lgkmcnt(0)
	v_mfma_f32_16x16x32_bf16 v[124:127], v[148:151], v[164:167], v[124:127]
	v_mfma_f32_16x16x32_bf16 v[120:123], v[156:159], v[164:167], v[120:123]
	v_mfma_f32_16x16x32_bf16 v[116:119], v[148:151], v[172:175], v[116:119]
	v_mfma_f32_16x16x32_bf16 v[112:115], v[156:159], v[172:175], v[112:115]
	v_mfma_f32_16x16x32_bf16 v[108:111], v[148:151], v[180:183], v[108:111]
	v_mfma_f32_16x16x32_bf16 v[104:107], v[156:159], v[180:183], v[104:107]
	v_mfma_f32_16x16x32_bf16 v[100:103], v[148:151], v[188:191], v[100:103]
	v_mfma_f32_16x16x32_bf16 v[96:99], v[156:159], v[188:191], v[96:99]
	v_mfma_f32_16x16x32_bf16 v[124:127], v[152:155], v[168:171], v[124:127]
	v_mfma_f32_16x16x32_bf16 v[120:123], v[160:163], v[168:171], v[120:123]
	v_mfma_f32_16x16x32_bf16 v[116:119], v[152:155], v[176:179], v[116:119]
	v_mfma_f32_16x16x32_bf16 v[112:115], v[160:163], v[176:179], v[112:115]
	v_mfma_f32_16x16x32_bf16 v[108:111], v[152:155], v[184:187], v[108:111]
	v_mfma_f32_16x16x32_bf16 v[104:107], v[160:163], v[184:187], v[104:107]
	v_mfma_f32_16x16x32_bf16 v[100:103], v[152:155], v[194:197], v[100:103]
	v_mfma_f32_16x16x32_bf16 v[96:99], v[160:163], v[194:197], v[96:99]
	s_barrier
	s_setprio 0
	ds_read_b128 v[198:201], v138 offset:16384
	ds_read_b128 v[202:205], v138 offset:17408
	ds_read_b128 v[206:209], v138 offset:18432
	ds_read_b128 v[226:229], v138 offset:19456
	v_lshl_add_u64 v[234:235], vcc, 0, v[128:129]
	v_lshl_add_u64 v[236:237], v[234:235], 0, s[16:17]
	s_add_u32 m0, s24, s28
	s_nop 0
	global_load_lds_dwordx4 v[236:237], off
	v_lshl_add_u64 v[236:237], vcc, 0, v[130:131]
	v_lshl_add_u64 v[238:239], v[236:237], 0, s[16:17]
	s_add_u32 m0, s24, s28
	s_add_u32 m0, m0, 0x2000
	s_nop 0
	global_load_lds_dwordx4 v[238:239], off
	s_setprio 1
	s_barrier
	s_waitcnt lgkmcnt(0)
	v_mfma_f32_16x16x32_bf16 v[92:95], v[198:201], v[164:167], v[92:95]
	v_mfma_f32_16x16x32_bf16 v[88:91], v[206:209], v[164:167], v[88:91]
	v_mfma_f32_16x16x32_bf16 v[84:87], v[198:201], v[172:175], v[84:87]
	v_mfma_f32_16x16x32_bf16 v[80:83], v[206:209], v[172:175], v[80:83]
	v_mfma_f32_16x16x32_bf16 v[76:79], v[198:201], v[180:183], v[76:79]
	v_mfma_f32_16x16x32_bf16 v[72:75], v[206:209], v[180:183], v[72:75]
	v_mfma_f32_16x16x32_bf16 v[68:71], v[198:201], v[188:191], v[68:71]
	v_mfma_f32_16x16x32_bf16 v[64:67], v[206:209], v[188:191], v[64:67]
	v_mfma_f32_16x16x32_bf16 v[92:95], v[202:205], v[168:171], v[92:95]
	v_mfma_f32_16x16x32_bf16 v[88:91], v[226:229], v[168:171], v[88:91]
	v_mfma_f32_16x16x32_bf16 v[84:87], v[202:205], v[176:179], v[84:87]
	v_mfma_f32_16x16x32_bf16 v[80:83], v[226:229], v[176:179], v[80:83]
	v_mfma_f32_16x16x32_bf16 v[76:79], v[202:205], v[184:187], v[76:79]
	v_mfma_f32_16x16x32_bf16 v[72:75], v[226:229], v[184:187], v[72:75]
	v_mfma_f32_16x16x32_bf16 v[68:71], v[202:205], v[194:197], v[68:71]
	v_mfma_f32_16x16x32_bf16 v[64:67], v[226:229], v[194:197], v[64:67]
	s_barrier
	s_setprio 0
	ds_read_b128 v[164:167], v137 offset:16384
	ds_read_b128 v[168:171], v137 offset:17408
	ds_read_b128 v[172:175], v137 offset:18432
	ds_read_b128 v[176:179], v137 offset:19456
	ds_read_b128 v[180:183], v137 offset:20480
	ds_read_b128 v[184:187], v137 offset:21504
	ds_read_b128 v[188:191], v137 offset:22528
	ds_read_b128 v[194:197], v137 offset:23552
	v_lshl_add_u64 v[238:239], v[230:231], 0, s[18:19]
	s_add_u32 m0, s24, 0x0
	s_nop 0
	global_load_lds_dwordx4 v[238:239], off
	v_lshl_add_u64 v[238:239], v[232:233], 0, s[18:19]
	s_add_u32 m0, s24, 0x2000
	s_nop 0
	global_load_lds_dwordx4 v[238:239], off
	s_setprio 1
	s_barrier
	s_waitcnt lgkmcnt(0)
	v_mfma_f32_16x16x32_bf16 v[60:63], v[148:151], v[164:167], v[60:63]
	v_mfma_f32_16x16x32_bf16 v[56:59], v[156:159], v[164:167], v[56:59]
	v_mfma_f32_16x16x32_bf16 v[52:55], v[148:151], v[172:175], v[52:55]
	v_mfma_f32_16x16x32_bf16 v[48:51], v[156:159], v[172:175], v[48:51]
	v_mfma_f32_16x16x32_bf16 v[44:47], v[148:151], v[180:183], v[44:47]
	v_mfma_f32_16x16x32_bf16 v[40:43], v[156:159], v[180:183], v[40:43]
	v_mfma_f32_16x16x32_bf16 v[36:39], v[148:151], v[188:191], v[36:39]
	v_mfma_f32_16x16x32_bf16 v[32:35], v[156:159], v[188:191], v[32:35]
	v_mfma_f32_16x16x32_bf16 v[60:63], v[152:155], v[168:171], v[60:63]
	v_mfma_f32_16x16x32_bf16 v[56:59], v[160:163], v[168:171], v[56:59]
	v_mfma_f32_16x16x32_bf16 v[52:55], v[152:155], v[176:179], v[52:55]
	v_mfma_f32_16x16x32_bf16 v[48:51], v[160:163], v[176:179], v[48:51]
	v_mfma_f32_16x16x32_bf16 v[44:47], v[152:155], v[184:187], v[44:47]
	v_mfma_f32_16x16x32_bf16 v[40:43], v[160:163], v[184:187], v[40:43]
	v_mfma_f32_16x16x32_bf16 v[36:39], v[152:155], v[194:197], v[36:39]
	v_mfma_f32_16x16x32_bf16 v[32:35], v[160:163], v[194:197], v[32:35]
	s_barrier
; #define WAIT_V(n) asm volatile("s_waitcnt vmcnt(" #n ")" ::: "memory")
; #define WAIT_L(n) asm volatile("s_waitcnt lgkmcnt(" #n ")" ::: "memory")
; #define BAR __builtin_amdgcn_s_barrier()
; #define SCHED __builtin_amdgcn_sched_barrier(0)
; #define STAGE(P, BASE, br, kt) do { const char* _g = (const char*)((BASE) + (size_t)(br) * GK + (kt) * BK); \
;     __builtin_amdgcn_global_load_lds((const unsigned*)(_g + voff0), (unsigned*)((char*)(P) + tx * 16), 16, 0, 0); \
;     __builtin_amdgcn_global_load_lds((const unsigned*)(_g + voff1), (unsigned*)((char*)(P) + tx * 16 + 8192), 16, 0, 0); } while (0)
; #define LDA(dst, b, h) _Pragma("unroll") for (int m = 0; m < 4; ++m) _Pragma("unroll") for (int k = 0; k < 2; ++k) \
;     dst[m][k] = *reinterpret_cast<const bf16x8*>((char*)shm + abase + (((b) * 2 + (h)) * 16384 + (m * 2 + k) * 1024))
; #define LDB(dst, b, h) _Pragma("unroll") for (int n = 0; n < 2; ++n) _Pragma("unroll") for (int k = 0; k < 2; ++k) \
;     dst[n][k] = *reinterpret_cast<const bf16x8*>((char*)shm + bbase + (((b) * 2 + (h)) * 16384 + (n * 2 + k) * 1024))
; template <bool SWAP>
; __device__ __forceinline__ void gemm_main(const u16* __restrict__ A, const u16* __restrict__ Bt, int brow, int bcol,
;                                           u16* shm, f32x4 (&acc)[2][2][4][2]) {
;     ...
;     WAIT_V(6); BAR; MMA(1, 1, At, B1); BAR;
;     LDB(B0, 1, 0); SCHED; LDA(At, 1, 0); STAGE(SA(0, 1), A, brow + HALF, t + 2);
;     WAIT_L(8); BAR; WAIT_L(0); MMA(0, 0, At, B0); BAR; SCHED;
;     LDB(B1, 1, 1); STAGE(SB(1, 0), Bt, bcol, t + 3);
;     BAR; WAIT_L(0); MMA(0, 1, At, B1); BAR;
;     LDA(At, 1, 1); STAGE(SA(1, 0), A, brow, t + 3);
;     BAR; WAIT_L(0); MMA(1, 0, At, B0); BAR; SCHED;
	s_setprio 0
	v_lshl_add_u64 v[148:149], v[234:235], 0, s[42:43]
	s_add_u32 m0, s24, s29
	s_nop 0
	global_load_lds_dwordx4 v[148:149], off
	v_lshl_add_u64 v[148:149], v[236:237], 0, s[42:43]
	s_add_u32 m0, s24, s29
	s_add_u32 m0, m0, 0x2000
	s_nop 0
	global_load_lds_dwordx4 v[148:149], off
	s_waitcnt vmcnt(6)
	s_setprio 1
	s_barrier
	v_mfma_f32_16x16x32_bf16 v[28:31], v[198:201], v[164:167], v[28:31]
	v_mfma_f32_16x16x32_bf16 v[24:27], v[206:209], v[164:167], v[24:27]
	v_mfma_f32_16x16x32_bf16 v[20:23], v[198:201], v[172:175], v[20:23]
	v_mfma_f32_16x16x32_bf16 v[16:19], v[206:209], v[172:175], v[16:19]
	v_mfma_f32_16x16x32_bf16 v[12:15], v[198:201], v[180:183], v[12:15]
	v_mfma_f32_16x16x32_bf16 v[8:11], v[206:209], v[180:183], v[8:11]
	v_mfma_f32_16x16x32_bf16 v[4:7], v[198:201], v[188:191], v[4:7]
	v_mfma_f32_16x16x32_bf16 v[0:3], v[206:209], v[188:191], v[0:3]
	v_mfma_f32_16x16x32_bf16 v[28:31], v[202:205], v[168:171], v[28:31]
	v_mfma_f32_16x16x32_bf16 v[24:27], v[226:229], v[168:171], v[24:27]
	v_mfma_f32_16x16x32_bf16 v[20:23], v[202:205], v[176:179], v[20:23]
	v_mfma_f32_16x16x32_bf16 v[16:19], v[226:229], v[176:179], v[16:19]
	v_mfma_f32_16x16x32_bf16 v[12:15], v[202:205], v[184:187], v[12:15]
	v_mfma_f32_16x16x32_bf16 v[8:11], v[226:229], v[184:187], v[8:11]
	v_mfma_f32_16x16x32_bf16 v[4:7], v[202:205], v[194:197], v[4:7]
	v_mfma_f32_16x16x32_bf16 v[0:3], v[226:229], v[194:197], v[0:3]
	s_barrier
	s_setprio 0
	ds_read_b128 v[148:151], v138 offset:32768
	ds_read_b128 v[152:155], v138 offset:33792
	ds_read_b128 v[156:159], v138 offset:34816
	ds_read_b128 v[160:163], v138 offset:35840
	ds_read_b128 v[164:167], v137 offset:32768
	ds_read_b128 v[168:171], v137 offset:33792
	ds_read_b128 v[172:175], v137 offset:34816
	ds_read_b128 v[176:179], v137 offset:35840
	ds_read_b128 v[180:183], v137 offset:36864
	ds_read_b128 v[184:187], v137 offset:37888
	ds_read_b128 v[188:191], v137 offset:38912
	ds_read_b128 v[194:197], v137 offset:39936
	v_lshl_add_u64 v[198:199], v[230:231], 0, s[22:23]
	s_add_u32 m0, s24, 0x4000
	s_nop 0
	global_load_lds_dwordx4 v[198:199], off
	v_lshl_add_u64 v[198:199], v[232:233], 0, s[22:23]
	s_add_u32 m0, s24, 0x6000
	s_nop 0
	global_load_lds_dwordx4 v[198:199], off
	s_waitcnt lgkmcnt(8)
	s_setprio 1
	s_barrier
	s_waitcnt lgkmcnt(0)
	v_mfma_f32_16x16x32_bf16 v[124:127], v[148:151], v[164:167], v[124:127]
	v_mfma_f32_16x16x32_bf16 v[120:123], v[156:159], v[164:167], v[120:123]
	v_mfma_f32_16x16x32_bf16 v[116:119], v[148:151], v[172:175], v[116:119]
	v_mfma_f32_16x16x32_bf16 v[112:115], v[156:159], v[172:175], v[112:115]
	v_mfma_f32_16x16x32_bf16 v[108:111], v[148:151], v[180:183], v[108:111]
	v_mfma_f32_16x16x32_bf16 v[104:107], v[156:159], v[180:183], v[104:107]
	v_mfma_f32_16x16x32_bf16 v[100:103], v[148:151], v[188:191], v[100:103]
	v_mfma_f32_16x16x32_bf16 v[96:99], v[156:159], v[188:191], v[96:99]
	v_mfma_f32_16x16x32_bf16 v[124:127], v[152:155], v[168:171], v[124:127]
	v_mfma_f32_16x16x32_bf16 v[120:123], v[160:163], v[168:171], v[120:123]
	v_mfma_f32_16x16x32_bf16 v[116:119], v[152:155], v[176:179], v[116:119]
	v_mfma_f32_16x16x32_bf16 v[112:115], v[160:163], v[176:179], v[112:115]
	v_mfma_f32_16x16x32_bf16 v[108:111], v[152:155], v[184:187], v[108:111]
	v_mfma_f32_16x16x32_bf16 v[104:107], v[160:163], v[184:187], v[104:107]
	v_mfma_f32_16x16x32_bf16 v[100:103], v[152:155], v[194:197], v[100:103]
	v_mfma_f32_16x16x32_bf16 v[96:99], v[160:163], v[194:197], v[96:99]
	s_barrier
	s_setprio 0
	ds_read_b128 v[198:201], v138 offset:49152
	ds_read_b128 v[202:205], v138 offset:50176
	ds_read_b128 v[206:209], v138 offset:51200
	ds_read_b128 v[226:229], v138 offset:52224
	v_lshl_add_u64 v[238:239], v[234:235], 0, s[20:21]
	s_add_u32 m0, s24, s30
	s_nop 0
	global_load_lds_dwordx4 v[238:239], off
	v_lshl_add_u64 v[238:239], v[236:237], 0, s[20:21]
	s_add_u32 m0, s24, s30
	s_add_u32 m0, m0, 0x2000
	s_nop 0
	global_load_lds_dwordx4 v[238:239], off
	s_setprio 1
	s_barrier
	s_waitcnt lgkmcnt(0)
	v_mfma_f32_16x16x32_bf16 v[92:95], v[198:201], v[164:167], v[92:95]
	v_mfma_f32_16x16x32_bf16 v[88:91], v[206:209], v[164:167], v[88:91]
	v_mfma_f32_16x16x32_bf16 v[84:87], v[198:201], v[172:175], v[84:87]
	v_mfma_f32_16x16x32_bf16 v[80:83], v[206:209], v[172:175], v[80:83]
	v_mfma_f32_16x16x32_bf16 v[76:79], v[198:201], v[180:183], v[76:79]
	v_mfma_f32_16x16x32_bf16 v[72:75], v[206:209], v[180:183], v[72:75]
	v_mfma_f32_16x16x32_bf16 v[68:71], v[198:201], v[188:191], v[68:71]
	v_mfma_f32_16x16x32_bf16 v[64:67], v[206:209], v[188:191], v[64:67]
	v_mfma_f32_16x16x32_bf16 v[92:95], v[202:205], v[168:171], v[92:95]
	v_mfma_f32_16x16x32_bf16 v[88:91], v[226:229], v[168:171], v[88:91]
	v_mfma_f32_16x16x32_bf16 v[84:87], v[202:205], v[176:179], v[84:87]
	v_mfma_f32_16x16x32_bf16 v[80:83], v[226:229], v[176:179], v[80:83]
	v_mfma_f32_16x16x32_bf16 v[76:79], v[202:205], v[184:187], v[76:79]
	v_mfma_f32_16x16x32_bf16 v[72:75], v[226:229], v[184:187], v[72:75]
	v_mfma_f32_16x16x32_bf16 v[68:71], v[202:205], v[194:197], v[68:71]
	v_mfma_f32_16x16x32_bf16 v[64:67], v[226:229], v[194:197], v[64:67]
	s_barrier
	s_setprio 0
	ds_read_b128 v[164:167], v137 offset:49152
	ds_read_b128 v[168:171], v137 offset:50176
	ds_read_b128 v[172:175], v137 offset:51200
	ds_read_b128 v[176:179], v137 offset:52224
	ds_read_b128 v[180:183], v137 offset:53248
	ds_read_b128 v[184:187], v137 offset:54272
	ds_read_b128 v[188:191], v137 offset:55296
	ds_read_b128 v[194:197], v137 offset:56320
	v_lshl_add_u64 v[230:231], v[230:231], 0, s[92:93]
	s_add_u32 m0, s24, 0x8000
	s_nop 0
	global_load_lds_dwordx4 v[230:231], off
	v_lshl_add_u64 v[230:231], v[232:233], 0, s[92:93]
	s_add_u32 m0, s24, 0xa000
	s_nop 0
	global_load_lds_dwordx4 v[230:231], off
	s_setprio 1
	s_barrier
; #define WAIT_V(n) asm volatile("s_waitcnt vmcnt(" #n ")" ::: "memory")
; #define WAIT_L(n) asm volatile("s_waitcnt lgkmcnt(" #n ")" ::: "memory")
; #define BAR __builtin_amdgcn_s_barrier()
; #define SCHED __builtin_amdgcn_sched_barrier(0)
; #define STAGE(P, BASE, br, kt) do { const char* _g = (const char*)((BASE) + (size_t)(br) * GK + (kt) * BK); \
;     __builtin_amdgcn_global_load_lds((const unsigned*)(_g + voff0), (unsigned*)((char*)(P) + tx * 16), 16, 0, 0); \
;     __builtin_amdgcn_global_load_lds((const unsigned*)(_g + voff1), (unsigned*)((char*)(P) + tx * 16 + 8192), 16, 0, 0); } while (0)
; #define LDA(dst, b, h) _Pragma("unroll") for (int m = 0; m < 4; ++m) _Pragma("unroll") for (int k = 0; k < 2; ++k) \
;     dst[m][k] = *reinterpret_cast<const bf16x8*>((char*)shm + abase + (((b) * 2 + (h)) * 16384 + (m * 2 + k) * 1024))
; #define LDB(dst, b, h) _Pragma("unroll") for (int n = 0; n < 2; ++n) _Pragma("unroll") for (int k = 0; k < 2; ++k) \
;     dst[n][k] = *reinterpret_cast<const bf16x8*>((char*)shm + bbase + (((b) * 2 + (h)) * 16384 + (n * 2 + k) * 1024))
; template <bool SWAP>
; __device__ __forceinline__ void gemm_main(const u16* __restrict__ A, const u16* __restrict__ Bt, int brow, int bcol,
;                                           u16* shm, f32x4 (&acc)[2][2][4][2]) {
;     ...
;     BAR; WAIT_L(0); MMA(1, 0, At, B0); BAR; SCHED;
;     STAGE(SB(1, 1), Bt, bcol + HALF, t + 3);
;     WAIT_V(6); BAR; MMA(1, 1, At, B1); BAR;
;   }
;   { LDB(B0, 0, 0); LDA(At, 0, 0); STAGE(SA(1, 1), A, brow + HALF, nt - 1);
;     BAR; WAIT_L(0); MMA(0, 0, At, B0); BAR;
;     LDB(B1, 0, 1); BAR; WAIT_L(0); MMA(0, 1, At, B1); BAR;
	s_waitcnt lgkmcnt(0)
	v_mfma_f32_16x16x32_bf16 v[60:63], v[148:151], v[164:167], v[60:63]
	v_mfma_f32_16x16x32_bf16 v[56:59], v[156:159], v[164:167], v[56:59]
	v_mfma_f32_16x16x32_bf16 v[52:55], v[148:151], v[172:175], v[52:55]
	v_mfma_f32_16x16x32_bf16 v[48:51], v[156:159], v[172:175], v[48:51]
	v_mfma_f32_16x16x32_bf16 v[44:47], v[148:151], v[180:183], v[44:47]
	v_mfma_f32_16x16x32_bf16 v[40:43], v[156:159], v[180:183], v[40:43]
	v_mfma_f32_16x16x32_bf16 v[36:39], v[148:151], v[188:191], v[36:39]
	v_mfma_f32_16x16x32_bf16 v[32:35], v[156:159], v[188:191], v[32:35]
	v_mfma_f32_16x16x32_bf16 v[60:63], v[152:155], v[168:171], v[60:63]
	v_mfma_f32_16x16x32_bf16 v[56:59], v[160:163], v[168:171], v[56:59]
	v_mfma_f32_16x16x32_bf16 v[52:55], v[152:155], v[176:179], v[52:55]
	v_mfma_f32_16x16x32_bf16 v[48:51], v[160:163], v[176:179], v[48:51]
	v_mfma_f32_16x16x32_bf16 v[44:47], v[152:155], v[184:187], v[44:47]
	v_mfma_f32_16x16x32_bf16 v[40:43], v[160:163], v[184:187], v[40:43]
	v_mfma_f32_16x16x32_bf16 v[36:39], v[152:155], v[194:197], v[36:39]
	v_mfma_f32_16x16x32_bf16 v[32:35], v[160:163], v[194:197], v[32:35]
	s_barrier
	s_setprio 0
	v_lshl_add_u64 v[148:149], v[234:235], 0, s[72:73]
	s_add_u32 m0, s24, s31
	s_nop 0
	global_load_lds_dwordx4 v[148:149], off
	v_lshl_add_u64 v[148:149], v[236:237], 0, s[72:73]
	s_add_u32 m0, s24, s31
	s_add_u32 m0, m0, 0x2000
	s_nop 0
	global_load_lds_dwordx4 v[148:149], off
	s_waitcnt vmcnt(6)
	s_setprio 1
	s_barrier
	v_mfma_f32_16x16x32_bf16 v[28:31], v[198:201], v[164:167], v[28:31]
	v_mfma_f32_16x16x32_bf16 v[24:27], v[206:209], v[164:167], v[24:27]
	v_mfma_f32_16x16x32_bf16 v[20:23], v[198:201], v[172:175], v[20:23]
	v_mfma_f32_16x16x32_bf16 v[16:19], v[206:209], v[172:175], v[16:19]
	v_mfma_f32_16x16x32_bf16 v[12:15], v[198:201], v[180:183], v[12:15]
	v_mfma_f32_16x16x32_bf16 v[8:11], v[206:209], v[180:183], v[8:11]
	v_mfma_f32_16x16x32_bf16 v[4:7], v[198:201], v[188:191], v[4:7]
	v_mfma_f32_16x16x32_bf16 v[0:3], v[206:209], v[188:191], v[0:3]
	v_mfma_f32_16x16x32_bf16 v[28:31], v[202:205], v[168:171], v[28:31]
	v_mfma_f32_16x16x32_bf16 v[24:27], v[226:229], v[168:171], v[24:27]
	v_mfma_f32_16x16x32_bf16 v[20:23], v[202:205], v[176:179], v[20:23]
	v_mfma_f32_16x16x32_bf16 v[16:19], v[226:229], v[176:179], v[16:19]
	v_mfma_f32_16x16x32_bf16 v[12:15], v[202:205], v[184:187], v[12:15]
	v_mfma_f32_16x16x32_bf16 v[8:11], v[226:229], v[184:187], v[8:11]
	v_mfma_f32_16x16x32_bf16 v[4:7], v[202:205], v[194:197], v[4:7]
	v_mfma_f32_16x16x32_bf16 v[0:3], v[226:229], v[194:197], v[0:3]
	s_add_i32 s3, s3, 2
	s_add_u32 vcc_lo, vcc_lo, 0x100
	s_addc_u32 vcc_hi, vcc_hi, 0
	s_cmp_lt_u32 s3, 28
	s_barrier
	s_setprio 0
	s_cbranch_scc1 .LBB0_570
	v_lshlrev_b32_e32 v128, 3, v139
	v_lshlrev_b32_e32 v129, 5, v139
	v_and_b32_e32 v128, 0xffff0, v128
	v_and_b32_e32 v129, 32, v129
	v_add_u32_e32 v129, v129, v142
	v_add_lshl_u32 v128, v141, v128, 12
	v_lshl_add_u32 v192, v129, 1, v128
	v_lshlrev_b32_e32 v128, 3, v143
	v_lshlrev_b32_e32 v129, 5, v143
	v_and_b32_e32 v128, 0xffff0, v128
	v_and_b32_e32 v129, 32, v129
	v_add_u32_e32 v129, v129, v145
	v_add_lshl_u32 v128, v144, v128, 12
	v_lshl_add_u32 v144, v129, 1, v128
	v_mov_b32_e32 v145, v193
	v_lshl_add_u64 v[184:185], s[4:5], 0, v[192:193]
	s_mov_b64 s[14:15], 0xf80
	v_readfirstlane_b32 s3, v146
	v_lshl_add_u64 v[184:185], v[184:185], 0, s[14:15]
	s_mov_b32 m0, s3
	v_lshl_add_u64 v[144:145], s[4:5], 0, v[144:145]
	v_readfirstlane_b32 s3, v147
	ds_read_b128 v[128:131], v138
	ds_read_b128 v[132:135], v138 offset:1024
	ds_read_b128 v[140:143], v138 offset:2048
	ds_read_b128 v[148:151], v138 offset:3072
	ds_read_b128 v[152:155], v137
	ds_read_b128 v[156:159], v137 offset:1024
	ds_read_b128 v[160:163], v137 offset:2048
	ds_read_b128 v[164:167], v137 offset:3072
	ds_read_b128 v[168:171], v137 offset:4096
	ds_read_b128 v[172:175], v137 offset:5120
	ds_read_b128 v[176:179], v137 offset:6144
	ds_read_b128 v[180:183], v137 offset:7168
	global_load_lds_dwordx4 v[184:185], off
	v_lshl_add_u64 v[144:145], v[144:145], 0, s[14:15]
	s_mov_b32 m0, s3
	s_nop 0
	global_load_lds_dwordx4 v[144:145], off
	s_barrier
	s_waitcnt lgkmcnt(0)
	s_setprio 1
	s_waitcnt lgkmcnt(0)
	v_mfma_f32_16x16x32_bf16 v[116:119], v[128:131], v[160:163], v[116:119]
	v_mfma_f32_16x16x32_bf16 v[112:115], v[140:143], v[160:163], v[112:115]
	v_mfma_f32_16x16x32_bf16 v[100:103], v[128:131], v[176:179], v[100:103]
	v_mfma_f32_16x16x32_bf16 v[96:99], v[140:143], v[176:179], v[96:99]
	v_mfma_f32_16x16x32_bf16 v[124:127], v[128:131], v[152:155], v[124:127]
	v_mfma_f32_16x16x32_bf16 v[120:123], v[140:143], v[152:155], v[120:123]
	v_mfma_f32_16x16x32_bf16 v[116:119], v[132:135], v[164:167], v[116:119]
	v_mfma_f32_16x16x32_bf16 v[112:115], v[148:151], v[164:167], v[112:115]
	v_mfma_f32_16x16x32_bf16 v[108:111], v[128:131], v[168:171], v[108:111]
	v_mfma_f32_16x16x32_bf16 v[104:107], v[140:143], v[168:171], v[104:107]
	v_mfma_f32_16x16x32_bf16 v[100:103], v[132:135], v[180:183], v[100:103]
	v_mfma_f32_16x16x32_bf16 v[96:99], v[148:151], v[180:183], v[96:99]
	v_mfma_f32_16x16x32_bf16 v[124:127], v[132:135], v[156:159], v[124:127]
	v_mfma_f32_16x16x32_bf16 v[120:123], v[148:151], v[156:159], v[120:123]
	v_mfma_f32_16x16x32_bf16 v[108:111], v[132:135], v[172:175], v[108:111]
	v_mfma_f32_16x16x32_bf16 v[104:107], v[148:151], v[172:175], v[104:107]
	s_setprio 0
	s_barrier
	ds_read_b128 v[144:147], v138 offset:16384
	ds_read_b128 v[184:187], v138 offset:17408
	ds_read_b128 v[188:191], v138 offset:18432
	ds_read_b128 v[194:197], v138 offset:19456
	s_barrier
; #define WAIT_V(n) asm volatile("s_waitcnt vmcnt(" #n ")" ::: "memory")
; #define WAIT_L(n) asm volatile("s_waitcnt lgkmcnt(" #n ")" ::: "memory")
; #define BAR __builtin_amdgcn_s_barrier()
; #define LDA(dst, b, h) _Pragma("unroll") for (int m = 0; m < 4; ++m) _Pragma("unroll") for (int k = 0; k < 2; ++k) \
;     dst[m][k] = *reinterpret_cast<const bf16x8*>((char*)shm + abase + (((b) * 2 + (h)) * 16384 + (m * 2 + k) * 1024))
; #define LDB(dst, b, h) _Pragma("unroll") for (int n = 0; n < 2; ++n) _Pragma("unroll") for (int k = 0; k < 2; ++k) \
;     dst[n][k] = *reinterpret_cast<const bf16x8*>((char*)shm + bbase + (((b) * 2 + (h)) * 16384 + (n * 2 + k) * 1024))
; template <bool SWAP>
; __device__ __forceinline__ void gemm_main(const u16* __restrict__ A, const u16* __restrict__ Bt, int brow, int bcol,
;                                           u16* shm, f32x4 (&acc)[2][2][4][2]) {
;     ...
;     LDB(B1, 0, 1); BAR; WAIT_L(0); MMA(0, 1, At, B1); BAR;
;     LDA(At, 0, 1); WAIT_V(4); BAR; WAIT_L(0); MMA(1, 0, At, B0); MMA(1, 1, At, B1); BAR; }
;   { LDB(B0, 1, 0); LDA(At, 1, 0); WAIT_V(2); BAR; WAIT_L(0); MMA(0, 0, At, B0); BAR;
;     LDB(B1, 1, 1); WAIT_V(0); BAR; WAIT_L(0); MMA(0, 1, At, B1); BAR;
	s_waitcnt lgkmcnt(0)
	s_setprio 1
	s_waitcnt lgkmcnt(0)
	v_mfma_f32_16x16x32_bf16 v[92:95], v[144:147], v[152:155], v[92:95]
	v_mfma_f32_16x16x32_bf16 v[88:91], v[188:191], v[152:155], v[88:91]
	v_mfma_f32_16x16x32_bf16 v[84:87], v[144:147], v[160:163], v[84:87]
	v_mfma_f32_16x16x32_bf16 v[80:83], v[188:191], v[160:163], v[80:83]
	v_mfma_f32_16x16x32_bf16 v[76:79], v[144:147], v[168:171], v[76:79]
	v_mfma_f32_16x16x32_bf16 v[72:75], v[188:191], v[168:171], v[72:75]
	v_mfma_f32_16x16x32_bf16 v[68:71], v[144:147], v[176:179], v[68:71]
	v_mfma_f32_16x16x32_bf16 v[64:67], v[188:191], v[176:179], v[64:67]
	v_mfma_f32_16x16x32_bf16 v[92:95], v[184:187], v[156:159], v[92:95]
	v_mfma_f32_16x16x32_bf16 v[88:91], v[194:197], v[156:159], v[88:91]
	v_mfma_f32_16x16x32_bf16 v[84:87], v[184:187], v[164:167], v[84:87]
	v_mfma_f32_16x16x32_bf16 v[80:83], v[194:197], v[164:167], v[80:83]
	v_mfma_f32_16x16x32_bf16 v[76:79], v[184:187], v[172:175], v[76:79]
	v_mfma_f32_16x16x32_bf16 v[72:75], v[194:197], v[172:175], v[72:75]
	v_mfma_f32_16x16x32_bf16 v[68:71], v[184:187], v[180:183], v[68:71]
	v_mfma_f32_16x16x32_bf16 v[64:67], v[194:197], v[180:183], v[64:67]
	s_setprio 0
	s_barrier
	ds_read_b128 v[152:155], v137 offset:16384
	ds_read_b128 v[156:159], v137 offset:17408
	ds_read_b128 v[160:163], v137 offset:18432
	ds_read_b128 v[164:167], v137 offset:19456
	ds_read_b128 v[168:171], v137 offset:20480
	ds_read_b128 v[172:175], v137 offset:21504
	ds_read_b128 v[176:179], v137 offset:22528
	ds_read_b128 v[180:183], v137 offset:23552
	s_waitcnt vmcnt(4)
	s_barrier
	s_waitcnt lgkmcnt(0)
	s_setprio 1
	s_waitcnt lgkmcnt(0)
	v_mfma_f32_16x16x32_bf16 v[60:63], v[128:131], v[152:155], v[60:63]
	v_mfma_f32_16x16x32_bf16 v[56:59], v[140:143], v[152:155], v[56:59]
	v_mfma_f32_16x16x32_bf16 v[52:55], v[128:131], v[160:163], v[52:55]
	v_mfma_f32_16x16x32_bf16 v[48:51], v[140:143], v[160:163], v[48:51]
	v_mfma_f32_16x16x32_bf16 v[44:47], v[128:131], v[168:171], v[44:47]
	v_mfma_f32_16x16x32_bf16 v[40:43], v[140:143], v[168:171], v[40:43]
	v_mfma_f32_16x16x32_bf16 v[36:39], v[128:131], v[176:179], v[36:39]
	v_mfma_f32_16x16x32_bf16 v[32:35], v[140:143], v[176:179], v[32:35]
	v_mfma_f32_16x16x32_bf16 v[60:63], v[132:135], v[156:159], v[60:63]
	v_mfma_f32_16x16x32_bf16 v[56:59], v[148:151], v[156:159], v[56:59]
	v_mfma_f32_16x16x32_bf16 v[52:55], v[132:135], v[164:167], v[52:55]
	v_mfma_f32_16x16x32_bf16 v[48:51], v[148:151], v[164:167], v[48:51]
	v_mfma_f32_16x16x32_bf16 v[44:47], v[132:135], v[172:175], v[44:47]
	v_mfma_f32_16x16x32_bf16 v[40:43], v[148:151], v[172:175], v[40:43]
	v_mfma_f32_16x16x32_bf16 v[36:39], v[132:135], v[180:183], v[36:39]
	v_mfma_f32_16x16x32_bf16 v[32:35], v[148:151], v[180:183], v[32:35]
	s_setprio 0
	s_setprio 1
	v_mfma_f32_16x16x32_bf16 v[28:31], v[144:147], v[152:155], v[28:31]
	v_mfma_f32_16x16x32_bf16 v[24:27], v[188:191], v[152:155], v[24:27]
	v_mfma_f32_16x16x32_bf16 v[20:23], v[144:147], v[160:163], v[20:23]
	v_mfma_f32_16x16x32_bf16 v[16:19], v[188:191], v[160:163], v[16:19]
	v_mfma_f32_16x16x32_bf16 v[12:15], v[144:147], v[168:171], v[12:15]
	v_mfma_f32_16x16x32_bf16 v[8:11], v[188:191], v[168:171], v[8:11]
	v_mfma_f32_16x16x32_bf16 v[4:7], v[144:147], v[176:179], v[4:7]
	v_mfma_f32_16x16x32_bf16 v[0:3], v[188:191], v[176:179], v[0:3]
	v_mfma_f32_16x16x32_bf16 v[28:31], v[184:187], v[156:159], v[28:31]
	v_mfma_f32_16x16x32_bf16 v[24:27], v[194:197], v[156:159], v[24:27]
	v_mfma_f32_16x16x32_bf16 v[20:23], v[184:187], v[164:167], v[20:23]
	v_mfma_f32_16x16x32_bf16 v[16:19], v[194:197], v[164:167], v[16:19]
	v_mfma_f32_16x16x32_bf16 v[12:15], v[184:187], v[172:175], v[12:15]
	v_mfma_f32_16x16x32_bf16 v[8:11], v[194:197], v[172:175], v[8:11]
	v_mfma_f32_16x16x32_bf16 v[4:7], v[184:187], v[180:183], v[4:7]
	v_mfma_f32_16x16x32_bf16 v[0:3], v[194:197], v[180:183], v[0:3]
	s_setprio 0
	s_barrier
	ds_read_b128 v[140:143], v138 offset:32768
	ds_read_b128 v[152:155], v138 offset:33792
	ds_read_b128 v[156:159], v138 offset:34816
	ds_read_b128 v[160:163], v138 offset:35840
	ds_read_b128 v[164:167], v137 offset:32768
	ds_read_b128 v[168:171], v137 offset:33792
	ds_read_b128 v[172:175], v137 offset:34816
	ds_read_b128 v[176:179], v137 offset:35840
	ds_read_b128 v[180:183], v137 offset:36864
	ds_read_b128 v[184:187], v137 offset:37888
	ds_read_b128 v[188:191], v137 offset:38912
	ds_read_b128 v[194:197], v137 offset:39936
	s_waitcnt vmcnt(2)
	s_barrier
; #define WAIT_V(n) asm volatile("s_waitcnt vmcnt(" #n ")" ::: "memory")
; #define WAIT_L(n) asm volatile("s_waitcnt lgkmcnt(" #n ")" ::: "memory")
; #define BAR __builtin_amdgcn_s_barrier()
; #define LDA(dst, b, h) _Pragma("unroll") for (int m = 0; m < 4; ++m) _Pragma("unroll") for (int k = 0; k < 2; ++k) \
;     dst[m][k] = *reinterpret_cast<const bf16x8*>((char*)shm + abase + (((b) * 2 + (h)) * 16384 + (m * 2 + k) * 1024))
; #define LDB(dst, b, h) _Pragma("unroll") for (int n = 0; n < 2; ++n) _Pragma("unroll") for (int k = 0; k < 2; ++k) \
;     dst[n][k] = *reinterpret_cast<const bf16x8*>((char*)shm + bbase + (((b) * 2 + (h)) * 16384 + (n * 2 + k) * 1024))
; template <bool SWAP>
; __device__ __forceinline__ void gemm_main(const u16* __restrict__ A, const u16* __restrict__ Bt, int brow, int bcol,
;                                           u16* shm, f32x4 (&acc)[2][2][4][2]) {
;     ...
;     LDA(At, 0, 1); WAIT_V(4); BAR; WAIT_L(0); MMA(1, 0, At, B0); MMA(1, 1, At, B1); BAR; }
;   { LDB(B0, 1, 0); LDA(At, 1, 0); WAIT_V(2); BAR; WAIT_L(0); MMA(0, 0, At, B0); BAR;
;     LDB(B1, 1, 1); WAIT_V(0); BAR; WAIT_L(0); MMA(0, 1, At, B1); BAR;
;     LDA(At, 1, 1); BAR; WAIT_L(0); MMA(1, 0, At, B0); MMA(1, 1, At, B1); BAR; }
;   if (wr == 0) BAR;
	s_waitcnt lgkmcnt(0)
	s_setprio 1
	s_waitcnt lgkmcnt(0)
	v_mfma_f32_16x16x32_bf16 v[124:127], v[140:143], v[164:167], v[124:127]
	v_mfma_f32_16x16x32_bf16 v[120:123], v[156:159], v[164:167], v[120:123]
	v_mfma_f32_16x16x32_bf16 v[116:119], v[140:143], v[172:175], v[116:119]
	v_mfma_f32_16x16x32_bf16 v[112:115], v[156:159], v[172:175], v[112:115]
	v_mfma_f32_16x16x32_bf16 v[108:111], v[140:143], v[180:183], v[108:111]
	v_mfma_f32_16x16x32_bf16 v[104:107], v[156:159], v[180:183], v[104:107]
	v_mfma_f32_16x16x32_bf16 v[100:103], v[140:143], v[188:191], v[100:103]
	v_mfma_f32_16x16x32_bf16 v[96:99], v[156:159], v[188:191], v[96:99]
	v_mfma_f32_16x16x32_bf16 v[148:151], v[152:155], v[168:171], v[124:127]
	v_mfma_f32_16x16x32_bf16 v[144:147], v[160:163], v[168:171], v[120:123]
	v_mfma_f32_16x16x32_bf16 v[132:135], v[152:155], v[176:179], v[116:119]
	v_mfma_f32_16x16x32_bf16 v[128:131], v[160:163], v[176:179], v[112:115]
	v_mfma_f32_16x16x32_bf16 v[116:119], v[152:155], v[184:187], v[108:111]
	v_mfma_f32_16x16x32_bf16 v[112:115], v[160:163], v[184:187], v[104:107]
	v_mfma_f32_16x16x32_bf16 v[100:103], v[152:155], v[194:197], v[100:103]
	v_mfma_f32_16x16x32_bf16 v[96:99], v[160:163], v[194:197], v[96:99]
	s_setprio 0
	s_barrier
	ds_read_b128 v[104:107], v138 offset:49152
	ds_read_b128 v[108:111], v138 offset:50176
	ds_read_b128 v[120:123], v138 offset:51200
	ds_read_b128 v[124:127], v138 offset:52224
	s_waitcnt vmcnt(0)
	s_barrier
	s_waitcnt lgkmcnt(0)
	s_setprio 1
	s_waitcnt lgkmcnt(0)
	v_mfma_f32_16x16x32_bf16 v[92:95], v[104:107], v[164:167], v[92:95]
	v_mfma_f32_16x16x32_bf16 v[88:91], v[120:123], v[164:167], v[88:91]
	v_mfma_f32_16x16x32_bf16 v[84:87], v[104:107], v[172:175], v[84:87]
	v_mfma_f32_16x16x32_bf16 v[80:83], v[120:123], v[172:175], v[80:83]
	v_mfma_f32_16x16x32_bf16 v[76:79], v[104:107], v[180:183], v[76:79]
	v_mfma_f32_16x16x32_bf16 v[72:75], v[120:123], v[180:183], v[72:75]
	v_mfma_f32_16x16x32_bf16 v[68:71], v[104:107], v[188:191], v[68:71]
	v_mfma_f32_16x16x32_bf16 v[64:67], v[120:123], v[188:191], v[64:67]
	v_mfma_f32_16x16x32_bf16 v[92:95], v[108:111], v[168:171], v[92:95]
	v_mfma_f32_16x16x32_bf16 v[88:91], v[124:127], v[168:171], v[88:91]
	v_mfma_f32_16x16x32_bf16 v[84:87], v[108:111], v[176:179], v[84:87]
	v_mfma_f32_16x16x32_bf16 v[80:83], v[124:127], v[176:179], v[80:83]
	v_mfma_f32_16x16x32_bf16 v[76:79], v[108:111], v[184:187], v[76:79]
	v_mfma_f32_16x16x32_bf16 v[72:75], v[124:127], v[184:187], v[72:75]
	v_mfma_f32_16x16x32_bf16 v[68:71], v[108:111], v[194:197], v[68:71]
	v_mfma_f32_16x16x32_bf16 v[64:67], v[124:127], v[194:197], v[64:67]
	s_setprio 0
	s_barrier
	ds_read_b128 v[164:167], v137 offset:49152
	ds_read_b128 v[168:171], v137 offset:50176
	ds_read_b128 v[172:175], v137 offset:51200
	ds_read_b128 v[176:179], v137 offset:52224
	ds_read_b128 v[180:183], v137 offset:53248
	ds_read_b128 v[184:187], v137 offset:54272
	ds_read_b128 v[188:191], v137 offset:55296
	ds_read_b128 v[194:197], v137 offset:56320
	s_barrier
	s_waitcnt lgkmcnt(0)
	s_setprio 1
	s_waitcnt lgkmcnt(0)
	v_mfma_f32_16x16x32_bf16 v[60:63], v[140:143], v[164:167], v[60:63]
	v_mfma_f32_16x16x32_bf16 v[56:59], v[156:159], v[164:167], v[56:59]
	v_mfma_f32_16x16x32_bf16 v[52:55], v[140:143], v[172:175], v[52:55]
	v_mfma_f32_16x16x32_bf16 v[48:51], v[156:159], v[172:175], v[48:51]
	v_mfma_f32_16x16x32_bf16 v[44:47], v[140:143], v[180:183], v[44:47]
	v_mfma_f32_16x16x32_bf16 v[40:43], v[156:159], v[180:183], v[40:43]
	v_mfma_f32_16x16x32_bf16 v[36:39], v[140:143], v[188:191], v[36:39]
	v_mfma_f32_16x16x32_bf16 v[32:35], v[156:159], v[188:191], v[32:35]
	v_mfma_f32_16x16x32_bf16 v[60:63], v[152:155], v[168:171], v[60:63]
	v_mfma_f32_16x16x32_bf16 v[56:59], v[160:163], v[168:171], v[56:59]
	v_mfma_f32_16x16x32_bf16 v[52:55], v[152:155], v[176:179], v[52:55]
	v_mfma_f32_16x16x32_bf16 v[48:51], v[160:163], v[176:179], v[48:51]
	v_mfma_f32_16x16x32_bf16 v[44:47], v[152:155], v[184:187], v[44:47]
	v_mfma_f32_16x16x32_bf16 v[40:43], v[160:163], v[184:187], v[40:43]
	v_mfma_f32_16x16x32_bf16 v[36:39], v[152:155], v[194:197], v[36:39]
	v_mfma_f32_16x16x32_bf16 v[32:35], v[160:163], v[194:197], v[32:35]
	s_setprio 0
	s_setprio 1
	v_mfma_f32_16x16x32_bf16 v[28:31], v[104:107], v[164:167], v[28:31]
	v_mfma_f32_16x16x32_bf16 v[24:27], v[120:123], v[164:167], v[24:27]
	v_mfma_f32_16x16x32_bf16 v[20:23], v[104:107], v[172:175], v[20:23]
	v_mfma_f32_16x16x32_bf16 v[16:19], v[120:123], v[172:175], v[16:19]
	v_mfma_f32_16x16x32_bf16 v[12:15], v[104:107], v[180:183], v[12:15]
	v_mfma_f32_16x16x32_bf16 v[8:11], v[120:123], v[180:183], v[8:11]
	v_mfma_f32_16x16x32_bf16 v[4:7], v[104:107], v[188:191], v[4:7]
	v_mfma_f32_16x16x32_bf16 v[0:3], v[120:123], v[188:191], v[0:3]
	v_mfma_f32_16x16x32_bf16 v[28:31], v[108:111], v[168:171], v[28:31]
	v_mfma_f32_16x16x32_bf16 v[24:27], v[124:127], v[168:171], v[24:27]
	v_mfma_f32_16x16x32_bf16 v[20:23], v[108:111], v[176:179], v[20:23]
	v_mfma_f32_16x16x32_bf16 v[16:19], v[124:127], v[176:179], v[16:19]
	v_mfma_f32_16x16x32_bf16 v[12:15], v[108:111], v[184:187], v[12:15]
	v_mfma_f32_16x16x32_bf16 v[8:11], v[124:127], v[184:187], v[8:11]
	v_mfma_f32_16x16x32_bf16 v[4:7], v[108:111], v[194:197], v[4:7]
	v_mfma_f32_16x16x32_bf16 v[0:3], v[124:127], v[194:197], v[0:3]
	s_setprio 0
	s_movk_i32 s3, 0x100
	v_cmp_gt_u32_e32 vcc, s3, v136
	s_barrier
	s_and_saveexec_b64 s[4:5], vcc
	s_cbranch_execz .LBB0_573
	s_barrier

; #define WAIT_V(n) asm volatile("s_waitcnt vmcnt(" #n ")" ::: "memory")
; #define BAR __builtin_amdgcn_s_barrier()
; template <bool SWAP>
; __device__ __forceinline__ void gemm_main(const u16* __restrict__ A, const u16* __restrict__ Bt, int brow, int bcol,
;                                           u16* shm, f32x4 (&acc)[2][2][4][2]) {
;     ...
;   int tx = threadIdx.x; asm volatile("" : "+v"(tx));
;   const int wid = tx >> 6, lane = tx & 63, wr = wid >> 2, wc = wid & 3, fr = lane & 15, fq = lane >> 4;
; #pragma unroll
;   for (int a = 0; a < 2; ++a)
; #pragma unroll
;     for (int b = 0; b < 2; ++b)
; #pragma unroll
;       for (int m = 0; m < 4; ++m)
; #pragma unroll
;         for (int n = 0; n < 2; ++n) acc[a][b][m][n] = f32x4{0.f, 0.f, 0.f, 0.f};
;   bf16x8 At[4][2], B0[2][2], B1[2][2];
;   constexpr int nt = GK / BK;
;   GEMM_VOFF
;   const int lpart = (fr * 64 + fq * 16) ^ ((fr >> 3) << 5);
;   const int abase = wr * 8192 + lpart; int bbase = 65536 + wc * 4096 + lpart;
;   asm volatile("" : "+v"(bbase));
;   if (wr == 1) BAR;
;   WAIT_V(0); BAR;
;   BAR;
.LBB0_575:
	s_or_b64 exec, exec, s[4:5]
	v_bfe_i32 v4, v136, 27, 1
	v_lshlrev_b32_e32 v140, 4, v136
	v_lshrrev_b32_e32 v4, 22, v4
	v_add_u32_e32 v4, v140, v4
	v_and_b32_e32 v4, 0xfffffc00, v4
	v_sub_u32_e32 v4, v140, v4
	v_lshrrev_b32_e32 v5, 4, v4
	v_bitop3_b32 v4, v5, v4, 32 bitop3:0x6c
	v_ashrrev_i32_e32 v5, 31, v4
	v_lshrrev_b32_e32 v5, 26, v5
	v_add_u32_e32 v5, v4, v5
	v_ashrrev_i32_e32 v141, 6, v5
	v_and_b32_e32 v5, 0xc0, v5
	v_sub_u32_e32 v4, v4, v5
	v_ashrrev_i16_sdwa v4, v215, sext(v4) dst_sel:DWORD dst_unused:UNUSED_PAD src0_sel:DWORD src1_sel:BYTE_0
	v_bfe_i32 v142, v4, 0, 16
	v_add_u32_e32 v4, 0x2000, v140
	v_ashrrev_i32_e32 v5, 31, v4
	v_lshrrev_b32_e32 v5, 22, v5
	v_add_u32_e32 v5, v4, v5
	v_ashrrev_i32_e32 v143, 10, v5
	v_mul_i32_i24_e32 v5, 0x400, v143
	v_sub_u32_e32 v4, v4, v5
	v_lshrrev_b32_e32 v5, 4, v4
	v_bitop3_b32 v4, v5, v4, 32 bitop3:0x6c
	v_ashrrev_i32_e32 v5, 31, v4
	v_lshrrev_b32_e32 v5, 26, v5
	v_ashrrev_i32_e32 v3, 31, v136
	v_add_u32_e32 v5, v4, v5
	v_lshrrev_b32_e32 v3, 26, v3
	v_ashrrev_i32_e32 v144, 6, v5
	v_and_b32_e32 v5, 0xc0, v5
	v_add_u32_e32 v3, v136, v3
	v_sub_u32_e32 v4, v4, v5
	v_ashrrev_i32_e32 v139, 6, v3
	v_ashrrev_i16_sdwa v4, v215, sext(v4) dst_sel:DWORD dst_unused:UNUSED_PAD src0_sel:DWORD src1_sel:BYTE_0
	v_bfe_i32 v145, v4, 0, 16
	v_lshlrev_b32_e32 v4, 13, v0
	v_lshlrev_b32_e32 v0, 15, v139
	v_and_b32_e32 v0, 0xffff0000, v0
	v_lshl_add_u32 v0, v141, 12, v0
	v_and_or_b32 v0, v3, 64, v0
	v_lshl_add_u32 v192, v142, 1, v0
	v_lshlrev_b32_e32 v0, 15, v143
	v_and_b32_e32 v0, 0xffff0000, v0
	v_add_u32_e32 v5, 0, v2
	v_lshl_add_u32 v0, v144, 12, v0
	v_lshlrev_b32_e32 v2, 6, v143
	s_waitcnt vmcnt(0)
	v_readlane_b32 s2, v253, 59
	v_and_or_b32 v0, v2, 64, v0
	v_readlane_b32 s3, v253, 60
	v_lshl_add_u32 v2, v145, 1, v0
	v_mov_b32_e32 v3, v193
	v_mov_b32_e32 v0, 0
	v_lshl_add_u64 v[128:129], s[2:3], 0, v[192:193]
	v_lshl_add_u64 v[130:131], s[2:3], 0, v[2:3]
	v_lshl_add_u64 v[132:133], s[10:11], 0, v[192:193]
	v_lshl_add_u64 v[134:135], s[10:11], 0, v[2:3]
	s_mov_b32 s2, -2
	v_add_u32_e32 v138, 0, v1
	v_add_u32_e32 v137, v5, v4
	s_mov_b64 s[4:5], s[50:51]
	v_mov_b32_e32 v1, v0
	v_mov_b32_e32 v2, v0
	v_mov_b32_e32 v3, v0
	v_mov_b32_e32 v4, v0
	v_mov_b32_e32 v5, v0
	v_mov_b32_e32 v6, v0
	v_mov_b32_e32 v7, v0
	v_mov_b32_e32 v8, v0
	v_mov_b32_e32 v9, v0
	v_mov_b32_e32 v10, v0
	v_mov_b32_e32 v11, v0
	v_mov_b32_e32 v12, v0
	v_mov_b32_e32 v13, v0
	v_mov_b32_e32 v14, v0
	v_mov_b32_e32 v15, v0
	v_mov_b32_e32 v16, v0
	v_mov_b32_e32 v17, v0
	v_mov_b32_e32 v18, v0
	v_mov_b32_e32 v19, v0
	v_mov_b32_e32 v20, v0
	v_mov_b32_e32 v21, v0
	v_mov_b32_e32 v22, v0
	v_mov_b32_e32 v23, v0
	v_mov_b32_e32 v24, v0
	v_mov_b32_e32 v25, v0
	v_mov_b32_e32 v26, v0
	v_mov_b32_e32 v27, v0
	v_mov_b32_e32 v28, v0
	v_mov_b32_e32 v29, v0
	v_mov_b32_e32 v30, v0
	v_mov_b32_e32 v31, v0
	v_mov_b32_e32 v32, v0
	v_mov_b32_e32 v33, v0
	v_mov_b32_e32 v34, v0
	v_mov_b32_e32 v35, v0
	v_mov_b32_e32 v36, v0
	v_mov_b32_e32 v37, v0
	v_mov_b32_e32 v38, v0
	v_mov_b32_e32 v39, v0
	v_mov_b32_e32 v40, v0
	v_mov_b32_e32 v41, v0
	v_mov_b32_e32 v42, v0
	v_mov_b32_e32 v43, v0
	v_mov_b32_e32 v44, v0
	v_mov_b32_e32 v45, v0
	v_mov_b32_e32 v46, v0
	v_mov_b32_e32 v47, v0
	v_mov_b32_e32 v48, v0
	v_mov_b32_e32 v49, v0
	v_mov_b32_e32 v50, v0
	v_mov_b32_e32 v51, v0
	v_mov_b32_e32 v52, v0
	v_mov_b32_e32 v53, v0
	v_mov_b32_e32 v54, v0
	v_mov_b32_e32 v55, v0
	v_mov_b32_e32 v56, v0
	v_mov_b32_e32 v57, v0
	v_mov_b32_e32 v58, v0
	v_mov_b32_e32 v59, v0
	v_mov_b32_e32 v60, v0
	v_mov_b32_e32 v61, v0
	v_mov_b32_e32 v62, v0
	v_mov_b32_e32 v63, v0
	v_mov_b32_e32 v64, v0
	v_mov_b32_e32 v65, v0
	v_mov_b32_e32 v66, v0
	v_mov_b32_e32 v67, v0
	v_mov_b32_e32 v68, v0
	v_mov_b32_e32 v69, v0
	v_mov_b32_e32 v70, v0
	v_mov_b32_e32 v71, v0
	v_mov_b32_e32 v72, v0
	v_mov_b32_e32 v73, v0
	v_mov_b32_e32 v74, v0
	v_mov_b32_e32 v75, v0
	v_mov_b32_e32 v76, v0
	v_mov_b32_e32 v77, v0
	v_mov_b32_e32 v78, v0
	v_mov_b32_e32 v79, v0
	v_mov_b32_e32 v80, v0
	v_mov_b32_e32 v81, v0
	v_mov_b32_e32 v82, v0
	v_mov_b32_e32 v83, v0
	v_mov_b32_e32 v84, v0
	v_mov_b32_e32 v85, v0
	v_mov_b32_e32 v86, v0
	v_mov_b32_e32 v87, v0
	v_mov_b32_e32 v88, v0
	v_mov_b32_e32 v89, v0
	v_mov_b32_e32 v90, v0
	v_mov_b32_e32 v91, v0
	v_mov_b32_e32 v92, v0
	v_mov_b32_e32 v93, v0
	v_mov_b32_e32 v94, v0
	v_mov_b32_e32 v95, v0
	v_mov_b32_e32 v96, v0
	v_mov_b32_e32 v97, v0
	v_mov_b32_e32 v98, v0
	v_mov_b32_e32 v99, v0
	v_mov_b32_e32 v100, v0
	v_mov_b32_e32 v101, v0
	v_mov_b32_e32 v102, v0
	v_mov_b32_e32 v103, v0
	v_mov_b32_e32 v104, v0
	v_mov_b32_e32 v105, v0
	v_mov_b32_e32 v106, v0
	v_mov_b32_e32 v107, v0
	v_mov_b32_e32 v108, v0
	v_mov_b32_e32 v109, v0
	v_mov_b32_e32 v110, v0
	v_mov_b32_e32 v111, v0
	v_mov_b32_e32 v112, v0
	v_mov_b32_e32 v113, v0
	v_mov_b32_e32 v114, v0
	v_mov_b32_e32 v115, v0
	v_mov_b32_e32 v116, v0
	v_mov_b32_e32 v117, v0
	v_mov_b32_e32 v118, v0
	v_mov_b32_e32 v119, v0
	v_mov_b32_e32 v120, v0
	v_mov_b32_e32 v121, v0
	v_mov_b32_e32 v122, v0
	v_mov_b32_e32 v123, v0
	v_mov_b32_e32 v124, v0
	v_mov_b32_e32 v125, v0
	v_mov_b32_e32 v126, v0
	v_mov_b32_e32 v127, v0
	s_mov_b64 s[10:11], 0x27580080
	s_mov_b64 s[12:13], 0x9100100
	s_mov_b64 s[14:15], 0x27500100
	v_readfirstlane_b32 s3, v140
	s_barrier
	s_barrier
; #define WAIT_V(n) asm volatile("s_waitcnt vmcnt(" #n ")" ::: "memory")
; #define WAIT_L(n) asm volatile("s_waitcnt lgkmcnt(" #n ")" ::: "memory")
; #define BAR __builtin_amdgcn_s_barrier()
; #define SCHED __builtin_amdgcn_sched_barrier(0)
; #define STAGE(P, BASE, br, kt) do { const char* _g = (const char*)((BASE) + (size_t)(br) * GK + (kt) * BK); \
;     __builtin_amdgcn_global_load_lds((const unsigned*)(_g + voff0), (unsigned*)((char*)(P) + tx * 16), 16, 0, 0); \
;     __builtin_amdgcn_global_load_lds((const unsigned*)(_g + voff1), (unsigned*)((char*)(P) + tx * 16 + 8192), 16, 0, 0); } while (0)
; #define LDA(dst, b, h) _Pragma("unroll") for (int m = 0; m < 4; ++m) _Pragma("unroll") for (int k = 0; k < 2; ++k) \
;     dst[m][k] = *reinterpret_cast<const bf16x8*>((char*)shm + abase + (((b) * 2 + (h)) * 16384 + (m * 2 + k) * 1024))
; #define LDB(dst, b, h) _Pragma("unroll") for (int n = 0; n < 2; ++n) _Pragma("unroll") for (int k = 0; k < 2; ++k) \
;     dst[n][k] = *reinterpret_cast<const bf16x8*>((char*)shm + bbase + (((b) * 2 + (h)) * 16384 + (n * 2 + k) * 1024))
; template <bool SWAP>
; __device__ __forceinline__ void gemm_main(const u16* __restrict__ A, const u16* __restrict__ Bt, int brow, int bcol,
;                                           u16* shm, f32x4 (&acc)[2][2][4][2]) {
;     ...
;   for (int t = 0; t < nt - 2; t += 2) {
;     LDB(B0, 0, 0); SCHED; LDA(At, 0, 0); STAGE(SA(1, 1), A, brow + HALF, t + 1);
;     WAIT_L(8); BAR; WAIT_L(0); MMA(0, 0, At, B0); BAR; SCHED;
;     LDB(B1, 0, 1); STAGE(SB(0, 0), Bt, bcol, t + 2);
;     BAR; WAIT_L(0); MMA(0, 1, At, B1); BAR;
;     LDA(At, 0, 1); STAGE(SA(0, 0), A, brow, t + 2);
;     BAR; WAIT_L(0); MMA(1, 0, At, B0); BAR; SCHED;
;     STAGE(SB(0, 1), Bt, bcol + HALF, t + 2);
;     WAIT_V(6); BAR; MMA(1, 1, At, B1); BAR;
.LBB0_576:
	ds_read_b128 v[148:151], v138
	ds_read_b128 v[152:155], v138 offset:1024
	ds_read_b128 v[156:159], v138 offset:2048
	ds_read_b128 v[160:163], v138 offset:3072
	ds_read_b128 v[164:167], v137
	ds_read_b128 v[168:171], v137 offset:1024
	ds_read_b128 v[172:175], v137 offset:2048
	ds_read_b128 v[176:179], v137 offset:3072
	ds_read_b128 v[180:183], v137 offset:4096
	ds_read_b128 v[184:187], v137 offset:5120
	ds_read_b128 v[188:191], v137 offset:6144
	ds_read_b128 v[194:197], v137 offset:7168
	v_add_u32_e32 v192, 0, v140
	v_add_u32_e32 v146, 0xc000, v192
	v_lshl_add_u64 v[230:231], s[4:5], 0, v[132:133]
	v_add_u32_e32 v147, 0xe000, v192
	v_lshl_add_u64 v[198:199], v[230:231], 0, s[10:11]
	s_add_u32 m0, s3, 0xc000
	v_lshl_add_u64 v[232:233], s[4:5], 0, v[134:135]
	global_load_lds_dwordx4 v[198:199], off
	v_lshl_add_u64 v[198:199], v[232:233], 0, s[10:11]
	s_add_u32 m0, s3, 0xe000
	s_nop 0
	global_load_lds_dwordx4 v[198:199], off
	s_waitcnt lgkmcnt(8)
	s_setprio 1
	s_barrier
	s_waitcnt lgkmcnt(0)
	v_mfma_f32_16x16x32_bf16 v[124:127], v[148:151], v[164:167], v[124:127]
	v_mfma_f32_16x16x32_bf16 v[120:123], v[156:159], v[164:167], v[120:123]
	v_mfma_f32_16x16x32_bf16 v[116:119], v[148:151], v[172:175], v[116:119]
	v_mfma_f32_16x16x32_bf16 v[112:115], v[156:159], v[172:175], v[112:115]
	v_mfma_f32_16x16x32_bf16 v[108:111], v[148:151], v[180:183], v[108:111]
	v_mfma_f32_16x16x32_bf16 v[104:107], v[156:159], v[180:183], v[104:107]
	v_mfma_f32_16x16x32_bf16 v[100:103], v[148:151], v[188:191], v[100:103]
	v_mfma_f32_16x16x32_bf16 v[96:99], v[156:159], v[188:191], v[96:99]
	v_mfma_f32_16x16x32_bf16 v[124:127], v[152:155], v[168:171], v[124:127]
	v_mfma_f32_16x16x32_bf16 v[120:123], v[160:163], v[168:171], v[120:123]
	v_mfma_f32_16x16x32_bf16 v[116:119], v[152:155], v[176:179], v[116:119]
	v_mfma_f32_16x16x32_bf16 v[112:115], v[160:163], v[176:179], v[112:115]
	v_mfma_f32_16x16x32_bf16 v[108:111], v[152:155], v[184:187], v[108:111]
	v_mfma_f32_16x16x32_bf16 v[104:107], v[160:163], v[184:187], v[104:107]
	v_mfma_f32_16x16x32_bf16 v[100:103], v[152:155], v[194:197], v[100:103]
	v_mfma_f32_16x16x32_bf16 v[96:99], v[160:163], v[194:197], v[96:99]
	s_barrier
	s_setprio 0
	ds_read_b128 v[198:201], v138 offset:16384
	ds_read_b128 v[202:205], v138 offset:17408
	ds_read_b128 v[206:209], v138 offset:18432
	ds_read_b128 v[226:229], v138 offset:19456
	v_lshl_add_u64 v[234:235], s[4:5], 0, v[128:129]
	v_lshl_add_u64 v[236:237], v[234:235], 0, s[12:13]
	s_add_u32 m0, s3, s28
	s_nop 0
	global_load_lds_dwordx4 v[236:237], off
	v_lshl_add_u64 v[236:237], s[4:5], 0, v[130:131]
	v_lshl_add_u64 v[238:239], v[236:237], 0, s[12:13]
	s_add_u32 m0, s3, s28
	s_add_u32 m0, m0, 0x2000
	s_nop 0
	global_load_lds_dwordx4 v[238:239], off
	s_setprio 1
	s_barrier
	s_waitcnt lgkmcnt(0)
	v_mfma_f32_16x16x32_bf16 v[92:95], v[198:201], v[164:167], v[92:95]
	v_mfma_f32_16x16x32_bf16 v[88:91], v[206:209], v[164:167], v[88:91]
	v_mfma_f32_16x16x32_bf16 v[84:87], v[198:201], v[172:175], v[84:87]
	v_mfma_f32_16x16x32_bf16 v[80:83], v[206:209], v[172:175], v[80:83]
	v_mfma_f32_16x16x32_bf16 v[76:79], v[198:201], v[180:183], v[76:79]
	v_mfma_f32_16x16x32_bf16 v[72:75], v[206:209], v[180:183], v[72:75]
	v_mfma_f32_16x16x32_bf16 v[68:71], v[198:201], v[188:191], v[68:71]
	v_mfma_f32_16x16x32_bf16 v[64:67], v[206:209], v[188:191], v[64:67]
	v_mfma_f32_16x16x32_bf16 v[92:95], v[202:205], v[168:171], v[92:95]
	v_mfma_f32_16x16x32_bf16 v[88:91], v[226:229], v[168:171], v[88:91]
	v_mfma_f32_16x16x32_bf16 v[84:87], v[202:205], v[176:179], v[84:87]
	v_mfma_f32_16x16x32_bf16 v[80:83], v[226:229], v[176:179], v[80:83]
	v_mfma_f32_16x16x32_bf16 v[76:79], v[202:205], v[184:187], v[76:79]
	v_mfma_f32_16x16x32_bf16 v[72:75], v[226:229], v[184:187], v[72:75]
	v_mfma_f32_16x16x32_bf16 v[68:71], v[202:205], v[194:197], v[68:71]
	v_mfma_f32_16x16x32_bf16 v[64:67], v[226:229], v[194:197], v[64:67]
	s_barrier
	s_setprio 0
	ds_read_b128 v[164:167], v137 offset:16384
	ds_read_b128 v[168:171], v137 offset:17408
	ds_read_b128 v[172:175], v137 offset:18432
	ds_read_b128 v[176:179], v137 offset:19456
	ds_read_b128 v[180:183], v137 offset:20480
	ds_read_b128 v[184:187], v137 offset:21504
	ds_read_b128 v[188:191], v137 offset:22528
	ds_read_b128 v[194:197], v137 offset:23552
	v_lshl_add_u64 v[238:239], v[230:231], 0, s[14:15]
	s_add_u32 m0, s3, 0x0
	s_nop 0
	global_load_lds_dwordx4 v[238:239], off
	v_lshl_add_u64 v[238:239], v[232:233], 0, s[14:15]
	s_add_u32 m0, s3, 0x2000
	s_nop 0
	global_load_lds_dwordx4 v[238:239], off
	s_setprio 1
	s_barrier
	s_waitcnt lgkmcnt(0)
	v_mfma_f32_16x16x32_bf16 v[60:63], v[148:151], v[164:167], v[60:63]
	v_mfma_f32_16x16x32_bf16 v[56:59], v[156:159], v[164:167], v[56:59]
	v_mfma_f32_16x16x32_bf16 v[52:55], v[148:151], v[172:175], v[52:55]
	v_mfma_f32_16x16x32_bf16 v[48:51], v[156:159], v[172:175], v[48:51]
	v_mfma_f32_16x16x32_bf16 v[44:47], v[148:151], v[180:183], v[44:47]
	v_mfma_f32_16x16x32_bf16 v[40:43], v[156:159], v[180:183], v[40:43]
	v_mfma_f32_16x16x32_bf16 v[36:39], v[148:151], v[188:191], v[36:39]
	v_mfma_f32_16x16x32_bf16 v[32:35], v[156:159], v[188:191], v[32:35]
	v_mfma_f32_16x16x32_bf16 v[60:63], v[152:155], v[168:171], v[60:63]
	v_mfma_f32_16x16x32_bf16 v[56:59], v[160:163], v[168:171], v[56:59]
	v_mfma_f32_16x16x32_bf16 v[52:55], v[152:155], v[176:179], v[52:55]
	v_mfma_f32_16x16x32_bf16 v[48:51], v[160:163], v[176:179], v[48:51]
	v_mfma_f32_16x16x32_bf16 v[44:47], v[152:155], v[184:187], v[44:47]
	v_mfma_f32_16x16x32_bf16 v[40:43], v[160:163], v[184:187], v[40:43]
	v_mfma_f32_16x16x32_bf16 v[36:39], v[152:155], v[194:197], v[36:39]
	v_mfma_f32_16x16x32_bf16 v[32:35], v[160:163], v[194:197], v[32:35]
	s_barrier
; #define WAIT_V(n) asm volatile("s_waitcnt vmcnt(" #n ")" ::: "memory")
; #define WAIT_L(n) asm volatile("s_waitcnt lgkmcnt(" #n ")" ::: "memory")
; #define BAR __builtin_amdgcn_s_barrier()
; #define SCHED __builtin_amdgcn_sched_barrier(0)
; #define STAGE(P, BASE, br, kt) do { const char* _g = (const char*)((BASE) + (size_t)(br) * GK + (kt) * BK); \
;     __builtin_amdgcn_global_load_lds((const unsigned*)(_g + voff0), (unsigned*)((char*)(P) + tx * 16), 16, 0, 0); \
;     __builtin_amdgcn_global_load_lds((const unsigned*)(_g + voff1), (unsigned*)((char*)(P) + tx * 16 + 8192), 16, 0, 0); } while (0)
; #define LDA(dst, b, h) _Pragma("unroll") for (int m = 0; m < 4; ++m) _Pragma("unroll") for (int k = 0; k < 2; ++k) \
;     dst[m][k] = *reinterpret_cast<const bf16x8*>((char*)shm + abase + (((b) * 2 + (h)) * 16384 + (m * 2 + k) * 1024))
; #define LDB(dst, b, h) _Pragma("unroll") for (int n = 0; n < 2; ++n) _Pragma("unroll") for (int k = 0; k < 2; ++k) \
;     dst[n][k] = *reinterpret_cast<const bf16x8*>((char*)shm + bbase + (((b) * 2 + (h)) * 16384 + (n * 2 + k) * 1024))
; template <bool SWAP>
; __device__ __forceinline__ void gemm_main(const u16* __restrict__ A, const u16* __restrict__ Bt, int brow, int bcol,
;                                           u16* shm, f32x4 (&acc)[2][2][4][2]) {
;     ...
;     WAIT_V(6); BAR; MMA(1, 1, At, B1); BAR;
;     LDB(B0, 1, 0); SCHED; LDA(At, 1, 0); STAGE(SA(0, 1), A, brow + HALF, t + 2);
;     WAIT_L(8); BAR; WAIT_L(0); MMA(0, 0, At, B0); BAR; SCHED;
;     LDB(B1, 1, 1); STAGE(SB(1, 0), Bt, bcol, t + 3);
;     BAR; WAIT_L(0); MMA(0, 1, At, B1); BAR;
;     LDA(At, 1, 1); STAGE(SA(1, 0), A, brow, t + 3);
;     BAR; WAIT_L(0); MMA(1, 0, At, B0); BAR; SCHED;
	s_setprio 0
	v_lshl_add_u64 v[148:149], v[234:235], 0, s[80:81]
	s_add_u32 m0, s3, s29
	s_nop 0
	global_load_lds_dwordx4 v[148:149], off
	v_lshl_add_u64 v[148:149], v[236:237], 0, s[80:81]
	s_add_u32 m0, s3, s29
	s_add_u32 m0, m0, 0x2000
	s_nop 0
	global_load_lds_dwordx4 v[148:149], off
	s_waitcnt vmcnt(6)
	s_setprio 1
	s_barrier
	v_mfma_f32_16x16x32_bf16 v[28:31], v[198:201], v[164:167], v[28:31]
	v_mfma_f32_16x16x32_bf16 v[24:27], v[206:209], v[164:167], v[24:27]
	v_mfma_f32_16x16x32_bf16 v[20:23], v[198:201], v[172:175], v[20:23]
	v_mfma_f32_16x16x32_bf16 v[16:19], v[206:209], v[172:175], v[16:19]
	v_mfma_f32_16x16x32_bf16 v[12:15], v[198:201], v[180:183], v[12:15]
	v_mfma_f32_16x16x32_bf16 v[8:11], v[206:209], v[180:183], v[8:11]
	v_mfma_f32_16x16x32_bf16 v[4:7], v[198:201], v[188:191], v[4:7]
	v_mfma_f32_16x16x32_bf16 v[0:3], v[206:209], v[188:191], v[0:3]
	v_mfma_f32_16x16x32_bf16 v[28:31], v[202:205], v[168:171], v[28:31]
	v_mfma_f32_16x16x32_bf16 v[24:27], v[226:229], v[168:171], v[24:27]
	v_mfma_f32_16x16x32_bf16 v[20:23], v[202:205], v[176:179], v[20:23]
	v_mfma_f32_16x16x32_bf16 v[16:19], v[226:229], v[176:179], v[16:19]
	v_mfma_f32_16x16x32_bf16 v[12:15], v[202:205], v[184:187], v[12:15]
	v_mfma_f32_16x16x32_bf16 v[8:11], v[226:229], v[184:187], v[8:11]
	v_mfma_f32_16x16x32_bf16 v[4:7], v[202:205], v[194:197], v[4:7]
	v_mfma_f32_16x16x32_bf16 v[0:3], v[226:229], v[194:197], v[0:3]
	s_barrier
	s_setprio 0
	ds_read_b128 v[148:151], v138 offset:32768
	ds_read_b128 v[152:155], v138 offset:33792
	ds_read_b128 v[156:159], v138 offset:34816
	ds_read_b128 v[160:163], v138 offset:35840
	ds_read_b128 v[164:167], v137 offset:32768
	ds_read_b128 v[168:171], v137 offset:33792
	ds_read_b128 v[172:175], v137 offset:34816
	ds_read_b128 v[176:179], v137 offset:35840
	ds_read_b128 v[180:183], v137 offset:36864
	ds_read_b128 v[184:187], v137 offset:37888
	ds_read_b128 v[188:191], v137 offset:38912
	ds_read_b128 v[194:197], v137 offset:39936
	v_lshl_add_u64 v[198:199], v[230:231], 0, s[66:67]
	s_add_u32 m0, s3, 0x4000
	s_nop 0
	global_load_lds_dwordx4 v[198:199], off
	v_lshl_add_u64 v[198:199], v[232:233], 0, s[66:67]
	s_add_u32 m0, s3, 0x6000
	s_nop 0
	global_load_lds_dwordx4 v[198:199], off
	s_waitcnt lgkmcnt(8)
	s_setprio 1
	s_barrier
	s_waitcnt lgkmcnt(0)
	v_mfma_f32_16x16x32_bf16 v[124:127], v[148:151], v[164:167], v[124:127]
	v_mfma_f32_16x16x32_bf16 v[120:123], v[156:159], v[164:167], v[120:123]
	v_mfma_f32_16x16x32_bf16 v[116:119], v[148:151], v[172:175], v[116:119]
	v_mfma_f32_16x16x32_bf16 v[112:115], v[156:159], v[172:175], v[112:115]
	v_mfma_f32_16x16x32_bf16 v[108:111], v[148:151], v[180:183], v[108:111]
	v_mfma_f32_16x16x32_bf16 v[104:107], v[156:159], v[180:183], v[104:107]
	v_mfma_f32_16x16x32_bf16 v[100:103], v[148:151], v[188:191], v[100:103]
	v_mfma_f32_16x16x32_bf16 v[96:99], v[156:159], v[188:191], v[96:99]
	v_mfma_f32_16x16x32_bf16 v[124:127], v[152:155], v[168:171], v[124:127]
	v_mfma_f32_16x16x32_bf16 v[120:123], v[160:163], v[168:171], v[120:123]
	v_mfma_f32_16x16x32_bf16 v[116:119], v[152:155], v[176:179], v[116:119]
	v_mfma_f32_16x16x32_bf16 v[112:115], v[160:163], v[176:179], v[112:115]
	v_mfma_f32_16x16x32_bf16 v[108:111], v[152:155], v[184:187], v[108:111]
	v_mfma_f32_16x16x32_bf16 v[104:107], v[160:163], v[184:187], v[104:107]
	v_mfma_f32_16x16x32_bf16 v[100:103], v[152:155], v[194:197], v[100:103]
	v_mfma_f32_16x16x32_bf16 v[96:99], v[160:163], v[194:197], v[96:99]
	s_barrier
	s_setprio 0
	ds_read_b128 v[198:201], v138 offset:49152
	ds_read_b128 v[202:205], v138 offset:50176
	ds_read_b128 v[206:209], v138 offset:51200
	ds_read_b128 v[226:229], v138 offset:52224
	v_lshl_add_u64 v[238:239], v[234:235], 0, s[86:87]
	s_add_u32 m0, s3, s30
	s_nop 0
	global_load_lds_dwordx4 v[238:239], off
	v_lshl_add_u64 v[238:239], v[236:237], 0, s[86:87]
	s_add_u32 m0, s3, s30
	s_add_u32 m0, m0, 0x2000
	s_nop 0
	global_load_lds_dwordx4 v[238:239], off
	s_setprio 1
	s_barrier
	s_waitcnt lgkmcnt(0)
	v_mfma_f32_16x16x32_bf16 v[92:95], v[198:201], v[164:167], v[92:95]
	v_mfma_f32_16x16x32_bf16 v[88:91], v[206:209], v[164:167], v[88:91]
	v_mfma_f32_16x16x32_bf16 v[84:87], v[198:201], v[172:175], v[84:87]
	v_mfma_f32_16x16x32_bf16 v[80:83], v[206:209], v[172:175], v[80:83]
	v_mfma_f32_16x16x32_bf16 v[76:79], v[198:201], v[180:183], v[76:79]
	v_mfma_f32_16x16x32_bf16 v[72:75], v[206:209], v[180:183], v[72:75]
	v_mfma_f32_16x16x32_bf16 v[68:71], v[198:201], v[188:191], v[68:71]
	v_mfma_f32_16x16x32_bf16 v[64:67], v[206:209], v[188:191], v[64:67]
	v_mfma_f32_16x16x32_bf16 v[92:95], v[202:205], v[168:171], v[92:95]
	v_mfma_f32_16x16x32_bf16 v[88:91], v[226:229], v[168:171], v[88:91]
	v_mfma_f32_16x16x32_bf16 v[84:87], v[202:205], v[176:179], v[84:87]
	v_mfma_f32_16x16x32_bf16 v[80:83], v[226:229], v[176:179], v[80:83]
	v_mfma_f32_16x16x32_bf16 v[76:79], v[202:205], v[184:187], v[76:79]
	v_mfma_f32_16x16x32_bf16 v[72:75], v[226:229], v[184:187], v[72:75]
	v_mfma_f32_16x16x32_bf16 v[68:71], v[202:205], v[194:197], v[68:71]
	v_mfma_f32_16x16x32_bf16 v[64:67], v[226:229], v[194:197], v[64:67]
	s_barrier
	s_setprio 0
	ds_read_b128 v[164:167], v137 offset:49152
	ds_read_b128 v[168:171], v137 offset:50176
	ds_read_b128 v[172:175], v137 offset:51200
	ds_read_b128 v[176:179], v137 offset:52224
	ds_read_b128 v[180:183], v137 offset:53248
	ds_read_b128 v[184:187], v137 offset:54272
	ds_read_b128 v[188:191], v137 offset:55296
	ds_read_b128 v[194:197], v137 offset:56320
	v_add_u32_e32 v225, 0x8000, v192
	v_lshl_add_u64 v[230:231], v[230:231], 0, s[26:27]
	s_add_u32 m0, s3, 0x8000
	s_nop 0
	global_load_lds_dwordx4 v[230:231], off
	v_lshl_add_u64 v[230:231], v[232:233], 0, s[26:27]
	s_add_u32 m0, s3, 0xa000
	s_nop 0
	global_load_lds_dwordx4 v[230:231], off
	s_setprio 1
	s_barrier
; #define WAIT_V(n) asm volatile("s_waitcnt vmcnt(" #n ")" ::: "memory")
; #define WAIT_L(n) asm volatile("s_waitcnt lgkmcnt(" #n ")" ::: "memory")
; #define BAR __builtin_amdgcn_s_barrier()
; #define SCHED __builtin_amdgcn_sched_barrier(0)
; #define STAGE(P, BASE, br, kt) do { const char* _g = (const char*)((BASE) + (size_t)(br) * GK + (kt) * BK); \
;     __builtin_amdgcn_global_load_lds((const unsigned*)(_g + voff0), (unsigned*)((char*)(P) + tx * 16), 16, 0, 0); \
;     __builtin_amdgcn_global_load_lds((const unsigned*)(_g + voff1), (unsigned*)((char*)(P) + tx * 16 + 8192), 16, 0, 0); } while (0)
; #define LDA(dst, b, h) _Pragma("unroll") for (int m = 0; m < 4; ++m) _Pragma("unroll") for (int k = 0; k < 2; ++k) \
;     dst[m][k] = *reinterpret_cast<const bf16x8*>((char*)shm + abase + (((b) * 2 + (h)) * 16384 + (m * 2 + k) * 1024))
; #define LDB(dst, b, h) _Pragma("unroll") for (int n = 0; n < 2; ++n) _Pragma("unroll") for (int k = 0; k < 2; ++k) \
;     dst[n][k] = *reinterpret_cast<const bf16x8*>((char*)shm + bbase + (((b) * 2 + (h)) * 16384 + (n * 2 + k) * 1024))
; template <bool SWAP>
; __device__ __forceinline__ void gemm_main(const u16* __restrict__ A, const u16* __restrict__ Bt, int brow, int bcol,
;                                           u16* shm, f32x4 (&acc)[2][2][4][2]) {
;     ...
;     BAR; WAIT_L(0); MMA(1, 0, At, B0); BAR; SCHED;
;     STAGE(SB(1, 1), Bt, bcol + HALF, t + 3);
;     WAIT_V(6); BAR; MMA(1, 1, At, B1); BAR;
;   }
;   { LDB(B0, 0, 0); LDA(At, 0, 0); STAGE(SA(1, 1), A, brow + HALF, nt - 1);
;     BAR; WAIT_L(0); MMA(0, 0, At, B0); BAR;
;     LDB(B1, 0, 1); BAR; WAIT_L(0); MMA(0, 1, At, B1); BAR;
	s_waitcnt lgkmcnt(0)
	v_mfma_f32_16x16x32_bf16 v[60:63], v[148:151], v[164:167], v[60:63]
	v_mfma_f32_16x16x32_bf16 v[56:59], v[156:159], v[164:167], v[56:59]
	v_mfma_f32_16x16x32_bf16 v[52:55], v[148:151], v[172:175], v[52:55]
	v_mfma_f32_16x16x32_bf16 v[48:51], v[156:159], v[172:175], v[48:51]
	v_mfma_f32_16x16x32_bf16 v[44:47], v[148:151], v[180:183], v[44:47]
	v_mfma_f32_16x16x32_bf16 v[40:43], v[156:159], v[180:183], v[40:43]
	v_mfma_f32_16x16x32_bf16 v[36:39], v[148:151], v[188:191], v[36:39]
	v_mfma_f32_16x16x32_bf16 v[32:35], v[156:159], v[188:191], v[32:35]
	v_mfma_f32_16x16x32_bf16 v[60:63], v[152:155], v[168:171], v[60:63]
	v_mfma_f32_16x16x32_bf16 v[56:59], v[160:163], v[168:171], v[56:59]
	v_mfma_f32_16x16x32_bf16 v[52:55], v[152:155], v[176:179], v[52:55]
	v_mfma_f32_16x16x32_bf16 v[48:51], v[160:163], v[176:179], v[48:51]
	v_mfma_f32_16x16x32_bf16 v[44:47], v[152:155], v[184:187], v[44:47]
	v_mfma_f32_16x16x32_bf16 v[40:43], v[160:163], v[184:187], v[40:43]
	v_mfma_f32_16x16x32_bf16 v[36:39], v[152:155], v[194:197], v[36:39]
	v_mfma_f32_16x16x32_bf16 v[32:35], v[160:163], v[194:197], v[32:35]
	s_barrier
	s_setprio 0
	v_lshl_add_u64 v[148:149], v[234:235], 0, s[56:57]
	s_add_u32 m0, s3, s31
	s_nop 0
	global_load_lds_dwordx4 v[148:149], off
	v_lshl_add_u64 v[148:149], v[236:237], 0, s[56:57]
	s_add_u32 m0, s3, s31
	s_add_u32 m0, m0, 0x2000
	s_nop 0
	global_load_lds_dwordx4 v[148:149], off
	s_waitcnt vmcnt(6)
	s_setprio 1
	s_barrier
	v_mfma_f32_16x16x32_bf16 v[28:31], v[198:201], v[164:167], v[28:31]
	v_mfma_f32_16x16x32_bf16 v[24:27], v[206:209], v[164:167], v[24:27]
	v_mfma_f32_16x16x32_bf16 v[20:23], v[198:201], v[172:175], v[20:23]
	v_mfma_f32_16x16x32_bf16 v[16:19], v[206:209], v[172:175], v[16:19]
	v_mfma_f32_16x16x32_bf16 v[12:15], v[198:201], v[180:183], v[12:15]
	v_mfma_f32_16x16x32_bf16 v[8:11], v[206:209], v[180:183], v[8:11]
	v_mfma_f32_16x16x32_bf16 v[4:7], v[198:201], v[188:191], v[4:7]
	v_mfma_f32_16x16x32_bf16 v[0:3], v[206:209], v[188:191], v[0:3]
	v_mfma_f32_16x16x32_bf16 v[28:31], v[202:205], v[168:171], v[28:31]
	v_mfma_f32_16x16x32_bf16 v[24:27], v[226:229], v[168:171], v[24:27]
	v_mfma_f32_16x16x32_bf16 v[20:23], v[202:205], v[176:179], v[20:23]
	v_mfma_f32_16x16x32_bf16 v[16:19], v[226:229], v[176:179], v[16:19]
	v_mfma_f32_16x16x32_bf16 v[12:15], v[202:205], v[184:187], v[12:15]
	v_mfma_f32_16x16x32_bf16 v[8:11], v[226:229], v[184:187], v[8:11]
	v_mfma_f32_16x16x32_bf16 v[4:7], v[202:205], v[194:197], v[4:7]
	v_mfma_f32_16x16x32_bf16 v[0:3], v[226:229], v[194:197], v[0:3]
	s_add_i32 s2, s2, 2
	s_add_u32 s4, s4, 0x100
	s_addc_u32 s5, s5, 0
	s_cmp_lt_u32 s2, 28
	s_barrier
	s_setprio 0
	s_cbranch_scc1 .LBB0_576
	v_lshlrev_b32_e32 v128, 3, v139
	v_lshlrev_b32_e32 v129, 5, v139
	v_and_b32_e32 v128, 0xffff0, v128
	v_and_b32_e32 v129, 32, v129
	v_add_u32_e32 v129, v129, v142
	v_add_lshl_u32 v128, v141, v128, 12
	v_lshl_add_u32 v192, v129, 1, v128
	v_lshlrev_b32_e32 v128, 3, v143
	v_lshlrev_b32_e32 v129, 5, v143
	v_and_b32_e32 v128, 0xffff0, v128
	v_and_b32_e32 v129, 32, v129
	v_add_u32_e32 v129, v129, v145
	v_add_lshl_u32 v128, v144, v128, 12
	v_lshl_add_u32 v144, v129, 1, v128
	v_mov_b32_e32 v145, v193
	v_lshl_add_u64 v[184:185], s[0:1], 0, v[192:193]
	s_mov_b64 s[4:5], 0xf80
	v_readfirstlane_b32 s2, v146
	v_lshl_add_u64 v[184:185], v[184:185], 0, s[4:5]
	s_mov_b32 m0, s2
	v_lshl_add_u64 v[144:145], s[0:1], 0, v[144:145]
	v_readfirstlane_b32 s0, v147
	ds_read_b128 v[128:131], v138
	ds_read_b128 v[132:135], v138 offset:1024
	ds_read_b128 v[140:143], v138 offset:2048
	ds_read_b128 v[148:151], v138 offset:3072
	ds_read_b128 v[152:155], v137
	ds_read_b128 v[156:159], v137 offset:1024
	ds_read_b128 v[160:163], v137 offset:2048
	ds_read_b128 v[164:167], v137 offset:3072
	ds_read_b128 v[168:171], v137 offset:4096
	ds_read_b128 v[172:175], v137 offset:5120
	ds_read_b128 v[176:179], v137 offset:6144
	ds_read_b128 v[180:183], v137 offset:7168
	global_load_lds_dwordx4 v[184:185], off
	v_lshl_add_u64 v[144:145], v[144:145], 0, s[4:5]
	s_mov_b32 m0, s0
	s_nop 0
	global_load_lds_dwordx4 v[144:145], off
	s_barrier
	s_waitcnt lgkmcnt(0)
	s_setprio 1
	s_waitcnt lgkmcnt(0)
	v_mfma_f32_16x16x32_bf16 v[124:127], v[128:131], v[152:155], v[124:127]
	v_mfma_f32_16x16x32_bf16 v[120:123], v[140:143], v[152:155], v[120:123]
	v_mfma_f32_16x16x32_bf16 v[116:119], v[128:131], v[160:163], v[116:119]
	v_mfma_f32_16x16x32_bf16 v[112:115], v[140:143], v[160:163], v[112:115]
	v_mfma_f32_16x16x32_bf16 v[108:111], v[128:131], v[168:171], v[108:111]
	v_mfma_f32_16x16x32_bf16 v[104:107], v[140:143], v[168:171], v[104:107]
	v_mfma_f32_16x16x32_bf16 v[100:103], v[128:131], v[176:179], v[100:103]
	v_mfma_f32_16x16x32_bf16 v[96:99], v[140:143], v[176:179], v[96:99]
	v_mfma_f32_16x16x32_bf16 v[124:127], v[132:135], v[156:159], v[124:127]
	v_mfma_f32_16x16x32_bf16 v[120:123], v[148:151], v[156:159], v[120:123]
	v_mfma_f32_16x16x32_bf16 v[116:119], v[132:135], v[164:167], v[116:119]
	v_mfma_f32_16x16x32_bf16 v[112:115], v[148:151], v[164:167], v[112:115]
	v_mfma_f32_16x16x32_bf16 v[108:111], v[132:135], v[172:175], v[108:111]
	v_mfma_f32_16x16x32_bf16 v[104:107], v[148:151], v[172:175], v[104:107]
	v_mfma_f32_16x16x32_bf16 v[100:103], v[132:135], v[180:183], v[100:103]
	v_mfma_f32_16x16x32_bf16 v[96:99], v[148:151], v[180:183], v[96:99]
	s_setprio 0
	s_barrier
	ds_read_b128 v[144:147], v138 offset:16384
	ds_read_b128 v[184:187], v138 offset:17408
	ds_read_b128 v[188:191], v138 offset:18432
	ds_read_b128 v[194:197], v138 offset:19456
	s_barrier
; #define WAIT_V(n) asm volatile("s_waitcnt vmcnt(" #n ")" ::: "memory")
; #define WAIT_L(n) asm volatile("s_waitcnt lgkmcnt(" #n ")" ::: "memory")
; #define BAR __builtin_amdgcn_s_barrier()
; #define LDA(dst, b, h) _Pragma("unroll") for (int m = 0; m < 4; ++m) _Pragma("unroll") for (int k = 0; k < 2; ++k) \
;     dst[m][k] = *reinterpret_cast<const bf16x8*>((char*)shm + abase + (((b) * 2 + (h)) * 16384 + (m * 2 + k) * 1024))
; #define LDB(dst, b, h) _Pragma("unroll") for (int n = 0; n < 2; ++n) _Pragma("unroll") for (int k = 0; k < 2; ++k) \
;     dst[n][k] = *reinterpret_cast<const bf16x8*>((char*)shm + bbase + (((b) * 2 + (h)) * 16384 + (n * 2 + k) * 1024))
; template <bool SWAP>
; __device__ __forceinline__ void gemm_main(const u16* __restrict__ A, const u16* __restrict__ Bt, int brow, int bcol,
;                                           u16* shm, f32x4 (&acc)[2][2][4][2]) {
;     ...
;     LDB(B1, 0, 1); BAR; WAIT_L(0); MMA(0, 1, At, B1); BAR;
;     LDA(At, 0, 1); WAIT_V(4); BAR; WAIT_L(0); MMA(1, 0, At, B0); MMA(1, 1, At, B1); BAR; }
;   { LDB(B0, 1, 0); LDA(At, 1, 0); WAIT_V(2); BAR; WAIT_L(0); MMA(0, 0, At, B0); BAR;
;     LDB(B1, 1, 1); WAIT_V(0); BAR; WAIT_L(0); MMA(0, 1, At, B1); BAR;
	s_waitcnt lgkmcnt(0)
	s_setprio 1
	s_waitcnt lgkmcnt(0)
	v_mfma_f32_16x16x32_bf16 v[92:95], v[144:147], v[152:155], v[92:95]
	v_mfma_f32_16x16x32_bf16 v[88:91], v[188:191], v[152:155], v[88:91]
	v_mfma_f32_16x16x32_bf16 v[84:87], v[144:147], v[160:163], v[84:87]
	v_mfma_f32_16x16x32_bf16 v[80:83], v[188:191], v[160:163], v[80:83]
	v_mfma_f32_16x16x32_bf16 v[76:79], v[144:147], v[168:171], v[76:79]
	v_mfma_f32_16x16x32_bf16 v[72:75], v[188:191], v[168:171], v[72:75]
	v_mfma_f32_16x16x32_bf16 v[68:71], v[144:147], v[176:179], v[68:71]
	v_mfma_f32_16x16x32_bf16 v[64:67], v[188:191], v[176:179], v[64:67]
	v_mfma_f32_16x16x32_bf16 v[92:95], v[184:187], v[156:159], v[92:95]
	v_mfma_f32_16x16x32_bf16 v[88:91], v[194:197], v[156:159], v[88:91]
	v_mfma_f32_16x16x32_bf16 v[84:87], v[184:187], v[164:167], v[84:87]
	v_mfma_f32_16x16x32_bf16 v[80:83], v[194:197], v[164:167], v[80:83]
	v_mfma_f32_16x16x32_bf16 v[76:79], v[184:187], v[172:175], v[76:79]
	v_mfma_f32_16x16x32_bf16 v[72:75], v[194:197], v[172:175], v[72:75]
	v_mfma_f32_16x16x32_bf16 v[68:71], v[184:187], v[180:183], v[68:71]
	v_mfma_f32_16x16x32_bf16 v[64:67], v[194:197], v[180:183], v[64:67]
	s_setprio 0
	s_barrier
	ds_read_b128 v[152:155], v137 offset:16384
	ds_read_b128 v[156:159], v137 offset:17408
	ds_read_b128 v[160:163], v137 offset:18432
	ds_read_b128 v[164:167], v137 offset:19456
	ds_read_b128 v[168:171], v137 offset:20480
	ds_read_b128 v[172:175], v137 offset:21504
	ds_read_b128 v[176:179], v137 offset:22528
	ds_read_b128 v[180:183], v137 offset:23552
	s_waitcnt vmcnt(4)
	s_barrier
	s_waitcnt lgkmcnt(0)
	s_setprio 1
	s_waitcnt lgkmcnt(0)
	v_mfma_f32_16x16x32_bf16 v[60:63], v[128:131], v[152:155], v[60:63]
	v_mfma_f32_16x16x32_bf16 v[56:59], v[140:143], v[152:155], v[56:59]
	v_mfma_f32_16x16x32_bf16 v[52:55], v[128:131], v[160:163], v[52:55]
	v_mfma_f32_16x16x32_bf16 v[48:51], v[140:143], v[160:163], v[48:51]
	v_mfma_f32_16x16x32_bf16 v[44:47], v[128:131], v[168:171], v[44:47]
	v_mfma_f32_16x16x32_bf16 v[40:43], v[140:143], v[168:171], v[40:43]
	v_mfma_f32_16x16x32_bf16 v[36:39], v[128:131], v[176:179], v[36:39]
	v_mfma_f32_16x16x32_bf16 v[32:35], v[140:143], v[176:179], v[32:35]
	v_mfma_f32_16x16x32_bf16 v[60:63], v[132:135], v[156:159], v[60:63]
	v_mfma_f32_16x16x32_bf16 v[56:59], v[148:151], v[156:159], v[56:59]
	v_mfma_f32_16x16x32_bf16 v[52:55], v[132:135], v[164:167], v[52:55]
	v_mfma_f32_16x16x32_bf16 v[48:51], v[148:151], v[164:167], v[48:51]
	v_mfma_f32_16x16x32_bf16 v[44:47], v[132:135], v[172:175], v[44:47]
	v_mfma_f32_16x16x32_bf16 v[40:43], v[148:151], v[172:175], v[40:43]
	v_mfma_f32_16x16x32_bf16 v[36:39], v[132:135], v[180:183], v[36:39]
	v_mfma_f32_16x16x32_bf16 v[32:35], v[148:151], v[180:183], v[32:35]
	s_setprio 0
	s_setprio 1
	v_mfma_f32_16x16x32_bf16 v[28:31], v[144:147], v[152:155], v[28:31]
	v_mfma_f32_16x16x32_bf16 v[24:27], v[188:191], v[152:155], v[24:27]
	v_mfma_f32_16x16x32_bf16 v[20:23], v[144:147], v[160:163], v[20:23]
	v_mfma_f32_16x16x32_bf16 v[16:19], v[188:191], v[160:163], v[16:19]
	v_mfma_f32_16x16x32_bf16 v[12:15], v[144:147], v[168:171], v[12:15]
	v_mfma_f32_16x16x32_bf16 v[8:11], v[188:191], v[168:171], v[8:11]
	v_mfma_f32_16x16x32_bf16 v[4:7], v[144:147], v[176:179], v[4:7]
	v_mfma_f32_16x16x32_bf16 v[0:3], v[188:191], v[176:179], v[0:3]
	v_mfma_f32_16x16x32_bf16 v[28:31], v[184:187], v[156:159], v[28:31]
	v_mfma_f32_16x16x32_bf16 v[24:27], v[194:197], v[156:159], v[24:27]
	v_mfma_f32_16x16x32_bf16 v[20:23], v[184:187], v[164:167], v[20:23]
	v_mfma_f32_16x16x32_bf16 v[16:19], v[194:197], v[164:167], v[16:19]
	v_mfma_f32_16x16x32_bf16 v[12:15], v[184:187], v[172:175], v[12:15]
	v_mfma_f32_16x16x32_bf16 v[8:11], v[194:197], v[172:175], v[8:11]
	v_mfma_f32_16x16x32_bf16 v[4:7], v[184:187], v[180:183], v[4:7]
	v_mfma_f32_16x16x32_bf16 v[0:3], v[194:197], v[180:183], v[0:3]
	s_setprio 0
	s_barrier
	ds_read_b128 v[128:131], v138 offset:32768
	ds_read_b128 v[132:135], v138 offset:33792
	ds_read_b128 v[140:143], v138 offset:34816
	ds_read_b128 v[144:147], v138 offset:35840
	ds_read_b128 v[148:151], v137 offset:32768
	ds_read_b128 v[152:155], v137 offset:33792
	ds_read_b128 v[156:159], v137 offset:34816
	ds_read_b128 v[160:163], v137 offset:35840
	ds_read_b128 v[164:167], v137 offset:36864
	ds_read_b128 v[168:171], v137 offset:37888
	ds_read_b128 v[172:175], v137 offset:38912
	ds_read_b128 v[176:179], v137 offset:39936
	s_waitcnt vmcnt(2)
	s_barrier
; #define WAIT_V(n) asm volatile("s_waitcnt vmcnt(" #n ")" ::: "memory")
; #define WAIT_L(n) asm volatile("s_waitcnt lgkmcnt(" #n ")" ::: "memory")
; #define BAR __builtin_amdgcn_s_barrier()
; #define LDA(dst, b, h) _Pragma("unroll") for (int m = 0; m < 4; ++m) _Pragma("unroll") for (int k = 0; k < 2; ++k) \
;     dst[m][k] = *reinterpret_cast<const bf16x8*>((char*)shm + abase + (((b) * 2 + (h)) * 16384 + (m * 2 + k) * 1024))
; #define LDB(dst, b, h) _Pragma("unroll") for (int n = 0; n < 2; ++n) _Pragma("unroll") for (int k = 0; k < 2; ++k) \
;     dst[n][k] = *reinterpret_cast<const bf16x8*>((char*)shm + bbase + (((b) * 2 + (h)) * 16384 + (n * 2 + k) * 1024))
; template <bool SWAP>
; __device__ __forceinline__ void gemm_main(const u16* __restrict__ A, const u16* __restrict__ Bt, int brow, int bcol,
;                                           u16* shm, f32x4 (&acc)[2][2][4][2]) {
;     ...
;     LDA(At, 0, 1); WAIT_V(4); BAR; WAIT_L(0); MMA(1, 0, At, B0); MMA(1, 1, At, B1); BAR; }
;   { LDB(B0, 1, 0); LDA(At, 1, 0); WAIT_V(2); BAR; WAIT_L(0); MMA(0, 0, At, B0); BAR;
;     LDB(B1, 1, 1); WAIT_V(0); BAR; WAIT_L(0); MMA(0, 1, At, B1); BAR;
;     LDA(At, 1, 1); BAR; WAIT_L(0); MMA(1, 0, At, B0); MMA(1, 1, At, B1); BAR; }
;   if (wr == 0) BAR;
	s_waitcnt lgkmcnt(0)
	s_setprio 1
	s_waitcnt lgkmcnt(0)
	v_mfma_f32_16x16x32_bf16 v[124:127], v[128:131], v[148:151], v[124:127]
	v_mfma_f32_16x16x32_bf16 v[120:123], v[140:143], v[148:151], v[120:123]
	v_mfma_f32_16x16x32_bf16 v[116:119], v[128:131], v[156:159], v[116:119]
	v_mfma_f32_16x16x32_bf16 v[112:115], v[140:143], v[156:159], v[112:115]
	v_mfma_f32_16x16x32_bf16 v[108:111], v[128:131], v[164:167], v[108:111]
	v_mfma_f32_16x16x32_bf16 v[104:107], v[140:143], v[164:167], v[104:107]
	v_mfma_f32_16x16x32_bf16 v[100:103], v[128:131], v[172:175], v[100:103]
	v_mfma_f32_16x16x32_bf16 v[96:99], v[140:143], v[172:175], v[96:99]
	v_mfma_f32_16x16x32_bf16 v[124:127], v[132:135], v[152:155], v[124:127]
	v_mfma_f32_16x16x32_bf16 v[120:123], v[144:147], v[152:155], v[120:123]
	v_mfma_f32_16x16x32_bf16 v[116:119], v[132:135], v[160:163], v[116:119]
	v_mfma_f32_16x16x32_bf16 v[112:115], v[144:147], v[160:163], v[112:115]
	v_mfma_f32_16x16x32_bf16 v[108:111], v[132:135], v[168:171], v[108:111]
	v_mfma_f32_16x16x32_bf16 v[104:107], v[144:147], v[168:171], v[104:107]
	v_mfma_f32_16x16x32_bf16 v[100:103], v[132:135], v[176:179], v[100:103]
	v_mfma_f32_16x16x32_bf16 v[96:99], v[144:147], v[176:179], v[96:99]
	s_setprio 0
	s_barrier
	ds_read_b128 v[180:183], v138 offset:49152
	ds_read_b128 v[184:187], v138 offset:50176
	ds_read_b128 v[188:191], v138 offset:51200
	ds_read_b128 v[194:197], v138 offset:52224
	s_waitcnt vmcnt(0)
	s_barrier
	s_waitcnt lgkmcnt(0)
	s_setprio 1
	s_waitcnt lgkmcnt(0)
	v_mfma_f32_16x16x32_bf16 v[92:95], v[180:183], v[148:151], v[92:95]
	v_mfma_f32_16x16x32_bf16 v[88:91], v[188:191], v[148:151], v[88:91]
	v_mfma_f32_16x16x32_bf16 v[84:87], v[180:183], v[156:159], v[84:87]
	v_mfma_f32_16x16x32_bf16 v[80:83], v[188:191], v[156:159], v[80:83]
	v_mfma_f32_16x16x32_bf16 v[76:79], v[180:183], v[164:167], v[76:79]
	v_mfma_f32_16x16x32_bf16 v[72:75], v[188:191], v[164:167], v[72:75]
	v_mfma_f32_16x16x32_bf16 v[68:71], v[180:183], v[172:175], v[68:71]
	v_mfma_f32_16x16x32_bf16 v[64:67], v[188:191], v[172:175], v[64:67]
	v_mfma_f32_16x16x32_bf16 v[92:95], v[184:187], v[152:155], v[92:95]
	v_mfma_f32_16x16x32_bf16 v[88:91], v[194:197], v[152:155], v[88:91]
	v_mfma_f32_16x16x32_bf16 v[84:87], v[184:187], v[160:163], v[84:87]
	v_mfma_f32_16x16x32_bf16 v[80:83], v[194:197], v[160:163], v[80:83]
	v_mfma_f32_16x16x32_bf16 v[76:79], v[184:187], v[168:171], v[76:79]
	v_mfma_f32_16x16x32_bf16 v[72:75], v[194:197], v[168:171], v[72:75]
	v_mfma_f32_16x16x32_bf16 v[68:71], v[184:187], v[176:179], v[68:71]
	v_mfma_f32_16x16x32_bf16 v[64:67], v[194:197], v[176:179], v[64:67]
	s_setprio 0
	s_barrier
	ds_read_b128 v[148:151], v137 offset:49152
	ds_read_b128 v[152:155], v137 offset:50176
	ds_read_b128 v[156:159], v137 offset:51200
	ds_read_b128 v[160:163], v137 offset:52224
	ds_read_b128 v[164:167], v137 offset:53248
	ds_read_b128 v[168:171], v137 offset:54272
	ds_read_b128 v[172:175], v137 offset:55296
	ds_read_b128 v[176:179], v137 offset:56320
	s_barrier
	s_waitcnt lgkmcnt(0)
	s_setprio 1
	s_waitcnt lgkmcnt(0)
	v_mfma_f32_16x16x32_bf16 v[60:63], v[128:131], v[148:151], v[60:63]
	v_mfma_f32_16x16x32_bf16 v[56:59], v[140:143], v[148:151], v[56:59]
	v_mfma_f32_16x16x32_bf16 v[52:55], v[128:131], v[156:159], v[52:55]
	v_mfma_f32_16x16x32_bf16 v[48:51], v[140:143], v[156:159], v[48:51]
	v_mfma_f32_16x16x32_bf16 v[44:47], v[128:131], v[164:167], v[44:47]
	v_mfma_f32_16x16x32_bf16 v[40:43], v[140:143], v[164:167], v[40:43]
	v_mfma_f32_16x16x32_bf16 v[36:39], v[128:131], v[172:175], v[36:39]
	v_mfma_f32_16x16x32_bf16 v[32:35], v[140:143], v[172:175], v[32:35]
	v_mfma_f32_16x16x32_bf16 v[60:63], v[132:135], v[152:155], v[60:63]
	v_mfma_f32_16x16x32_bf16 v[56:59], v[144:147], v[152:155], v[56:59]
	v_mfma_f32_16x16x32_bf16 v[52:55], v[132:135], v[160:163], v[52:55]
	v_mfma_f32_16x16x32_bf16 v[48:51], v[144:147], v[160:163], v[48:51]
	v_mfma_f32_16x16x32_bf16 v[44:47], v[132:135], v[168:171], v[44:47]
	v_mfma_f32_16x16x32_bf16 v[40:43], v[144:147], v[168:171], v[40:43]
	v_mfma_f32_16x16x32_bf16 v[36:39], v[132:135], v[176:179], v[36:39]
	v_mfma_f32_16x16x32_bf16 v[32:35], v[144:147], v[176:179], v[32:35]
	s_setprio 0
	s_setprio 1
	v_mfma_f32_16x16x32_bf16 v[28:31], v[180:183], v[148:151], v[28:31]
	v_mfma_f32_16x16x32_bf16 v[24:27], v[188:191], v[148:151], v[24:27]
	v_mfma_f32_16x16x32_bf16 v[20:23], v[180:183], v[156:159], v[20:23]
	v_mfma_f32_16x16x32_bf16 v[16:19], v[188:191], v[156:159], v[16:19]
	v_mfma_f32_16x16x32_bf16 v[12:15], v[180:183], v[164:167], v[12:15]
	v_mfma_f32_16x16x32_bf16 v[8:11], v[188:191], v[164:167], v[8:11]
	v_mfma_f32_16x16x32_bf16 v[4:7], v[180:183], v[172:175], v[4:7]
	v_mfma_f32_16x16x32_bf16 v[0:3], v[188:191], v[172:175], v[0:3]
	v_mfma_f32_16x16x32_bf16 v[28:31], v[184:187], v[152:155], v[28:31]
	v_mfma_f32_16x16x32_bf16 v[24:27], v[194:197], v[152:155], v[24:27]
	v_mfma_f32_16x16x32_bf16 v[20:23], v[184:187], v[160:163], v[20:23]
	v_mfma_f32_16x16x32_bf16 v[16:19], v[194:197], v[160:163], v[16:19]
	v_mfma_f32_16x16x32_bf16 v[12:15], v[184:187], v[168:171], v[12:15]
	v_mfma_f32_16x16x32_bf16 v[8:11], v[194:197], v[168:171], v[8:11]
	v_mfma_f32_16x16x32_bf16 v[4:7], v[184:187], v[176:179], v[4:7]
	v_mfma_f32_16x16x32_bf16 v[0:3], v[194:197], v[176:179], v[0:3]
	s_setprio 0
	s_movk_i32 s0, 0x100
	v_cmp_gt_u32_e32 vcc, s0, v136
	s_barrier
	s_and_saveexec_b64 s[0:1], vcc
	s_cbranch_execz .LBB0_579
	s_barrier

; #define WAIT_V(n) asm volatile("s_waitcnt vmcnt(" #n ")" ::: "memory")
; #define BAR __builtin_amdgcn_s_barrier()
; template <bool SWAP>
; __device__ __forceinline__ void gemm_main(const u16* __restrict__ A, const u16* __restrict__ Bt, int brow, int bcol,
;                                           u16* shm, f32x4 (&acc)[2][2][4][2]) {
;     ...
;   int tx = threadIdx.x; asm volatile("" : "+v"(tx));
;   const int wid = tx >> 6, lane = tx & 63, wr = wid >> 2, wc = wid & 3, fr = lane & 15, fq = lane >> 4;
; #pragma unroll
;   for (int a = 0; a < 2; ++a)
; #pragma unroll
;     for (int b = 0; b < 2; ++b)
; #pragma unroll
;       for (int m = 0; m < 4; ++m)
; #pragma unroll
;         for (int n = 0; n < 2; ++n) acc[a][b][m][n] = f32x4{0.f, 0.f, 0.f, 0.f};
;   bf16x8 At[4][2], B0[2][2], B1[2][2];
;   constexpr int nt = GK / BK;
;   GEMM_VOFF
;   const int lpart = (fr * 64 + fq * 16) ^ ((fr >> 3) << 5);
;   const int abase = wr * 8192 + lpart; int bbase = 65536 + wc * 4096 + lpart;
;   asm volatile("" : "+v"(bbase));
;   if (wr == 1) BAR;
;   WAIT_V(0); BAR;
;   BAR;
.LBB0_626:
	s_or_b64 exec, exec, s[4:5]
	v_bfe_i32 v4, v138, 27, 1
	v_lshlrev_b32_e32 v142, 4, v138
	v_lshrrev_b32_e32 v4, 22, v4
	v_add_u32_e32 v4, v142, v4
	v_and_b32_e32 v4, 0xfffffc00, v4
	v_sub_u32_e32 v4, v142, v4
	v_lshrrev_b32_e32 v5, 4, v4
	v_bitop3_b32 v4, v5, v4, 32 bitop3:0x6c
	v_ashrrev_i32_e32 v5, 31, v4
	v_lshrrev_b32_e32 v5, 26, v5
	v_add_u32_e32 v5, v4, v5
	v_ashrrev_i32_e32 v143, 6, v5
	v_and_b32_e32 v5, 0xc0, v5
	v_sub_u32_e32 v4, v4, v5
	v_ashrrev_i16_sdwa v4, v215, sext(v4) dst_sel:DWORD dst_unused:UNUSED_PAD src0_sel:DWORD src1_sel:BYTE_0
	v_bfe_i32 v144, v4, 0, 16
	v_add_u32_e32 v4, 0x2000, v142
	v_ashrrev_i32_e32 v5, 31, v4
	v_lshrrev_b32_e32 v5, 22, v5
	v_add_u32_e32 v5, v4, v5
	v_ashrrev_i32_e32 v145, 10, v5
	v_mul_i32_i24_e32 v5, 0x400, v145
	v_sub_u32_e32 v4, v4, v5
	v_lshrrev_b32_e32 v5, 4, v4
	v_bitop3_b32 v4, v5, v4, 32 bitop3:0x6c
	v_ashrrev_i32_e32 v5, 31, v4
	v_lshrrev_b32_e32 v5, 26, v5
	v_ashrrev_i32_e32 v3, 31, v138
	v_add_u32_e32 v5, v4, v5
	v_lshrrev_b32_e32 v3, 26, v3
	v_ashrrev_i32_e32 v146, 6, v5
	v_and_b32_e32 v5, 0xc0, v5
	v_add_u32_e32 v3, v138, v3
	v_sub_u32_e32 v4, v4, v5
	v_ashrrev_i32_e32 v141, 6, v3
	v_ashrrev_i16_sdwa v4, v215, sext(v4) dst_sel:DWORD dst_unused:UNUSED_PAD src0_sel:DWORD src1_sel:BYTE_0
	s_lshl_b32 s4, s3, 12
	v_readlane_b32 s8, v253, 59
	v_bfe_i32 v147, v4, 0, 16
	v_lshlrev_b32_e32 v4, 13, v0
	v_lshlrev_b32_e32 v0, 15, v141
	v_readlane_b32 s9, v253, 60
	s_and_b32 s8, s4, 0x700000
	s_and_b32 s4, s2, 31
	v_and_b32_e32 v0, 0xffff0000, v0
	s_lshl_b32 s4, s4, 8
	v_lshl_add_u32 v0, v143, 12, v0
	s_mov_b32 s5, s9
	s_ashr_i32 s7, s6, 3
	v_and_or_b32 v0, v3, 64, v0
	v_writelane_b32 v253, s4, 59
	v_lshl_add_u32 v192, v144, 1, v0
	v_lshlrev_b32_e32 v0, 15, v145
	v_writelane_b32 v253, s5, 60
	s_lshl_b32 s5, s7, 8
	v_and_b32_e32 v0, 0xffff0000, v0
	s_and_b32 s5, s5, 0xffffe000
	v_add_u32_e32 v5, 0, v2
	v_lshl_add_u32 v0, v146, 12, v0
	v_lshlrev_b32_e32 v2, 6, v145
	s_or_b32 s4, s5, s4
	s_waitcnt vmcnt(0)
	v_and_or_b32 v0, v2, 64, v0
	s_ashr_i32 s5, s4, 31
	v_lshl_add_u32 v2, v147, 1, v0
	v_mov_b32_e32 v3, v193
	s_lshl_b64 s[4:5], s[4:5], 12
	v_mov_b32_e32 v0, 0
	v_lshl_add_u64 v[128:129], s[8:9], 0, v[192:193]
	v_lshl_add_u64 v[130:131], s[8:9], 0, v[2:3]
	v_lshl_add_u64 v[132:133], s[4:5], 0, v[192:193]
	v_lshl_add_u64 v[134:135], s[4:5], 0, v[2:3]
	s_mov_b32 s8, -2
	v_add_u32_e32 v140, 0, v1
	v_add_u32_e32 v139, v5, v4
	s_mov_b64 s[4:5], s[50:51]
	v_mov_b32_e32 v1, v0
	v_mov_b32_e32 v2, v0
	v_mov_b32_e32 v3, v0
	v_mov_b32_e32 v4, v0
	v_mov_b32_e32 v5, v0
	v_mov_b32_e32 v6, v0
	v_mov_b32_e32 v7, v0
	v_mov_b32_e32 v8, v0
	v_mov_b32_e32 v9, v0
	v_mov_b32_e32 v10, v0
	v_mov_b32_e32 v11, v0
	v_mov_b32_e32 v12, v0
	v_mov_b32_e32 v13, v0
	v_mov_b32_e32 v14, v0
	v_mov_b32_e32 v15, v0
	v_mov_b32_e32 v16, v0
	v_mov_b32_e32 v17, v0
	v_mov_b32_e32 v18, v0
	v_mov_b32_e32 v19, v0
	v_mov_b32_e32 v20, v0
	v_mov_b32_e32 v21, v0
	v_mov_b32_e32 v22, v0
	v_mov_b32_e32 v23, v0
	v_mov_b32_e32 v24, v0
	v_mov_b32_e32 v25, v0
	v_mov_b32_e32 v26, v0
	v_mov_b32_e32 v27, v0
	v_mov_b32_e32 v28, v0
	v_mov_b32_e32 v29, v0
	v_mov_b32_e32 v30, v0
	v_mov_b32_e32 v31, v0
	v_mov_b32_e32 v32, v0
	v_mov_b32_e32 v33, v0
	v_mov_b32_e32 v34, v0
	v_mov_b32_e32 v35, v0
	v_mov_b32_e32 v36, v0
	v_mov_b32_e32 v37, v0
	v_mov_b32_e32 v38, v0
	v_mov_b32_e32 v39, v0
	v_mov_b32_e32 v40, v0
	v_mov_b32_e32 v41, v0
	v_mov_b32_e32 v42, v0
	v_mov_b32_e32 v43, v0
	v_mov_b32_e32 v44, v0
	v_mov_b32_e32 v45, v0
	v_mov_b32_e32 v46, v0
	v_mov_b32_e32 v47, v0
	v_mov_b32_e32 v48, v0
	v_mov_b32_e32 v49, v0
	v_mov_b32_e32 v50, v0
	v_mov_b32_e32 v51, v0
	v_mov_b32_e32 v52, v0
	v_mov_b32_e32 v53, v0
	v_mov_b32_e32 v54, v0
	v_mov_b32_e32 v55, v0
	v_mov_b32_e32 v56, v0
	v_mov_b32_e32 v57, v0
	v_mov_b32_e32 v58, v0
	v_mov_b32_e32 v59, v0
	v_mov_b32_e32 v60, v0
	v_mov_b32_e32 v61, v0
	v_mov_b32_e32 v62, v0
	v_mov_b32_e32 v63, v0
	v_mov_b32_e32 v64, v0
	v_mov_b32_e32 v65, v0
	v_mov_b32_e32 v66, v0
	v_mov_b32_e32 v67, v0
	v_mov_b32_e32 v68, v0
	v_mov_b32_e32 v69, v0
	v_mov_b32_e32 v70, v0
	v_mov_b32_e32 v71, v0
	v_mov_b32_e32 v72, v0
	v_mov_b32_e32 v73, v0
	v_mov_b32_e32 v74, v0
	v_mov_b32_e32 v75, v0
	v_mov_b32_e32 v76, v0
	v_mov_b32_e32 v77, v0
	v_mov_b32_e32 v78, v0
	v_mov_b32_e32 v79, v0
	v_mov_b32_e32 v80, v0
	v_mov_b32_e32 v81, v0
	v_mov_b32_e32 v82, v0
	v_mov_b32_e32 v83, v0
	v_mov_b32_e32 v84, v0
	v_mov_b32_e32 v85, v0
	v_mov_b32_e32 v86, v0
	v_mov_b32_e32 v87, v0
	v_mov_b32_e32 v88, v0
	v_mov_b32_e32 v89, v0
	v_mov_b32_e32 v90, v0
	v_mov_b32_e32 v91, v0
	v_mov_b32_e32 v92, v0
	v_mov_b32_e32 v93, v0
	v_mov_b32_e32 v94, v0
	v_mov_b32_e32 v95, v0
	v_mov_b32_e32 v96, v0
	v_mov_b32_e32 v97, v0
	v_mov_b32_e32 v98, v0
	v_mov_b32_e32 v99, v0
	v_mov_b32_e32 v100, v0
	v_mov_b32_e32 v101, v0
	v_mov_b32_e32 v102, v0
	v_mov_b32_e32 v103, v0
	v_mov_b32_e32 v104, v0
	v_mov_b32_e32 v105, v0
	v_mov_b32_e32 v106, v0
	v_mov_b32_e32 v107, v0
	v_mov_b32_e32 v108, v0
	v_mov_b32_e32 v109, v0
	v_mov_b32_e32 v110, v0
	v_mov_b32_e32 v111, v0
	v_mov_b32_e32 v112, v0
	v_mov_b32_e32 v113, v0
	v_mov_b32_e32 v114, v0
	v_mov_b32_e32 v115, v0
	v_mov_b32_e32 v116, v0
	v_mov_b32_e32 v117, v0
	v_mov_b32_e32 v118, v0
	v_mov_b32_e32 v119, v0
	v_mov_b32_e32 v120, v0
	v_mov_b32_e32 v121, v0
	v_mov_b32_e32 v122, v0
	v_mov_b32_e32 v123, v0
	v_mov_b32_e32 v124, v0
	v_mov_b32_e32 v125, v0
	v_mov_b32_e32 v126, v0
	v_mov_b32_e32 v127, v0
	v_readfirstlane_b32 s9, v142
	s_barrier
	s_barrier
; #define WAIT_V(n) asm volatile("s_waitcnt vmcnt(" #n ")" ::: "memory")
; #define WAIT_L(n) asm volatile("s_waitcnt lgkmcnt(" #n ")" ::: "memory")
; #define BAR __builtin_amdgcn_s_barrier()
; #define SCHED __builtin_amdgcn_sched_barrier(0)
; #define STAGE(P, BASE, br, kt) do { const char* _g = (const char*)((BASE) + (size_t)(br) * GK + (kt) * BK); \
;     __builtin_amdgcn_global_load_lds((const unsigned*)(_g + voff0), (unsigned*)((char*)(P) + tx * 16), 16, 0, 0); \
;     __builtin_amdgcn_global_load_lds((const unsigned*)(_g + voff1), (unsigned*)((char*)(P) + tx * 16 + 8192), 16, 0, 0); } while (0)
; #define LDA(dst, b, h) _Pragma("unroll") for (int m = 0; m < 4; ++m) _Pragma("unroll") for (int k = 0; k < 2; ++k) \
;     dst[m][k] = *reinterpret_cast<const bf16x8*>((char*)shm + abase + (((b) * 2 + (h)) * 16384 + (m * 2 + k) * 1024))
; #define LDB(dst, b, h) _Pragma("unroll") for (int n = 0; n < 2; ++n) _Pragma("unroll") for (int k = 0; k < 2; ++k) \
;     dst[n][k] = *reinterpret_cast<const bf16x8*>((char*)shm + bbase + (((b) * 2 + (h)) * 16384 + (n * 2 + k) * 1024))
; template <bool SWAP>
; __device__ __forceinline__ void gemm_main(const u16* __restrict__ A, const u16* __restrict__ Bt, int brow, int bcol,
;                                           u16* shm, f32x4 (&acc)[2][2][4][2]) {
;     ...
;   for (int t = 0; t < nt - 2; t += 2) {
;     LDB(B0, 0, 0); SCHED; LDA(At, 0, 0); STAGE(SA(1, 1), A, brow + HALF, t + 1);
;     WAIT_L(8); BAR; WAIT_L(0); MMA(0, 0, At, B0); BAR; SCHED;
;     LDB(B1, 0, 1); STAGE(SB(0, 0), Bt, bcol, t + 2);
;     BAR; WAIT_L(0); MMA(0, 1, At, B1); BAR;
;     LDA(At, 0, 1); STAGE(SA(0, 0), A, brow, t + 2);
;     BAR; WAIT_L(0); MMA(1, 0, At, B0); BAR; SCHED;
;     STAGE(SB(0, 1), Bt, bcol + HALF, t + 2);
;     WAIT_V(6); BAR; MMA(1, 1, At, B1); BAR;
.LBB0_627:
	ds_read_b128 v[150:153], v140
	ds_read_b128 v[154:157], v140 offset:1024
	ds_read_b128 v[158:161], v140 offset:2048
	ds_read_b128 v[162:165], v140 offset:3072
	ds_read_b128 v[166:169], v139
	ds_read_b128 v[170:173], v139 offset:1024
	ds_read_b128 v[174:177], v139 offset:2048
	ds_read_b128 v[178:181], v139 offset:3072
	ds_read_b128 v[182:185], v139 offset:4096
	ds_read_b128 v[186:189], v139 offset:5120
	ds_read_b128 v[194:197], v139 offset:6144
	ds_read_b128 v[198:201], v139 offset:7168
	v_add_u32_e32 v192, 0, v142
	v_add_u32_e32 v148, 0xc000, v192
	v_lshl_add_u64 v[190:191], s[4:5], 0, v[132:133]
	v_add_u32_e32 v149, 0xe000, v192
	v_lshl_add_u64 v[202:203], v[190:191], 0, s[68:69]
	s_add_u32 m0, s9, 0xc000
	v_lshl_add_u64 v[232:233], s[4:5], 0, v[134:135]
	global_load_lds_dwordx4 v[202:203], off
	v_lshl_add_u64 v[202:203], v[232:233], 0, s[68:69]
	s_add_u32 m0, s9, 0xe000
	s_nop 0
	global_load_lds_dwordx4 v[202:203], off
	s_waitcnt lgkmcnt(8)
	s_setprio 1
	s_barrier
	s_waitcnt lgkmcnt(0)
	v_mfma_f32_16x16x32_bf16 v[124:127], v[150:153], v[166:169], v[124:127]
	v_mfma_f32_16x16x32_bf16 v[120:123], v[158:161], v[166:169], v[120:123]
	v_mfma_f32_16x16x32_bf16 v[116:119], v[150:153], v[174:177], v[116:119]
	v_mfma_f32_16x16x32_bf16 v[112:115], v[158:161], v[174:177], v[112:115]
	v_mfma_f32_16x16x32_bf16 v[108:111], v[150:153], v[182:185], v[108:111]
	v_mfma_f32_16x16x32_bf16 v[104:107], v[158:161], v[182:185], v[104:107]
	v_mfma_f32_16x16x32_bf16 v[100:103], v[150:153], v[194:197], v[100:103]
	v_mfma_f32_16x16x32_bf16 v[96:99], v[158:161], v[194:197], v[96:99]
	v_mfma_f32_16x16x32_bf16 v[124:127], v[154:157], v[170:173], v[124:127]
	v_mfma_f32_16x16x32_bf16 v[120:123], v[162:165], v[170:173], v[120:123]
	v_mfma_f32_16x16x32_bf16 v[116:119], v[154:157], v[178:181], v[116:119]
	v_mfma_f32_16x16x32_bf16 v[112:115], v[162:165], v[178:181], v[112:115]
	v_mfma_f32_16x16x32_bf16 v[108:111], v[154:157], v[186:189], v[108:111]
	v_mfma_f32_16x16x32_bf16 v[104:107], v[162:165], v[186:189], v[104:107]
	v_mfma_f32_16x16x32_bf16 v[100:103], v[154:157], v[198:201], v[100:103]
	v_mfma_f32_16x16x32_bf16 v[96:99], v[162:165], v[198:201], v[96:99]
	s_barrier
	s_setprio 0
	ds_read_b128 v[202:205], v140 offset:16384
	ds_read_b128 v[206:209], v140 offset:17408
	ds_read_b128 v[224:227], v140 offset:18432
	ds_read_b128 v[228:231], v140 offset:19456
	v_lshl_add_u64 v[234:235], s[4:5], 0, v[128:129]
	v_lshl_add_u64 v[236:237], v[234:235], 0, s[94:95]
	s_add_u32 m0, s9, s28
	s_nop 0
	global_load_lds_dwordx4 v[236:237], off
	v_lshl_add_u64 v[236:237], s[4:5], 0, v[130:131]
	v_lshl_add_u64 v[238:239], v[236:237], 0, s[94:95]
	s_add_u32 m0, s9, s28
	s_add_u32 m0, m0, 0x2000
	s_nop 0
	global_load_lds_dwordx4 v[238:239], off
	s_setprio 1
	s_barrier
	s_waitcnt lgkmcnt(0)
	v_mfma_f32_16x16x32_bf16 v[92:95], v[202:205], v[166:169], v[92:95]
	v_mfma_f32_16x16x32_bf16 v[88:91], v[224:227], v[166:169], v[88:91]
	v_mfma_f32_16x16x32_bf16 v[84:87], v[202:205], v[174:177], v[84:87]
	v_mfma_f32_16x16x32_bf16 v[80:83], v[224:227], v[174:177], v[80:83]
	v_mfma_f32_16x16x32_bf16 v[76:79], v[202:205], v[182:185], v[76:79]
	v_mfma_f32_16x16x32_bf16 v[72:75], v[224:227], v[182:185], v[72:75]
	v_mfma_f32_16x16x32_bf16 v[68:71], v[202:205], v[194:197], v[68:71]
	v_mfma_f32_16x16x32_bf16 v[64:67], v[224:227], v[194:197], v[64:67]
	v_mfma_f32_16x16x32_bf16 v[92:95], v[206:209], v[170:173], v[92:95]
	v_mfma_f32_16x16x32_bf16 v[88:91], v[228:231], v[170:173], v[88:91]
	v_mfma_f32_16x16x32_bf16 v[84:87], v[206:209], v[178:181], v[84:87]
	v_mfma_f32_16x16x32_bf16 v[80:83], v[228:231], v[178:181], v[80:83]
	v_mfma_f32_16x16x32_bf16 v[76:79], v[206:209], v[186:189], v[76:79]
	v_mfma_f32_16x16x32_bf16 v[72:75], v[228:231], v[186:189], v[72:75]
	v_mfma_f32_16x16x32_bf16 v[68:71], v[206:209], v[198:201], v[68:71]
	v_mfma_f32_16x16x32_bf16 v[64:67], v[228:231], v[198:201], v[64:67]
	s_barrier
	s_setprio 0
	ds_read_b128 v[166:169], v139 offset:16384
	ds_read_b128 v[170:173], v139 offset:17408
	ds_read_b128 v[174:177], v139 offset:18432
	ds_read_b128 v[178:181], v139 offset:19456
	ds_read_b128 v[182:185], v139 offset:20480
	ds_read_b128 v[186:189], v139 offset:21504
	ds_read_b128 v[194:197], v139 offset:22528
	ds_read_b128 v[198:201], v139 offset:23552
	v_lshl_add_u64 v[238:239], v[190:191], 0, s[62:63]
	s_add_u32 m0, s9, 0x0
	s_nop 0
	global_load_lds_dwordx4 v[238:239], off
	v_lshl_add_u64 v[238:239], v[232:233], 0, s[62:63]
	s_add_u32 m0, s9, 0x2000
	s_nop 0
	global_load_lds_dwordx4 v[238:239], off
	s_setprio 1
	s_barrier
	s_waitcnt lgkmcnt(0)
	v_mfma_f32_16x16x32_bf16 v[60:63], v[150:153], v[166:169], v[60:63]
	v_mfma_f32_16x16x32_bf16 v[56:59], v[158:161], v[166:169], v[56:59]
	v_mfma_f32_16x16x32_bf16 v[52:55], v[150:153], v[174:177], v[52:55]
	v_mfma_f32_16x16x32_bf16 v[48:51], v[158:161], v[174:177], v[48:51]
	v_mfma_f32_16x16x32_bf16 v[44:47], v[150:153], v[182:185], v[44:47]
	v_mfma_f32_16x16x32_bf16 v[40:43], v[158:161], v[182:185], v[40:43]
	v_mfma_f32_16x16x32_bf16 v[36:39], v[150:153], v[194:197], v[36:39]
	v_mfma_f32_16x16x32_bf16 v[32:35], v[158:161], v[194:197], v[32:35]
	v_mfma_f32_16x16x32_bf16 v[60:63], v[154:157], v[170:173], v[60:63]
	v_mfma_f32_16x16x32_bf16 v[56:59], v[162:165], v[170:173], v[56:59]
	v_mfma_f32_16x16x32_bf16 v[52:55], v[154:157], v[178:181], v[52:55]
	v_mfma_f32_16x16x32_bf16 v[48:51], v[162:165], v[178:181], v[48:51]
	v_mfma_f32_16x16x32_bf16 v[44:47], v[154:157], v[186:189], v[44:47]
	v_mfma_f32_16x16x32_bf16 v[40:43], v[162:165], v[186:189], v[40:43]
	v_mfma_f32_16x16x32_bf16 v[36:39], v[154:157], v[198:201], v[36:39]
	v_mfma_f32_16x16x32_bf16 v[32:35], v[162:165], v[198:201], v[32:35]
	s_barrier
; #define WAIT_V(n) asm volatile("s_waitcnt vmcnt(" #n ")" ::: "memory")
; #define WAIT_L(n) asm volatile("s_waitcnt lgkmcnt(" #n ")" ::: "memory")
; #define BAR __builtin_amdgcn_s_barrier()
; #define SCHED __builtin_amdgcn_sched_barrier(0)
; #define STAGE(P, BASE, br, kt) do { const char* _g = (const char*)((BASE) + (size_t)(br) * GK + (kt) * BK); \
;     __builtin_amdgcn_global_load_lds((const unsigned*)(_g + voff0), (unsigned*)((char*)(P) + tx * 16), 16, 0, 0); \
;     __builtin_amdgcn_global_load_lds((const unsigned*)(_g + voff1), (unsigned*)((char*)(P) + tx * 16 + 8192), 16, 0, 0); } while (0)
; #define LDA(dst, b, h) _Pragma("unroll") for (int m = 0; m < 4; ++m) _Pragma("unroll") for (int k = 0; k < 2; ++k) \
;     dst[m][k] = *reinterpret_cast<const bf16x8*>((char*)shm + abase + (((b) * 2 + (h)) * 16384 + (m * 2 + k) * 1024))
; #define LDB(dst, b, h) _Pragma("unroll") for (int n = 0; n < 2; ++n) _Pragma("unroll") for (int k = 0; k < 2; ++k) \
;     dst[n][k] = *reinterpret_cast<const bf16x8*>((char*)shm + bbase + (((b) * 2 + (h)) * 16384 + (n * 2 + k) * 1024))
; template <bool SWAP>
; __device__ __forceinline__ void gemm_main(const u16* __restrict__ A, const u16* __restrict__ Bt, int brow, int bcol,
;                                           u16* shm, f32x4 (&acc)[2][2][4][2]) {
;     ...
;     WAIT_V(6); BAR; MMA(1, 1, At, B1); BAR;
;     LDB(B0, 1, 0); SCHED; LDA(At, 1, 0); STAGE(SA(0, 1), A, brow + HALF, t + 2);
;     WAIT_L(8); BAR; WAIT_L(0); MMA(0, 0, At, B0); BAR; SCHED;
;     LDB(B1, 1, 1); STAGE(SB(1, 0), Bt, bcol, t + 3);
;     BAR; WAIT_L(0); MMA(0, 1, At, B1); BAR;
;     LDA(At, 1, 1); STAGE(SA(1, 0), A, brow, t + 3);
;     BAR; WAIT_L(0); MMA(1, 0, At, B0); BAR; SCHED;
	s_setprio 0
	v_lshl_add_u64 v[150:151], v[234:235], 0, s[78:79]
	s_add_u32 m0, s9, s29
	s_nop 0
	global_load_lds_dwordx4 v[150:151], off
	v_lshl_add_u64 v[150:151], v[236:237], 0, s[78:79]
	s_add_u32 m0, s9, s29
	s_add_u32 m0, m0, 0x2000
	s_nop 0
	global_load_lds_dwordx4 v[150:151], off
	s_waitcnt vmcnt(6)
	s_setprio 1
	s_barrier
	v_mfma_f32_16x16x32_bf16 v[28:31], v[202:205], v[166:169], v[28:31]
	v_mfma_f32_16x16x32_bf16 v[24:27], v[224:227], v[166:169], v[24:27]
	v_mfma_f32_16x16x32_bf16 v[20:23], v[202:205], v[174:177], v[20:23]
	v_mfma_f32_16x16x32_bf16 v[16:19], v[224:227], v[174:177], v[16:19]
	v_mfma_f32_16x16x32_bf16 v[12:15], v[202:205], v[182:185], v[12:15]
	v_mfma_f32_16x16x32_bf16 v[8:11], v[224:227], v[182:185], v[8:11]
	v_mfma_f32_16x16x32_bf16 v[4:7], v[202:205], v[194:197], v[4:7]
	v_mfma_f32_16x16x32_bf16 v[0:3], v[224:227], v[194:197], v[0:3]
	v_mfma_f32_16x16x32_bf16 v[28:31], v[206:209], v[170:173], v[28:31]
	v_mfma_f32_16x16x32_bf16 v[24:27], v[228:231], v[170:173], v[24:27]
	v_mfma_f32_16x16x32_bf16 v[20:23], v[206:209], v[178:181], v[20:23]
	v_mfma_f32_16x16x32_bf16 v[16:19], v[228:231], v[178:181], v[16:19]
	v_mfma_f32_16x16x32_bf16 v[12:15], v[206:209], v[186:189], v[12:15]
	v_mfma_f32_16x16x32_bf16 v[8:11], v[228:231], v[186:189], v[8:11]
	v_mfma_f32_16x16x32_bf16 v[4:7], v[206:209], v[198:201], v[4:7]
	v_mfma_f32_16x16x32_bf16 v[0:3], v[228:231], v[198:201], v[0:3]
	s_barrier
	s_setprio 0
	ds_read_b128 v[150:153], v140 offset:32768
	ds_read_b128 v[154:157], v140 offset:33792
	ds_read_b128 v[158:161], v140 offset:34816
	ds_read_b128 v[162:165], v140 offset:35840
	ds_read_b128 v[166:169], v139 offset:32768
	ds_read_b128 v[170:173], v139 offset:33792
	ds_read_b128 v[174:177], v139 offset:34816
	ds_read_b128 v[178:181], v139 offset:35840
	ds_read_b128 v[182:185], v139 offset:36864
	ds_read_b128 v[186:189], v139 offset:37888
	ds_read_b128 v[194:197], v139 offset:38912
	ds_read_b128 v[198:201], v139 offset:39936
	v_lshl_add_u64 v[202:203], v[190:191], 0, s[88:89]
	s_add_u32 m0, s9, 0x4000
	s_nop 0
	global_load_lds_dwordx4 v[202:203], off
	v_lshl_add_u64 v[202:203], v[232:233], 0, s[88:89]
	s_add_u32 m0, s9, 0x6000
	s_nop 0
	global_load_lds_dwordx4 v[202:203], off
	s_waitcnt lgkmcnt(8)
	s_setprio 1
	s_barrier
	s_waitcnt lgkmcnt(0)
	v_mfma_f32_16x16x32_bf16 v[124:127], v[150:153], v[166:169], v[124:127]
	v_mfma_f32_16x16x32_bf16 v[120:123], v[158:161], v[166:169], v[120:123]
	v_mfma_f32_16x16x32_bf16 v[116:119], v[150:153], v[174:177], v[116:119]
	v_mfma_f32_16x16x32_bf16 v[112:115], v[158:161], v[174:177], v[112:115]
	v_mfma_f32_16x16x32_bf16 v[108:111], v[150:153], v[182:185], v[108:111]
	v_mfma_f32_16x16x32_bf16 v[104:107], v[158:161], v[182:185], v[104:107]
	v_mfma_f32_16x16x32_bf16 v[100:103], v[150:153], v[194:197], v[100:103]
	v_mfma_f32_16x16x32_bf16 v[96:99], v[158:161], v[194:197], v[96:99]
	v_mfma_f32_16x16x32_bf16 v[124:127], v[154:157], v[170:173], v[124:127]
	v_mfma_f32_16x16x32_bf16 v[120:123], v[162:165], v[170:173], v[120:123]
	v_mfma_f32_16x16x32_bf16 v[116:119], v[154:157], v[178:181], v[116:119]
	v_mfma_f32_16x16x32_bf16 v[112:115], v[162:165], v[178:181], v[112:115]
	v_mfma_f32_16x16x32_bf16 v[108:111], v[154:157], v[186:189], v[108:111]
	v_mfma_f32_16x16x32_bf16 v[104:107], v[162:165], v[186:189], v[104:107]
	v_mfma_f32_16x16x32_bf16 v[100:103], v[154:157], v[198:201], v[100:103]
	v_mfma_f32_16x16x32_bf16 v[96:99], v[162:165], v[198:201], v[96:99]
	s_barrier
	s_setprio 0
	ds_read_b128 v[202:205], v140 offset:49152
	ds_read_b128 v[206:209], v140 offset:50176
	ds_read_b128 v[224:227], v140 offset:51200
	ds_read_b128 v[228:231], v140 offset:52224
	v_lshl_add_u64 v[238:239], v[234:235], 0, s[52:53]
	s_add_u32 m0, s9, s30
	s_nop 0
	global_load_lds_dwordx4 v[238:239], off
	v_lshl_add_u64 v[238:239], v[236:237], 0, s[52:53]
	s_add_u32 m0, s9, s30
	s_add_u32 m0, m0, 0x2000
	s_nop 0
	global_load_lds_dwordx4 v[238:239], off
	s_setprio 1
	s_barrier
	s_waitcnt lgkmcnt(0)
	v_mfma_f32_16x16x32_bf16 v[92:95], v[202:205], v[166:169], v[92:95]
	v_mfma_f32_16x16x32_bf16 v[88:91], v[224:227], v[166:169], v[88:91]
	v_mfma_f32_16x16x32_bf16 v[84:87], v[202:205], v[174:177], v[84:87]
	v_mfma_f32_16x16x32_bf16 v[80:83], v[224:227], v[174:177], v[80:83]
	v_mfma_f32_16x16x32_bf16 v[76:79], v[202:205], v[182:185], v[76:79]
	v_mfma_f32_16x16x32_bf16 v[72:75], v[224:227], v[182:185], v[72:75]
	v_mfma_f32_16x16x32_bf16 v[68:71], v[202:205], v[194:197], v[68:71]
	v_mfma_f32_16x16x32_bf16 v[64:67], v[224:227], v[194:197], v[64:67]
	v_mfma_f32_16x16x32_bf16 v[92:95], v[206:209], v[170:173], v[92:95]
	v_mfma_f32_16x16x32_bf16 v[88:91], v[228:231], v[170:173], v[88:91]
	v_mfma_f32_16x16x32_bf16 v[84:87], v[206:209], v[178:181], v[84:87]
	v_mfma_f32_16x16x32_bf16 v[80:83], v[228:231], v[178:181], v[80:83]
	v_mfma_f32_16x16x32_bf16 v[76:79], v[206:209], v[186:189], v[76:79]
	v_mfma_f32_16x16x32_bf16 v[72:75], v[228:231], v[186:189], v[72:75]
	v_mfma_f32_16x16x32_bf16 v[68:71], v[206:209], v[198:201], v[68:71]
	v_mfma_f32_16x16x32_bf16 v[64:67], v[228:231], v[198:201], v[64:67]
	s_barrier
	s_setprio 0
	ds_read_b128 v[166:169], v139 offset:49152
	ds_read_b128 v[170:173], v139 offset:50176
	ds_read_b128 v[174:177], v139 offset:51200
	ds_read_b128 v[178:181], v139 offset:52224
	ds_read_b128 v[182:185], v139 offset:53248
	ds_read_b128 v[186:189], v139 offset:54272
	ds_read_b128 v[194:197], v139 offset:55296
	ds_read_b128 v[198:201], v139 offset:56320
	v_add_u32_e32 v223, 0x8000, v192
	v_lshl_add_u64 v[190:191], v[190:191], 0, s[44:45]
	s_add_u32 m0, s9, 0x8000
	s_nop 0
	global_load_lds_dwordx4 v[190:191], off
	v_lshl_add_u64 v[190:191], v[232:233], 0, s[44:45]
	s_add_u32 m0, s9, 0xa000
	s_nop 0
	global_load_lds_dwordx4 v[190:191], off
	s_setprio 1
	s_barrier
; #define WAIT_V(n) asm volatile("s_waitcnt vmcnt(" #n ")" ::: "memory")
; #define WAIT_L(n) asm volatile("s_waitcnt lgkmcnt(" #n ")" ::: "memory")
; #define BAR __builtin_amdgcn_s_barrier()
; #define SCHED __builtin_amdgcn_sched_barrier(0)
; #define STAGE(P, BASE, br, kt) do { const char* _g = (const char*)((BASE) + (size_t)(br) * GK + (kt) * BK); \
;     __builtin_amdgcn_global_load_lds((const unsigned*)(_g + voff0), (unsigned*)((char*)(P) + tx * 16), 16, 0, 0); \
;     __builtin_amdgcn_global_load_lds((const unsigned*)(_g + voff1), (unsigned*)((char*)(P) + tx * 16 + 8192), 16, 0, 0); } while (0)
; #define LDA(dst, b, h) _Pragma("unroll") for (int m = 0; m < 4; ++m) _Pragma("unroll") for (int k = 0; k < 2; ++k) \
;     dst[m][k] = *reinterpret_cast<const bf16x8*>((char*)shm + abase + (((b) * 2 + (h)) * 16384 + (m * 2 + k) * 1024))
; #define LDB(dst, b, h) _Pragma("unroll") for (int n = 0; n < 2; ++n) _Pragma("unroll") for (int k = 0; k < 2; ++k) \
;     dst[n][k] = *reinterpret_cast<const bf16x8*>((char*)shm + bbase + (((b) * 2 + (h)) * 16384 + (n * 2 + k) * 1024))
; template <bool SWAP>
; __device__ __forceinline__ void gemm_main(const u16* __restrict__ A, const u16* __restrict__ Bt, int brow, int bcol,
;                                           u16* shm, f32x4 (&acc)[2][2][4][2]) {
;     ...
;     BAR; WAIT_L(0); MMA(1, 0, At, B0); BAR; SCHED;
;     STAGE(SB(1, 1), Bt, bcol + HALF, t + 3);
;     WAIT_V(6); BAR; MMA(1, 1, At, B1); BAR;
;   }
;   { LDB(B0, 0, 0); LDA(At, 0, 0); STAGE(SA(1, 1), A, brow + HALF, nt - 1);
;     BAR; WAIT_L(0); MMA(0, 0, At, B0); BAR;
;     LDB(B1, 0, 1); BAR; WAIT_L(0); MMA(0, 1, At, B1); BAR;
	s_waitcnt lgkmcnt(0)
	v_mfma_f32_16x16x32_bf16 v[60:63], v[150:153], v[166:169], v[60:63]
	v_mfma_f32_16x16x32_bf16 v[56:59], v[158:161], v[166:169], v[56:59]
	v_mfma_f32_16x16x32_bf16 v[52:55], v[150:153], v[174:177], v[52:55]
	v_mfma_f32_16x16x32_bf16 v[48:51], v[158:161], v[174:177], v[48:51]
	v_mfma_f32_16x16x32_bf16 v[44:47], v[150:153], v[182:185], v[44:47]
	v_mfma_f32_16x16x32_bf16 v[40:43], v[158:161], v[182:185], v[40:43]
	v_mfma_f32_16x16x32_bf16 v[36:39], v[150:153], v[194:197], v[36:39]
	v_mfma_f32_16x16x32_bf16 v[32:35], v[158:161], v[194:197], v[32:35]
	v_mfma_f32_16x16x32_bf16 v[60:63], v[154:157], v[170:173], v[60:63]
	v_mfma_f32_16x16x32_bf16 v[56:59], v[162:165], v[170:173], v[56:59]
	v_mfma_f32_16x16x32_bf16 v[52:55], v[154:157], v[178:181], v[52:55]
	v_mfma_f32_16x16x32_bf16 v[48:51], v[162:165], v[178:181], v[48:51]
	v_mfma_f32_16x16x32_bf16 v[44:47], v[154:157], v[186:189], v[44:47]
	v_mfma_f32_16x16x32_bf16 v[40:43], v[162:165], v[186:189], v[40:43]
	v_mfma_f32_16x16x32_bf16 v[36:39], v[154:157], v[198:201], v[36:39]
	v_mfma_f32_16x16x32_bf16 v[32:35], v[162:165], v[198:201], v[32:35]
	s_barrier
	s_setprio 0
	v_lshl_add_u64 v[150:151], v[234:235], 0, s[38:39]
	s_add_u32 m0, s9, s31
	s_nop 0
	global_load_lds_dwordx4 v[150:151], off
	v_lshl_add_u64 v[150:151], v[236:237], 0, s[38:39]
	s_add_u32 m0, s9, s31
	s_add_u32 m0, m0, 0x2000
	s_nop 0
	global_load_lds_dwordx4 v[150:151], off
	s_waitcnt vmcnt(6)
	s_setprio 1
	s_barrier
	v_mfma_f32_16x16x32_bf16 v[28:31], v[202:205], v[166:169], v[28:31]
	v_mfma_f32_16x16x32_bf16 v[24:27], v[224:227], v[166:169], v[24:27]
	v_mfma_f32_16x16x32_bf16 v[20:23], v[202:205], v[174:177], v[20:23]
	v_mfma_f32_16x16x32_bf16 v[16:19], v[224:227], v[174:177], v[16:19]
	v_mfma_f32_16x16x32_bf16 v[12:15], v[202:205], v[182:185], v[12:15]
	v_mfma_f32_16x16x32_bf16 v[8:11], v[224:227], v[182:185], v[8:11]
	v_mfma_f32_16x16x32_bf16 v[4:7], v[202:205], v[194:197], v[4:7]
	v_mfma_f32_16x16x32_bf16 v[0:3], v[224:227], v[194:197], v[0:3]
	v_mfma_f32_16x16x32_bf16 v[28:31], v[206:209], v[170:173], v[28:31]
	v_mfma_f32_16x16x32_bf16 v[24:27], v[228:231], v[170:173], v[24:27]
	v_mfma_f32_16x16x32_bf16 v[20:23], v[206:209], v[178:181], v[20:23]
	v_mfma_f32_16x16x32_bf16 v[16:19], v[228:231], v[178:181], v[16:19]
	v_mfma_f32_16x16x32_bf16 v[12:15], v[206:209], v[186:189], v[12:15]
	v_mfma_f32_16x16x32_bf16 v[8:11], v[228:231], v[186:189], v[8:11]
	v_mfma_f32_16x16x32_bf16 v[4:7], v[206:209], v[198:201], v[4:7]
	v_mfma_f32_16x16x32_bf16 v[0:3], v[228:231], v[198:201], v[0:3]
	s_add_i32 s8, s8, 2
	s_add_u32 s4, s4, 0x100
	s_addc_u32 s5, s5, 0
	s_cmp_lt_u32 s8, 28
	s_barrier
	s_setprio 0
	s_cbranch_scc1 .LBB0_627
	s_and_b32 s4, s7, 0xffffe0
	s_and_b32 s5, s6, 31
	s_or_b32 s4, s4, s5
	s_lshl_b32 s10, s4, 8
	v_lshlrev_b32_e32 v128, 3, v141
	v_lshlrev_b32_e32 v129, 5, v141
	v_and_b32_e32 v128, 0xffff0, v128
	v_and_b32_e32 v129, 32, v129
	s_or_b32 s4, s10, 0x80
	v_add_u32_e32 v129, v129, v144
	v_add_lshl_u32 v128, v143, v128, 12
	s_ashr_i32 s5, s4, 31
	v_lshl_add_u32 v192, v129, 1, v128
	v_lshlrev_b32_e32 v128, 3, v145
	v_lshlrev_b32_e32 v129, 5, v145
	s_lshl_b64 s[4:5], s[4:5], 12
	v_and_b32_e32 v128, 0xffff0, v128
	v_and_b32_e32 v129, 32, v129
	s_add_u32 s4, s84, s4
	v_add_u32_e32 v129, v129, v147
	v_add_lshl_u32 v128, v146, v128, 12
	s_addc_u32 s5, s85, s5
	v_lshl_add_u32 v146, v129, 1, v128
	v_mov_b32_e32 v147, v193
	v_lshl_add_u64 v[186:187], s[4:5], 0, v[192:193]
	s_mov_b64 s[8:9], 0xf80
	v_readfirstlane_b32 s7, v148
	v_lshl_add_u64 v[186:187], v[186:187], 0, s[8:9]
	s_mov_b32 m0, s7
	v_lshl_add_u64 v[146:147], s[4:5], 0, v[146:147]
	v_readfirstlane_b32 s4, v149
	ds_read_b128 v[128:131], v140
	ds_read_b128 v[132:135], v140 offset:1024
	ds_read_b128 v[142:145], v140 offset:2048
	ds_read_b128 v[150:153], v140 offset:3072
	ds_read_b128 v[154:157], v139
	ds_read_b128 v[158:161], v139 offset:1024
	ds_read_b128 v[162:165], v139 offset:2048
	ds_read_b128 v[166:169], v139 offset:3072
	ds_read_b128 v[170:173], v139 offset:4096
	ds_read_b128 v[174:177], v139 offset:5120
	ds_read_b128 v[178:181], v139 offset:6144
	ds_read_b128 v[182:185], v139 offset:7168
	global_load_lds_dwordx4 v[186:187], off
	v_lshl_add_u64 v[146:147], v[146:147], 0, s[8:9]
	s_mov_b32 m0, s4
	s_nop 0
	global_load_lds_dwordx4 v[146:147], off
	s_barrier
	s_waitcnt lgkmcnt(0)
	s_setprio 1
	s_waitcnt lgkmcnt(0)
	v_mfma_f32_16x16x32_bf16 v[124:127], v[128:131], v[154:157], v[124:127]
	v_mfma_f32_16x16x32_bf16 v[116:119], v[128:131], v[162:165], v[116:119]
	v_mfma_f32_16x16x32_bf16 v[108:111], v[128:131], v[170:173], v[108:111]
	v_mfma_f32_16x16x32_bf16 v[100:103], v[128:131], v[178:181], v[100:103]
	v_mfma_f32_16x16x32_bf16 v[124:127], v[132:135], v[158:161], v[124:127]
	v_mfma_f32_16x16x32_bf16 v[120:123], v[142:145], v[154:157], v[120:123]
	v_mfma_f32_16x16x32_bf16 v[116:119], v[132:135], v[166:169], v[116:119]
	v_mfma_f32_16x16x32_bf16 v[112:115], v[142:145], v[162:165], v[112:115]
	v_mfma_f32_16x16x32_bf16 v[108:111], v[132:135], v[174:177], v[108:111]
	v_mfma_f32_16x16x32_bf16 v[104:107], v[142:145], v[170:173], v[104:107]
	v_mfma_f32_16x16x32_bf16 v[100:103], v[132:135], v[182:185], v[100:103]
	v_mfma_f32_16x16x32_bf16 v[96:99], v[142:145], v[178:181], v[96:99]
	v_mfma_f32_16x16x32_bf16 v[146:149], v[150:153], v[158:161], v[120:123]
	v_mfma_f32_16x16x32_bf16 v[186:189], v[150:153], v[166:169], v[112:115]
	v_mfma_f32_16x16x32_bf16 v[194:197], v[150:153], v[174:177], v[104:107]
	v_mfma_f32_16x16x32_bf16 v[198:201], v[150:153], v[182:185], v[96:99]
	s_setprio 0
	s_barrier
; #define WAIT_V(n) asm volatile("s_waitcnt vmcnt(" #n ")" ::: "memory")
; #define WAIT_L(n) asm volatile("s_waitcnt lgkmcnt(" #n ")" ::: "memory")
; #define BAR __builtin_amdgcn_s_barrier()
; #define LDA(dst, b, h) _Pragma("unroll") for (int m = 0; m < 4; ++m) _Pragma("unroll") for (int k = 0; k < 2; ++k) \
;     dst[m][k] = *reinterpret_cast<const bf16x8*>((char*)shm + abase + (((b) * 2 + (h)) * 16384 + (m * 2 + k) * 1024))
; #define LDB(dst, b, h) _Pragma("unroll") for (int n = 0; n < 2; ++n) _Pragma("unroll") for (int k = 0; k < 2; ++k) \
;     dst[n][k] = *reinterpret_cast<const bf16x8*>((char*)shm + bbase + (((b) * 2 + (h)) * 16384 + (n * 2 + k) * 1024))
; template <bool SWAP>
; __device__ __forceinline__ void gemm_main(const u16* __restrict__ A, const u16* __restrict__ Bt, int brow, int bcol,
;                                           u16* shm, f32x4 (&acc)[2][2][4][2]) {
;     ...
;     LDB(B1, 0, 1); BAR; WAIT_L(0); MMA(0, 1, At, B1); BAR;
;     LDA(At, 0, 1); WAIT_V(4); BAR; WAIT_L(0); MMA(1, 0, At, B0); MMA(1, 1, At, B1); BAR; }
;   { LDB(B0, 1, 0); LDA(At, 1, 0); WAIT_V(2); BAR; WAIT_L(0); MMA(0, 0, At, B0); BAR;
;     LDB(B1, 1, 1); WAIT_V(0); BAR; WAIT_L(0); MMA(0, 1, At, B1); BAR;
	s_nop 1
	ds_read_b128 v[96:99], v140 offset:16384
	ds_read_b128 v[104:107], v140 offset:17408
	ds_read_b128 v[112:115], v140 offset:18432
	ds_read_b128 v[120:123], v140 offset:19456
	s_barrier
	s_waitcnt lgkmcnt(0)
	s_setprio 1
	s_waitcnt lgkmcnt(0)
	v_mfma_f32_16x16x32_bf16 v[92:95], v[96:99], v[154:157], v[92:95]
	v_mfma_f32_16x16x32_bf16 v[84:87], v[96:99], v[162:165], v[84:87]
	v_mfma_f32_16x16x32_bf16 v[76:79], v[96:99], v[170:173], v[76:79]
	v_mfma_f32_16x16x32_bf16 v[68:71], v[96:99], v[178:181], v[68:71]
	v_mfma_f32_16x16x32_bf16 v[92:95], v[104:107], v[158:161], v[92:95]
	v_mfma_f32_16x16x32_bf16 v[88:91], v[112:115], v[154:157], v[88:91]
	v_mfma_f32_16x16x32_bf16 v[84:87], v[104:107], v[166:169], v[84:87]
	v_mfma_f32_16x16x32_bf16 v[80:83], v[112:115], v[162:165], v[80:83]
	v_mfma_f32_16x16x32_bf16 v[76:79], v[104:107], v[174:177], v[76:79]
	v_mfma_f32_16x16x32_bf16 v[72:75], v[112:115], v[170:173], v[72:75]
	v_mfma_f32_16x16x32_bf16 v[68:71], v[104:107], v[182:185], v[68:71]
	v_mfma_f32_16x16x32_bf16 v[64:67], v[112:115], v[178:181], v[64:67]
	v_mfma_f32_16x16x32_bf16 v[154:157], v[120:123], v[158:161], v[88:91]
	v_mfma_f32_16x16x32_bf16 v[158:161], v[120:123], v[166:169], v[80:83]
	v_mfma_f32_16x16x32_bf16 v[162:165], v[120:123], v[174:177], v[72:75]
	v_mfma_f32_16x16x32_bf16 v[166:169], v[120:123], v[182:185], v[64:67]
	s_setprio 0
	s_barrier
	s_nop 1
	ds_read_b128 v[64:67], v139 offset:16384
	ds_read_b128 v[72:75], v139 offset:17408
	ds_read_b128 v[80:83], v139 offset:18432
	ds_read_b128 v[88:91], v139 offset:19456
	ds_read_b128 v[170:173], v139 offset:20480
	ds_read_b128 v[174:177], v139 offset:21504
	ds_read_b128 v[178:181], v139 offset:22528
	ds_read_b128 v[182:185], v139 offset:23552
	s_waitcnt vmcnt(4)
	s_barrier
	s_waitcnt lgkmcnt(0)
	s_setprio 1
	s_waitcnt lgkmcnt(0)
	v_mfma_f32_16x16x32_bf16 v[60:63], v[128:131], v[64:67], v[60:63]
	v_mfma_f32_16x16x32_bf16 v[52:55], v[128:131], v[80:83], v[52:55]
	v_mfma_f32_16x16x32_bf16 v[44:47], v[128:131], v[170:173], v[44:47]
	v_mfma_f32_16x16x32_bf16 v[36:39], v[128:131], v[178:181], v[36:39]
	v_mfma_f32_16x16x32_bf16 v[60:63], v[132:135], v[72:75], v[60:63]
	v_mfma_f32_16x16x32_bf16 v[56:59], v[142:145], v[64:67], v[56:59]
	v_mfma_f32_16x16x32_bf16 v[52:55], v[132:135], v[88:91], v[52:55]
	v_mfma_f32_16x16x32_bf16 v[48:51], v[142:145], v[80:83], v[48:51]
	v_mfma_f32_16x16x32_bf16 v[44:47], v[132:135], v[174:177], v[44:47]
	v_mfma_f32_16x16x32_bf16 v[40:43], v[142:145], v[170:173], v[40:43]
	v_mfma_f32_16x16x32_bf16 v[36:39], v[132:135], v[182:185], v[36:39]
	v_mfma_f32_16x16x32_bf16 v[32:35], v[142:145], v[178:181], v[32:35]
	v_mfma_f32_16x16x32_bf16 v[202:205], v[150:153], v[72:75], v[56:59]
	v_mfma_f32_16x16x32_bf16 v[206:209], v[150:153], v[88:91], v[48:51]
	v_mfma_f32_16x16x32_bf16 v[224:227], v[150:153], v[174:177], v[40:43]
	v_mfma_f32_16x16x32_bf16 v[128:131], v[150:153], v[182:185], v[32:35]
	s_setprio 0
	s_setprio 1
	v_mfma_f32_16x16x32_bf16 v[28:31], v[96:99], v[64:67], v[28:31]
	v_mfma_f32_16x16x32_bf16 v[20:23], v[96:99], v[80:83], v[20:23]
	v_mfma_f32_16x16x32_bf16 v[12:15], v[96:99], v[170:173], v[12:15]
	v_mfma_f32_16x16x32_bf16 v[4:7], v[96:99], v[178:181], v[4:7]
	v_mfma_f32_16x16x32_bf16 v[28:31], v[104:107], v[72:75], v[28:31]
	v_mfma_f32_16x16x32_bf16 v[24:27], v[112:115], v[64:67], v[24:27]
	v_mfma_f32_16x16x32_bf16 v[20:23], v[104:107], v[88:91], v[20:23]
	v_mfma_f32_16x16x32_bf16 v[16:19], v[112:115], v[80:83], v[16:19]
	v_mfma_f32_16x16x32_bf16 v[12:15], v[104:107], v[174:177], v[12:15]
	v_mfma_f32_16x16x32_bf16 v[8:11], v[112:115], v[170:173], v[8:11]
	v_mfma_f32_16x16x32_bf16 v[4:7], v[104:107], v[182:185], v[4:7]
	v_mfma_f32_16x16x32_bf16 v[0:3], v[112:115], v[178:181], v[0:3]
	v_mfma_f32_16x16x32_bf16 v[132:135], v[120:123], v[72:75], v[24:27]
	v_mfma_f32_16x16x32_bf16 v[142:145], v[120:123], v[88:91], v[16:19]
	v_mfma_f32_16x16x32_bf16 v[150:153], v[120:123], v[174:177], v[8:11]
	v_mfma_f32_16x16x32_bf16 v[170:173], v[120:123], v[182:185], v[0:3]
	s_setprio 0
	s_barrier
	s_nop 1
	ds_read_b128 v[0:3], v140 offset:32768
	ds_read_b128 v[8:11], v140 offset:33792
	ds_read_b128 v[16:19], v140 offset:34816
	ds_read_b128 v[24:27], v140 offset:35840
	ds_read_b128 v[32:35], v139 offset:32768
	ds_read_b128 v[40:43], v139 offset:33792
	ds_read_b128 v[48:51], v139 offset:34816
	ds_read_b128 v[56:59], v139 offset:35840
	ds_read_b128 v[64:67], v139 offset:36864
	ds_read_b128 v[174:177], v139 offset:37888
	ds_read_b128 v[178:181], v139 offset:38912
	ds_read_b128 v[182:185], v139 offset:39936
	s_waitcnt vmcnt(2)
	s_barrier
; #define WAIT_V(n) asm volatile("s_waitcnt vmcnt(" #n ")" ::: "memory")
; #define WAIT_L(n) asm volatile("s_waitcnt lgkmcnt(" #n ")" ::: "memory")
; #define BAR __builtin_amdgcn_s_barrier()
; #define LDA(dst, b, h) _Pragma("unroll") for (int m = 0; m < 4; ++m) _Pragma("unroll") for (int k = 0; k < 2; ++k) \
;     dst[m][k] = *reinterpret_cast<const bf16x8*>((char*)shm + abase + (((b) * 2 + (h)) * 16384 + (m * 2 + k) * 1024))
; #define LDB(dst, b, h) _Pragma("unroll") for (int n = 0; n < 2; ++n) _Pragma("unroll") for (int k = 0; k < 2; ++k) \
;     dst[n][k] = *reinterpret_cast<const bf16x8*>((char*)shm + bbase + (((b) * 2 + (h)) * 16384 + (n * 2 + k) * 1024))
; template <bool SWAP>
; __device__ __forceinline__ void gemm_main(const u16* __restrict__ A, const u16* __restrict__ Bt, int brow, int bcol,
;                                           u16* shm, f32x4 (&acc)[2][2][4][2]) {
;     ...
;     LDA(At, 0, 1); WAIT_V(4); BAR; WAIT_L(0); MMA(1, 0, At, B0); MMA(1, 1, At, B1); BAR; }
;   { LDB(B0, 1, 0); LDA(At, 1, 0); WAIT_V(2); BAR; WAIT_L(0); MMA(0, 0, At, B0); BAR;
;     LDB(B1, 1, 1); WAIT_V(0); BAR; WAIT_L(0); MMA(0, 1, At, B1); BAR;
;     LDA(At, 1, 1); BAR; WAIT_L(0); MMA(1, 0, At, B0); MMA(1, 1, At, B1); BAR; }
;   if (wr == 0) BAR;
	s_waitcnt lgkmcnt(0)
	s_setprio 1
	s_waitcnt lgkmcnt(0)
	v_mfma_f32_16x16x32_bf16 v[72:75], v[0:3], v[32:35], v[124:127]
	v_mfma_f32_16x16x32_bf16 v[120:123], v[8:11], v[40:43], v[72:75]
	v_mfma_f32_16x16x32_bf16 v[72:75], v[16:19], v[32:35], v[146:149]
	v_mfma_f32_16x16x32_bf16 v[124:127], v[24:27], v[40:43], v[72:75]
	v_mfma_f32_16x16x32_bf16 v[72:75], v[0:3], v[48:51], v[116:119]
	v_mfma_f32_16x16x32_bf16 v[112:115], v[8:11], v[56:59], v[72:75]
	v_mfma_f32_16x16x32_bf16 v[72:75], v[16:19], v[48:51], v[186:189]
	v_mfma_f32_16x16x32_bf16 v[116:119], v[24:27], v[56:59], v[72:75]
	v_mfma_f32_16x16x32_bf16 v[72:75], v[0:3], v[64:67], v[108:111]
	v_mfma_f32_16x16x32_bf16 v[104:107], v[8:11], v[174:177], v[72:75]
	v_mfma_f32_16x16x32_bf16 v[72:75], v[16:19], v[64:67], v[194:197]
	v_mfma_f32_16x16x32_bf16 v[108:111], v[24:27], v[174:177], v[72:75]
	v_mfma_f32_16x16x32_bf16 v[72:75], v[0:3], v[178:181], v[100:103]
	v_mfma_f32_16x16x32_bf16 v[96:99], v[8:11], v[182:185], v[72:75]
	v_mfma_f32_16x16x32_bf16 v[72:75], v[16:19], v[178:181], v[198:201]
	v_mfma_f32_16x16x32_bf16 v[100:103], v[24:27], v[182:185], v[72:75]
	s_setprio 0
	s_barrier
	ds_read_b128 v[146:149], v140 offset:49152
	ds_read_b128 v[186:189], v140 offset:50176
	ds_read_b128 v[194:197], v140 offset:51200
	ds_read_b128 v[198:201], v140 offset:52224
	s_waitcnt vmcnt(0)
	s_barrier
	s_waitcnt lgkmcnt(0)
	s_setprio 1
	s_waitcnt lgkmcnt(0)
	v_mfma_f32_16x16x32_bf16 v[72:75], v[146:149], v[32:35], v[92:95]
	v_mfma_f32_16x16x32_bf16 v[32:35], v[194:197], v[32:35], v[154:157]
	v_mfma_f32_16x16x32_bf16 v[92:95], v[198:201], v[40:43], v[32:35]
	v_mfma_f32_16x16x32_bf16 v[32:35], v[146:149], v[48:51], v[84:87]
	v_mfma_f32_16x16x32_bf16 v[80:83], v[186:189], v[56:59], v[32:35]
	v_mfma_f32_16x16x32_bf16 v[32:35], v[194:197], v[48:51], v[158:161]
	v_mfma_f32_16x16x32_bf16 v[84:87], v[198:201], v[56:59], v[32:35]
	v_mfma_f32_16x16x32_bf16 v[32:35], v[146:149], v[64:67], v[76:79]
	v_mfma_f32_16x16x32_bf16 v[88:91], v[186:189], v[40:43], v[72:75]
	v_mfma_f32_16x16x32_bf16 v[72:75], v[186:189], v[174:177], v[32:35]
	v_mfma_f32_16x16x32_bf16 v[32:35], v[194:197], v[64:67], v[162:165]
	v_mfma_f32_16x16x32_bf16 v[76:79], v[198:201], v[174:177], v[32:35]
	v_mfma_f32_16x16x32_bf16 v[32:35], v[146:149], v[178:181], v[68:71]
	v_mfma_f32_16x16x32_bf16 v[64:67], v[186:189], v[182:185], v[32:35]
	v_mfma_f32_16x16x32_bf16 v[32:35], v[194:197], v[178:181], v[166:169]
	v_mfma_f32_16x16x32_bf16 v[68:71], v[198:201], v[182:185], v[32:35]
	s_setprio 0
	s_barrier
	ds_read_b128 v[154:157], v139 offset:49152
	ds_read_b128 v[158:161], v139 offset:50176
	ds_read_b128 v[162:165], v139 offset:51200
	ds_read_b128 v[166:169], v139 offset:52224
	ds_read_b128 v[174:177], v139 offset:53248
	ds_read_b128 v[178:181], v139 offset:54272
	ds_read_b128 v[182:185], v139 offset:55296
	ds_read_b128 v[228:231], v139 offset:56320
	s_barrier
	s_waitcnt lgkmcnt(0)
	s_setprio 1
	s_waitcnt lgkmcnt(0)
	v_mfma_f32_16x16x32_bf16 v[32:35], v[0:3], v[154:157], v[60:63]
	v_mfma_f32_16x16x32_bf16 v[56:59], v[8:11], v[158:161], v[32:35]
	v_mfma_f32_16x16x32_bf16 v[32:35], v[16:19], v[154:157], v[202:205]
	v_mfma_f32_16x16x32_bf16 v[60:63], v[24:27], v[158:161], v[32:35]
	v_mfma_f32_16x16x32_bf16 v[32:35], v[0:3], v[162:165], v[52:55]
	v_mfma_f32_16x16x32_bf16 v[48:51], v[8:11], v[166:169], v[32:35]
	v_mfma_f32_16x16x32_bf16 v[32:35], v[16:19], v[162:165], v[206:209]
	v_mfma_f32_16x16x32_bf16 v[52:55], v[24:27], v[166:169], v[32:35]
	v_mfma_f32_16x16x32_bf16 v[32:35], v[0:3], v[174:177], v[44:47]
	v_mfma_f32_16x16x32_bf16 v[40:43], v[8:11], v[178:181], v[32:35]
	v_mfma_f32_16x16x32_bf16 v[32:35], v[16:19], v[174:177], v[224:227]
	v_mfma_f32_16x16x32_bf16 v[0:3], v[0:3], v[182:185], v[36:39]
	v_mfma_f32_16x16x32_bf16 v[44:47], v[24:27], v[178:181], v[32:35]
	v_mfma_f32_16x16x32_bf16 v[32:35], v[8:11], v[228:231], v[0:3]
	v_mfma_f32_16x16x32_bf16 v[0:3], v[16:19], v[182:185], v[128:131]
	v_mfma_f32_16x16x32_bf16 v[36:39], v[24:27], v[228:231], v[0:3]
	s_setprio 0
	s_setprio 1
	v_mfma_f32_16x16x32_bf16 v[0:3], v[146:149], v[154:157], v[28:31]
	v_mfma_f32_16x16x32_bf16 v[24:27], v[186:189], v[158:161], v[0:3]
	v_mfma_f32_16x16x32_bf16 v[0:3], v[194:197], v[154:157], v[132:135]
	v_mfma_f32_16x16x32_bf16 v[28:31], v[198:201], v[158:161], v[0:3]
	v_mfma_f32_16x16x32_bf16 v[0:3], v[146:149], v[162:165], v[20:23]
	v_mfma_f32_16x16x32_bf16 v[16:19], v[186:189], v[166:169], v[0:3]
	v_mfma_f32_16x16x32_bf16 v[0:3], v[194:197], v[162:165], v[142:145]
	v_mfma_f32_16x16x32_bf16 v[20:23], v[198:201], v[166:169], v[0:3]
	v_mfma_f32_16x16x32_bf16 v[0:3], v[146:149], v[174:177], v[12:15]
	v_mfma_f32_16x16x32_bf16 v[8:11], v[186:189], v[178:181], v[0:3]
	v_mfma_f32_16x16x32_bf16 v[0:3], v[194:197], v[174:177], v[150:153]
	v_mfma_f32_16x16x32_bf16 v[12:15], v[198:201], v[178:181], v[0:3]
	v_mfma_f32_16x16x32_bf16 v[0:3], v[146:149], v[182:185], v[4:7]
	v_mfma_f32_16x16x32_bf16 v[4:7], v[194:197], v[182:185], v[170:173]
	v_mfma_f32_16x16x32_bf16 v[0:3], v[186:189], v[228:231], v[0:3]
	v_mfma_f32_16x16x32_bf16 v[4:7], v[198:201], v[228:231], v[4:7]
	s_setprio 0
	s_movk_i32 s4, 0x100
	v_cmp_gt_u32_e32 vcc, s4, v138
	s_barrier
	s_and_saveexec_b64 s[4:5], vcc
	s_cbranch_execz .LBB0_630
	s_barrier
